# v7 + win GEMM k-loops (both variants, both layers) re-emitted with v_mfma_f32_16x16x32_bf16, 8 fragment slots
# speedup vs baseline: 1.0041x; 1.0041x over previous
.LBB0_227:
.LBB0_228:
	s_cmp_gt_i32 s52, 2
	s_cselect_b64 s[0:1], -1, 0
	s_cmp_lt_i32 s53, 3
	s_cselect_b64 s[2:3], -1, 0
	s_or_b64 s[0:1], s[0:1], s[2:3]
	v_bfe_u32 v131, v1, 5, 1
	s_and_b64 vcc, exec, s[0:1]
	v_lshrrev_b32_e32 v133, 7, v1
	v_and_b32_e32 v132, 31, v1
	v_lshrrev_b32_e32 v135, 9, v1
	v_lshlrev_b32_e32 v134, 3, v131
	s_cbranch_vccnz .LBB0_550
	s_add_u32 s0, s82, 0xe954000
	v_readlane_b32 s2, v248, 0
	s_addc_u32 s1, s83, 0
	s_lshr_b32 s23, s2, 3
	s_and_b32 s2, s2, 7
	s_add_i32 s3, s2, 0xfffc
	s_and_b32 s3, s3, 0xffff
	v_lshlrev_b32_e32 v4, 4, v1
	s_lshr_b32 s40, s50, 3
	s_min_u32 s41, s2, s3
	v_and_b32_e32 v82, 0x70, v4
	v_mov_b32_e32 v83, 0
	s_cmp_gt_u32 s2, 3
	v_lshrrev_b32_e32 v154, 3, v1
	v_lshl_add_u64 v[2:3], s[82:83], 0, v[82:83]
	s_mov_b64 s[2:3], 0x8400000
	v_lshl_add_u64 v[84:85], v[2:3], 0, s[2:3]
	v_add_u32_e32 v155, 32, v154
	s_mov_b64 s[2:3], 0xb100000
	v_lshl_add_u64 v[86:87], v[2:3], 0, s[2:3]
	v_lshlrev_b32_e32 v2, 6, v155
	v_add_u32_e32 v156, 64, v154
	s_movk_i32 s4, 0x1000
	v_and_b32_e32 v2, 0xfc0, v2
	v_lshrrev_b32_e32 v3, 6, v155
	v_or3_b32 v159, v3, v2, s4
	v_lshlrev_b32_e32 v2, 6, v156
	v_add_u32_e32 v157, 0x60, v154
	v_and_b32_e32 v2, 0xfc0, v2
	v_lshrrev_b32_e32 v3, 6, v156
	s_cselect_b32 s42, 48, 0
	v_or3_b32 v160, v3, v2, s4
	v_lshlrev_b32_e32 v2, 6, v157
	s_add_u32 s14, s80, 0x6000000
	v_and_b32_e32 v2, 0xfc0, v2
	v_lshrrev_b32_e32 v3, 6, v157
	s_addc_u32 s15, s81, 0
	v_or3_b32 v161, v3, v2, s4
	v_lshrrev_b32_e32 v2, 1, v1
	s_movk_i32 s2, 0x1c0
	s_add_u32 s16, s80, 0x5000000
	v_and_or_b32 v3, v2, s2, v132
	v_and_b32_e32 v2, 16, v2
	s_movk_i32 s2, 0x90
	v_and_b32_e32 v163, 0x5f, v1
	s_addc_u32 s17, s81, 0
	v_mad_u32_u24 v162, v3, s2, v2
	v_mad_u32_u24 v164, v163, s2, v2
	v_mul_u32_u24_e32 v2, 0x48, v154
	v_lshlrev_b32_e32 v88, 2, v131
	s_add_u32 s18, s80, 0x4000000
	s_movk_i32 s2, 0x1f0
	v_lshl_add_u32 v165, v2, 1, v82
	v_lshrrev_b32_e32 v246, 3, v1
	v_and_b32_e32 v246, 15, v246
	v_add_u32_e32 v246, 4, v246
	v_bfe_u32 v246, v246, 3, 1
	v_and_b32_e32 v249, 1, v1
	v_lshlrev_b32_e32 v249, 1, v249
	v_sub_u32_e32 v249, 1, v249
	v_mul_i32_i24_e32 v246, v246, v249
	v_lshlrev_b32_e32 v246, 4, v246
	v_add_u32_e32 v165, v246, v165
	s_addc_u32 s19, s81, 0
	v_and_or_b32 v2, v4, s2, v88
	v_lshlrev_b32_e32 v5, 6, v154
	v_lshlrev_b32_e32 v167, 6, v133
	s_add_u32 s20, s80, 0x3000000
	v_lshlrev_b32_e32 v82, 3, v2
	s_mul_i32 s41, s41, 11
	s_mov_b32 s13, 0
	v_or3_b32 v158, v5, v135, s4
	v_add_u32_e32 v166, 0x9000, v165
	v_or_b32_e32 v168, 0x200000, v167
	v_or_b32_e32 v90, 1, v88
	v_or_b32_e32 v92, 2, v88
	v_or_b32_e32 v94, 3, v88
	v_mov_b32_e32 v89, v83
	v_mov_b32_e32 v91, v83
	v_mov_b32_e32 v93, v83
	v_mov_b32_e32 v95, v83
	v_or_b32_e32 v96, 8, v88
	v_mov_b32_e32 v97, v83
	v_or_b32_e32 v98, 9, v88
	v_mov_b32_e32 v99, v83
	v_or_b32_e32 v100, 10, v88
	v_mov_b32_e32 v101, v83
	v_or_b32_e32 v102, 11, v88
	v_mov_b32_e32 v103, v83
	v_or_b32_e32 v104, 16, v88
	v_mov_b32_e32 v105, v83
	v_or_b32_e32 v106, 17, v88
	v_mov_b32_e32 v107, v83
	v_or_b32_e32 v108, 18, v88
	v_mov_b32_e32 v109, v83
	v_or_b32_e32 v110, 19, v88
	v_mov_b32_e32 v111, v83
	v_or_b32_e32 v112, 24, v88
	v_mov_b32_e32 v113, v83
	v_or_b32_e32 v114, 25, v88
	v_mov_b32_e32 v115, v83
	v_or_b32_e32 v116, 26, v88
	v_mov_b32_e32 v117, v83
	v_or_b32_e32 v118, 27, v88
	v_mov_b32_e32 v119, v83
	s_addc_u32 s21, s81, 0
	v_lshl_add_u64 v[120:121], s[0:1], 0, v[82:83]
	v_or_b32_e32 v169, 32, v88
	s_movk_i32 s43, 0x3f0
	s_mov_b32 s22, 0x3e38aa3b
	s_mov_b64 s[24:25], 0x200000
	v_mov_b32_e32 v170, 0x200000
	v_mov_b32_e32 v171, 0x200020
	s_branch .LBB0_232

.LBB0_257:
	v_ashrrev_i32_e32 v3, 31, v2
	v_lshlrev_b64 v[2:3], 11, v[2:3]
	v_lshl_add_u64 v[70:71], v[86:87], 0, v[2:3]
	v_or_b32_e32 v2, s56, v154
	v_ashrrev_i32_e32 v3, 31, v2
	v_lshlrev_b64 v[2:3], 11, v[2:3]
	v_lshl_add_u64 v[72:73], v[84:85], 0, v[2:3]
	v_add_u32_e32 v2, s56, v155
	v_ashrrev_i32_e32 v3, 31, v2
	v_lshlrev_b64 v[2:3], 11, v[2:3]
	v_lshl_add_u64 v[74:75], v[84:85], 0, v[2:3]
	v_add_u32_e32 v2, s56, v156
	v_ashrrev_i32_e32 v3, 31, v2
	v_lshlrev_b64 v[2:3], 11, v[2:3]
	v_lshl_add_u64 v[76:77], v[84:85], 0, v[2:3]
	v_add_u32_e32 v2, s56, v157
	v_ashrrev_i32_e32 v3, 31, v2
	v_ashrrev_i32_e32 v9, 31, v8
	v_ashrrev_i32_e32 v5, 31, v4
	v_lshlrev_b64 v[2:3], 11, v[2:3]
	v_ashrrev_i32_e32 v7, 31, v6
	v_lshlrev_b64 v[8:9], 11, v[8:9]
	v_lshlrev_b64 v[4:5], 11, v[4:5]
	v_lshl_add_u64 v[78:79], v[84:85], 0, v[2:3]
	v_lshlrev_b64 v[2:3], 11, v[6:7]
	v_lshl_add_u64 v[66:67], v[86:87], 0, v[8:9]
	v_lshl_add_u64 v[68:69], v[86:87], 0, v[4:5]
	v_lshl_add_u64 v[80:81], v[86:87], 0, v[2:3]
	global_load_dwordx4 v[2:5], v[70:71], off
	global_load_dwordx4 v[6:9], v[68:69], off
	global_load_dwordx4 v[10:13], v[66:67], off
	global_load_dwordx4 v[14:17], v[80:81], off
	global_load_dwordx4 v[18:21], v[72:73], off
	global_load_dwordx4 v[22:25], v[74:75], off
	global_load_dwordx4 v[26:29], v[76:77], off
	global_load_dwordx4 v[30:33], v[78:79], off
	global_load_dwordx4 v[122:125], v[70:71], off offset:128
	global_load_dwordx4 v[126:129], v[68:69], off offset:128
	global_load_dwordx4 v[136:139], v[66:67], off offset:128
	global_load_dwordx4 v[140:143], v[80:81], off offset:128
	global_load_dwordx4 v[144:147], v[72:73], off offset:128
	global_load_dwordx4 v[148:151], v[74:75], off offset:128
	global_load_dwordx4 v[172:175], v[76:77], off offset:128
	global_load_dwordx4 v[176:179], v[78:79], off offset:128
	s_waitcnt vmcnt(15)
	ds_write_b128 v165, v[2:5] offset:36864
	s_waitcnt vmcnt(14)
	ds_write_b128 v165, v[6:9] offset:41472
	s_waitcnt vmcnt(13)
	ds_write_b128 v165, v[10:13] offset:46080
	s_waitcnt vmcnt(12)
	ds_write_b128 v165, v[14:17] offset:50688
	s_waitcnt vmcnt(11)
	ds_write_b128 v165, v[18:21]
	s_waitcnt vmcnt(10)
	ds_write_b128 v165, v[22:25] offset:4608
	s_waitcnt vmcnt(9)
	ds_write_b128 v165, v[26:29] offset:9216
	s_waitcnt vmcnt(8)
	ds_write_b128 v165, v[30:33] offset:13824
	s_waitcnt lgkmcnt(0)
	s_barrier
	global_load_dwordx4 v[180:183], v[74:75], off offset:256
	global_load_dwordx4 v[184:187], v[76:77], off offset:256
	global_load_dwordx4 v[188:191], v[72:73], off offset:256
	global_load_dwordx4 v[192:195], v[70:71], off offset:256
	global_load_dwordx4 v[196:199], v[68:69], off offset:256
	global_load_dwordx4 v[200:203], v[66:67], off offset:256
	global_load_dwordx4 v[204:207], v[78:79], off offset:256
	global_load_dwordx4 v[208:211], v[80:81], off offset:256
	v_and_b32_e32 v246, 15, v1
	v_add_u32_e32 v246, 4, v246
	v_bfe_u32 v246, v246, 3, 1
	v_bfe_u32 v249, v1, 4, 2
	v_xor_b32_e32 v246, v246, v249
	v_bfe_u32 v249, v1, 5, 1
	v_sub_u32_e32 v246, v246, v249
	v_lshlrev_b32_e32 v246, 4, v246
	v_bfe_u32 v249, v1, 4, 1
	v_mul_u32_u24_e32 v249, 0x900, v249
	v_sub_u32_e32 v246, v246, v249
	v_add_u32_e32 v244, v246, v162
	v_add_u32_e32 v245, v246, v164
	ds_read_b128 v[228:231], v245 offset:36864
	ds_read_b128 v[212:215], v244
	ds_read_b128 v[236:239], v245 offset:39168
	ds_read_b128 v[240:243], v245 offset:41472
	ds_read_b128 v[252:255], v245 offset:43776
	ds_read_b128 v[216:219], v244 offset:2304
	ds_read_b128 v[220:223], v244 offset:4608
	ds_read_b128 v[224:227], v244 offset:6912
	s_waitcnt lgkmcnt(6)
	v_mfma_f32_16x16x32_bf16 v[50:53], v[212:215], v[228:231], 0
	s_waitcnt lgkmcnt(5)
	v_mfma_f32_16x16x32_bf16 v[54:57], v[212:215], v[236:239], 0
	s_waitcnt lgkmcnt(4)
	v_mfma_f32_16x16x32_bf16 v[34:37], v[212:215], v[240:243], 0
	s_waitcnt lgkmcnt(3)
	v_mfma_f32_16x16x32_bf16 v[38:41], v[212:215], v[252:255], 0
	ds_read_b128 v[212:215], v244 offset:64
	s_waitcnt lgkmcnt(3)
	v_mfma_f32_16x16x32_bf16 v[58:61], v[216:219], v[228:231], 0
	v_mfma_f32_16x16x32_bf16 v[62:65], v[216:219], v[236:239], 0
	v_mfma_f32_16x16x32_bf16 v[42:45], v[216:219], v[240:243], 0
	v_mfma_f32_16x16x32_bf16 v[46:49], v[216:219], v[252:255], 0
	ds_read_b128 v[216:219], v244 offset:2368
	s_waitcnt vmcnt(11)
	ds_write_b128 v165, v[144:147] offset:18432
	s_waitcnt vmcnt(10)
	ds_write_b128 v165, v[148:151] offset:23040
	s_waitcnt lgkmcnt(5)
	v_mfma_f32_16x16x32_bf16 v[18:21], v[220:223], v[228:231], 0
	v_mfma_f32_16x16x32_bf16 v[22:25], v[220:223], v[236:239], 0
	v_mfma_f32_16x16x32_bf16 v[2:5], v[220:223], v[240:243], 0
	v_mfma_f32_16x16x32_bf16 v[6:9], v[220:223], v[252:255], 0
	ds_read_b128 v[220:223], v244 offset:4672
	s_waitcnt vmcnt(9)
	ds_write_b128 v165, v[172:175] offset:27648
	s_waitcnt vmcnt(8)
	ds_write_b128 v165, v[176:179] offset:32256
	s_waitcnt lgkmcnt(7)
	v_mfma_f32_16x16x32_bf16 v[26:29], v[224:227], v[228:231], 0
	ds_read_b128 v[228:231], v245 offset:36928
	v_mfma_f32_16x16x32_bf16 v[30:33], v[224:227], v[236:239], 0
	ds_read_b128 v[236:239], v245 offset:39232
	v_mfma_f32_16x16x32_bf16 v[10:13], v[224:227], v[240:243], 0
	ds_read_b128 v[240:243], v245 offset:41536
	v_mfma_f32_16x16x32_bf16 v[14:17], v[224:227], v[252:255], 0
	ds_read_b128 v[252:255], v245 offset:43840
	ds_read_b128 v[224:227], v244 offset:6976
	s_waitcnt lgkmcnt(4)
	v_mfma_f32_16x16x32_bf16 v[50:53], v[212:215], v[228:231], v[50:53]
	s_waitcnt lgkmcnt(3)
	v_mfma_f32_16x16x32_bf16 v[54:57], v[212:215], v[236:239], v[54:57]
	s_waitcnt lgkmcnt(2)
	v_mfma_f32_16x16x32_bf16 v[34:37], v[212:215], v[240:243], v[34:37]
	s_waitcnt lgkmcnt(1)
	v_mfma_f32_16x16x32_bf16 v[38:41], v[212:215], v[252:255], v[38:41]
	ds_write_b128 v165, v[122:125] offset:55296
	ds_write_b128 v165, v[126:129] offset:59904
	v_mfma_f32_16x16x32_bf16 v[58:61], v[216:219], v[228:231], v[58:61]
	v_mfma_f32_16x16x32_bf16 v[62:65], v[216:219], v[236:239], v[62:65]
	v_mfma_f32_16x16x32_bf16 v[42:45], v[216:219], v[240:243], v[42:45]
	v_mfma_f32_16x16x32_bf16 v[46:49], v[216:219], v[252:255], v[46:49]
	ds_write_b128 v165, v[136:139] offset:64512
	ds_write_b128 v166, v[140:143] offset:32256
	v_mfma_f32_16x16x32_bf16 v[18:21], v[220:223], v[228:231], v[18:21]
	v_mfma_f32_16x16x32_bf16 v[22:25], v[220:223], v[236:239], v[22:25]
	v_mfma_f32_16x16x32_bf16 v[2:5], v[220:223], v[240:243], v[2:5]
	v_mfma_f32_16x16x32_bf16 v[6:9], v[220:223], v[252:255], v[6:9]
	s_waitcnt lgkmcnt(4)
	v_mfma_f32_16x16x32_bf16 v[26:29], v[224:227], v[228:231], v[26:29]
	v_mfma_f32_16x16x32_bf16 v[30:33], v[224:227], v[236:239], v[30:33]
	v_mfma_f32_16x16x32_bf16 v[10:13], v[224:227], v[240:243], v[10:13]
	v_mfma_f32_16x16x32_bf16 v[14:17], v[224:227], v[252:255], v[14:17]
	s_waitcnt lgkmcnt(0)
	s_barrier
	global_load_dwordx4 v[122:125], v[72:73], off offset:384
	global_load_dwordx4 v[126:129], v[74:75], off offset:384
	global_load_dwordx4 v[136:139], v[76:77], off offset:384
	global_load_dwordx4 v[140:143], v[78:79], off offset:384
	global_load_dwordx4 v[144:147], v[70:71], off offset:384
	global_load_dwordx4 v[148:151], v[68:69], off offset:384
	global_load_dwordx4 v[172:175], v[66:67], off offset:384
	global_load_dwordx4 v[176:179], v[80:81], off offset:384
	ds_read_b128 v[228:231], v245 offset:55296
	ds_read_b128 v[212:215], v244 offset:18432
	ds_read_b128 v[236:239], v245 offset:57600
	ds_read_b128 v[240:243], v245 offset:59904
	ds_read_b128 v[252:255], v245 offset:62208
	ds_read_b128 v[216:219], v244 offset:20736
	ds_read_b128 v[220:223], v244 offset:23040
	ds_read_b128 v[224:227], v244 offset:25344
	s_waitcnt lgkmcnt(6)
	v_mfma_f32_16x16x32_bf16 v[50:53], v[212:215], v[228:231], v[50:53]
	s_waitcnt lgkmcnt(5)
	v_mfma_f32_16x16x32_bf16 v[54:57], v[212:215], v[236:239], v[54:57]
	s_waitcnt lgkmcnt(4)
	v_mfma_f32_16x16x32_bf16 v[34:37], v[212:215], v[240:243], v[34:37]
	s_waitcnt lgkmcnt(3)
	v_mfma_f32_16x16x32_bf16 v[38:41], v[212:215], v[252:255], v[38:41]
	ds_read_b128 v[212:215], v244 offset:18496
	s_waitcnt lgkmcnt(3)
	v_mfma_f32_16x16x32_bf16 v[58:61], v[216:219], v[228:231], v[58:61]
	v_mfma_f32_16x16x32_bf16 v[62:65], v[216:219], v[236:239], v[62:65]
	v_mfma_f32_16x16x32_bf16 v[42:45], v[216:219], v[240:243], v[42:45]
	v_mfma_f32_16x16x32_bf16 v[46:49], v[216:219], v[252:255], v[46:49]
	ds_read_b128 v[216:219], v244 offset:20800
	s_waitcnt vmcnt(13)
	ds_write_b128 v165, v[188:191]
	ds_write_b128 v165, v[180:183] offset:4608
	s_waitcnt lgkmcnt(5)
	v_mfma_f32_16x16x32_bf16 v[18:21], v[220:223], v[228:231], v[18:21]
	v_mfma_f32_16x16x32_bf16 v[22:25], v[220:223], v[236:239], v[22:25]
	v_mfma_f32_16x16x32_bf16 v[2:5], v[220:223], v[240:243], v[2:5]
	v_mfma_f32_16x16x32_bf16 v[6:9], v[220:223], v[252:255], v[6:9]
	ds_read_b128 v[220:223], v244 offset:23104
	ds_write_b128 v165, v[184:187] offset:9216
	s_waitcnt vmcnt(9)
	ds_write_b128 v165, v[204:207] offset:13824
	s_waitcnt lgkmcnt(7)
	v_mfma_f32_16x16x32_bf16 v[26:29], v[224:227], v[228:231], v[26:29]
	ds_read_b128 v[228:231], v245 offset:55360
	v_mfma_f32_16x16x32_bf16 v[30:33], v[224:227], v[236:239], v[30:33]
	ds_read_b128 v[236:239], v245 offset:57664
	v_mfma_f32_16x16x32_bf16 v[10:13], v[224:227], v[240:243], v[10:13]
	ds_read_b128 v[240:243], v245 offset:59968
	v_mfma_f32_16x16x32_bf16 v[14:17], v[224:227], v[252:255], v[14:17]
	ds_read_b128 v[252:255], v245 offset:62272
	ds_read_b128 v[224:227], v244 offset:25408
	s_waitcnt lgkmcnt(4)
	v_mfma_f32_16x16x32_bf16 v[50:53], v[212:215], v[228:231], v[50:53]
	s_waitcnt lgkmcnt(3)
	v_mfma_f32_16x16x32_bf16 v[54:57], v[212:215], v[236:239], v[54:57]
	s_waitcnt lgkmcnt(2)
	v_mfma_f32_16x16x32_bf16 v[34:37], v[212:215], v[240:243], v[34:37]
	s_waitcnt lgkmcnt(1)
	v_mfma_f32_16x16x32_bf16 v[38:41], v[212:215], v[252:255], v[38:41]
	ds_write_b128 v165, v[192:195] offset:36864
	ds_write_b128 v165, v[196:199] offset:41472
	v_mfma_f32_16x16x32_bf16 v[58:61], v[216:219], v[228:231], v[58:61]
	v_mfma_f32_16x16x32_bf16 v[62:65], v[216:219], v[236:239], v[62:65]
	v_mfma_f32_16x16x32_bf16 v[42:45], v[216:219], v[240:243], v[42:45]
	v_mfma_f32_16x16x32_bf16 v[46:49], v[216:219], v[252:255], v[46:49]
	ds_write_b128 v165, v[200:203] offset:46080
	s_waitcnt vmcnt(8)
	ds_write_b128 v165, v[208:211] offset:50688
	v_mfma_f32_16x16x32_bf16 v[18:21], v[220:223], v[228:231], v[18:21]
	v_mfma_f32_16x16x32_bf16 v[22:25], v[220:223], v[236:239], v[22:25]
	v_mfma_f32_16x16x32_bf16 v[2:5], v[220:223], v[240:243], v[2:5]
	v_mfma_f32_16x16x32_bf16 v[6:9], v[220:223], v[252:255], v[6:9]
	s_waitcnt lgkmcnt(4)
	v_mfma_f32_16x16x32_bf16 v[26:29], v[224:227], v[228:231], v[26:29]
	v_mfma_f32_16x16x32_bf16 v[30:33], v[224:227], v[236:239], v[30:33]
	v_mfma_f32_16x16x32_bf16 v[10:13], v[224:227], v[240:243], v[10:13]
	v_mfma_f32_16x16x32_bf16 v[14:17], v[224:227], v[252:255], v[14:17]
	s_waitcnt lgkmcnt(0)
	s_barrier
	global_load_dwordx4 v[180:183], v[72:73], off offset:512
	global_load_dwordx4 v[184:187], v[74:75], off offset:512
	global_load_dwordx4 v[188:191], v[76:77], off offset:512
	global_load_dwordx4 v[192:195], v[78:79], off offset:512
	global_load_dwordx4 v[196:199], v[70:71], off offset:512
	global_load_dwordx4 v[200:203], v[68:69], off offset:512
	global_load_dwordx4 v[204:207], v[66:67], off offset:512
	global_load_dwordx4 v[208:211], v[80:81], off offset:512
	ds_read_b128 v[228:231], v245 offset:36864
	ds_read_b128 v[212:215], v244
	ds_read_b128 v[236:239], v245 offset:39168
	ds_read_b128 v[240:243], v245 offset:41472
	ds_read_b128 v[252:255], v245 offset:43776
	ds_read_b128 v[216:219], v244 offset:2304
	ds_read_b128 v[220:223], v244 offset:4608
	ds_read_b128 v[224:227], v244 offset:6912
	s_waitcnt lgkmcnt(6)
	v_mfma_f32_16x16x32_bf16 v[50:53], v[212:215], v[228:231], v[50:53]
	s_waitcnt lgkmcnt(5)
	v_mfma_f32_16x16x32_bf16 v[54:57], v[212:215], v[236:239], v[54:57]
	s_waitcnt lgkmcnt(4)
	v_mfma_f32_16x16x32_bf16 v[34:37], v[212:215], v[240:243], v[34:37]
	s_waitcnt lgkmcnt(3)
	v_mfma_f32_16x16x32_bf16 v[38:41], v[212:215], v[252:255], v[38:41]
	ds_read_b128 v[212:215], v244 offset:64
	s_waitcnt lgkmcnt(3)
	v_mfma_f32_16x16x32_bf16 v[58:61], v[216:219], v[228:231], v[58:61]
	v_mfma_f32_16x16x32_bf16 v[62:65], v[216:219], v[236:239], v[62:65]
	v_mfma_f32_16x16x32_bf16 v[42:45], v[216:219], v[240:243], v[42:45]
	v_mfma_f32_16x16x32_bf16 v[46:49], v[216:219], v[252:255], v[46:49]
	ds_read_b128 v[216:219], v244 offset:2368
	s_waitcnt vmcnt(15)
	ds_write_b128 v165, v[122:125] offset:18432
	s_waitcnt vmcnt(14)
	ds_write_b128 v165, v[126:129] offset:23040
	s_waitcnt lgkmcnt(5)
	v_mfma_f32_16x16x32_bf16 v[18:21], v[220:223], v[228:231], v[18:21]
	v_mfma_f32_16x16x32_bf16 v[22:25], v[220:223], v[236:239], v[22:25]
	v_mfma_f32_16x16x32_bf16 v[2:5], v[220:223], v[240:243], v[2:5]
	v_mfma_f32_16x16x32_bf16 v[6:9], v[220:223], v[252:255], v[6:9]
	ds_read_b128 v[220:223], v244 offset:4672
	s_waitcnt vmcnt(13)
	ds_write_b128 v165, v[136:139] offset:27648
	s_waitcnt vmcnt(12)
	ds_write_b128 v165, v[140:143] offset:32256
	s_waitcnt lgkmcnt(7)
	v_mfma_f32_16x16x32_bf16 v[26:29], v[224:227], v[228:231], v[26:29]
	ds_read_b128 v[228:231], v245 offset:36928
	v_mfma_f32_16x16x32_bf16 v[30:33], v[224:227], v[236:239], v[30:33]
	ds_read_b128 v[236:239], v245 offset:39232
	v_mfma_f32_16x16x32_bf16 v[10:13], v[224:227], v[240:243], v[10:13]
	ds_read_b128 v[240:243], v245 offset:41536
	v_mfma_f32_16x16x32_bf16 v[14:17], v[224:227], v[252:255], v[14:17]
	ds_read_b128 v[252:255], v245 offset:43840
	ds_read_b128 v[224:227], v244 offset:6976
	s_waitcnt lgkmcnt(4)
	v_mfma_f32_16x16x32_bf16 v[50:53], v[212:215], v[228:231], v[50:53]
	s_waitcnt lgkmcnt(3)
	v_mfma_f32_16x16x32_bf16 v[54:57], v[212:215], v[236:239], v[54:57]
	s_waitcnt lgkmcnt(2)
	v_mfma_f32_16x16x32_bf16 v[34:37], v[212:215], v[240:243], v[34:37]
	s_waitcnt lgkmcnt(1)
	v_mfma_f32_16x16x32_bf16 v[38:41], v[212:215], v[252:255], v[38:41]
	s_waitcnt vmcnt(11)
	ds_write_b128 v165, v[144:147] offset:55296
	s_waitcnt vmcnt(10)
	ds_write_b128 v165, v[148:151] offset:59904
	v_mfma_f32_16x16x32_bf16 v[58:61], v[216:219], v[228:231], v[58:61]
	v_mfma_f32_16x16x32_bf16 v[62:65], v[216:219], v[236:239], v[62:65]
	v_mfma_f32_16x16x32_bf16 v[42:45], v[216:219], v[240:243], v[42:45]
	v_mfma_f32_16x16x32_bf16 v[46:49], v[216:219], v[252:255], v[46:49]
	s_waitcnt vmcnt(9)
	ds_write_b128 v165, v[172:175] offset:64512
	s_waitcnt vmcnt(8)
	ds_write_b128 v166, v[176:179] offset:32256
	v_mfma_f32_16x16x32_bf16 v[18:21], v[220:223], v[228:231], v[18:21]
	v_mfma_f32_16x16x32_bf16 v[22:25], v[220:223], v[236:239], v[22:25]
	v_mfma_f32_16x16x32_bf16 v[2:5], v[220:223], v[240:243], v[2:5]
	v_mfma_f32_16x16x32_bf16 v[6:9], v[220:223], v[252:255], v[6:9]
	s_waitcnt lgkmcnt(4)
	v_mfma_f32_16x16x32_bf16 v[26:29], v[224:227], v[228:231], v[26:29]
	v_mfma_f32_16x16x32_bf16 v[30:33], v[224:227], v[236:239], v[30:33]
	v_mfma_f32_16x16x32_bf16 v[10:13], v[224:227], v[240:243], v[10:13]
	v_mfma_f32_16x16x32_bf16 v[14:17], v[224:227], v[252:255], v[14:17]
	s_waitcnt lgkmcnt(0)
	s_barrier
	global_load_dwordx4 v[122:125], v[72:73], off offset:640
	global_load_dwordx4 v[126:129], v[74:75], off offset:640
	global_load_dwordx4 v[136:139], v[76:77], off offset:640
	global_load_dwordx4 v[140:143], v[78:79], off offset:640
	global_load_dwordx4 v[144:147], v[70:71], off offset:640
	global_load_dwordx4 v[148:151], v[68:69], off offset:640
	global_load_dwordx4 v[172:175], v[66:67], off offset:640
	global_load_dwordx4 v[176:179], v[80:81], off offset:640
	ds_read_b128 v[228:231], v245 offset:55296
	ds_read_b128 v[212:215], v244 offset:18432
	ds_read_b128 v[236:239], v245 offset:57600
	ds_read_b128 v[240:243], v245 offset:59904
	ds_read_b128 v[252:255], v245 offset:62208
	ds_read_b128 v[216:219], v244 offset:20736
	ds_read_b128 v[220:223], v244 offset:23040
	ds_read_b128 v[224:227], v244 offset:25344
	s_waitcnt lgkmcnt(6)
	v_mfma_f32_16x16x32_bf16 v[50:53], v[212:215], v[228:231], v[50:53]
	s_waitcnt lgkmcnt(5)
	v_mfma_f32_16x16x32_bf16 v[54:57], v[212:215], v[236:239], v[54:57]
	s_waitcnt lgkmcnt(4)
	v_mfma_f32_16x16x32_bf16 v[34:37], v[212:215], v[240:243], v[34:37]
	s_waitcnt lgkmcnt(3)
	v_mfma_f32_16x16x32_bf16 v[38:41], v[212:215], v[252:255], v[38:41]
	ds_read_b128 v[212:215], v244 offset:18496
	s_waitcnt lgkmcnt(3)
	v_mfma_f32_16x16x32_bf16 v[58:61], v[216:219], v[228:231], v[58:61]
	v_mfma_f32_16x16x32_bf16 v[62:65], v[216:219], v[236:239], v[62:65]
	v_mfma_f32_16x16x32_bf16 v[42:45], v[216:219], v[240:243], v[42:45]
	v_mfma_f32_16x16x32_bf16 v[46:49], v[216:219], v[252:255], v[46:49]
	ds_read_b128 v[216:219], v244 offset:20800
	s_waitcnt vmcnt(15)
	ds_write_b128 v165, v[180:183]
	s_waitcnt vmcnt(14)
	ds_write_b128 v165, v[184:187] offset:4608
	s_waitcnt lgkmcnt(5)
	v_mfma_f32_16x16x32_bf16 v[18:21], v[220:223], v[228:231], v[18:21]
	v_mfma_f32_16x16x32_bf16 v[22:25], v[220:223], v[236:239], v[22:25]
	v_mfma_f32_16x16x32_bf16 v[2:5], v[220:223], v[240:243], v[2:5]
	v_mfma_f32_16x16x32_bf16 v[6:9], v[220:223], v[252:255], v[6:9]
	ds_read_b128 v[220:223], v244 offset:23104
	s_waitcnt vmcnt(13)
	ds_write_b128 v165, v[188:191] offset:9216
	s_waitcnt vmcnt(12)
	ds_write_b128 v165, v[192:195] offset:13824
	s_waitcnt lgkmcnt(7)
	v_mfma_f32_16x16x32_bf16 v[26:29], v[224:227], v[228:231], v[26:29]
	ds_read_b128 v[228:231], v245 offset:55360
	v_mfma_f32_16x16x32_bf16 v[30:33], v[224:227], v[236:239], v[30:33]
	ds_read_b128 v[236:239], v245 offset:57664
	v_mfma_f32_16x16x32_bf16 v[10:13], v[224:227], v[240:243], v[10:13]
	ds_read_b128 v[240:243], v245 offset:59968
	v_mfma_f32_16x16x32_bf16 v[14:17], v[224:227], v[252:255], v[14:17]
	ds_read_b128 v[252:255], v245 offset:62272
	ds_read_b128 v[224:227], v244 offset:25408
	s_waitcnt lgkmcnt(4)
	v_mfma_f32_16x16x32_bf16 v[50:53], v[212:215], v[228:231], v[50:53]
	s_waitcnt lgkmcnt(3)
	v_mfma_f32_16x16x32_bf16 v[54:57], v[212:215], v[236:239], v[54:57]
	s_waitcnt lgkmcnt(2)
	v_mfma_f32_16x16x32_bf16 v[34:37], v[212:215], v[240:243], v[34:37]
	s_waitcnt lgkmcnt(1)
	v_mfma_f32_16x16x32_bf16 v[38:41], v[212:215], v[252:255], v[38:41]
	s_waitcnt vmcnt(11)
	ds_write_b128 v165, v[196:199] offset:36864
	s_waitcnt vmcnt(10)
	ds_write_b128 v165, v[200:203] offset:41472
	v_mfma_f32_16x16x32_bf16 v[58:61], v[216:219], v[228:231], v[58:61]
	v_mfma_f32_16x16x32_bf16 v[62:65], v[216:219], v[236:239], v[62:65]
	v_mfma_f32_16x16x32_bf16 v[42:45], v[216:219], v[240:243], v[42:45]
	v_mfma_f32_16x16x32_bf16 v[46:49], v[216:219], v[252:255], v[46:49]
	s_waitcnt vmcnt(9)
	ds_write_b128 v165, v[204:207] offset:46080
	s_waitcnt vmcnt(8)
	ds_write_b128 v165, v[208:211] offset:50688
	v_mfma_f32_16x16x32_bf16 v[18:21], v[220:223], v[228:231], v[18:21]
	v_mfma_f32_16x16x32_bf16 v[22:25], v[220:223], v[236:239], v[22:25]
	v_mfma_f32_16x16x32_bf16 v[2:5], v[220:223], v[240:243], v[2:5]
	v_mfma_f32_16x16x32_bf16 v[6:9], v[220:223], v[252:255], v[6:9]
	s_waitcnt lgkmcnt(4)
	v_mfma_f32_16x16x32_bf16 v[26:29], v[224:227], v[228:231], v[26:29]
	v_mfma_f32_16x16x32_bf16 v[30:33], v[224:227], v[236:239], v[30:33]
	v_mfma_f32_16x16x32_bf16 v[10:13], v[224:227], v[240:243], v[10:13]
	v_mfma_f32_16x16x32_bf16 v[14:17], v[224:227], v[252:255], v[14:17]
	s_waitcnt lgkmcnt(0)
	s_barrier
	global_load_dwordx4 v[180:183], v[72:73], off offset:768
	global_load_dwordx4 v[184:187], v[74:75], off offset:768
	global_load_dwordx4 v[188:191], v[76:77], off offset:768
	global_load_dwordx4 v[192:195], v[78:79], off offset:768
	global_load_dwordx4 v[196:199], v[70:71], off offset:768
	global_load_dwordx4 v[200:203], v[68:69], off offset:768
	global_load_dwordx4 v[204:207], v[66:67], off offset:768
	global_load_dwordx4 v[208:211], v[80:81], off offset:768
	ds_read_b128 v[228:231], v245 offset:36864
	ds_read_b128 v[212:215], v244
	ds_read_b128 v[236:239], v245 offset:39168
	ds_read_b128 v[240:243], v245 offset:41472
	ds_read_b128 v[252:255], v245 offset:43776
	ds_read_b128 v[216:219], v244 offset:2304
	ds_read_b128 v[220:223], v244 offset:4608
	ds_read_b128 v[224:227], v244 offset:6912
	s_waitcnt lgkmcnt(6)
	v_mfma_f32_16x16x32_bf16 v[50:53], v[212:215], v[228:231], v[50:53]
	s_waitcnt lgkmcnt(5)
	v_mfma_f32_16x16x32_bf16 v[54:57], v[212:215], v[236:239], v[54:57]
	s_waitcnt lgkmcnt(4)
	v_mfma_f32_16x16x32_bf16 v[34:37], v[212:215], v[240:243], v[34:37]
	s_waitcnt lgkmcnt(3)
	v_mfma_f32_16x16x32_bf16 v[38:41], v[212:215], v[252:255], v[38:41]
	ds_read_b128 v[212:215], v244 offset:64
	s_waitcnt lgkmcnt(3)
	v_mfma_f32_16x16x32_bf16 v[58:61], v[216:219], v[228:231], v[58:61]
	v_mfma_f32_16x16x32_bf16 v[62:65], v[216:219], v[236:239], v[62:65]
	v_mfma_f32_16x16x32_bf16 v[42:45], v[216:219], v[240:243], v[42:45]
	v_mfma_f32_16x16x32_bf16 v[46:49], v[216:219], v[252:255], v[46:49]
	ds_read_b128 v[216:219], v244 offset:2368
	s_waitcnt vmcnt(15)
	ds_write_b128 v165, v[122:125] offset:18432
	s_waitcnt vmcnt(14)
	ds_write_b128 v165, v[126:129] offset:23040
	s_waitcnt lgkmcnt(5)
	v_mfma_f32_16x16x32_bf16 v[18:21], v[220:223], v[228:231], v[18:21]
	v_mfma_f32_16x16x32_bf16 v[22:25], v[220:223], v[236:239], v[22:25]
	v_mfma_f32_16x16x32_bf16 v[2:5], v[220:223], v[240:243], v[2:5]
	v_mfma_f32_16x16x32_bf16 v[6:9], v[220:223], v[252:255], v[6:9]
	ds_read_b128 v[220:223], v244 offset:4672
	s_waitcnt vmcnt(13)
	ds_write_b128 v165, v[136:139] offset:27648
	s_waitcnt vmcnt(12)
	ds_write_b128 v165, v[140:143] offset:32256
	s_waitcnt lgkmcnt(7)
	v_mfma_f32_16x16x32_bf16 v[26:29], v[224:227], v[228:231], v[26:29]
	ds_read_b128 v[228:231], v245 offset:36928
	v_mfma_f32_16x16x32_bf16 v[30:33], v[224:227], v[236:239], v[30:33]
	ds_read_b128 v[236:239], v245 offset:39232
	v_mfma_f32_16x16x32_bf16 v[10:13], v[224:227], v[240:243], v[10:13]
	ds_read_b128 v[240:243], v245 offset:41536
	v_mfma_f32_16x16x32_bf16 v[14:17], v[224:227], v[252:255], v[14:17]
	ds_read_b128 v[252:255], v245 offset:43840
	ds_read_b128 v[224:227], v244 offset:6976
	s_waitcnt lgkmcnt(4)
	v_mfma_f32_16x16x32_bf16 v[50:53], v[212:215], v[228:231], v[50:53]
	s_waitcnt lgkmcnt(3)
	v_mfma_f32_16x16x32_bf16 v[54:57], v[212:215], v[236:239], v[54:57]
	s_waitcnt lgkmcnt(2)
	v_mfma_f32_16x16x32_bf16 v[34:37], v[212:215], v[240:243], v[34:37]
	s_waitcnt lgkmcnt(1)
	v_mfma_f32_16x16x32_bf16 v[38:41], v[212:215], v[252:255], v[38:41]
	s_waitcnt vmcnt(11)
	ds_write_b128 v165, v[144:147] offset:55296
	s_waitcnt vmcnt(10)
	ds_write_b128 v165, v[148:151] offset:59904
	v_mfma_f32_16x16x32_bf16 v[58:61], v[216:219], v[228:231], v[58:61]
	v_mfma_f32_16x16x32_bf16 v[62:65], v[216:219], v[236:239], v[62:65]
	v_mfma_f32_16x16x32_bf16 v[42:45], v[216:219], v[240:243], v[42:45]
	v_mfma_f32_16x16x32_bf16 v[46:49], v[216:219], v[252:255], v[46:49]
	s_waitcnt vmcnt(9)
	ds_write_b128 v165, v[172:175] offset:64512
	s_waitcnt vmcnt(8)
	ds_write_b128 v166, v[176:179] offset:32256
	v_mfma_f32_16x16x32_bf16 v[18:21], v[220:223], v[228:231], v[18:21]
	v_mfma_f32_16x16x32_bf16 v[22:25], v[220:223], v[236:239], v[22:25]
	v_mfma_f32_16x16x32_bf16 v[2:5], v[220:223], v[240:243], v[2:5]
	v_mfma_f32_16x16x32_bf16 v[6:9], v[220:223], v[252:255], v[6:9]
	s_waitcnt lgkmcnt(4)
	v_mfma_f32_16x16x32_bf16 v[26:29], v[224:227], v[228:231], v[26:29]
	v_mfma_f32_16x16x32_bf16 v[30:33], v[224:227], v[236:239], v[30:33]
	v_mfma_f32_16x16x32_bf16 v[10:13], v[224:227], v[240:243], v[10:13]
	v_mfma_f32_16x16x32_bf16 v[14:17], v[224:227], v[252:255], v[14:17]
	s_waitcnt lgkmcnt(0)
	s_barrier
	global_load_dwordx4 v[122:125], v[72:73], off offset:896
	global_load_dwordx4 v[126:129], v[74:75], off offset:896
	global_load_dwordx4 v[136:139], v[76:77], off offset:896
	global_load_dwordx4 v[140:143], v[78:79], off offset:896
	global_load_dwordx4 v[144:147], v[70:71], off offset:896
	global_load_dwordx4 v[148:151], v[68:69], off offset:896
	global_load_dwordx4 v[172:175], v[66:67], off offset:896
	global_load_dwordx4 v[176:179], v[80:81], off offset:896
	ds_read_b128 v[228:231], v245 offset:55296
	ds_read_b128 v[212:215], v244 offset:18432
	ds_read_b128 v[236:239], v245 offset:57600
	ds_read_b128 v[240:243], v245 offset:59904
	ds_read_b128 v[252:255], v245 offset:62208
	ds_read_b128 v[216:219], v244 offset:20736
	ds_read_b128 v[220:223], v244 offset:23040
	ds_read_b128 v[224:227], v244 offset:25344
	s_waitcnt lgkmcnt(6)
	v_mfma_f32_16x16x32_bf16 v[50:53], v[212:215], v[228:231], v[50:53]
	s_waitcnt lgkmcnt(5)
	v_mfma_f32_16x16x32_bf16 v[54:57], v[212:215], v[236:239], v[54:57]
	s_waitcnt lgkmcnt(4)
	v_mfma_f32_16x16x32_bf16 v[34:37], v[212:215], v[240:243], v[34:37]
	s_waitcnt lgkmcnt(3)
	v_mfma_f32_16x16x32_bf16 v[38:41], v[212:215], v[252:255], v[38:41]
	ds_read_b128 v[212:215], v244 offset:18496
	s_waitcnt lgkmcnt(3)
	v_mfma_f32_16x16x32_bf16 v[58:61], v[216:219], v[228:231], v[58:61]
	v_mfma_f32_16x16x32_bf16 v[62:65], v[216:219], v[236:239], v[62:65]
	v_mfma_f32_16x16x32_bf16 v[42:45], v[216:219], v[240:243], v[42:45]
	v_mfma_f32_16x16x32_bf16 v[46:49], v[216:219], v[252:255], v[46:49]
	ds_read_b128 v[216:219], v244 offset:20800
	s_waitcnt vmcnt(15)
	ds_write_b128 v165, v[180:183]
	s_waitcnt vmcnt(14)
	ds_write_b128 v165, v[184:187] offset:4608
	s_waitcnt lgkmcnt(5)
	v_mfma_f32_16x16x32_bf16 v[18:21], v[220:223], v[228:231], v[18:21]
	v_mfma_f32_16x16x32_bf16 v[22:25], v[220:223], v[236:239], v[22:25]
	v_mfma_f32_16x16x32_bf16 v[2:5], v[220:223], v[240:243], v[2:5]
	v_mfma_f32_16x16x32_bf16 v[6:9], v[220:223], v[252:255], v[6:9]
	ds_read_b128 v[220:223], v244 offset:23104
	s_waitcnt vmcnt(13)
	ds_write_b128 v165, v[188:191] offset:9216
	s_waitcnt vmcnt(12)
	ds_write_b128 v165, v[192:195] offset:13824
	s_waitcnt lgkmcnt(7)
	v_mfma_f32_16x16x32_bf16 v[26:29], v[224:227], v[228:231], v[26:29]
	ds_read_b128 v[228:231], v245 offset:55360
	v_mfma_f32_16x16x32_bf16 v[30:33], v[224:227], v[236:239], v[30:33]
	ds_read_b128 v[236:239], v245 offset:57664
	v_mfma_f32_16x16x32_bf16 v[10:13], v[224:227], v[240:243], v[10:13]
	ds_read_b128 v[240:243], v245 offset:59968
	v_mfma_f32_16x16x32_bf16 v[14:17], v[224:227], v[252:255], v[14:17]
	ds_read_b128 v[252:255], v245 offset:62272
	ds_read_b128 v[224:227], v244 offset:25408
	s_waitcnt lgkmcnt(4)
	v_mfma_f32_16x16x32_bf16 v[50:53], v[212:215], v[228:231], v[50:53]
	s_waitcnt lgkmcnt(3)
	v_mfma_f32_16x16x32_bf16 v[54:57], v[212:215], v[236:239], v[54:57]
	s_waitcnt lgkmcnt(2)
	v_mfma_f32_16x16x32_bf16 v[34:37], v[212:215], v[240:243], v[34:37]
	s_waitcnt lgkmcnt(1)
	v_mfma_f32_16x16x32_bf16 v[38:41], v[212:215], v[252:255], v[38:41]
	s_waitcnt vmcnt(11)
	ds_write_b128 v165, v[196:199] offset:36864
	s_waitcnt vmcnt(10)
	ds_write_b128 v165, v[200:203] offset:41472
	v_mfma_f32_16x16x32_bf16 v[58:61], v[216:219], v[228:231], v[58:61]
	v_mfma_f32_16x16x32_bf16 v[62:65], v[216:219], v[236:239], v[62:65]
	v_mfma_f32_16x16x32_bf16 v[42:45], v[216:219], v[240:243], v[42:45]
	v_mfma_f32_16x16x32_bf16 v[46:49], v[216:219], v[252:255], v[46:49]
	s_waitcnt vmcnt(9)
	ds_write_b128 v165, v[204:207] offset:46080
	s_waitcnt vmcnt(8)
	ds_write_b128 v165, v[208:211] offset:50688
	v_mfma_f32_16x16x32_bf16 v[18:21], v[220:223], v[228:231], v[18:21]
	v_mfma_f32_16x16x32_bf16 v[22:25], v[220:223], v[236:239], v[22:25]
	v_mfma_f32_16x16x32_bf16 v[2:5], v[220:223], v[240:243], v[2:5]
	v_mfma_f32_16x16x32_bf16 v[6:9], v[220:223], v[252:255], v[6:9]
	s_waitcnt lgkmcnt(4)
	v_mfma_f32_16x16x32_bf16 v[26:29], v[224:227], v[228:231], v[26:29]
	v_mfma_f32_16x16x32_bf16 v[30:33], v[224:227], v[236:239], v[30:33]
	v_mfma_f32_16x16x32_bf16 v[10:13], v[224:227], v[240:243], v[10:13]
	v_mfma_f32_16x16x32_bf16 v[14:17], v[224:227], v[252:255], v[14:17]
	s_waitcnt lgkmcnt(0)
	s_barrier
	global_load_dwordx4 v[180:183], v[72:73], off offset:1024
	global_load_dwordx4 v[184:187], v[74:75], off offset:1024
	global_load_dwordx4 v[188:191], v[76:77], off offset:1024
	global_load_dwordx4 v[192:195], v[78:79], off offset:1024
	global_load_dwordx4 v[196:199], v[70:71], off offset:1024
	global_load_dwordx4 v[200:203], v[68:69], off offset:1024
	global_load_dwordx4 v[204:207], v[66:67], off offset:1024
	global_load_dwordx4 v[208:211], v[80:81], off offset:1024
	ds_read_b128 v[228:231], v245 offset:36864
	ds_read_b128 v[212:215], v244
	ds_read_b128 v[236:239], v245 offset:39168
	ds_read_b128 v[240:243], v245 offset:41472
	ds_read_b128 v[252:255], v245 offset:43776
	ds_read_b128 v[216:219], v244 offset:2304
	ds_read_b128 v[220:223], v244 offset:4608
	ds_read_b128 v[224:227], v244 offset:6912
	s_waitcnt lgkmcnt(6)
	v_mfma_f32_16x16x32_bf16 v[50:53], v[212:215], v[228:231], v[50:53]
	s_waitcnt lgkmcnt(5)
	v_mfma_f32_16x16x32_bf16 v[54:57], v[212:215], v[236:239], v[54:57]
	s_waitcnt lgkmcnt(4)
	v_mfma_f32_16x16x32_bf16 v[34:37], v[212:215], v[240:243], v[34:37]
	s_waitcnt lgkmcnt(3)
	v_mfma_f32_16x16x32_bf16 v[38:41], v[212:215], v[252:255], v[38:41]
	ds_read_b128 v[212:215], v244 offset:64
	s_waitcnt lgkmcnt(3)
	v_mfma_f32_16x16x32_bf16 v[58:61], v[216:219], v[228:231], v[58:61]
	v_mfma_f32_16x16x32_bf16 v[62:65], v[216:219], v[236:239], v[62:65]
	v_mfma_f32_16x16x32_bf16 v[42:45], v[216:219], v[240:243], v[42:45]
	v_mfma_f32_16x16x32_bf16 v[46:49], v[216:219], v[252:255], v[46:49]
	ds_read_b128 v[216:219], v244 offset:2368
	s_waitcnt vmcnt(15)
	ds_write_b128 v165, v[122:125] offset:18432
	s_waitcnt vmcnt(14)
	ds_write_b128 v165, v[126:129] offset:23040
	s_waitcnt lgkmcnt(5)
	v_mfma_f32_16x16x32_bf16 v[18:21], v[220:223], v[228:231], v[18:21]
	v_mfma_f32_16x16x32_bf16 v[22:25], v[220:223], v[236:239], v[22:25]
	v_mfma_f32_16x16x32_bf16 v[2:5], v[220:223], v[240:243], v[2:5]
	v_mfma_f32_16x16x32_bf16 v[6:9], v[220:223], v[252:255], v[6:9]
	ds_read_b128 v[220:223], v244 offset:4672
	s_waitcnt vmcnt(13)
	ds_write_b128 v165, v[136:139] offset:27648
	s_waitcnt vmcnt(12)
	ds_write_b128 v165, v[140:143] offset:32256
	s_waitcnt lgkmcnt(7)
	v_mfma_f32_16x16x32_bf16 v[26:29], v[224:227], v[228:231], v[26:29]
	ds_read_b128 v[228:231], v245 offset:36928
	v_mfma_f32_16x16x32_bf16 v[30:33], v[224:227], v[236:239], v[30:33]
	ds_read_b128 v[236:239], v245 offset:39232
	v_mfma_f32_16x16x32_bf16 v[10:13], v[224:227], v[240:243], v[10:13]
	ds_read_b128 v[240:243], v245 offset:41536
	v_mfma_f32_16x16x32_bf16 v[14:17], v[224:227], v[252:255], v[14:17]
	ds_read_b128 v[252:255], v245 offset:43840
	ds_read_b128 v[224:227], v244 offset:6976
	s_waitcnt lgkmcnt(4)
	v_mfma_f32_16x16x32_bf16 v[50:53], v[212:215], v[228:231], v[50:53]
	s_waitcnt lgkmcnt(3)
	v_mfma_f32_16x16x32_bf16 v[54:57], v[212:215], v[236:239], v[54:57]
	s_waitcnt lgkmcnt(2)
	v_mfma_f32_16x16x32_bf16 v[34:37], v[212:215], v[240:243], v[34:37]
	s_waitcnt lgkmcnt(1)
	v_mfma_f32_16x16x32_bf16 v[38:41], v[212:215], v[252:255], v[38:41]
	s_waitcnt vmcnt(11)
	ds_write_b128 v165, v[144:147] offset:55296
	s_waitcnt vmcnt(10)
	ds_write_b128 v165, v[148:151] offset:59904
	v_mfma_f32_16x16x32_bf16 v[58:61], v[216:219], v[228:231], v[58:61]
	v_mfma_f32_16x16x32_bf16 v[62:65], v[216:219], v[236:239], v[62:65]
	v_mfma_f32_16x16x32_bf16 v[42:45], v[216:219], v[240:243], v[42:45]
	v_mfma_f32_16x16x32_bf16 v[46:49], v[216:219], v[252:255], v[46:49]
	s_waitcnt vmcnt(9)
	ds_write_b128 v165, v[172:175] offset:64512
	s_waitcnt vmcnt(8)
	ds_write_b128 v166, v[176:179] offset:32256
	v_mfma_f32_16x16x32_bf16 v[18:21], v[220:223], v[228:231], v[18:21]
	v_mfma_f32_16x16x32_bf16 v[22:25], v[220:223], v[236:239], v[22:25]
	v_mfma_f32_16x16x32_bf16 v[2:5], v[220:223], v[240:243], v[2:5]
	v_mfma_f32_16x16x32_bf16 v[6:9], v[220:223], v[252:255], v[6:9]
	s_waitcnt lgkmcnt(4)
	v_mfma_f32_16x16x32_bf16 v[26:29], v[224:227], v[228:231], v[26:29]
	v_mfma_f32_16x16x32_bf16 v[30:33], v[224:227], v[236:239], v[30:33]
	v_mfma_f32_16x16x32_bf16 v[10:13], v[224:227], v[240:243], v[10:13]
	v_mfma_f32_16x16x32_bf16 v[14:17], v[224:227], v[252:255], v[14:17]
	s_waitcnt lgkmcnt(0)
	s_barrier
	global_load_dwordx4 v[122:125], v[72:73], off offset:1152
	global_load_dwordx4 v[126:129], v[74:75], off offset:1152
	global_load_dwordx4 v[136:139], v[76:77], off offset:1152
	global_load_dwordx4 v[140:143], v[78:79], off offset:1152
	global_load_dwordx4 v[144:147], v[70:71], off offset:1152
	global_load_dwordx4 v[148:151], v[68:69], off offset:1152
	global_load_dwordx4 v[172:175], v[66:67], off offset:1152
	global_load_dwordx4 v[176:179], v[80:81], off offset:1152
	ds_read_b128 v[228:231], v245 offset:55296
	ds_read_b128 v[212:215], v244 offset:18432
	ds_read_b128 v[236:239], v245 offset:57600
	ds_read_b128 v[240:243], v245 offset:59904
	ds_read_b128 v[252:255], v245 offset:62208
	ds_read_b128 v[216:219], v244 offset:20736
	ds_read_b128 v[220:223], v244 offset:23040
	ds_read_b128 v[224:227], v244 offset:25344
	s_waitcnt lgkmcnt(6)
	v_mfma_f32_16x16x32_bf16 v[50:53], v[212:215], v[228:231], v[50:53]
	s_waitcnt lgkmcnt(5)
	v_mfma_f32_16x16x32_bf16 v[54:57], v[212:215], v[236:239], v[54:57]
	s_waitcnt lgkmcnt(4)
	v_mfma_f32_16x16x32_bf16 v[34:37], v[212:215], v[240:243], v[34:37]
	s_waitcnt lgkmcnt(3)
	v_mfma_f32_16x16x32_bf16 v[38:41], v[212:215], v[252:255], v[38:41]
	ds_read_b128 v[212:215], v244 offset:18496
	s_waitcnt lgkmcnt(3)
	v_mfma_f32_16x16x32_bf16 v[58:61], v[216:219], v[228:231], v[58:61]
	v_mfma_f32_16x16x32_bf16 v[62:65], v[216:219], v[236:239], v[62:65]
	v_mfma_f32_16x16x32_bf16 v[42:45], v[216:219], v[240:243], v[42:45]
	v_mfma_f32_16x16x32_bf16 v[46:49], v[216:219], v[252:255], v[46:49]
	ds_read_b128 v[216:219], v244 offset:20800
	s_waitcnt vmcnt(15)
	ds_write_b128 v165, v[180:183]
	s_waitcnt vmcnt(14)
	ds_write_b128 v165, v[184:187] offset:4608
	s_waitcnt lgkmcnt(5)
	v_mfma_f32_16x16x32_bf16 v[18:21], v[220:223], v[228:231], v[18:21]
	v_mfma_f32_16x16x32_bf16 v[22:25], v[220:223], v[236:239], v[22:25]
	v_mfma_f32_16x16x32_bf16 v[2:5], v[220:223], v[240:243], v[2:5]
	v_mfma_f32_16x16x32_bf16 v[6:9], v[220:223], v[252:255], v[6:9]
	ds_read_b128 v[220:223], v244 offset:23104
	s_waitcnt vmcnt(13)
	ds_write_b128 v165, v[188:191] offset:9216
	s_waitcnt vmcnt(12)
	ds_write_b128 v165, v[192:195] offset:13824
	s_waitcnt lgkmcnt(7)
	v_mfma_f32_16x16x32_bf16 v[26:29], v[224:227], v[228:231], v[26:29]
	ds_read_b128 v[228:231], v245 offset:55360
	v_mfma_f32_16x16x32_bf16 v[30:33], v[224:227], v[236:239], v[30:33]
	ds_read_b128 v[236:239], v245 offset:57664
	v_mfma_f32_16x16x32_bf16 v[10:13], v[224:227], v[240:243], v[10:13]
	ds_read_b128 v[240:243], v245 offset:59968
	v_mfma_f32_16x16x32_bf16 v[14:17], v[224:227], v[252:255], v[14:17]
	ds_read_b128 v[252:255], v245 offset:62272
	ds_read_b128 v[224:227], v244 offset:25408
	s_waitcnt lgkmcnt(4)
	v_mfma_f32_16x16x32_bf16 v[50:53], v[212:215], v[228:231], v[50:53]
	s_waitcnt lgkmcnt(3)
	v_mfma_f32_16x16x32_bf16 v[54:57], v[212:215], v[236:239], v[54:57]
	s_waitcnt lgkmcnt(2)
	v_mfma_f32_16x16x32_bf16 v[34:37], v[212:215], v[240:243], v[34:37]
	s_waitcnt lgkmcnt(1)
	v_mfma_f32_16x16x32_bf16 v[38:41], v[212:215], v[252:255], v[38:41]
	s_waitcnt vmcnt(11)
	ds_write_b128 v165, v[196:199] offset:36864
	s_waitcnt vmcnt(10)
	ds_write_b128 v165, v[200:203] offset:41472
	v_mfma_f32_16x16x32_bf16 v[58:61], v[216:219], v[228:231], v[58:61]
	v_mfma_f32_16x16x32_bf16 v[62:65], v[216:219], v[236:239], v[62:65]
	v_mfma_f32_16x16x32_bf16 v[42:45], v[216:219], v[240:243], v[42:45]
	v_mfma_f32_16x16x32_bf16 v[46:49], v[216:219], v[252:255], v[46:49]
	s_waitcnt vmcnt(9)
	ds_write_b128 v165, v[204:207] offset:46080
	s_waitcnt vmcnt(8)
	ds_write_b128 v165, v[208:211] offset:50688
	v_mfma_f32_16x16x32_bf16 v[18:21], v[220:223], v[228:231], v[18:21]
	v_mfma_f32_16x16x32_bf16 v[22:25], v[220:223], v[236:239], v[22:25]
	v_mfma_f32_16x16x32_bf16 v[2:5], v[220:223], v[240:243], v[2:5]
	v_mfma_f32_16x16x32_bf16 v[6:9], v[220:223], v[252:255], v[6:9]
	s_waitcnt lgkmcnt(4)
	v_mfma_f32_16x16x32_bf16 v[26:29], v[224:227], v[228:231], v[26:29]
	v_mfma_f32_16x16x32_bf16 v[30:33], v[224:227], v[236:239], v[30:33]
	v_mfma_f32_16x16x32_bf16 v[10:13], v[224:227], v[240:243], v[10:13]
	v_mfma_f32_16x16x32_bf16 v[14:17], v[224:227], v[252:255], v[14:17]
	s_waitcnt lgkmcnt(0)
	s_barrier
	global_load_dwordx4 v[180:183], v[72:73], off offset:1280
	global_load_dwordx4 v[184:187], v[74:75], off offset:1280
	global_load_dwordx4 v[188:191], v[76:77], off offset:1280
	global_load_dwordx4 v[192:195], v[78:79], off offset:1280
	global_load_dwordx4 v[196:199], v[70:71], off offset:1280
	global_load_dwordx4 v[200:203], v[68:69], off offset:1280
	global_load_dwordx4 v[204:207], v[66:67], off offset:1280
	global_load_dwordx4 v[208:211], v[80:81], off offset:1280
	ds_read_b128 v[228:231], v245 offset:36864
	ds_read_b128 v[212:215], v244
	ds_read_b128 v[236:239], v245 offset:39168
	ds_read_b128 v[240:243], v245 offset:41472
	ds_read_b128 v[252:255], v245 offset:43776
	ds_read_b128 v[216:219], v244 offset:2304
	ds_read_b128 v[220:223], v244 offset:4608
	ds_read_b128 v[224:227], v244 offset:6912
	s_waitcnt lgkmcnt(6)
	v_mfma_f32_16x16x32_bf16 v[50:53], v[212:215], v[228:231], v[50:53]
	s_waitcnt lgkmcnt(5)
	v_mfma_f32_16x16x32_bf16 v[54:57], v[212:215], v[236:239], v[54:57]
	s_waitcnt lgkmcnt(4)
	v_mfma_f32_16x16x32_bf16 v[34:37], v[212:215], v[240:243], v[34:37]
	s_waitcnt lgkmcnt(3)
	v_mfma_f32_16x16x32_bf16 v[38:41], v[212:215], v[252:255], v[38:41]
	ds_read_b128 v[212:215], v244 offset:64
	s_waitcnt lgkmcnt(3)
	v_mfma_f32_16x16x32_bf16 v[58:61], v[216:219], v[228:231], v[58:61]
	v_mfma_f32_16x16x32_bf16 v[62:65], v[216:219], v[236:239], v[62:65]
	v_mfma_f32_16x16x32_bf16 v[42:45], v[216:219], v[240:243], v[42:45]
	v_mfma_f32_16x16x32_bf16 v[46:49], v[216:219], v[252:255], v[46:49]
	ds_read_b128 v[216:219], v244 offset:2368
	s_waitcnt vmcnt(15)
	ds_write_b128 v165, v[122:125] offset:18432
	s_waitcnt vmcnt(14)
	ds_write_b128 v165, v[126:129] offset:23040
	s_waitcnt lgkmcnt(5)
	v_mfma_f32_16x16x32_bf16 v[18:21], v[220:223], v[228:231], v[18:21]
	v_mfma_f32_16x16x32_bf16 v[22:25], v[220:223], v[236:239], v[22:25]
	v_mfma_f32_16x16x32_bf16 v[2:5], v[220:223], v[240:243], v[2:5]
	v_mfma_f32_16x16x32_bf16 v[6:9], v[220:223], v[252:255], v[6:9]
	ds_read_b128 v[220:223], v244 offset:4672
	s_waitcnt vmcnt(13)
	ds_write_b128 v165, v[136:139] offset:27648
	s_waitcnt vmcnt(12)
	ds_write_b128 v165, v[140:143] offset:32256
	s_waitcnt lgkmcnt(7)
	v_mfma_f32_16x16x32_bf16 v[26:29], v[224:227], v[228:231], v[26:29]
	ds_read_b128 v[228:231], v245 offset:36928
	v_mfma_f32_16x16x32_bf16 v[30:33], v[224:227], v[236:239], v[30:33]
	ds_read_b128 v[236:239], v245 offset:39232
	v_mfma_f32_16x16x32_bf16 v[10:13], v[224:227], v[240:243], v[10:13]
	ds_read_b128 v[240:243], v245 offset:41536
	v_mfma_f32_16x16x32_bf16 v[14:17], v[224:227], v[252:255], v[14:17]
	ds_read_b128 v[252:255], v245 offset:43840
	ds_read_b128 v[224:227], v244 offset:6976
	s_waitcnt lgkmcnt(4)
	v_mfma_f32_16x16x32_bf16 v[50:53], v[212:215], v[228:231], v[50:53]
	s_waitcnt lgkmcnt(3)
	v_mfma_f32_16x16x32_bf16 v[54:57], v[212:215], v[236:239], v[54:57]
	s_waitcnt lgkmcnt(2)
	v_mfma_f32_16x16x32_bf16 v[34:37], v[212:215], v[240:243], v[34:37]
	s_waitcnt lgkmcnt(1)
	v_mfma_f32_16x16x32_bf16 v[38:41], v[212:215], v[252:255], v[38:41]
	s_waitcnt vmcnt(11)
	ds_write_b128 v165, v[144:147] offset:55296
	s_waitcnt vmcnt(10)
	ds_write_b128 v165, v[148:151] offset:59904
	v_mfma_f32_16x16x32_bf16 v[58:61], v[216:219], v[228:231], v[58:61]
	v_mfma_f32_16x16x32_bf16 v[62:65], v[216:219], v[236:239], v[62:65]
	v_mfma_f32_16x16x32_bf16 v[42:45], v[216:219], v[240:243], v[42:45]
	v_mfma_f32_16x16x32_bf16 v[46:49], v[216:219], v[252:255], v[46:49]
	s_waitcnt vmcnt(9)
	ds_write_b128 v165, v[172:175] offset:64512
	s_waitcnt vmcnt(8)
	ds_write_b128 v166, v[176:179] offset:32256
	v_mfma_f32_16x16x32_bf16 v[18:21], v[220:223], v[228:231], v[18:21]
	v_mfma_f32_16x16x32_bf16 v[22:25], v[220:223], v[236:239], v[22:25]
	v_mfma_f32_16x16x32_bf16 v[2:5], v[220:223], v[240:243], v[2:5]
	v_mfma_f32_16x16x32_bf16 v[6:9], v[220:223], v[252:255], v[6:9]
	s_waitcnt lgkmcnt(4)
	v_mfma_f32_16x16x32_bf16 v[26:29], v[224:227], v[228:231], v[26:29]
	v_mfma_f32_16x16x32_bf16 v[30:33], v[224:227], v[236:239], v[30:33]
	v_mfma_f32_16x16x32_bf16 v[10:13], v[224:227], v[240:243], v[10:13]
	v_mfma_f32_16x16x32_bf16 v[14:17], v[224:227], v[252:255], v[14:17]
	s_waitcnt lgkmcnt(0)
	s_barrier
	global_load_dwordx4 v[122:125], v[72:73], off offset:1408
	global_load_dwordx4 v[126:129], v[74:75], off offset:1408
	global_load_dwordx4 v[136:139], v[76:77], off offset:1408
	global_load_dwordx4 v[140:143], v[78:79], off offset:1408
	global_load_dwordx4 v[144:147], v[70:71], off offset:1408
	global_load_dwordx4 v[148:151], v[68:69], off offset:1408
	global_load_dwordx4 v[172:175], v[66:67], off offset:1408
	global_load_dwordx4 v[176:179], v[80:81], off offset:1408
	ds_read_b128 v[228:231], v245 offset:55296
	ds_read_b128 v[212:215], v244 offset:18432
	ds_read_b128 v[236:239], v245 offset:57600
	ds_read_b128 v[240:243], v245 offset:59904
	ds_read_b128 v[252:255], v245 offset:62208
	ds_read_b128 v[216:219], v244 offset:20736
	ds_read_b128 v[220:223], v244 offset:23040
	ds_read_b128 v[224:227], v244 offset:25344
	s_waitcnt lgkmcnt(6)
	v_mfma_f32_16x16x32_bf16 v[50:53], v[212:215], v[228:231], v[50:53]
	s_waitcnt lgkmcnt(5)
	v_mfma_f32_16x16x32_bf16 v[54:57], v[212:215], v[236:239], v[54:57]
	s_waitcnt lgkmcnt(4)
	v_mfma_f32_16x16x32_bf16 v[34:37], v[212:215], v[240:243], v[34:37]
	s_waitcnt lgkmcnt(3)
	v_mfma_f32_16x16x32_bf16 v[38:41], v[212:215], v[252:255], v[38:41]
	ds_read_b128 v[212:215], v244 offset:18496
	s_waitcnt lgkmcnt(3)
	v_mfma_f32_16x16x32_bf16 v[58:61], v[216:219], v[228:231], v[58:61]
	v_mfma_f32_16x16x32_bf16 v[62:65], v[216:219], v[236:239], v[62:65]
	v_mfma_f32_16x16x32_bf16 v[42:45], v[216:219], v[240:243], v[42:45]
	v_mfma_f32_16x16x32_bf16 v[46:49], v[216:219], v[252:255], v[46:49]
	ds_read_b128 v[216:219], v244 offset:20800
	s_waitcnt vmcnt(15)
	ds_write_b128 v165, v[180:183]
	s_waitcnt vmcnt(14)
	ds_write_b128 v165, v[184:187] offset:4608
	s_waitcnt lgkmcnt(5)
	v_mfma_f32_16x16x32_bf16 v[18:21], v[220:223], v[228:231], v[18:21]
	v_mfma_f32_16x16x32_bf16 v[22:25], v[220:223], v[236:239], v[22:25]
	v_mfma_f32_16x16x32_bf16 v[2:5], v[220:223], v[240:243], v[2:5]
	v_mfma_f32_16x16x32_bf16 v[6:9], v[220:223], v[252:255], v[6:9]
	ds_read_b128 v[220:223], v244 offset:23104
	s_waitcnt vmcnt(13)
	ds_write_b128 v165, v[188:191] offset:9216
	s_waitcnt vmcnt(12)
	ds_write_b128 v165, v[192:195] offset:13824
	s_waitcnt lgkmcnt(7)
	v_mfma_f32_16x16x32_bf16 v[26:29], v[224:227], v[228:231], v[26:29]
	ds_read_b128 v[228:231], v245 offset:55360
	v_mfma_f32_16x16x32_bf16 v[30:33], v[224:227], v[236:239], v[30:33]
	ds_read_b128 v[236:239], v245 offset:57664
	v_mfma_f32_16x16x32_bf16 v[10:13], v[224:227], v[240:243], v[10:13]
	ds_read_b128 v[240:243], v245 offset:59968
	v_mfma_f32_16x16x32_bf16 v[14:17], v[224:227], v[252:255], v[14:17]
	ds_read_b128 v[252:255], v245 offset:62272
	ds_read_b128 v[224:227], v244 offset:25408
	s_waitcnt lgkmcnt(4)
	v_mfma_f32_16x16x32_bf16 v[50:53], v[212:215], v[228:231], v[50:53]
	s_waitcnt lgkmcnt(3)
	v_mfma_f32_16x16x32_bf16 v[54:57], v[212:215], v[236:239], v[54:57]
	s_waitcnt lgkmcnt(2)
	v_mfma_f32_16x16x32_bf16 v[34:37], v[212:215], v[240:243], v[34:37]
	s_waitcnt lgkmcnt(1)
	v_mfma_f32_16x16x32_bf16 v[38:41], v[212:215], v[252:255], v[38:41]
	s_waitcnt vmcnt(11)
	ds_write_b128 v165, v[196:199] offset:36864
	s_waitcnt vmcnt(10)
	ds_write_b128 v165, v[200:203] offset:41472
	v_mfma_f32_16x16x32_bf16 v[58:61], v[216:219], v[228:231], v[58:61]
	v_mfma_f32_16x16x32_bf16 v[62:65], v[216:219], v[236:239], v[62:65]
	v_mfma_f32_16x16x32_bf16 v[42:45], v[216:219], v[240:243], v[42:45]
	v_mfma_f32_16x16x32_bf16 v[46:49], v[216:219], v[252:255], v[46:49]
	s_waitcnt vmcnt(9)
	ds_write_b128 v165, v[204:207] offset:46080
	s_waitcnt vmcnt(8)
	ds_write_b128 v165, v[208:211] offset:50688
	v_mfma_f32_16x16x32_bf16 v[18:21], v[220:223], v[228:231], v[18:21]
	v_mfma_f32_16x16x32_bf16 v[22:25], v[220:223], v[236:239], v[22:25]
	v_mfma_f32_16x16x32_bf16 v[2:5], v[220:223], v[240:243], v[2:5]
	v_mfma_f32_16x16x32_bf16 v[6:9], v[220:223], v[252:255], v[6:9]
	s_waitcnt lgkmcnt(4)
	v_mfma_f32_16x16x32_bf16 v[26:29], v[224:227], v[228:231], v[26:29]
	v_mfma_f32_16x16x32_bf16 v[30:33], v[224:227], v[236:239], v[30:33]
	v_mfma_f32_16x16x32_bf16 v[10:13], v[224:227], v[240:243], v[10:13]
	v_mfma_f32_16x16x32_bf16 v[14:17], v[224:227], v[252:255], v[14:17]
	s_waitcnt lgkmcnt(0)
	s_barrier
	global_load_dwordx4 v[180:183], v[72:73], off offset:1536
	global_load_dwordx4 v[184:187], v[74:75], off offset:1536
	global_load_dwordx4 v[188:191], v[76:77], off offset:1536
	global_load_dwordx4 v[192:195], v[78:79], off offset:1536
	global_load_dwordx4 v[196:199], v[70:71], off offset:1536
	global_load_dwordx4 v[200:203], v[68:69], off offset:1536
	global_load_dwordx4 v[204:207], v[66:67], off offset:1536
	global_load_dwordx4 v[208:211], v[80:81], off offset:1536
	ds_read_b128 v[228:231], v245 offset:36864
	ds_read_b128 v[212:215], v244
	ds_read_b128 v[236:239], v245 offset:39168
	ds_read_b128 v[240:243], v245 offset:41472
	ds_read_b128 v[252:255], v245 offset:43776
	ds_read_b128 v[216:219], v244 offset:2304
	ds_read_b128 v[220:223], v244 offset:4608
	ds_read_b128 v[224:227], v244 offset:6912
	s_waitcnt lgkmcnt(6)
	v_mfma_f32_16x16x32_bf16 v[50:53], v[212:215], v[228:231], v[50:53]
	s_waitcnt lgkmcnt(5)
	v_mfma_f32_16x16x32_bf16 v[54:57], v[212:215], v[236:239], v[54:57]
	s_waitcnt lgkmcnt(4)
	v_mfma_f32_16x16x32_bf16 v[34:37], v[212:215], v[240:243], v[34:37]
	s_waitcnt lgkmcnt(3)
	v_mfma_f32_16x16x32_bf16 v[38:41], v[212:215], v[252:255], v[38:41]
	ds_read_b128 v[212:215], v244 offset:64
	s_waitcnt lgkmcnt(3)
	v_mfma_f32_16x16x32_bf16 v[58:61], v[216:219], v[228:231], v[58:61]
	v_mfma_f32_16x16x32_bf16 v[62:65], v[216:219], v[236:239], v[62:65]
	v_mfma_f32_16x16x32_bf16 v[42:45], v[216:219], v[240:243], v[42:45]
	v_mfma_f32_16x16x32_bf16 v[46:49], v[216:219], v[252:255], v[46:49]
	ds_read_b128 v[216:219], v244 offset:2368
	s_waitcnt vmcnt(15)
	ds_write_b128 v165, v[122:125] offset:18432
	s_waitcnt vmcnt(14)
	ds_write_b128 v165, v[126:129] offset:23040
	s_waitcnt lgkmcnt(5)
	v_mfma_f32_16x16x32_bf16 v[18:21], v[220:223], v[228:231], v[18:21]
	v_mfma_f32_16x16x32_bf16 v[22:25], v[220:223], v[236:239], v[22:25]
	v_mfma_f32_16x16x32_bf16 v[2:5], v[220:223], v[240:243], v[2:5]
	v_mfma_f32_16x16x32_bf16 v[6:9], v[220:223], v[252:255], v[6:9]
	ds_read_b128 v[220:223], v244 offset:4672
	s_waitcnt vmcnt(13)
	ds_write_b128 v165, v[136:139] offset:27648
	s_waitcnt vmcnt(12)
	ds_write_b128 v165, v[140:143] offset:32256
	s_waitcnt lgkmcnt(7)
	v_mfma_f32_16x16x32_bf16 v[26:29], v[224:227], v[228:231], v[26:29]
	ds_read_b128 v[228:231], v245 offset:36928
	v_mfma_f32_16x16x32_bf16 v[30:33], v[224:227], v[236:239], v[30:33]
	ds_read_b128 v[236:239], v245 offset:39232
	v_mfma_f32_16x16x32_bf16 v[10:13], v[224:227], v[240:243], v[10:13]
	ds_read_b128 v[240:243], v245 offset:41536
	v_mfma_f32_16x16x32_bf16 v[14:17], v[224:227], v[252:255], v[14:17]
	ds_read_b128 v[252:255], v245 offset:43840
	ds_read_b128 v[224:227], v244 offset:6976
	s_waitcnt lgkmcnt(4)
	v_mfma_f32_16x16x32_bf16 v[50:53], v[212:215], v[228:231], v[50:53]
	s_waitcnt lgkmcnt(3)
	v_mfma_f32_16x16x32_bf16 v[54:57], v[212:215], v[236:239], v[54:57]
	s_waitcnt lgkmcnt(2)
	v_mfma_f32_16x16x32_bf16 v[34:37], v[212:215], v[240:243], v[34:37]
	s_waitcnt lgkmcnt(1)
	v_mfma_f32_16x16x32_bf16 v[38:41], v[212:215], v[252:255], v[38:41]
	s_waitcnt vmcnt(11)
	ds_write_b128 v165, v[144:147] offset:55296
	s_waitcnt vmcnt(10)
	ds_write_b128 v165, v[148:151] offset:59904
	v_mfma_f32_16x16x32_bf16 v[58:61], v[216:219], v[228:231], v[58:61]
	v_mfma_f32_16x16x32_bf16 v[62:65], v[216:219], v[236:239], v[62:65]
	v_mfma_f32_16x16x32_bf16 v[42:45], v[216:219], v[240:243], v[42:45]
	v_mfma_f32_16x16x32_bf16 v[46:49], v[216:219], v[252:255], v[46:49]
	s_waitcnt vmcnt(9)
	ds_write_b128 v165, v[172:175] offset:64512
	s_waitcnt vmcnt(8)
	ds_write_b128 v166, v[176:179] offset:32256
	v_mfma_f32_16x16x32_bf16 v[18:21], v[220:223], v[228:231], v[18:21]
	v_mfma_f32_16x16x32_bf16 v[22:25], v[220:223], v[236:239], v[22:25]
	v_mfma_f32_16x16x32_bf16 v[2:5], v[220:223], v[240:243], v[2:5]
	v_mfma_f32_16x16x32_bf16 v[6:9], v[220:223], v[252:255], v[6:9]
	s_waitcnt lgkmcnt(4)
	v_mfma_f32_16x16x32_bf16 v[26:29], v[224:227], v[228:231], v[26:29]
	v_mfma_f32_16x16x32_bf16 v[30:33], v[224:227], v[236:239], v[30:33]
	v_mfma_f32_16x16x32_bf16 v[10:13], v[224:227], v[240:243], v[10:13]
	v_mfma_f32_16x16x32_bf16 v[14:17], v[224:227], v[252:255], v[14:17]
	s_waitcnt lgkmcnt(0)
	s_barrier
	global_load_dwordx4 v[122:125], v[72:73], off offset:1664
	global_load_dwordx4 v[126:129], v[74:75], off offset:1664
	global_load_dwordx4 v[136:139], v[76:77], off offset:1664
	global_load_dwordx4 v[140:143], v[78:79], off offset:1664
	global_load_dwordx4 v[144:147], v[70:71], off offset:1664
	global_load_dwordx4 v[148:151], v[68:69], off offset:1664
	global_load_dwordx4 v[172:175], v[66:67], off offset:1664
	global_load_dwordx4 v[176:179], v[80:81], off offset:1664
	ds_read_b128 v[228:231], v245 offset:55296
	ds_read_b128 v[212:215], v244 offset:18432
	ds_read_b128 v[236:239], v245 offset:57600
	ds_read_b128 v[240:243], v245 offset:59904
	ds_read_b128 v[252:255], v245 offset:62208
	ds_read_b128 v[216:219], v244 offset:20736
	ds_read_b128 v[220:223], v244 offset:23040
	ds_read_b128 v[224:227], v244 offset:25344
	s_waitcnt lgkmcnt(6)
	v_mfma_f32_16x16x32_bf16 v[50:53], v[212:215], v[228:231], v[50:53]
	s_waitcnt lgkmcnt(5)
	v_mfma_f32_16x16x32_bf16 v[54:57], v[212:215], v[236:239], v[54:57]
	s_waitcnt lgkmcnt(4)
	v_mfma_f32_16x16x32_bf16 v[34:37], v[212:215], v[240:243], v[34:37]
	s_waitcnt lgkmcnt(3)
	v_mfma_f32_16x16x32_bf16 v[38:41], v[212:215], v[252:255], v[38:41]
	ds_read_b128 v[212:215], v244 offset:18496
	s_waitcnt lgkmcnt(3)
	v_mfma_f32_16x16x32_bf16 v[58:61], v[216:219], v[228:231], v[58:61]
	v_mfma_f32_16x16x32_bf16 v[62:65], v[216:219], v[236:239], v[62:65]
	v_mfma_f32_16x16x32_bf16 v[42:45], v[216:219], v[240:243], v[42:45]
	v_mfma_f32_16x16x32_bf16 v[46:49], v[216:219], v[252:255], v[46:49]
	ds_read_b128 v[216:219], v244 offset:20800
	s_waitcnt vmcnt(15)
	ds_write_b128 v165, v[180:183]
	s_waitcnt vmcnt(14)
	ds_write_b128 v165, v[184:187] offset:4608
	s_waitcnt lgkmcnt(5)
	v_mfma_f32_16x16x32_bf16 v[18:21], v[220:223], v[228:231], v[18:21]
	v_mfma_f32_16x16x32_bf16 v[22:25], v[220:223], v[236:239], v[22:25]
	v_mfma_f32_16x16x32_bf16 v[2:5], v[220:223], v[240:243], v[2:5]
	v_mfma_f32_16x16x32_bf16 v[6:9], v[220:223], v[252:255], v[6:9]
	ds_read_b128 v[220:223], v244 offset:23104
	s_waitcnt vmcnt(13)
	ds_write_b128 v165, v[188:191] offset:9216
	s_waitcnt vmcnt(12)
	ds_write_b128 v165, v[192:195] offset:13824
	s_waitcnt lgkmcnt(7)
	v_mfma_f32_16x16x32_bf16 v[26:29], v[224:227], v[228:231], v[26:29]
	ds_read_b128 v[228:231], v245 offset:55360
	v_mfma_f32_16x16x32_bf16 v[30:33], v[224:227], v[236:239], v[30:33]
	ds_read_b128 v[236:239], v245 offset:57664
	v_mfma_f32_16x16x32_bf16 v[10:13], v[224:227], v[240:243], v[10:13]
	ds_read_b128 v[240:243], v245 offset:59968
	v_mfma_f32_16x16x32_bf16 v[14:17], v[224:227], v[252:255], v[14:17]
	ds_read_b128 v[252:255], v245 offset:62272
	ds_read_b128 v[224:227], v244 offset:25408
	s_waitcnt lgkmcnt(4)
	v_mfma_f32_16x16x32_bf16 v[50:53], v[212:215], v[228:231], v[50:53]
	s_waitcnt lgkmcnt(3)
	v_mfma_f32_16x16x32_bf16 v[54:57], v[212:215], v[236:239], v[54:57]
	s_waitcnt lgkmcnt(2)
	v_mfma_f32_16x16x32_bf16 v[34:37], v[212:215], v[240:243], v[34:37]
	s_waitcnt lgkmcnt(1)
	v_mfma_f32_16x16x32_bf16 v[38:41], v[212:215], v[252:255], v[38:41]
	s_waitcnt vmcnt(11)
	ds_write_b128 v165, v[196:199] offset:36864
	s_waitcnt vmcnt(10)
	ds_write_b128 v165, v[200:203] offset:41472
	v_mfma_f32_16x16x32_bf16 v[58:61], v[216:219], v[228:231], v[58:61]
	v_mfma_f32_16x16x32_bf16 v[62:65], v[216:219], v[236:239], v[62:65]
	v_mfma_f32_16x16x32_bf16 v[42:45], v[216:219], v[240:243], v[42:45]
	v_mfma_f32_16x16x32_bf16 v[46:49], v[216:219], v[252:255], v[46:49]
	s_waitcnt vmcnt(9)
	ds_write_b128 v165, v[204:207] offset:46080
	s_waitcnt vmcnt(8)
	ds_write_b128 v165, v[208:211] offset:50688
	v_mfma_f32_16x16x32_bf16 v[18:21], v[220:223], v[228:231], v[18:21]
	v_mfma_f32_16x16x32_bf16 v[22:25], v[220:223], v[236:239], v[22:25]
	v_mfma_f32_16x16x32_bf16 v[2:5], v[220:223], v[240:243], v[2:5]
	v_mfma_f32_16x16x32_bf16 v[6:9], v[220:223], v[252:255], v[6:9]
	s_waitcnt lgkmcnt(4)
	v_mfma_f32_16x16x32_bf16 v[26:29], v[224:227], v[228:231], v[26:29]
	v_mfma_f32_16x16x32_bf16 v[30:33], v[224:227], v[236:239], v[30:33]
	v_mfma_f32_16x16x32_bf16 v[10:13], v[224:227], v[240:243], v[10:13]
	v_mfma_f32_16x16x32_bf16 v[14:17], v[224:227], v[252:255], v[14:17]
	s_waitcnt lgkmcnt(0)
	s_barrier
	global_load_dwordx4 v[180:183], v[72:73], off offset:1792
	global_load_dwordx4 v[184:187], v[74:75], off offset:1792
	global_load_dwordx4 v[188:191], v[76:77], off offset:1792
	global_load_dwordx4 v[192:195], v[78:79], off offset:1792
	global_load_dwordx4 v[196:199], v[70:71], off offset:1792
	global_load_dwordx4 v[200:203], v[68:69], off offset:1792
	global_load_dwordx4 v[204:207], v[66:67], off offset:1792
	global_load_dwordx4 v[208:211], v[80:81], off offset:1792
	ds_read_b128 v[228:231], v245 offset:36864
	ds_read_b128 v[212:215], v244
	ds_read_b128 v[236:239], v245 offset:39168
	ds_read_b128 v[240:243], v245 offset:41472
	ds_read_b128 v[252:255], v245 offset:43776
	ds_read_b128 v[216:219], v244 offset:2304
	ds_read_b128 v[220:223], v244 offset:4608
	ds_read_b128 v[224:227], v244 offset:6912
	s_waitcnt lgkmcnt(6)
	v_mfma_f32_16x16x32_bf16 v[50:53], v[212:215], v[228:231], v[50:53]
	s_waitcnt lgkmcnt(5)
	v_mfma_f32_16x16x32_bf16 v[54:57], v[212:215], v[236:239], v[54:57]
	s_waitcnt lgkmcnt(4)
	v_mfma_f32_16x16x32_bf16 v[34:37], v[212:215], v[240:243], v[34:37]
	s_waitcnt lgkmcnt(3)
	v_mfma_f32_16x16x32_bf16 v[38:41], v[212:215], v[252:255], v[38:41]
	ds_read_b128 v[212:215], v244 offset:64
	s_waitcnt lgkmcnt(3)
	v_mfma_f32_16x16x32_bf16 v[58:61], v[216:219], v[228:231], v[58:61]
	v_mfma_f32_16x16x32_bf16 v[62:65], v[216:219], v[236:239], v[62:65]
	v_mfma_f32_16x16x32_bf16 v[42:45], v[216:219], v[240:243], v[42:45]
	v_mfma_f32_16x16x32_bf16 v[46:49], v[216:219], v[252:255], v[46:49]
	ds_read_b128 v[216:219], v244 offset:2368
	s_waitcnt vmcnt(15)
	ds_write_b128 v165, v[122:125] offset:18432
	s_waitcnt vmcnt(14)
	ds_write_b128 v165, v[126:129] offset:23040
	s_waitcnt lgkmcnt(5)
	v_mfma_f32_16x16x32_bf16 v[18:21], v[220:223], v[228:231], v[18:21]
	v_mfma_f32_16x16x32_bf16 v[22:25], v[220:223], v[236:239], v[22:25]
	v_mfma_f32_16x16x32_bf16 v[2:5], v[220:223], v[240:243], v[2:5]
	v_mfma_f32_16x16x32_bf16 v[6:9], v[220:223], v[252:255], v[6:9]
	ds_read_b128 v[220:223], v244 offset:4672
	s_waitcnt vmcnt(13)
	ds_write_b128 v165, v[136:139] offset:27648
	s_waitcnt vmcnt(12)
	ds_write_b128 v165, v[140:143] offset:32256
	s_waitcnt lgkmcnt(7)
	v_mfma_f32_16x16x32_bf16 v[26:29], v[224:227], v[228:231], v[26:29]
	ds_read_b128 v[228:231], v245 offset:36928
	v_mfma_f32_16x16x32_bf16 v[30:33], v[224:227], v[236:239], v[30:33]
	ds_read_b128 v[236:239], v245 offset:39232
	v_mfma_f32_16x16x32_bf16 v[10:13], v[224:227], v[240:243], v[10:13]
	ds_read_b128 v[240:243], v245 offset:41536
	v_mfma_f32_16x16x32_bf16 v[14:17], v[224:227], v[252:255], v[14:17]
	ds_read_b128 v[252:255], v245 offset:43840
	ds_read_b128 v[224:227], v244 offset:6976
	s_waitcnt lgkmcnt(4)
	v_mfma_f32_16x16x32_bf16 v[50:53], v[212:215], v[228:231], v[50:53]
	s_waitcnt lgkmcnt(3)
	v_mfma_f32_16x16x32_bf16 v[54:57], v[212:215], v[236:239], v[54:57]
	s_waitcnt lgkmcnt(2)
	v_mfma_f32_16x16x32_bf16 v[34:37], v[212:215], v[240:243], v[34:37]
	s_waitcnt lgkmcnt(1)
	v_mfma_f32_16x16x32_bf16 v[38:41], v[212:215], v[252:255], v[38:41]
	s_waitcnt vmcnt(11)
	ds_write_b128 v165, v[144:147] offset:55296
	s_waitcnt vmcnt(10)
	ds_write_b128 v165, v[148:151] offset:59904
	v_mfma_f32_16x16x32_bf16 v[58:61], v[216:219], v[228:231], v[58:61]
	v_mfma_f32_16x16x32_bf16 v[62:65], v[216:219], v[236:239], v[62:65]
	v_mfma_f32_16x16x32_bf16 v[42:45], v[216:219], v[240:243], v[42:45]
	v_mfma_f32_16x16x32_bf16 v[46:49], v[216:219], v[252:255], v[46:49]
	s_waitcnt vmcnt(9)
	ds_write_b128 v165, v[172:175] offset:64512
	s_waitcnt vmcnt(8)
	ds_write_b128 v166, v[176:179] offset:32256
	v_mfma_f32_16x16x32_bf16 v[18:21], v[220:223], v[228:231], v[18:21]
	v_mfma_f32_16x16x32_bf16 v[22:25], v[220:223], v[236:239], v[22:25]
	v_mfma_f32_16x16x32_bf16 v[2:5], v[220:223], v[240:243], v[2:5]
	v_mfma_f32_16x16x32_bf16 v[6:9], v[220:223], v[252:255], v[6:9]
	s_waitcnt lgkmcnt(4)
	v_mfma_f32_16x16x32_bf16 v[26:29], v[224:227], v[228:231], v[26:29]
	v_mfma_f32_16x16x32_bf16 v[30:33], v[224:227], v[236:239], v[30:33]
	v_mfma_f32_16x16x32_bf16 v[10:13], v[224:227], v[240:243], v[10:13]
	v_mfma_f32_16x16x32_bf16 v[14:17], v[224:227], v[252:255], v[14:17]
	s_waitcnt lgkmcnt(0)
	s_barrier
	global_load_dwordx4 v[122:125], v[72:73], off offset:1920
	s_nop 0
	global_load_dwordx4 v[72:75], v[74:75], off offset:1920
	s_nop 0
	global_load_dwordx4 v[126:129], v[76:77], off offset:1920
	s_nop 0
	global_load_dwordx4 v[76:79], v[78:79], off offset:1920
	s_nop 0
	global_load_dwordx4 v[136:139], v[70:71], off offset:1920
	s_nop 0
	global_load_dwordx4 v[68:71], v[68:69], off offset:1920
	s_nop 0
	global_load_dwordx4 v[140:143], v[66:67], off offset:1920
	global_load_dwordx4 v[144:147], v[80:81], off offset:1920
	ds_read_b128 v[228:231], v245 offset:55296
	ds_read_b128 v[212:215], v244 offset:18432
	ds_read_b128 v[236:239], v245 offset:57600
	ds_read_b128 v[240:243], v245 offset:59904
	ds_read_b128 v[252:255], v245 offset:62208
	ds_read_b128 v[216:219], v244 offset:20736
	ds_read_b128 v[220:223], v244 offset:23040
	ds_read_b128 v[224:227], v244 offset:25344
	s_waitcnt lgkmcnt(6)
	v_mfma_f32_16x16x32_bf16 v[50:53], v[212:215], v[228:231], v[50:53]
	s_waitcnt lgkmcnt(5)
	v_mfma_f32_16x16x32_bf16 v[54:57], v[212:215], v[236:239], v[54:57]
	s_waitcnt lgkmcnt(4)
	v_mfma_f32_16x16x32_bf16 v[34:37], v[212:215], v[240:243], v[34:37]
	s_waitcnt lgkmcnt(3)
	v_mfma_f32_16x16x32_bf16 v[38:41], v[212:215], v[252:255], v[38:41]
	ds_read_b128 v[212:215], v244 offset:18496
	s_waitcnt lgkmcnt(3)
	v_mfma_f32_16x16x32_bf16 v[58:61], v[216:219], v[228:231], v[58:61]
	v_mfma_f32_16x16x32_bf16 v[62:65], v[216:219], v[236:239], v[62:65]
	v_mfma_f32_16x16x32_bf16 v[42:45], v[216:219], v[240:243], v[42:45]
	v_mfma_f32_16x16x32_bf16 v[46:49], v[216:219], v[252:255], v[46:49]
	ds_read_b128 v[216:219], v244 offset:20800
	s_waitcnt vmcnt(15)
	ds_write_b128 v165, v[180:183]
	s_waitcnt vmcnt(14)
	ds_write_b128 v165, v[184:187] offset:4608
	s_waitcnt lgkmcnt(5)
	v_mfma_f32_16x16x32_bf16 v[18:21], v[220:223], v[228:231], v[18:21]
	v_mfma_f32_16x16x32_bf16 v[22:25], v[220:223], v[236:239], v[22:25]
	v_mfma_f32_16x16x32_bf16 v[2:5], v[220:223], v[240:243], v[2:5]
	v_mfma_f32_16x16x32_bf16 v[6:9], v[220:223], v[252:255], v[6:9]
	ds_read_b128 v[220:223], v244 offset:23104
	s_waitcnt vmcnt(13)
	ds_write_b128 v165, v[188:191] offset:9216
	s_waitcnt vmcnt(12)
	ds_write_b128 v165, v[192:195] offset:13824
	s_waitcnt lgkmcnt(7)
	v_mfma_f32_16x16x32_bf16 v[26:29], v[224:227], v[228:231], v[26:29]
	ds_read_b128 v[228:231], v245 offset:55360
	v_mfma_f32_16x16x32_bf16 v[30:33], v[224:227], v[236:239], v[30:33]
	ds_read_b128 v[236:239], v245 offset:57664
	v_mfma_f32_16x16x32_bf16 v[10:13], v[224:227], v[240:243], v[10:13]
	ds_read_b128 v[240:243], v245 offset:59968
	v_mfma_f32_16x16x32_bf16 v[14:17], v[224:227], v[252:255], v[14:17]
	ds_read_b128 v[252:255], v245 offset:62272
	ds_read_b128 v[224:227], v244 offset:25408
	s_waitcnt lgkmcnt(4)
	v_mfma_f32_16x16x32_bf16 v[50:53], v[212:215], v[228:231], v[50:53]
	s_waitcnt lgkmcnt(3)
	v_mfma_f32_16x16x32_bf16 v[54:57], v[212:215], v[236:239], v[54:57]
	s_waitcnt lgkmcnt(2)
	v_mfma_f32_16x16x32_bf16 v[34:37], v[212:215], v[240:243], v[34:37]
	s_waitcnt lgkmcnt(1)
	v_mfma_f32_16x16x32_bf16 v[38:41], v[212:215], v[252:255], v[38:41]
	s_waitcnt vmcnt(11)
	ds_write_b128 v165, v[196:199] offset:36864
	s_waitcnt vmcnt(10)
	ds_write_b128 v165, v[200:203] offset:41472
	v_mfma_f32_16x16x32_bf16 v[58:61], v[216:219], v[228:231], v[58:61]
	v_mfma_f32_16x16x32_bf16 v[62:65], v[216:219], v[236:239], v[62:65]
	v_mfma_f32_16x16x32_bf16 v[42:45], v[216:219], v[240:243], v[42:45]
	v_mfma_f32_16x16x32_bf16 v[46:49], v[216:219], v[252:255], v[46:49]
	s_waitcnt vmcnt(9)
	ds_write_b128 v165, v[204:207] offset:46080
	s_waitcnt vmcnt(8)
	ds_write_b128 v165, v[208:211] offset:50688
	v_mfma_f32_16x16x32_bf16 v[18:21], v[220:223], v[228:231], v[18:21]
	v_mfma_f32_16x16x32_bf16 v[22:25], v[220:223], v[236:239], v[22:25]
	v_mfma_f32_16x16x32_bf16 v[2:5], v[220:223], v[240:243], v[2:5]
	v_mfma_f32_16x16x32_bf16 v[6:9], v[220:223], v[252:255], v[6:9]
	s_waitcnt lgkmcnt(4)
	v_mfma_f32_16x16x32_bf16 v[26:29], v[224:227], v[228:231], v[26:29]
	v_mfma_f32_16x16x32_bf16 v[30:33], v[224:227], v[236:239], v[30:33]
	v_mfma_f32_16x16x32_bf16 v[10:13], v[224:227], v[240:243], v[10:13]
	v_mfma_f32_16x16x32_bf16 v[14:17], v[224:227], v[252:255], v[14:17]
	s_waitcnt lgkmcnt(0)
	s_barrier
	ds_read_b128 v[228:231], v245 offset:36864
	ds_read_b128 v[212:215], v244
	ds_read_b128 v[236:239], v245 offset:39168
	ds_read_b128 v[240:243], v245 offset:41472
	ds_read_b128 v[252:255], v245 offset:43776
	ds_read_b128 v[216:219], v244 offset:2304
	ds_read_b128 v[220:223], v244 offset:4608
	ds_read_b128 v[224:227], v244 offset:6912
	s_waitcnt lgkmcnt(6)
	v_mfma_f32_16x16x32_bf16 v[50:53], v[212:215], v[228:231], v[50:53]
	s_waitcnt lgkmcnt(5)
	v_mfma_f32_16x16x32_bf16 v[54:57], v[212:215], v[236:239], v[54:57]
	s_waitcnt lgkmcnt(4)
	v_mfma_f32_16x16x32_bf16 v[34:37], v[212:215], v[240:243], v[34:37]
	s_waitcnt lgkmcnt(3)
	v_mfma_f32_16x16x32_bf16 v[38:41], v[212:215], v[252:255], v[38:41]
	ds_read_b128 v[212:215], v244 offset:64
	s_waitcnt lgkmcnt(3)
	v_mfma_f32_16x16x32_bf16 v[58:61], v[216:219], v[228:231], v[58:61]
	v_mfma_f32_16x16x32_bf16 v[62:65], v[216:219], v[236:239], v[62:65]
	v_mfma_f32_16x16x32_bf16 v[42:45], v[216:219], v[240:243], v[42:45]
	v_mfma_f32_16x16x32_bf16 v[46:49], v[216:219], v[252:255], v[46:49]
	ds_read_b128 v[216:219], v244 offset:2368
	s_waitcnt vmcnt(7)
	ds_write_b128 v165, v[122:125] offset:18432
	s_waitcnt vmcnt(6)
	ds_write_b128 v165, v[72:75] offset:23040
	s_waitcnt lgkmcnt(5)
	v_mfma_f32_16x16x32_bf16 v[18:21], v[220:223], v[228:231], v[18:21]
	v_mfma_f32_16x16x32_bf16 v[22:25], v[220:223], v[236:239], v[22:25]
	v_mfma_f32_16x16x32_bf16 v[2:5], v[220:223], v[240:243], v[2:5]
	v_mfma_f32_16x16x32_bf16 v[6:9], v[220:223], v[252:255], v[6:9]
	ds_read_b128 v[220:223], v244 offset:4672
	s_waitcnt vmcnt(5)
	ds_write_b128 v165, v[126:129] offset:27648
	s_waitcnt vmcnt(4)
	ds_write_b128 v165, v[76:79] offset:32256
	s_waitcnt lgkmcnt(7)
	v_mfma_f32_16x16x32_bf16 v[26:29], v[224:227], v[228:231], v[26:29]
	ds_read_b128 v[228:231], v245 offset:36928
	v_mfma_f32_16x16x32_bf16 v[30:33], v[224:227], v[236:239], v[30:33]
	ds_read_b128 v[236:239], v245 offset:39232
	v_mfma_f32_16x16x32_bf16 v[10:13], v[224:227], v[240:243], v[10:13]
	ds_read_b128 v[240:243], v245 offset:41536
	v_mfma_f32_16x16x32_bf16 v[14:17], v[224:227], v[252:255], v[14:17]
	ds_read_b128 v[252:255], v245 offset:43840
	ds_read_b128 v[224:227], v244 offset:6976
	s_waitcnt lgkmcnt(4)
	v_mfma_f32_16x16x32_bf16 v[50:53], v[212:215], v[228:231], v[50:53]
	s_waitcnt lgkmcnt(3)
	v_mfma_f32_16x16x32_bf16 v[54:57], v[212:215], v[236:239], v[54:57]
	s_waitcnt lgkmcnt(2)
	v_mfma_f32_16x16x32_bf16 v[34:37], v[212:215], v[240:243], v[34:37]
	s_waitcnt lgkmcnt(1)
	v_mfma_f32_16x16x32_bf16 v[38:41], v[212:215], v[252:255], v[38:41]
	s_waitcnt vmcnt(3)
	ds_write_b128 v165, v[136:139] offset:55296
	s_waitcnt vmcnt(2)
	ds_write_b128 v165, v[68:71] offset:59904
	v_mfma_f32_16x16x32_bf16 v[58:61], v[216:219], v[228:231], v[58:61]
	v_mfma_f32_16x16x32_bf16 v[62:65], v[216:219], v[236:239], v[62:65]
	v_mfma_f32_16x16x32_bf16 v[42:45], v[216:219], v[240:243], v[42:45]
	v_mfma_f32_16x16x32_bf16 v[46:49], v[216:219], v[252:255], v[46:49]
	s_waitcnt vmcnt(1)
	ds_write_b128 v165, v[140:143] offset:64512
	s_waitcnt vmcnt(0)
	ds_write_b128 v166, v[144:147] offset:32256
	v_mfma_f32_16x16x32_bf16 v[18:21], v[220:223], v[228:231], v[18:21]
	v_mfma_f32_16x16x32_bf16 v[22:25], v[220:223], v[236:239], v[22:25]
	v_mfma_f32_16x16x32_bf16 v[2:5], v[220:223], v[240:243], v[2:5]
	v_mfma_f32_16x16x32_bf16 v[6:9], v[220:223], v[252:255], v[6:9]
	s_waitcnt lgkmcnt(4)
	v_mfma_f32_16x16x32_bf16 v[26:29], v[224:227], v[228:231], v[26:29]
	v_mfma_f32_16x16x32_bf16 v[30:33], v[224:227], v[236:239], v[30:33]
	v_mfma_f32_16x16x32_bf16 v[10:13], v[224:227], v[240:243], v[10:13]
	v_mfma_f32_16x16x32_bf16 v[14:17], v[224:227], v[252:255], v[14:17]
	s_waitcnt lgkmcnt(0)
	s_barrier
	ds_read_b128 v[228:231], v245 offset:55296
	ds_read_b128 v[212:215], v244 offset:18432
	ds_read_b128 v[236:239], v245 offset:57600
	ds_read_b128 v[240:243], v245 offset:59904
	ds_read_b128 v[252:255], v245 offset:62208
	ds_read_b128 v[216:219], v244 offset:20736
	ds_read_b128 v[220:223], v244 offset:23040
	ds_read_b128 v[224:227], v244 offset:25344
	s_waitcnt lgkmcnt(6)
	v_mfma_f32_16x16x32_bf16 v[50:53], v[212:215], v[228:231], v[50:53]
	s_waitcnt lgkmcnt(5)
	v_mfma_f32_16x16x32_bf16 v[54:57], v[212:215], v[236:239], v[54:57]
	s_waitcnt lgkmcnt(4)
	v_mfma_f32_16x16x32_bf16 v[34:37], v[212:215], v[240:243], v[34:37]
	s_waitcnt lgkmcnt(3)
	v_mfma_f32_16x16x32_bf16 v[38:41], v[212:215], v[252:255], v[38:41]
	ds_read_b128 v[212:215], v244 offset:18496
	s_waitcnt lgkmcnt(3)
	v_mfma_f32_16x16x32_bf16 v[58:61], v[216:219], v[228:231], v[58:61]
	v_mfma_f32_16x16x32_bf16 v[62:65], v[216:219], v[236:239], v[62:65]
	v_mfma_f32_16x16x32_bf16 v[42:45], v[216:219], v[240:243], v[42:45]
	v_mfma_f32_16x16x32_bf16 v[46:49], v[216:219], v[252:255], v[46:49]
	ds_read_b128 v[216:219], v244 offset:20800
	s_waitcnt lgkmcnt(3)
	v_mfma_f32_16x16x32_bf16 v[18:21], v[220:223], v[228:231], v[18:21]
	v_mfma_f32_16x16x32_bf16 v[22:25], v[220:223], v[236:239], v[22:25]
	v_mfma_f32_16x16x32_bf16 v[2:5], v[220:223], v[240:243], v[2:5]
	v_mfma_f32_16x16x32_bf16 v[6:9], v[220:223], v[252:255], v[6:9]
	ds_read_b128 v[220:223], v244 offset:23104
	s_waitcnt lgkmcnt(3)
	v_mfma_f32_16x16x32_bf16 v[26:29], v[224:227], v[228:231], v[26:29]
	ds_read_b128 v[228:231], v245 offset:55360
	v_mfma_f32_16x16x32_bf16 v[30:33], v[224:227], v[236:239], v[30:33]
	ds_read_b128 v[236:239], v245 offset:57664
	v_mfma_f32_16x16x32_bf16 v[10:13], v[224:227], v[240:243], v[10:13]
	ds_read_b128 v[240:243], v245 offset:59968
	v_mfma_f32_16x16x32_bf16 v[14:17], v[224:227], v[252:255], v[14:17]
	ds_read_b128 v[252:255], v245 offset:62272
	ds_read_b128 v[224:227], v244 offset:25408
	s_waitcnt lgkmcnt(4)
	v_mfma_f32_16x16x32_bf16 v[50:53], v[212:215], v[228:231], v[50:53]
	s_waitcnt lgkmcnt(3)
	v_mfma_f32_16x16x32_bf16 v[54:57], v[212:215], v[236:239], v[54:57]
	s_waitcnt lgkmcnt(2)
	v_mfma_f32_16x16x32_bf16 v[34:37], v[212:215], v[240:243], v[34:37]
	s_waitcnt lgkmcnt(1)
	v_mfma_f32_16x16x32_bf16 v[38:41], v[212:215], v[252:255], v[38:41]
	v_mfma_f32_16x16x32_bf16 v[58:61], v[216:219], v[228:231], v[58:61]
	v_mfma_f32_16x16x32_bf16 v[62:65], v[216:219], v[236:239], v[62:65]
	v_mfma_f32_16x16x32_bf16 v[42:45], v[216:219], v[240:243], v[42:45]
	v_mfma_f32_16x16x32_bf16 v[46:49], v[216:219], v[252:255], v[46:49]
	v_mfma_f32_16x16x32_bf16 v[18:21], v[220:223], v[228:231], v[18:21]
	v_mfma_f32_16x16x32_bf16 v[22:25], v[220:223], v[236:239], v[22:25]
	v_mfma_f32_16x16x32_bf16 v[2:5], v[220:223], v[240:243], v[2:5]
	v_mfma_f32_16x16x32_bf16 v[6:9], v[220:223], v[252:255], v[6:9]
	s_waitcnt lgkmcnt(0)
	v_mfma_f32_16x16x32_bf16 v[26:29], v[224:227], v[228:231], v[26:29]
	v_mfma_f32_16x16x32_bf16 v[30:33], v[224:227], v[236:239], v[30:33]
	v_mfma_f32_16x16x32_bf16 v[10:13], v[224:227], v[240:243], v[10:13]
	v_mfma_f32_16x16x32_bf16 v[14:17], v[224:227], v[252:255], v[14:17]
	s_mov_b64 s[2:3], 0
	s_waitcnt lgkmcnt(0)
	s_barrier
	s_nop 7
	v_permlane16_swap_b32_e32 v50, v54
	v_permlane16_swap_b32_e32 v51, v55
	v_permlane16_swap_b32_e32 v52, v56
	v_permlane16_swap_b32_e32 v53, v57
	v_permlane16_swap_b32_e32 v58, v62
	v_permlane16_swap_b32_e32 v59, v63
	v_permlane16_swap_b32_e32 v60, v64
	v_permlane16_swap_b32_e32 v61, v65
	v_permlane16_swap_b32_e32 v34, v38
	v_permlane16_swap_b32_e32 v35, v39
	v_permlane16_swap_b32_e32 v36, v40
	v_permlane16_swap_b32_e32 v37, v41
	v_permlane16_swap_b32_e32 v42, v46
	v_permlane16_swap_b32_e32 v43, v47
	v_permlane16_swap_b32_e32 v44, v48
	v_permlane16_swap_b32_e32 v45, v49
	v_permlane16_swap_b32_e32 v18, v22
	v_permlane16_swap_b32_e32 v19, v23
	v_permlane16_swap_b32_e32 v20, v24
	v_permlane16_swap_b32_e32 v21, v25
	v_permlane16_swap_b32_e32 v26, v30
	v_permlane16_swap_b32_e32 v27, v31
	v_permlane16_swap_b32_e32 v28, v32
	v_permlane16_swap_b32_e32 v29, v33
	v_permlane16_swap_b32_e32 v2, v6
	v_permlane16_swap_b32_e32 v3, v7
	v_permlane16_swap_b32_e32 v4, v8
	v_permlane16_swap_b32_e32 v5, v9
	v_permlane16_swap_b32_e32 v10, v14
	v_permlane16_swap_b32_e32 v11, v15
	v_permlane16_swap_b32_e32 v12, v16
	v_permlane16_swap_b32_e32 v13, v17
	v_permlane32_swap_b32_e32 v50, v54
	v_permlane32_swap_b32_e32 v51, v55
	v_permlane32_swap_b32_e32 v52, v56
	v_permlane32_swap_b32_e32 v53, v57
	v_permlane32_swap_b32_e32 v58, v62
	v_permlane32_swap_b32_e32 v59, v63
	v_permlane32_swap_b32_e32 v60, v64
	v_permlane32_swap_b32_e32 v61, v65
	v_permlane32_swap_b32_e32 v34, v38
	v_permlane32_swap_b32_e32 v35, v39
	v_permlane32_swap_b32_e32 v36, v40
	v_permlane32_swap_b32_e32 v37, v41
	v_permlane32_swap_b32_e32 v42, v46
	v_permlane32_swap_b32_e32 v43, v47
	v_permlane32_swap_b32_e32 v44, v48
	v_permlane32_swap_b32_e32 v45, v49
	v_permlane32_swap_b32_e32 v18, v22
	v_permlane32_swap_b32_e32 v19, v23
	v_permlane32_swap_b32_e32 v20, v24
	v_permlane32_swap_b32_e32 v21, v25
	v_permlane32_swap_b32_e32 v26, v30
	v_permlane32_swap_b32_e32 v27, v31
	v_permlane32_swap_b32_e32 v28, v32
	v_permlane32_swap_b32_e32 v29, v33
	v_permlane32_swap_b32_e32 v2, v6
	v_permlane32_swap_b32_e32 v3, v7
	v_permlane32_swap_b32_e32 v4, v8
	v_permlane32_swap_b32_e32 v5, v9
	v_permlane32_swap_b32_e32 v10, v14
	v_permlane32_swap_b32_e32 v11, v15
	v_permlane32_swap_b32_e32 v12, v16
	v_permlane32_swap_b32_e32 v13, v17

.LBB0_275:
	v_ashrrev_i32_e32 v3, 31, v2
	v_lshlrev_b64 v[2:3], 11, v[2:3]
	v_ashrrev_i32_e32 v9, 31, v8
	v_lshl_add_u64 v[70:71], v[86:87], 0, v[2:3]
	v_lshlrev_b64 v[2:3], 11, v[8:9]
	v_lshl_add_u64 v[72:73], v[86:87], 0, v[2:3]
	v_or_b32_e32 v2, s56, v154
	v_ashrrev_i32_e32 v3, 31, v2
	v_lshlrev_b64 v[2:3], 11, v[2:3]
	v_lshl_add_u64 v[74:75], v[84:85], 0, v[2:3]
	v_add_u32_e32 v2, s56, v155
	v_ashrrev_i32_e32 v3, 31, v2
	v_lshlrev_b64 v[2:3], 11, v[2:3]
	v_lshl_add_u64 v[76:77], v[84:85], 0, v[2:3]
	v_add_u32_e32 v2, s56, v156
	v_ashrrev_i32_e32 v3, 31, v2
	v_lshlrev_b64 v[2:3], 11, v[2:3]
	v_lshl_add_u64 v[78:79], v[84:85], 0, v[2:3]
	v_add_u32_e32 v2, s56, v157
	v_ashrrev_i32_e32 v7, 31, v6
	v_ashrrev_i32_e32 v5, 31, v4
	v_ashrrev_i32_e32 v3, 31, v2
	v_lshlrev_b64 v[6:7], 11, v[6:7]
	v_lshlrev_b64 v[4:5], 11, v[4:5]
	v_lshlrev_b64 v[2:3], 11, v[2:3]
	v_lshl_add_u64 v[66:67], v[86:87], 0, v[6:7]
	v_lshl_add_u64 v[68:69], v[86:87], 0, v[4:5]
	v_lshl_add_u64 v[80:81], v[84:85], 0, v[2:3]
	global_load_dwordx4 v[2:5], v[70:71], off
	global_load_dwordx4 v[6:9], v[68:69], off
	global_load_dwordx4 v[10:13], v[66:67], off
	global_load_dwordx4 v[14:17], v[72:73], off
	global_load_dwordx4 v[18:21], v[74:75], off
	global_load_dwordx4 v[22:25], v[76:77], off
	global_load_dwordx4 v[26:29], v[78:79], off
	global_load_dwordx4 v[30:33], v[80:81], off
	global_load_dwordx4 v[122:125], v[70:71], off offset:128
	global_load_dwordx4 v[126:129], v[68:69], off offset:128
	global_load_dwordx4 v[136:139], v[66:67], off offset:128
	global_load_dwordx4 v[140:143], v[72:73], off offset:128
	global_load_dwordx4 v[144:147], v[74:75], off offset:128
	global_load_dwordx4 v[148:151], v[76:77], off offset:128
	global_load_dwordx4 v[172:175], v[78:79], off offset:128
	global_load_dwordx4 v[176:179], v[80:81], off offset:128
	s_waitcnt vmcnt(15)
	ds_write_b128 v165, v[2:5]
	s_waitcnt vmcnt(14)
	ds_write_b128 v165, v[6:9] offset:4608
	s_waitcnt vmcnt(13)
	ds_write_b128 v165, v[10:13] offset:9216
	s_waitcnt vmcnt(12)
	ds_write_b128 v165, v[14:17] offset:13824
	s_waitcnt vmcnt(11)
	ds_write_b128 v165, v[18:21] offset:36864
	s_waitcnt vmcnt(10)
	ds_write_b128 v165, v[22:25] offset:41472
	s_waitcnt vmcnt(9)
	ds_write_b128 v165, v[26:29] offset:46080
	s_waitcnt vmcnt(8)
	ds_write_b128 v165, v[30:33] offset:50688
	s_waitcnt lgkmcnt(0)
	s_barrier
	global_load_dwordx4 v[180:183], v[68:69], off offset:256
	global_load_dwordx4 v[184:187], v[66:67], off offset:256
	global_load_dwordx4 v[188:191], v[70:71], off offset:256
	global_load_dwordx4 v[192:195], v[72:73], off offset:256
	global_load_dwordx4 v[196:199], v[74:75], off offset:256
	global_load_dwordx4 v[200:203], v[76:77], off offset:256
	global_load_dwordx4 v[204:207], v[78:79], off offset:256
	global_load_dwordx4 v[208:211], v[80:81], off offset:256
	v_and_b32_e32 v246, 15, v1
	v_add_u32_e32 v246, 4, v246
	v_bfe_u32 v246, v246, 3, 1
	v_bfe_u32 v249, v1, 4, 2
	v_xor_b32_e32 v246, v246, v249
	v_bfe_u32 v249, v1, 5, 1
	v_sub_u32_e32 v246, v246, v249
	v_lshlrev_b32_e32 v246, 4, v246
	v_bfe_u32 v249, v1, 4, 1
	v_mul_u32_u24_e32 v249, 0x900, v249
	v_sub_u32_e32 v246, v246, v249
	v_add_u32_e32 v244, v246, v162
	v_add_u32_e32 v245, v246, v164
	ds_read_b128 v[228:231], v245 offset:36864
	ds_read_b128 v[212:215], v244
	ds_read_b128 v[236:239], v245 offset:39168
	ds_read_b128 v[240:243], v245 offset:41472
	ds_read_b128 v[252:255], v245 offset:43776
	ds_read_b128 v[216:219], v244 offset:2304
	ds_read_b128 v[220:223], v244 offset:4608
	ds_read_b128 v[224:227], v244 offset:6912
	s_waitcnt lgkmcnt(6)
	v_mfma_f32_16x16x32_bf16 v[50:53], v[212:215], v[228:231], 0
	s_waitcnt lgkmcnt(5)
	v_mfma_f32_16x16x32_bf16 v[54:57], v[212:215], v[236:239], 0
	s_waitcnt lgkmcnt(4)
	v_mfma_f32_16x16x32_bf16 v[34:37], v[212:215], v[240:243], 0
	s_waitcnt lgkmcnt(3)
	v_mfma_f32_16x16x32_bf16 v[38:41], v[212:215], v[252:255], 0
	ds_read_b128 v[212:215], v244 offset:64
	s_waitcnt lgkmcnt(3)
	v_mfma_f32_16x16x32_bf16 v[58:61], v[216:219], v[228:231], 0
	v_mfma_f32_16x16x32_bf16 v[62:65], v[216:219], v[236:239], 0
	v_mfma_f32_16x16x32_bf16 v[42:45], v[216:219], v[240:243], 0
	v_mfma_f32_16x16x32_bf16 v[46:49], v[216:219], v[252:255], 0
	ds_read_b128 v[216:219], v244 offset:2368
	s_waitcnt vmcnt(15)
	ds_write_b128 v165, v[122:125] offset:18432
	s_waitcnt vmcnt(14)
	ds_write_b128 v165, v[126:129] offset:23040
	s_waitcnt lgkmcnt(5)
	v_mfma_f32_16x16x32_bf16 v[18:21], v[220:223], v[228:231], 0
	v_mfma_f32_16x16x32_bf16 v[22:25], v[220:223], v[236:239], 0
	v_mfma_f32_16x16x32_bf16 v[2:5], v[220:223], v[240:243], 0
	v_mfma_f32_16x16x32_bf16 v[6:9], v[220:223], v[252:255], 0
	ds_read_b128 v[220:223], v244 offset:4672
	s_waitcnt vmcnt(13)
	ds_write_b128 v165, v[136:139] offset:27648
	s_waitcnt vmcnt(12)
	ds_write_b128 v165, v[140:143] offset:32256
	s_waitcnt lgkmcnt(7)
	v_mfma_f32_16x16x32_bf16 v[26:29], v[224:227], v[228:231], 0
	ds_read_b128 v[228:231], v245 offset:36928
	v_mfma_f32_16x16x32_bf16 v[30:33], v[224:227], v[236:239], 0
	ds_read_b128 v[236:239], v245 offset:39232
	v_mfma_f32_16x16x32_bf16 v[10:13], v[224:227], v[240:243], 0
	ds_read_b128 v[240:243], v245 offset:41536
	v_mfma_f32_16x16x32_bf16 v[14:17], v[224:227], v[252:255], 0
	ds_read_b128 v[252:255], v245 offset:43840
	ds_read_b128 v[224:227], v244 offset:6976
	s_waitcnt lgkmcnt(4)
	v_mfma_f32_16x16x32_bf16 v[50:53], v[212:215], v[228:231], v[50:53]
	s_waitcnt lgkmcnt(3)
	v_mfma_f32_16x16x32_bf16 v[54:57], v[212:215], v[236:239], v[54:57]
	s_waitcnt lgkmcnt(2)
	v_mfma_f32_16x16x32_bf16 v[34:37], v[212:215], v[240:243], v[34:37]
	s_waitcnt lgkmcnt(1)
	v_mfma_f32_16x16x32_bf16 v[38:41], v[212:215], v[252:255], v[38:41]
	s_waitcnt vmcnt(11)
	ds_write_b128 v165, v[144:147] offset:55296
	s_waitcnt vmcnt(10)
	ds_write_b128 v165, v[148:151] offset:59904
	v_mfma_f32_16x16x32_bf16 v[58:61], v[216:219], v[228:231], v[58:61]
	v_mfma_f32_16x16x32_bf16 v[62:65], v[216:219], v[236:239], v[62:65]
	v_mfma_f32_16x16x32_bf16 v[42:45], v[216:219], v[240:243], v[42:45]
	v_mfma_f32_16x16x32_bf16 v[46:49], v[216:219], v[252:255], v[46:49]
	s_waitcnt vmcnt(9)
	ds_write_b128 v165, v[172:175] offset:64512
	s_waitcnt vmcnt(8)
	ds_write_b128 v166, v[176:179] offset:32256
	v_mfma_f32_16x16x32_bf16 v[18:21], v[220:223], v[228:231], v[18:21]
	v_mfma_f32_16x16x32_bf16 v[22:25], v[220:223], v[236:239], v[22:25]
	v_mfma_f32_16x16x32_bf16 v[2:5], v[220:223], v[240:243], v[2:5]
	v_mfma_f32_16x16x32_bf16 v[6:9], v[220:223], v[252:255], v[6:9]
	s_waitcnt lgkmcnt(4)
	v_mfma_f32_16x16x32_bf16 v[26:29], v[224:227], v[228:231], v[26:29]
	v_mfma_f32_16x16x32_bf16 v[30:33], v[224:227], v[236:239], v[30:33]
	v_mfma_f32_16x16x32_bf16 v[10:13], v[224:227], v[240:243], v[10:13]
	v_mfma_f32_16x16x32_bf16 v[14:17], v[224:227], v[252:255], v[14:17]
	s_waitcnt lgkmcnt(0)
	s_barrier
	global_load_dwordx4 v[122:125], v[70:71], off offset:384
	global_load_dwordx4 v[126:129], v[68:69], off offset:384
	global_load_dwordx4 v[136:139], v[66:67], off offset:384
	global_load_dwordx4 v[140:143], v[72:73], off offset:384
	global_load_dwordx4 v[144:147], v[74:75], off offset:384
	global_load_dwordx4 v[148:151], v[76:77], off offset:384
	global_load_dwordx4 v[172:175], v[78:79], off offset:384
	global_load_dwordx4 v[176:179], v[80:81], off offset:384
	ds_read_b128 v[228:231], v245 offset:55296
	ds_read_b128 v[212:215], v244 offset:18432
	ds_read_b128 v[236:239], v245 offset:57600
	ds_read_b128 v[240:243], v245 offset:59904
	ds_read_b128 v[252:255], v245 offset:62208
	ds_read_b128 v[216:219], v244 offset:20736
	ds_read_b128 v[220:223], v244 offset:23040
	ds_read_b128 v[224:227], v244 offset:25344
	s_waitcnt lgkmcnt(6)
	v_mfma_f32_16x16x32_bf16 v[50:53], v[212:215], v[228:231], v[50:53]
	s_waitcnt lgkmcnt(5)
	v_mfma_f32_16x16x32_bf16 v[54:57], v[212:215], v[236:239], v[54:57]
	s_waitcnt lgkmcnt(4)
	v_mfma_f32_16x16x32_bf16 v[34:37], v[212:215], v[240:243], v[34:37]
	s_waitcnt lgkmcnt(3)
	v_mfma_f32_16x16x32_bf16 v[38:41], v[212:215], v[252:255], v[38:41]
	ds_read_b128 v[212:215], v244 offset:18496
	s_waitcnt lgkmcnt(3)
	v_mfma_f32_16x16x32_bf16 v[58:61], v[216:219], v[228:231], v[58:61]
	v_mfma_f32_16x16x32_bf16 v[62:65], v[216:219], v[236:239], v[62:65]
	v_mfma_f32_16x16x32_bf16 v[42:45], v[216:219], v[240:243], v[42:45]
	v_mfma_f32_16x16x32_bf16 v[46:49], v[216:219], v[252:255], v[46:49]
	ds_read_b128 v[216:219], v244 offset:20800
	s_waitcnt vmcnt(13)
	ds_write_b128 v165, v[188:191]
	ds_write_b128 v165, v[180:183] offset:4608
	s_waitcnt lgkmcnt(5)
	v_mfma_f32_16x16x32_bf16 v[18:21], v[220:223], v[228:231], v[18:21]
	v_mfma_f32_16x16x32_bf16 v[22:25], v[220:223], v[236:239], v[22:25]
	v_mfma_f32_16x16x32_bf16 v[2:5], v[220:223], v[240:243], v[2:5]
	v_mfma_f32_16x16x32_bf16 v[6:9], v[220:223], v[252:255], v[6:9]
	ds_read_b128 v[220:223], v244 offset:23104
	ds_write_b128 v165, v[184:187] offset:9216
	s_waitcnt vmcnt(12)
	ds_write_b128 v165, v[192:195] offset:13824
	s_waitcnt lgkmcnt(7)
	v_mfma_f32_16x16x32_bf16 v[26:29], v[224:227], v[228:231], v[26:29]
	ds_read_b128 v[228:231], v245 offset:55360
	v_mfma_f32_16x16x32_bf16 v[30:33], v[224:227], v[236:239], v[30:33]
	ds_read_b128 v[236:239], v245 offset:57664
	v_mfma_f32_16x16x32_bf16 v[10:13], v[224:227], v[240:243], v[10:13]
	ds_read_b128 v[240:243], v245 offset:59968
	v_mfma_f32_16x16x32_bf16 v[14:17], v[224:227], v[252:255], v[14:17]
	ds_read_b128 v[252:255], v245 offset:62272
	ds_read_b128 v[224:227], v244 offset:25408
	s_waitcnt lgkmcnt(4)
	v_mfma_f32_16x16x32_bf16 v[50:53], v[212:215], v[228:231], v[50:53]
	s_waitcnt lgkmcnt(3)
	v_mfma_f32_16x16x32_bf16 v[54:57], v[212:215], v[236:239], v[54:57]
	s_waitcnt lgkmcnt(2)
	v_mfma_f32_16x16x32_bf16 v[34:37], v[212:215], v[240:243], v[34:37]
	s_waitcnt lgkmcnt(1)
	v_mfma_f32_16x16x32_bf16 v[38:41], v[212:215], v[252:255], v[38:41]
	s_waitcnt vmcnt(11)
	ds_write_b128 v165, v[196:199] offset:36864
	s_waitcnt vmcnt(10)
	ds_write_b128 v165, v[200:203] offset:41472
	v_mfma_f32_16x16x32_bf16 v[58:61], v[216:219], v[228:231], v[58:61]
	v_mfma_f32_16x16x32_bf16 v[62:65], v[216:219], v[236:239], v[62:65]
	v_mfma_f32_16x16x32_bf16 v[42:45], v[216:219], v[240:243], v[42:45]
	v_mfma_f32_16x16x32_bf16 v[46:49], v[216:219], v[252:255], v[46:49]
	s_waitcnt vmcnt(9)
	ds_write_b128 v165, v[204:207] offset:46080
	s_waitcnt vmcnt(8)
	ds_write_b128 v165, v[208:211] offset:50688
	v_mfma_f32_16x16x32_bf16 v[18:21], v[220:223], v[228:231], v[18:21]
	v_mfma_f32_16x16x32_bf16 v[22:25], v[220:223], v[236:239], v[22:25]
	v_mfma_f32_16x16x32_bf16 v[2:5], v[220:223], v[240:243], v[2:5]
	v_mfma_f32_16x16x32_bf16 v[6:9], v[220:223], v[252:255], v[6:9]
	s_waitcnt lgkmcnt(4)
	v_mfma_f32_16x16x32_bf16 v[26:29], v[224:227], v[228:231], v[26:29]
	v_mfma_f32_16x16x32_bf16 v[30:33], v[224:227], v[236:239], v[30:33]
	v_mfma_f32_16x16x32_bf16 v[10:13], v[224:227], v[240:243], v[10:13]
	v_mfma_f32_16x16x32_bf16 v[14:17], v[224:227], v[252:255], v[14:17]
	s_waitcnt lgkmcnt(0)
	s_barrier
	global_load_dwordx4 v[180:183], v[70:71], off offset:512
	global_load_dwordx4 v[184:187], v[68:69], off offset:512
	global_load_dwordx4 v[188:191], v[66:67], off offset:512
	global_load_dwordx4 v[192:195], v[72:73], off offset:512
	global_load_dwordx4 v[196:199], v[74:75], off offset:512
	global_load_dwordx4 v[200:203], v[76:77], off offset:512
	global_load_dwordx4 v[204:207], v[78:79], off offset:512
	global_load_dwordx4 v[208:211], v[80:81], off offset:512
	ds_read_b128 v[228:231], v245 offset:36864
	ds_read_b128 v[212:215], v244
	ds_read_b128 v[236:239], v245 offset:39168
	ds_read_b128 v[240:243], v245 offset:41472
	ds_read_b128 v[252:255], v245 offset:43776
	ds_read_b128 v[216:219], v244 offset:2304
	ds_read_b128 v[220:223], v244 offset:4608
	ds_read_b128 v[224:227], v244 offset:6912
	s_waitcnt lgkmcnt(6)
	v_mfma_f32_16x16x32_bf16 v[50:53], v[212:215], v[228:231], v[50:53]
	s_waitcnt lgkmcnt(5)
	v_mfma_f32_16x16x32_bf16 v[54:57], v[212:215], v[236:239], v[54:57]
	s_waitcnt lgkmcnt(4)
	v_mfma_f32_16x16x32_bf16 v[34:37], v[212:215], v[240:243], v[34:37]
	s_waitcnt lgkmcnt(3)
	v_mfma_f32_16x16x32_bf16 v[38:41], v[212:215], v[252:255], v[38:41]
	ds_read_b128 v[212:215], v244 offset:64
	s_waitcnt lgkmcnt(3)
	v_mfma_f32_16x16x32_bf16 v[58:61], v[216:219], v[228:231], v[58:61]
	v_mfma_f32_16x16x32_bf16 v[62:65], v[216:219], v[236:239], v[62:65]
	v_mfma_f32_16x16x32_bf16 v[42:45], v[216:219], v[240:243], v[42:45]
	v_mfma_f32_16x16x32_bf16 v[46:49], v[216:219], v[252:255], v[46:49]
	ds_read_b128 v[216:219], v244 offset:2368
	s_waitcnt vmcnt(15)
	ds_write_b128 v165, v[122:125] offset:18432
	s_waitcnt vmcnt(14)
	ds_write_b128 v165, v[126:129] offset:23040
	s_waitcnt lgkmcnt(5)
	v_mfma_f32_16x16x32_bf16 v[18:21], v[220:223], v[228:231], v[18:21]
	v_mfma_f32_16x16x32_bf16 v[22:25], v[220:223], v[236:239], v[22:25]
	v_mfma_f32_16x16x32_bf16 v[2:5], v[220:223], v[240:243], v[2:5]
	v_mfma_f32_16x16x32_bf16 v[6:9], v[220:223], v[252:255], v[6:9]
	ds_read_b128 v[220:223], v244 offset:4672
	s_waitcnt vmcnt(13)
	ds_write_b128 v165, v[136:139] offset:27648
	s_waitcnt vmcnt(12)
	ds_write_b128 v165, v[140:143] offset:32256
	s_waitcnt lgkmcnt(7)
	v_mfma_f32_16x16x32_bf16 v[26:29], v[224:227], v[228:231], v[26:29]
	ds_read_b128 v[228:231], v245 offset:36928
	v_mfma_f32_16x16x32_bf16 v[30:33], v[224:227], v[236:239], v[30:33]
	ds_read_b128 v[236:239], v245 offset:39232
	v_mfma_f32_16x16x32_bf16 v[10:13], v[224:227], v[240:243], v[10:13]
	ds_read_b128 v[240:243], v245 offset:41536
	v_mfma_f32_16x16x32_bf16 v[14:17], v[224:227], v[252:255], v[14:17]
	ds_read_b128 v[252:255], v245 offset:43840
	ds_read_b128 v[224:227], v244 offset:6976
	s_waitcnt lgkmcnt(4)
	v_mfma_f32_16x16x32_bf16 v[50:53], v[212:215], v[228:231], v[50:53]
	s_waitcnt lgkmcnt(3)
	v_mfma_f32_16x16x32_bf16 v[54:57], v[212:215], v[236:239], v[54:57]
	s_waitcnt lgkmcnt(2)
	v_mfma_f32_16x16x32_bf16 v[34:37], v[212:215], v[240:243], v[34:37]
	s_waitcnt lgkmcnt(1)
	v_mfma_f32_16x16x32_bf16 v[38:41], v[212:215], v[252:255], v[38:41]
	s_waitcnt vmcnt(11)
	ds_write_b128 v165, v[144:147] offset:55296
	s_waitcnt vmcnt(10)
	ds_write_b128 v165, v[148:151] offset:59904
	v_mfma_f32_16x16x32_bf16 v[58:61], v[216:219], v[228:231], v[58:61]
	v_mfma_f32_16x16x32_bf16 v[62:65], v[216:219], v[236:239], v[62:65]
	v_mfma_f32_16x16x32_bf16 v[42:45], v[216:219], v[240:243], v[42:45]
	v_mfma_f32_16x16x32_bf16 v[46:49], v[216:219], v[252:255], v[46:49]
	s_waitcnt vmcnt(9)
	ds_write_b128 v165, v[172:175] offset:64512
	s_waitcnt vmcnt(8)
	ds_write_b128 v166, v[176:179] offset:32256
	v_mfma_f32_16x16x32_bf16 v[18:21], v[220:223], v[228:231], v[18:21]
	v_mfma_f32_16x16x32_bf16 v[22:25], v[220:223], v[236:239], v[22:25]
	v_mfma_f32_16x16x32_bf16 v[2:5], v[220:223], v[240:243], v[2:5]
	v_mfma_f32_16x16x32_bf16 v[6:9], v[220:223], v[252:255], v[6:9]
	s_waitcnt lgkmcnt(4)
	v_mfma_f32_16x16x32_bf16 v[26:29], v[224:227], v[228:231], v[26:29]
	v_mfma_f32_16x16x32_bf16 v[30:33], v[224:227], v[236:239], v[30:33]
	v_mfma_f32_16x16x32_bf16 v[10:13], v[224:227], v[240:243], v[10:13]
	v_mfma_f32_16x16x32_bf16 v[14:17], v[224:227], v[252:255], v[14:17]
	s_waitcnt lgkmcnt(0)
	s_barrier
	global_load_dwordx4 v[122:125], v[70:71], off offset:640
	global_load_dwordx4 v[126:129], v[68:69], off offset:640
	global_load_dwordx4 v[136:139], v[66:67], off offset:640
	global_load_dwordx4 v[140:143], v[72:73], off offset:640
	global_load_dwordx4 v[144:147], v[74:75], off offset:640
	global_load_dwordx4 v[148:151], v[76:77], off offset:640
	global_load_dwordx4 v[172:175], v[78:79], off offset:640
	global_load_dwordx4 v[176:179], v[80:81], off offset:640
	ds_read_b128 v[228:231], v245 offset:55296
	ds_read_b128 v[212:215], v244 offset:18432
	ds_read_b128 v[236:239], v245 offset:57600
	ds_read_b128 v[240:243], v245 offset:59904
	ds_read_b128 v[252:255], v245 offset:62208
	ds_read_b128 v[216:219], v244 offset:20736
	ds_read_b128 v[220:223], v244 offset:23040
	ds_read_b128 v[224:227], v244 offset:25344
	s_waitcnt lgkmcnt(6)
	v_mfma_f32_16x16x32_bf16 v[50:53], v[212:215], v[228:231], v[50:53]
	s_waitcnt lgkmcnt(5)
	v_mfma_f32_16x16x32_bf16 v[54:57], v[212:215], v[236:239], v[54:57]
	s_waitcnt lgkmcnt(4)
	v_mfma_f32_16x16x32_bf16 v[34:37], v[212:215], v[240:243], v[34:37]
	s_waitcnt lgkmcnt(3)
	v_mfma_f32_16x16x32_bf16 v[38:41], v[212:215], v[252:255], v[38:41]
	ds_read_b128 v[212:215], v244 offset:18496
	s_waitcnt lgkmcnt(3)
	v_mfma_f32_16x16x32_bf16 v[58:61], v[216:219], v[228:231], v[58:61]
	v_mfma_f32_16x16x32_bf16 v[62:65], v[216:219], v[236:239], v[62:65]
	v_mfma_f32_16x16x32_bf16 v[42:45], v[216:219], v[240:243], v[42:45]
	v_mfma_f32_16x16x32_bf16 v[46:49], v[216:219], v[252:255], v[46:49]
	ds_read_b128 v[216:219], v244 offset:20800
	s_waitcnt vmcnt(15)
	ds_write_b128 v165, v[180:183]
	s_waitcnt vmcnt(14)
	ds_write_b128 v165, v[184:187] offset:4608
	s_waitcnt lgkmcnt(5)
	v_mfma_f32_16x16x32_bf16 v[18:21], v[220:223], v[228:231], v[18:21]
	v_mfma_f32_16x16x32_bf16 v[22:25], v[220:223], v[236:239], v[22:25]
	v_mfma_f32_16x16x32_bf16 v[2:5], v[220:223], v[240:243], v[2:5]
	v_mfma_f32_16x16x32_bf16 v[6:9], v[220:223], v[252:255], v[6:9]
	ds_read_b128 v[220:223], v244 offset:23104
	s_waitcnt vmcnt(13)
	ds_write_b128 v165, v[188:191] offset:9216
	s_waitcnt vmcnt(12)
	ds_write_b128 v165, v[192:195] offset:13824
	s_waitcnt lgkmcnt(7)
	v_mfma_f32_16x16x32_bf16 v[26:29], v[224:227], v[228:231], v[26:29]
	ds_read_b128 v[228:231], v245 offset:55360
	v_mfma_f32_16x16x32_bf16 v[30:33], v[224:227], v[236:239], v[30:33]
	ds_read_b128 v[236:239], v245 offset:57664
	v_mfma_f32_16x16x32_bf16 v[10:13], v[224:227], v[240:243], v[10:13]
	ds_read_b128 v[240:243], v245 offset:59968
	v_mfma_f32_16x16x32_bf16 v[14:17], v[224:227], v[252:255], v[14:17]
	ds_read_b128 v[252:255], v245 offset:62272
	ds_read_b128 v[224:227], v244 offset:25408
	s_waitcnt lgkmcnt(4)
	v_mfma_f32_16x16x32_bf16 v[50:53], v[212:215], v[228:231], v[50:53]
	s_waitcnt lgkmcnt(3)
	v_mfma_f32_16x16x32_bf16 v[54:57], v[212:215], v[236:239], v[54:57]
	s_waitcnt lgkmcnt(2)
	v_mfma_f32_16x16x32_bf16 v[34:37], v[212:215], v[240:243], v[34:37]
	s_waitcnt lgkmcnt(1)
	v_mfma_f32_16x16x32_bf16 v[38:41], v[212:215], v[252:255], v[38:41]
	s_waitcnt vmcnt(11)
	ds_write_b128 v165, v[196:199] offset:36864
	s_waitcnt vmcnt(10)
	ds_write_b128 v165, v[200:203] offset:41472
	v_mfma_f32_16x16x32_bf16 v[58:61], v[216:219], v[228:231], v[58:61]
	v_mfma_f32_16x16x32_bf16 v[62:65], v[216:219], v[236:239], v[62:65]
	v_mfma_f32_16x16x32_bf16 v[42:45], v[216:219], v[240:243], v[42:45]
	v_mfma_f32_16x16x32_bf16 v[46:49], v[216:219], v[252:255], v[46:49]
	s_waitcnt vmcnt(9)
	ds_write_b128 v165, v[204:207] offset:46080
	s_waitcnt vmcnt(8)
	ds_write_b128 v165, v[208:211] offset:50688
	v_mfma_f32_16x16x32_bf16 v[18:21], v[220:223], v[228:231], v[18:21]
	v_mfma_f32_16x16x32_bf16 v[22:25], v[220:223], v[236:239], v[22:25]
	v_mfma_f32_16x16x32_bf16 v[2:5], v[220:223], v[240:243], v[2:5]
	v_mfma_f32_16x16x32_bf16 v[6:9], v[220:223], v[252:255], v[6:9]
	s_waitcnt lgkmcnt(4)
	v_mfma_f32_16x16x32_bf16 v[26:29], v[224:227], v[228:231], v[26:29]
	v_mfma_f32_16x16x32_bf16 v[30:33], v[224:227], v[236:239], v[30:33]
	v_mfma_f32_16x16x32_bf16 v[10:13], v[224:227], v[240:243], v[10:13]
	v_mfma_f32_16x16x32_bf16 v[14:17], v[224:227], v[252:255], v[14:17]
	s_waitcnt lgkmcnt(0)
	s_barrier
	global_load_dwordx4 v[180:183], v[70:71], off offset:768
	global_load_dwordx4 v[184:187], v[68:69], off offset:768
	global_load_dwordx4 v[188:191], v[66:67], off offset:768
	global_load_dwordx4 v[192:195], v[72:73], off offset:768
	global_load_dwordx4 v[196:199], v[74:75], off offset:768
	global_load_dwordx4 v[200:203], v[76:77], off offset:768
	global_load_dwordx4 v[204:207], v[78:79], off offset:768
	global_load_dwordx4 v[208:211], v[80:81], off offset:768
	ds_read_b128 v[228:231], v245 offset:36864
	ds_read_b128 v[212:215], v244
	ds_read_b128 v[236:239], v245 offset:39168
	ds_read_b128 v[240:243], v245 offset:41472
	ds_read_b128 v[252:255], v245 offset:43776
	ds_read_b128 v[216:219], v244 offset:2304
	ds_read_b128 v[220:223], v244 offset:4608
	ds_read_b128 v[224:227], v244 offset:6912
	s_waitcnt lgkmcnt(6)
	v_mfma_f32_16x16x32_bf16 v[50:53], v[212:215], v[228:231], v[50:53]
	s_waitcnt lgkmcnt(5)
	v_mfma_f32_16x16x32_bf16 v[54:57], v[212:215], v[236:239], v[54:57]
	s_waitcnt lgkmcnt(4)
	v_mfma_f32_16x16x32_bf16 v[34:37], v[212:215], v[240:243], v[34:37]
	s_waitcnt lgkmcnt(3)
	v_mfma_f32_16x16x32_bf16 v[38:41], v[212:215], v[252:255], v[38:41]
	ds_read_b128 v[212:215], v244 offset:64
	s_waitcnt lgkmcnt(3)
	v_mfma_f32_16x16x32_bf16 v[58:61], v[216:219], v[228:231], v[58:61]
	v_mfma_f32_16x16x32_bf16 v[62:65], v[216:219], v[236:239], v[62:65]
	v_mfma_f32_16x16x32_bf16 v[42:45], v[216:219], v[240:243], v[42:45]
	v_mfma_f32_16x16x32_bf16 v[46:49], v[216:219], v[252:255], v[46:49]
	ds_read_b128 v[216:219], v244 offset:2368
	s_waitcnt vmcnt(15)
	ds_write_b128 v165, v[122:125] offset:18432
	s_waitcnt vmcnt(14)
	ds_write_b128 v165, v[126:129] offset:23040
	s_waitcnt lgkmcnt(5)
	v_mfma_f32_16x16x32_bf16 v[18:21], v[220:223], v[228:231], v[18:21]
	v_mfma_f32_16x16x32_bf16 v[22:25], v[220:223], v[236:239], v[22:25]
	v_mfma_f32_16x16x32_bf16 v[2:5], v[220:223], v[240:243], v[2:5]
	v_mfma_f32_16x16x32_bf16 v[6:9], v[220:223], v[252:255], v[6:9]
	ds_read_b128 v[220:223], v244 offset:4672
	s_waitcnt vmcnt(13)
	ds_write_b128 v165, v[136:139] offset:27648
	s_waitcnt vmcnt(12)
	ds_write_b128 v165, v[140:143] offset:32256
	s_waitcnt lgkmcnt(7)
	v_mfma_f32_16x16x32_bf16 v[26:29], v[224:227], v[228:231], v[26:29]
	ds_read_b128 v[228:231], v245 offset:36928
	v_mfma_f32_16x16x32_bf16 v[30:33], v[224:227], v[236:239], v[30:33]
	ds_read_b128 v[236:239], v245 offset:39232
	v_mfma_f32_16x16x32_bf16 v[10:13], v[224:227], v[240:243], v[10:13]
	ds_read_b128 v[240:243], v245 offset:41536
	v_mfma_f32_16x16x32_bf16 v[14:17], v[224:227], v[252:255], v[14:17]
	ds_read_b128 v[252:255], v245 offset:43840
	ds_read_b128 v[224:227], v244 offset:6976
	s_waitcnt lgkmcnt(4)
	v_mfma_f32_16x16x32_bf16 v[50:53], v[212:215], v[228:231], v[50:53]
	s_waitcnt lgkmcnt(3)
	v_mfma_f32_16x16x32_bf16 v[54:57], v[212:215], v[236:239], v[54:57]
	s_waitcnt lgkmcnt(2)
	v_mfma_f32_16x16x32_bf16 v[34:37], v[212:215], v[240:243], v[34:37]
	s_waitcnt lgkmcnt(1)
	v_mfma_f32_16x16x32_bf16 v[38:41], v[212:215], v[252:255], v[38:41]
	s_waitcnt vmcnt(11)
	ds_write_b128 v165, v[144:147] offset:55296
	s_waitcnt vmcnt(10)
	ds_write_b128 v165, v[148:151] offset:59904
	v_mfma_f32_16x16x32_bf16 v[58:61], v[216:219], v[228:231], v[58:61]
	v_mfma_f32_16x16x32_bf16 v[62:65], v[216:219], v[236:239], v[62:65]
	v_mfma_f32_16x16x32_bf16 v[42:45], v[216:219], v[240:243], v[42:45]
	v_mfma_f32_16x16x32_bf16 v[46:49], v[216:219], v[252:255], v[46:49]
	s_waitcnt vmcnt(9)
	ds_write_b128 v165, v[172:175] offset:64512
	s_waitcnt vmcnt(8)
	ds_write_b128 v166, v[176:179] offset:32256
	v_mfma_f32_16x16x32_bf16 v[18:21], v[220:223], v[228:231], v[18:21]
	v_mfma_f32_16x16x32_bf16 v[22:25], v[220:223], v[236:239], v[22:25]
	v_mfma_f32_16x16x32_bf16 v[2:5], v[220:223], v[240:243], v[2:5]
	v_mfma_f32_16x16x32_bf16 v[6:9], v[220:223], v[252:255], v[6:9]
	s_waitcnt lgkmcnt(4)
	v_mfma_f32_16x16x32_bf16 v[26:29], v[224:227], v[228:231], v[26:29]
	v_mfma_f32_16x16x32_bf16 v[30:33], v[224:227], v[236:239], v[30:33]
	v_mfma_f32_16x16x32_bf16 v[10:13], v[224:227], v[240:243], v[10:13]
	v_mfma_f32_16x16x32_bf16 v[14:17], v[224:227], v[252:255], v[14:17]
	s_waitcnt lgkmcnt(0)
	s_barrier
	global_load_dwordx4 v[122:125], v[70:71], off offset:896
	global_load_dwordx4 v[126:129], v[68:69], off offset:896
	global_load_dwordx4 v[136:139], v[66:67], off offset:896
	global_load_dwordx4 v[140:143], v[72:73], off offset:896
	global_load_dwordx4 v[144:147], v[74:75], off offset:896
	global_load_dwordx4 v[148:151], v[76:77], off offset:896
	global_load_dwordx4 v[172:175], v[78:79], off offset:896
	global_load_dwordx4 v[176:179], v[80:81], off offset:896
	ds_read_b128 v[228:231], v245 offset:55296
	ds_read_b128 v[212:215], v244 offset:18432
	ds_read_b128 v[236:239], v245 offset:57600
	ds_read_b128 v[240:243], v245 offset:59904
	ds_read_b128 v[252:255], v245 offset:62208
	ds_read_b128 v[216:219], v244 offset:20736
	ds_read_b128 v[220:223], v244 offset:23040
	ds_read_b128 v[224:227], v244 offset:25344
	s_waitcnt lgkmcnt(6)
	v_mfma_f32_16x16x32_bf16 v[50:53], v[212:215], v[228:231], v[50:53]
	s_waitcnt lgkmcnt(5)
	v_mfma_f32_16x16x32_bf16 v[54:57], v[212:215], v[236:239], v[54:57]
	s_waitcnt lgkmcnt(4)
	v_mfma_f32_16x16x32_bf16 v[34:37], v[212:215], v[240:243], v[34:37]
	s_waitcnt lgkmcnt(3)
	v_mfma_f32_16x16x32_bf16 v[38:41], v[212:215], v[252:255], v[38:41]
	ds_read_b128 v[212:215], v244 offset:18496
	s_waitcnt lgkmcnt(3)
	v_mfma_f32_16x16x32_bf16 v[58:61], v[216:219], v[228:231], v[58:61]
	v_mfma_f32_16x16x32_bf16 v[62:65], v[216:219], v[236:239], v[62:65]
	v_mfma_f32_16x16x32_bf16 v[42:45], v[216:219], v[240:243], v[42:45]
	v_mfma_f32_16x16x32_bf16 v[46:49], v[216:219], v[252:255], v[46:49]
	ds_read_b128 v[216:219], v244 offset:20800
	s_waitcnt vmcnt(15)
	ds_write_b128 v165, v[180:183]
	s_waitcnt vmcnt(14)
	ds_write_b128 v165, v[184:187] offset:4608
	s_waitcnt lgkmcnt(5)
	v_mfma_f32_16x16x32_bf16 v[18:21], v[220:223], v[228:231], v[18:21]
	v_mfma_f32_16x16x32_bf16 v[22:25], v[220:223], v[236:239], v[22:25]
	v_mfma_f32_16x16x32_bf16 v[2:5], v[220:223], v[240:243], v[2:5]
	v_mfma_f32_16x16x32_bf16 v[6:9], v[220:223], v[252:255], v[6:9]
	ds_read_b128 v[220:223], v244 offset:23104
	s_waitcnt vmcnt(13)
	ds_write_b128 v165, v[188:191] offset:9216
	s_waitcnt vmcnt(12)
	ds_write_b128 v165, v[192:195] offset:13824
	s_waitcnt lgkmcnt(7)
	v_mfma_f32_16x16x32_bf16 v[26:29], v[224:227], v[228:231], v[26:29]
	ds_read_b128 v[228:231], v245 offset:55360
	v_mfma_f32_16x16x32_bf16 v[30:33], v[224:227], v[236:239], v[30:33]
	ds_read_b128 v[236:239], v245 offset:57664
	v_mfma_f32_16x16x32_bf16 v[10:13], v[224:227], v[240:243], v[10:13]
	ds_read_b128 v[240:243], v245 offset:59968
	v_mfma_f32_16x16x32_bf16 v[14:17], v[224:227], v[252:255], v[14:17]
	ds_read_b128 v[252:255], v245 offset:62272
	ds_read_b128 v[224:227], v244 offset:25408
	s_waitcnt lgkmcnt(4)
	v_mfma_f32_16x16x32_bf16 v[50:53], v[212:215], v[228:231], v[50:53]
	s_waitcnt lgkmcnt(3)
	v_mfma_f32_16x16x32_bf16 v[54:57], v[212:215], v[236:239], v[54:57]
	s_waitcnt lgkmcnt(2)
	v_mfma_f32_16x16x32_bf16 v[34:37], v[212:215], v[240:243], v[34:37]
	s_waitcnt lgkmcnt(1)
	v_mfma_f32_16x16x32_bf16 v[38:41], v[212:215], v[252:255], v[38:41]
	s_waitcnt vmcnt(11)
	ds_write_b128 v165, v[196:199] offset:36864
	s_waitcnt vmcnt(10)
	ds_write_b128 v165, v[200:203] offset:41472
	v_mfma_f32_16x16x32_bf16 v[58:61], v[216:219], v[228:231], v[58:61]
	v_mfma_f32_16x16x32_bf16 v[62:65], v[216:219], v[236:239], v[62:65]
	v_mfma_f32_16x16x32_bf16 v[42:45], v[216:219], v[240:243], v[42:45]
	v_mfma_f32_16x16x32_bf16 v[46:49], v[216:219], v[252:255], v[46:49]
	s_waitcnt vmcnt(9)
	ds_write_b128 v165, v[204:207] offset:46080
	s_waitcnt vmcnt(8)
	ds_write_b128 v165, v[208:211] offset:50688
	v_mfma_f32_16x16x32_bf16 v[18:21], v[220:223], v[228:231], v[18:21]
	v_mfma_f32_16x16x32_bf16 v[22:25], v[220:223], v[236:239], v[22:25]
	v_mfma_f32_16x16x32_bf16 v[2:5], v[220:223], v[240:243], v[2:5]
	v_mfma_f32_16x16x32_bf16 v[6:9], v[220:223], v[252:255], v[6:9]
	s_waitcnt lgkmcnt(4)
	v_mfma_f32_16x16x32_bf16 v[26:29], v[224:227], v[228:231], v[26:29]
	v_mfma_f32_16x16x32_bf16 v[30:33], v[224:227], v[236:239], v[30:33]
	v_mfma_f32_16x16x32_bf16 v[10:13], v[224:227], v[240:243], v[10:13]
	v_mfma_f32_16x16x32_bf16 v[14:17], v[224:227], v[252:255], v[14:17]
	s_waitcnt lgkmcnt(0)
	s_barrier
	global_load_dwordx4 v[180:183], v[70:71], off offset:1024
	global_load_dwordx4 v[184:187], v[68:69], off offset:1024
	global_load_dwordx4 v[188:191], v[66:67], off offset:1024
	global_load_dwordx4 v[192:195], v[72:73], off offset:1024
	global_load_dwordx4 v[196:199], v[74:75], off offset:1024
	global_load_dwordx4 v[200:203], v[76:77], off offset:1024
	global_load_dwordx4 v[204:207], v[78:79], off offset:1024
	global_load_dwordx4 v[208:211], v[80:81], off offset:1024
	ds_read_b128 v[228:231], v245 offset:36864
	ds_read_b128 v[212:215], v244
	ds_read_b128 v[236:239], v245 offset:39168
	ds_read_b128 v[240:243], v245 offset:41472
	ds_read_b128 v[252:255], v245 offset:43776
	ds_read_b128 v[216:219], v244 offset:2304
	ds_read_b128 v[220:223], v244 offset:4608
	ds_read_b128 v[224:227], v244 offset:6912
	s_waitcnt lgkmcnt(6)
	v_mfma_f32_16x16x32_bf16 v[50:53], v[212:215], v[228:231], v[50:53]
	s_waitcnt lgkmcnt(5)
	v_mfma_f32_16x16x32_bf16 v[54:57], v[212:215], v[236:239], v[54:57]
	s_waitcnt lgkmcnt(4)
	v_mfma_f32_16x16x32_bf16 v[34:37], v[212:215], v[240:243], v[34:37]
	s_waitcnt lgkmcnt(3)
	v_mfma_f32_16x16x32_bf16 v[38:41], v[212:215], v[252:255], v[38:41]
	ds_read_b128 v[212:215], v244 offset:64
	s_waitcnt lgkmcnt(3)
	v_mfma_f32_16x16x32_bf16 v[58:61], v[216:219], v[228:231], v[58:61]
	v_mfma_f32_16x16x32_bf16 v[62:65], v[216:219], v[236:239], v[62:65]
	v_mfma_f32_16x16x32_bf16 v[42:45], v[216:219], v[240:243], v[42:45]
	v_mfma_f32_16x16x32_bf16 v[46:49], v[216:219], v[252:255], v[46:49]
	ds_read_b128 v[216:219], v244 offset:2368
	s_waitcnt vmcnt(15)
	ds_write_b128 v165, v[122:125] offset:18432
	s_waitcnt vmcnt(14)
	ds_write_b128 v165, v[126:129] offset:23040
	s_waitcnt lgkmcnt(5)
	v_mfma_f32_16x16x32_bf16 v[18:21], v[220:223], v[228:231], v[18:21]
	v_mfma_f32_16x16x32_bf16 v[22:25], v[220:223], v[236:239], v[22:25]
	v_mfma_f32_16x16x32_bf16 v[2:5], v[220:223], v[240:243], v[2:5]
	v_mfma_f32_16x16x32_bf16 v[6:9], v[220:223], v[252:255], v[6:9]
	ds_read_b128 v[220:223], v244 offset:4672
	s_waitcnt vmcnt(13)
	ds_write_b128 v165, v[136:139] offset:27648
	s_waitcnt vmcnt(12)
	ds_write_b128 v165, v[140:143] offset:32256
	s_waitcnt lgkmcnt(7)
	v_mfma_f32_16x16x32_bf16 v[26:29], v[224:227], v[228:231], v[26:29]
	ds_read_b128 v[228:231], v245 offset:36928
	v_mfma_f32_16x16x32_bf16 v[30:33], v[224:227], v[236:239], v[30:33]
	ds_read_b128 v[236:239], v245 offset:39232
	v_mfma_f32_16x16x32_bf16 v[10:13], v[224:227], v[240:243], v[10:13]
	ds_read_b128 v[240:243], v245 offset:41536
	v_mfma_f32_16x16x32_bf16 v[14:17], v[224:227], v[252:255], v[14:17]
	ds_read_b128 v[252:255], v245 offset:43840
	ds_read_b128 v[224:227], v244 offset:6976
	s_waitcnt lgkmcnt(4)
	v_mfma_f32_16x16x32_bf16 v[50:53], v[212:215], v[228:231], v[50:53]
	s_waitcnt lgkmcnt(3)
	v_mfma_f32_16x16x32_bf16 v[54:57], v[212:215], v[236:239], v[54:57]
	s_waitcnt lgkmcnt(2)
	v_mfma_f32_16x16x32_bf16 v[34:37], v[212:215], v[240:243], v[34:37]
	s_waitcnt lgkmcnt(1)
	v_mfma_f32_16x16x32_bf16 v[38:41], v[212:215], v[252:255], v[38:41]
	s_waitcnt vmcnt(11)
	ds_write_b128 v165, v[144:147] offset:55296
	s_waitcnt vmcnt(10)
	ds_write_b128 v165, v[148:151] offset:59904
	v_mfma_f32_16x16x32_bf16 v[58:61], v[216:219], v[228:231], v[58:61]
	v_mfma_f32_16x16x32_bf16 v[62:65], v[216:219], v[236:239], v[62:65]
	v_mfma_f32_16x16x32_bf16 v[42:45], v[216:219], v[240:243], v[42:45]
	v_mfma_f32_16x16x32_bf16 v[46:49], v[216:219], v[252:255], v[46:49]
	s_waitcnt vmcnt(9)
	ds_write_b128 v165, v[172:175] offset:64512
	s_waitcnt vmcnt(8)
	ds_write_b128 v166, v[176:179] offset:32256
	v_mfma_f32_16x16x32_bf16 v[18:21], v[220:223], v[228:231], v[18:21]
	v_mfma_f32_16x16x32_bf16 v[22:25], v[220:223], v[236:239], v[22:25]
	v_mfma_f32_16x16x32_bf16 v[2:5], v[220:223], v[240:243], v[2:5]
	v_mfma_f32_16x16x32_bf16 v[6:9], v[220:223], v[252:255], v[6:9]
	s_waitcnt lgkmcnt(4)
	v_mfma_f32_16x16x32_bf16 v[26:29], v[224:227], v[228:231], v[26:29]
	v_mfma_f32_16x16x32_bf16 v[30:33], v[224:227], v[236:239], v[30:33]
	v_mfma_f32_16x16x32_bf16 v[10:13], v[224:227], v[240:243], v[10:13]
	v_mfma_f32_16x16x32_bf16 v[14:17], v[224:227], v[252:255], v[14:17]
	s_waitcnt lgkmcnt(0)
	s_barrier
	global_load_dwordx4 v[122:125], v[70:71], off offset:1152
	global_load_dwordx4 v[126:129], v[68:69], off offset:1152
	global_load_dwordx4 v[136:139], v[66:67], off offset:1152
	global_load_dwordx4 v[140:143], v[72:73], off offset:1152
	global_load_dwordx4 v[144:147], v[74:75], off offset:1152
	global_load_dwordx4 v[148:151], v[76:77], off offset:1152
	global_load_dwordx4 v[172:175], v[78:79], off offset:1152
	global_load_dwordx4 v[176:179], v[80:81], off offset:1152
	ds_read_b128 v[228:231], v245 offset:55296
	ds_read_b128 v[212:215], v244 offset:18432
	ds_read_b128 v[236:239], v245 offset:57600
	ds_read_b128 v[240:243], v245 offset:59904
	ds_read_b128 v[252:255], v245 offset:62208
	ds_read_b128 v[216:219], v244 offset:20736
	ds_read_b128 v[220:223], v244 offset:23040
	ds_read_b128 v[224:227], v244 offset:25344
	s_waitcnt lgkmcnt(6)
	v_mfma_f32_16x16x32_bf16 v[50:53], v[212:215], v[228:231], v[50:53]
	s_waitcnt lgkmcnt(5)
	v_mfma_f32_16x16x32_bf16 v[54:57], v[212:215], v[236:239], v[54:57]
	s_waitcnt lgkmcnt(4)
	v_mfma_f32_16x16x32_bf16 v[34:37], v[212:215], v[240:243], v[34:37]
	s_waitcnt lgkmcnt(3)
	v_mfma_f32_16x16x32_bf16 v[38:41], v[212:215], v[252:255], v[38:41]
	ds_read_b128 v[212:215], v244 offset:18496
	s_waitcnt lgkmcnt(3)
	v_mfma_f32_16x16x32_bf16 v[58:61], v[216:219], v[228:231], v[58:61]
	v_mfma_f32_16x16x32_bf16 v[62:65], v[216:219], v[236:239], v[62:65]
	v_mfma_f32_16x16x32_bf16 v[42:45], v[216:219], v[240:243], v[42:45]
	v_mfma_f32_16x16x32_bf16 v[46:49], v[216:219], v[252:255], v[46:49]
	ds_read_b128 v[216:219], v244 offset:20800
	s_waitcnt vmcnt(15)
	ds_write_b128 v165, v[180:183]
	s_waitcnt vmcnt(14)
	ds_write_b128 v165, v[184:187] offset:4608
	s_waitcnt lgkmcnt(5)
	v_mfma_f32_16x16x32_bf16 v[18:21], v[220:223], v[228:231], v[18:21]
	v_mfma_f32_16x16x32_bf16 v[22:25], v[220:223], v[236:239], v[22:25]
	v_mfma_f32_16x16x32_bf16 v[2:5], v[220:223], v[240:243], v[2:5]
	v_mfma_f32_16x16x32_bf16 v[6:9], v[220:223], v[252:255], v[6:9]
	ds_read_b128 v[220:223], v244 offset:23104
	s_waitcnt vmcnt(13)
	ds_write_b128 v165, v[188:191] offset:9216
	s_waitcnt vmcnt(12)
	ds_write_b128 v165, v[192:195] offset:13824
	s_waitcnt lgkmcnt(7)
	v_mfma_f32_16x16x32_bf16 v[26:29], v[224:227], v[228:231], v[26:29]
	ds_read_b128 v[228:231], v245 offset:55360
	v_mfma_f32_16x16x32_bf16 v[30:33], v[224:227], v[236:239], v[30:33]
	ds_read_b128 v[236:239], v245 offset:57664
	v_mfma_f32_16x16x32_bf16 v[10:13], v[224:227], v[240:243], v[10:13]
	ds_read_b128 v[240:243], v245 offset:59968
	v_mfma_f32_16x16x32_bf16 v[14:17], v[224:227], v[252:255], v[14:17]
	ds_read_b128 v[252:255], v245 offset:62272
	ds_read_b128 v[224:227], v244 offset:25408
	s_waitcnt lgkmcnt(4)
	v_mfma_f32_16x16x32_bf16 v[50:53], v[212:215], v[228:231], v[50:53]
	s_waitcnt lgkmcnt(3)
	v_mfma_f32_16x16x32_bf16 v[54:57], v[212:215], v[236:239], v[54:57]
	s_waitcnt lgkmcnt(2)
	v_mfma_f32_16x16x32_bf16 v[34:37], v[212:215], v[240:243], v[34:37]
	s_waitcnt lgkmcnt(1)
	v_mfma_f32_16x16x32_bf16 v[38:41], v[212:215], v[252:255], v[38:41]
	s_waitcnt vmcnt(11)
	ds_write_b128 v165, v[196:199] offset:36864
	s_waitcnt vmcnt(10)
	ds_write_b128 v165, v[200:203] offset:41472
	v_mfma_f32_16x16x32_bf16 v[58:61], v[216:219], v[228:231], v[58:61]
	v_mfma_f32_16x16x32_bf16 v[62:65], v[216:219], v[236:239], v[62:65]
	v_mfma_f32_16x16x32_bf16 v[42:45], v[216:219], v[240:243], v[42:45]
	v_mfma_f32_16x16x32_bf16 v[46:49], v[216:219], v[252:255], v[46:49]
	s_waitcnt vmcnt(9)
	ds_write_b128 v165, v[204:207] offset:46080
	s_waitcnt vmcnt(8)
	ds_write_b128 v165, v[208:211] offset:50688
	v_mfma_f32_16x16x32_bf16 v[18:21], v[220:223], v[228:231], v[18:21]
	v_mfma_f32_16x16x32_bf16 v[22:25], v[220:223], v[236:239], v[22:25]
	v_mfma_f32_16x16x32_bf16 v[2:5], v[220:223], v[240:243], v[2:5]
	v_mfma_f32_16x16x32_bf16 v[6:9], v[220:223], v[252:255], v[6:9]
	s_waitcnt lgkmcnt(4)
	v_mfma_f32_16x16x32_bf16 v[26:29], v[224:227], v[228:231], v[26:29]
	v_mfma_f32_16x16x32_bf16 v[30:33], v[224:227], v[236:239], v[30:33]
	v_mfma_f32_16x16x32_bf16 v[10:13], v[224:227], v[240:243], v[10:13]
	v_mfma_f32_16x16x32_bf16 v[14:17], v[224:227], v[252:255], v[14:17]
	s_waitcnt lgkmcnt(0)
	s_barrier
	global_load_dwordx4 v[180:183], v[70:71], off offset:1280
	global_load_dwordx4 v[184:187], v[68:69], off offset:1280
	global_load_dwordx4 v[188:191], v[66:67], off offset:1280
	global_load_dwordx4 v[192:195], v[72:73], off offset:1280
	global_load_dwordx4 v[196:199], v[74:75], off offset:1280
	global_load_dwordx4 v[200:203], v[76:77], off offset:1280
	global_load_dwordx4 v[204:207], v[78:79], off offset:1280
	global_load_dwordx4 v[208:211], v[80:81], off offset:1280
	ds_read_b128 v[228:231], v245 offset:36864
	ds_read_b128 v[212:215], v244
	ds_read_b128 v[236:239], v245 offset:39168
	ds_read_b128 v[240:243], v245 offset:41472
	ds_read_b128 v[252:255], v245 offset:43776
	ds_read_b128 v[216:219], v244 offset:2304
	ds_read_b128 v[220:223], v244 offset:4608
	ds_read_b128 v[224:227], v244 offset:6912
	s_waitcnt lgkmcnt(6)
	v_mfma_f32_16x16x32_bf16 v[50:53], v[212:215], v[228:231], v[50:53]
	s_waitcnt lgkmcnt(5)
	v_mfma_f32_16x16x32_bf16 v[54:57], v[212:215], v[236:239], v[54:57]
	s_waitcnt lgkmcnt(4)
	v_mfma_f32_16x16x32_bf16 v[34:37], v[212:215], v[240:243], v[34:37]
	s_waitcnt lgkmcnt(3)
	v_mfma_f32_16x16x32_bf16 v[38:41], v[212:215], v[252:255], v[38:41]
	ds_read_b128 v[212:215], v244 offset:64
	s_waitcnt lgkmcnt(3)
	v_mfma_f32_16x16x32_bf16 v[58:61], v[216:219], v[228:231], v[58:61]
	v_mfma_f32_16x16x32_bf16 v[62:65], v[216:219], v[236:239], v[62:65]
	v_mfma_f32_16x16x32_bf16 v[42:45], v[216:219], v[240:243], v[42:45]
	v_mfma_f32_16x16x32_bf16 v[46:49], v[216:219], v[252:255], v[46:49]
	ds_read_b128 v[216:219], v244 offset:2368
	s_waitcnt vmcnt(15)
	ds_write_b128 v165, v[122:125] offset:18432
	s_waitcnt vmcnt(14)
	ds_write_b128 v165, v[126:129] offset:23040
	s_waitcnt lgkmcnt(5)
	v_mfma_f32_16x16x32_bf16 v[18:21], v[220:223], v[228:231], v[18:21]
	v_mfma_f32_16x16x32_bf16 v[22:25], v[220:223], v[236:239], v[22:25]
	v_mfma_f32_16x16x32_bf16 v[2:5], v[220:223], v[240:243], v[2:5]
	v_mfma_f32_16x16x32_bf16 v[6:9], v[220:223], v[252:255], v[6:9]
	ds_read_b128 v[220:223], v244 offset:4672
	s_waitcnt vmcnt(13)
	ds_write_b128 v165, v[136:139] offset:27648
	s_waitcnt vmcnt(12)
	ds_write_b128 v165, v[140:143] offset:32256
	s_waitcnt lgkmcnt(7)
	v_mfma_f32_16x16x32_bf16 v[26:29], v[224:227], v[228:231], v[26:29]
	ds_read_b128 v[228:231], v245 offset:36928
	v_mfma_f32_16x16x32_bf16 v[30:33], v[224:227], v[236:239], v[30:33]
	ds_read_b128 v[236:239], v245 offset:39232
	v_mfma_f32_16x16x32_bf16 v[10:13], v[224:227], v[240:243], v[10:13]
	ds_read_b128 v[240:243], v245 offset:41536
	v_mfma_f32_16x16x32_bf16 v[14:17], v[224:227], v[252:255], v[14:17]
	ds_read_b128 v[252:255], v245 offset:43840
	ds_read_b128 v[224:227], v244 offset:6976
	s_waitcnt lgkmcnt(4)
	v_mfma_f32_16x16x32_bf16 v[50:53], v[212:215], v[228:231], v[50:53]
	s_waitcnt lgkmcnt(3)
	v_mfma_f32_16x16x32_bf16 v[54:57], v[212:215], v[236:239], v[54:57]
	s_waitcnt lgkmcnt(2)
	v_mfma_f32_16x16x32_bf16 v[34:37], v[212:215], v[240:243], v[34:37]
	s_waitcnt lgkmcnt(1)
	v_mfma_f32_16x16x32_bf16 v[38:41], v[212:215], v[252:255], v[38:41]
	s_waitcnt vmcnt(11)
	ds_write_b128 v165, v[144:147] offset:55296
	s_waitcnt vmcnt(10)
	ds_write_b128 v165, v[148:151] offset:59904
	v_mfma_f32_16x16x32_bf16 v[58:61], v[216:219], v[228:231], v[58:61]
	v_mfma_f32_16x16x32_bf16 v[62:65], v[216:219], v[236:239], v[62:65]
	v_mfma_f32_16x16x32_bf16 v[42:45], v[216:219], v[240:243], v[42:45]
	v_mfma_f32_16x16x32_bf16 v[46:49], v[216:219], v[252:255], v[46:49]
	s_waitcnt vmcnt(9)
	ds_write_b128 v165, v[172:175] offset:64512
	s_waitcnt vmcnt(8)
	ds_write_b128 v166, v[176:179] offset:32256
	v_mfma_f32_16x16x32_bf16 v[18:21], v[220:223], v[228:231], v[18:21]
	v_mfma_f32_16x16x32_bf16 v[22:25], v[220:223], v[236:239], v[22:25]
	v_mfma_f32_16x16x32_bf16 v[2:5], v[220:223], v[240:243], v[2:5]
	v_mfma_f32_16x16x32_bf16 v[6:9], v[220:223], v[252:255], v[6:9]
	s_waitcnt lgkmcnt(4)
	v_mfma_f32_16x16x32_bf16 v[26:29], v[224:227], v[228:231], v[26:29]
	v_mfma_f32_16x16x32_bf16 v[30:33], v[224:227], v[236:239], v[30:33]
	v_mfma_f32_16x16x32_bf16 v[10:13], v[224:227], v[240:243], v[10:13]
	v_mfma_f32_16x16x32_bf16 v[14:17], v[224:227], v[252:255], v[14:17]
	s_waitcnt lgkmcnt(0)
	s_barrier
	global_load_dwordx4 v[122:125], v[70:71], off offset:1408
	global_load_dwordx4 v[126:129], v[68:69], off offset:1408
	global_load_dwordx4 v[136:139], v[66:67], off offset:1408
	global_load_dwordx4 v[140:143], v[72:73], off offset:1408
	global_load_dwordx4 v[144:147], v[74:75], off offset:1408
	global_load_dwordx4 v[148:151], v[76:77], off offset:1408
	global_load_dwordx4 v[172:175], v[78:79], off offset:1408
	global_load_dwordx4 v[176:179], v[80:81], off offset:1408
	ds_read_b128 v[228:231], v245 offset:55296
	ds_read_b128 v[212:215], v244 offset:18432
	ds_read_b128 v[236:239], v245 offset:57600
	ds_read_b128 v[240:243], v245 offset:59904
	ds_read_b128 v[252:255], v245 offset:62208
	ds_read_b128 v[216:219], v244 offset:20736
	ds_read_b128 v[220:223], v244 offset:23040
	ds_read_b128 v[224:227], v244 offset:25344
	s_waitcnt lgkmcnt(6)
	v_mfma_f32_16x16x32_bf16 v[50:53], v[212:215], v[228:231], v[50:53]
	s_waitcnt lgkmcnt(5)
	v_mfma_f32_16x16x32_bf16 v[54:57], v[212:215], v[236:239], v[54:57]
	s_waitcnt lgkmcnt(4)
	v_mfma_f32_16x16x32_bf16 v[34:37], v[212:215], v[240:243], v[34:37]
	s_waitcnt lgkmcnt(3)
	v_mfma_f32_16x16x32_bf16 v[38:41], v[212:215], v[252:255], v[38:41]
	ds_read_b128 v[212:215], v244 offset:18496
	s_waitcnt lgkmcnt(3)
	v_mfma_f32_16x16x32_bf16 v[58:61], v[216:219], v[228:231], v[58:61]
	v_mfma_f32_16x16x32_bf16 v[62:65], v[216:219], v[236:239], v[62:65]
	v_mfma_f32_16x16x32_bf16 v[42:45], v[216:219], v[240:243], v[42:45]
	v_mfma_f32_16x16x32_bf16 v[46:49], v[216:219], v[252:255], v[46:49]
	ds_read_b128 v[216:219], v244 offset:20800
	s_waitcnt vmcnt(15)
	ds_write_b128 v165, v[180:183]
	s_waitcnt vmcnt(14)
	ds_write_b128 v165, v[184:187] offset:4608
	s_waitcnt lgkmcnt(5)
	v_mfma_f32_16x16x32_bf16 v[18:21], v[220:223], v[228:231], v[18:21]
	v_mfma_f32_16x16x32_bf16 v[22:25], v[220:223], v[236:239], v[22:25]
	v_mfma_f32_16x16x32_bf16 v[2:5], v[220:223], v[240:243], v[2:5]
	v_mfma_f32_16x16x32_bf16 v[6:9], v[220:223], v[252:255], v[6:9]
	ds_read_b128 v[220:223], v244 offset:23104
	s_waitcnt vmcnt(13)
	ds_write_b128 v165, v[188:191] offset:9216
	s_waitcnt vmcnt(12)
	ds_write_b128 v165, v[192:195] offset:13824
	s_waitcnt lgkmcnt(7)
	v_mfma_f32_16x16x32_bf16 v[26:29], v[224:227], v[228:231], v[26:29]
	ds_read_b128 v[228:231], v245 offset:55360
	v_mfma_f32_16x16x32_bf16 v[30:33], v[224:227], v[236:239], v[30:33]
	ds_read_b128 v[236:239], v245 offset:57664
	v_mfma_f32_16x16x32_bf16 v[10:13], v[224:227], v[240:243], v[10:13]
	ds_read_b128 v[240:243], v245 offset:59968
	v_mfma_f32_16x16x32_bf16 v[14:17], v[224:227], v[252:255], v[14:17]
	ds_read_b128 v[252:255], v245 offset:62272
	ds_read_b128 v[224:227], v244 offset:25408
	s_waitcnt lgkmcnt(4)
	v_mfma_f32_16x16x32_bf16 v[50:53], v[212:215], v[228:231], v[50:53]
	s_waitcnt lgkmcnt(3)
	v_mfma_f32_16x16x32_bf16 v[54:57], v[212:215], v[236:239], v[54:57]
	s_waitcnt lgkmcnt(2)
	v_mfma_f32_16x16x32_bf16 v[34:37], v[212:215], v[240:243], v[34:37]
	s_waitcnt lgkmcnt(1)
	v_mfma_f32_16x16x32_bf16 v[38:41], v[212:215], v[252:255], v[38:41]
	s_waitcnt vmcnt(11)
	ds_write_b128 v165, v[196:199] offset:36864
	s_waitcnt vmcnt(10)
	ds_write_b128 v165, v[200:203] offset:41472
	v_mfma_f32_16x16x32_bf16 v[58:61], v[216:219], v[228:231], v[58:61]
	v_mfma_f32_16x16x32_bf16 v[62:65], v[216:219], v[236:239], v[62:65]
	v_mfma_f32_16x16x32_bf16 v[42:45], v[216:219], v[240:243], v[42:45]
	v_mfma_f32_16x16x32_bf16 v[46:49], v[216:219], v[252:255], v[46:49]
	s_waitcnt vmcnt(9)
	ds_write_b128 v165, v[204:207] offset:46080
	s_waitcnt vmcnt(8)
	ds_write_b128 v165, v[208:211] offset:50688
	v_mfma_f32_16x16x32_bf16 v[18:21], v[220:223], v[228:231], v[18:21]
	v_mfma_f32_16x16x32_bf16 v[22:25], v[220:223], v[236:239], v[22:25]
	v_mfma_f32_16x16x32_bf16 v[2:5], v[220:223], v[240:243], v[2:5]
	v_mfma_f32_16x16x32_bf16 v[6:9], v[220:223], v[252:255], v[6:9]
	s_waitcnt lgkmcnt(4)
	v_mfma_f32_16x16x32_bf16 v[26:29], v[224:227], v[228:231], v[26:29]
	v_mfma_f32_16x16x32_bf16 v[30:33], v[224:227], v[236:239], v[30:33]
	v_mfma_f32_16x16x32_bf16 v[10:13], v[224:227], v[240:243], v[10:13]
	v_mfma_f32_16x16x32_bf16 v[14:17], v[224:227], v[252:255], v[14:17]
	s_waitcnt lgkmcnt(0)
	s_barrier
	global_load_dwordx4 v[180:183], v[70:71], off offset:1536
	global_load_dwordx4 v[184:187], v[68:69], off offset:1536
	global_load_dwordx4 v[188:191], v[66:67], off offset:1536
	global_load_dwordx4 v[192:195], v[72:73], off offset:1536
	global_load_dwordx4 v[196:199], v[74:75], off offset:1536
	global_load_dwordx4 v[200:203], v[76:77], off offset:1536
	global_load_dwordx4 v[204:207], v[78:79], off offset:1536
	global_load_dwordx4 v[208:211], v[80:81], off offset:1536
	ds_read_b128 v[228:231], v245 offset:36864
	ds_read_b128 v[212:215], v244
	ds_read_b128 v[236:239], v245 offset:39168
	ds_read_b128 v[240:243], v245 offset:41472
	ds_read_b128 v[252:255], v245 offset:43776
	ds_read_b128 v[216:219], v244 offset:2304
	ds_read_b128 v[220:223], v244 offset:4608
	ds_read_b128 v[224:227], v244 offset:6912
	s_waitcnt lgkmcnt(6)
	v_mfma_f32_16x16x32_bf16 v[50:53], v[212:215], v[228:231], v[50:53]
	s_waitcnt lgkmcnt(5)
	v_mfma_f32_16x16x32_bf16 v[54:57], v[212:215], v[236:239], v[54:57]
	s_waitcnt lgkmcnt(4)
	v_mfma_f32_16x16x32_bf16 v[34:37], v[212:215], v[240:243], v[34:37]
	s_waitcnt lgkmcnt(3)
	v_mfma_f32_16x16x32_bf16 v[38:41], v[212:215], v[252:255], v[38:41]
	ds_read_b128 v[212:215], v244 offset:64
	s_waitcnt lgkmcnt(3)
	v_mfma_f32_16x16x32_bf16 v[58:61], v[216:219], v[228:231], v[58:61]
	v_mfma_f32_16x16x32_bf16 v[62:65], v[216:219], v[236:239], v[62:65]
	v_mfma_f32_16x16x32_bf16 v[42:45], v[216:219], v[240:243], v[42:45]
	v_mfma_f32_16x16x32_bf16 v[46:49], v[216:219], v[252:255], v[46:49]
	ds_read_b128 v[216:219], v244 offset:2368
	s_waitcnt vmcnt(15)
	ds_write_b128 v165, v[122:125] offset:18432
	s_waitcnt vmcnt(14)
	ds_write_b128 v165, v[126:129] offset:23040
	s_waitcnt lgkmcnt(5)
	v_mfma_f32_16x16x32_bf16 v[18:21], v[220:223], v[228:231], v[18:21]
	v_mfma_f32_16x16x32_bf16 v[22:25], v[220:223], v[236:239], v[22:25]
	v_mfma_f32_16x16x32_bf16 v[2:5], v[220:223], v[240:243], v[2:5]
	v_mfma_f32_16x16x32_bf16 v[6:9], v[220:223], v[252:255], v[6:9]
	ds_read_b128 v[220:223], v244 offset:4672
	s_waitcnt vmcnt(13)
	ds_write_b128 v165, v[136:139] offset:27648
	s_waitcnt vmcnt(12)
	ds_write_b128 v165, v[140:143] offset:32256
	s_waitcnt lgkmcnt(7)
	v_mfma_f32_16x16x32_bf16 v[26:29], v[224:227], v[228:231], v[26:29]
	ds_read_b128 v[228:231], v245 offset:36928
	v_mfma_f32_16x16x32_bf16 v[30:33], v[224:227], v[236:239], v[30:33]
	ds_read_b128 v[236:239], v245 offset:39232
	v_mfma_f32_16x16x32_bf16 v[10:13], v[224:227], v[240:243], v[10:13]
	ds_read_b128 v[240:243], v245 offset:41536
	v_mfma_f32_16x16x32_bf16 v[14:17], v[224:227], v[252:255], v[14:17]
	ds_read_b128 v[252:255], v245 offset:43840
	ds_read_b128 v[224:227], v244 offset:6976
	s_waitcnt lgkmcnt(4)
	v_mfma_f32_16x16x32_bf16 v[50:53], v[212:215], v[228:231], v[50:53]
	s_waitcnt lgkmcnt(3)
	v_mfma_f32_16x16x32_bf16 v[54:57], v[212:215], v[236:239], v[54:57]
	s_waitcnt lgkmcnt(2)
	v_mfma_f32_16x16x32_bf16 v[34:37], v[212:215], v[240:243], v[34:37]
	s_waitcnt lgkmcnt(1)
	v_mfma_f32_16x16x32_bf16 v[38:41], v[212:215], v[252:255], v[38:41]
	s_waitcnt vmcnt(11)
	ds_write_b128 v165, v[144:147] offset:55296
	s_waitcnt vmcnt(10)
	ds_write_b128 v165, v[148:151] offset:59904
	v_mfma_f32_16x16x32_bf16 v[58:61], v[216:219], v[228:231], v[58:61]
	v_mfma_f32_16x16x32_bf16 v[62:65], v[216:219], v[236:239], v[62:65]
	v_mfma_f32_16x16x32_bf16 v[42:45], v[216:219], v[240:243], v[42:45]
	v_mfma_f32_16x16x32_bf16 v[46:49], v[216:219], v[252:255], v[46:49]
	s_waitcnt vmcnt(9)
	ds_write_b128 v165, v[172:175] offset:64512
	s_waitcnt vmcnt(8)
	ds_write_b128 v166, v[176:179] offset:32256
	v_mfma_f32_16x16x32_bf16 v[18:21], v[220:223], v[228:231], v[18:21]
	v_mfma_f32_16x16x32_bf16 v[22:25], v[220:223], v[236:239], v[22:25]
	v_mfma_f32_16x16x32_bf16 v[2:5], v[220:223], v[240:243], v[2:5]
	v_mfma_f32_16x16x32_bf16 v[6:9], v[220:223], v[252:255], v[6:9]
	s_waitcnt lgkmcnt(4)
	v_mfma_f32_16x16x32_bf16 v[26:29], v[224:227], v[228:231], v[26:29]
	v_mfma_f32_16x16x32_bf16 v[30:33], v[224:227], v[236:239], v[30:33]
	v_mfma_f32_16x16x32_bf16 v[10:13], v[224:227], v[240:243], v[10:13]
	v_mfma_f32_16x16x32_bf16 v[14:17], v[224:227], v[252:255], v[14:17]
	s_waitcnt lgkmcnt(0)
	s_barrier
	global_load_dwordx4 v[122:125], v[70:71], off offset:1664
	global_load_dwordx4 v[126:129], v[68:69], off offset:1664
	global_load_dwordx4 v[136:139], v[66:67], off offset:1664
	global_load_dwordx4 v[140:143], v[72:73], off offset:1664
	global_load_dwordx4 v[144:147], v[74:75], off offset:1664
	global_load_dwordx4 v[148:151], v[76:77], off offset:1664
	global_load_dwordx4 v[172:175], v[78:79], off offset:1664
	global_load_dwordx4 v[176:179], v[80:81], off offset:1664
	ds_read_b128 v[228:231], v245 offset:55296
	ds_read_b128 v[212:215], v244 offset:18432
	ds_read_b128 v[236:239], v245 offset:57600
	ds_read_b128 v[240:243], v245 offset:59904
	ds_read_b128 v[252:255], v245 offset:62208
	ds_read_b128 v[216:219], v244 offset:20736
	ds_read_b128 v[220:223], v244 offset:23040
	ds_read_b128 v[224:227], v244 offset:25344
	s_waitcnt lgkmcnt(6)
	v_mfma_f32_16x16x32_bf16 v[50:53], v[212:215], v[228:231], v[50:53]
	s_waitcnt lgkmcnt(5)
	v_mfma_f32_16x16x32_bf16 v[54:57], v[212:215], v[236:239], v[54:57]
	s_waitcnt lgkmcnt(4)
	v_mfma_f32_16x16x32_bf16 v[34:37], v[212:215], v[240:243], v[34:37]
	s_waitcnt lgkmcnt(3)
	v_mfma_f32_16x16x32_bf16 v[38:41], v[212:215], v[252:255], v[38:41]
	ds_read_b128 v[212:215], v244 offset:18496
	s_waitcnt lgkmcnt(3)
	v_mfma_f32_16x16x32_bf16 v[58:61], v[216:219], v[228:231], v[58:61]
	v_mfma_f32_16x16x32_bf16 v[62:65], v[216:219], v[236:239], v[62:65]
	v_mfma_f32_16x16x32_bf16 v[42:45], v[216:219], v[240:243], v[42:45]
	v_mfma_f32_16x16x32_bf16 v[46:49], v[216:219], v[252:255], v[46:49]
	ds_read_b128 v[216:219], v244 offset:20800
	s_waitcnt vmcnt(15)
	ds_write_b128 v165, v[180:183]
	s_waitcnt vmcnt(14)
	ds_write_b128 v165, v[184:187] offset:4608
	s_waitcnt lgkmcnt(5)
	v_mfma_f32_16x16x32_bf16 v[18:21], v[220:223], v[228:231], v[18:21]
	v_mfma_f32_16x16x32_bf16 v[22:25], v[220:223], v[236:239], v[22:25]
	v_mfma_f32_16x16x32_bf16 v[2:5], v[220:223], v[240:243], v[2:5]
	v_mfma_f32_16x16x32_bf16 v[6:9], v[220:223], v[252:255], v[6:9]
	ds_read_b128 v[220:223], v244 offset:23104
	s_waitcnt vmcnt(13)
	ds_write_b128 v165, v[188:191] offset:9216
	s_waitcnt vmcnt(12)
	ds_write_b128 v165, v[192:195] offset:13824
	s_waitcnt lgkmcnt(7)
	v_mfma_f32_16x16x32_bf16 v[26:29], v[224:227], v[228:231], v[26:29]
	ds_read_b128 v[228:231], v245 offset:55360
	v_mfma_f32_16x16x32_bf16 v[30:33], v[224:227], v[236:239], v[30:33]
	ds_read_b128 v[236:239], v245 offset:57664
	v_mfma_f32_16x16x32_bf16 v[10:13], v[224:227], v[240:243], v[10:13]
	ds_read_b128 v[240:243], v245 offset:59968
	v_mfma_f32_16x16x32_bf16 v[14:17], v[224:227], v[252:255], v[14:17]
	ds_read_b128 v[252:255], v245 offset:62272
	ds_read_b128 v[224:227], v244 offset:25408
	s_waitcnt lgkmcnt(4)
	v_mfma_f32_16x16x32_bf16 v[50:53], v[212:215], v[228:231], v[50:53]
	s_waitcnt lgkmcnt(3)
	v_mfma_f32_16x16x32_bf16 v[54:57], v[212:215], v[236:239], v[54:57]
	s_waitcnt lgkmcnt(2)
	v_mfma_f32_16x16x32_bf16 v[34:37], v[212:215], v[240:243], v[34:37]
	s_waitcnt lgkmcnt(1)
	v_mfma_f32_16x16x32_bf16 v[38:41], v[212:215], v[252:255], v[38:41]
	s_waitcnt vmcnt(11)
	ds_write_b128 v165, v[196:199] offset:36864
	s_waitcnt vmcnt(10)
	ds_write_b128 v165, v[200:203] offset:41472
	v_mfma_f32_16x16x32_bf16 v[58:61], v[216:219], v[228:231], v[58:61]
	v_mfma_f32_16x16x32_bf16 v[62:65], v[216:219], v[236:239], v[62:65]
	v_mfma_f32_16x16x32_bf16 v[42:45], v[216:219], v[240:243], v[42:45]
	v_mfma_f32_16x16x32_bf16 v[46:49], v[216:219], v[252:255], v[46:49]
	s_waitcnt vmcnt(9)
	ds_write_b128 v165, v[204:207] offset:46080
	s_waitcnt vmcnt(8)
	ds_write_b128 v165, v[208:211] offset:50688
	v_mfma_f32_16x16x32_bf16 v[18:21], v[220:223], v[228:231], v[18:21]
	v_mfma_f32_16x16x32_bf16 v[22:25], v[220:223], v[236:239], v[22:25]
	v_mfma_f32_16x16x32_bf16 v[2:5], v[220:223], v[240:243], v[2:5]
	v_mfma_f32_16x16x32_bf16 v[6:9], v[220:223], v[252:255], v[6:9]
	s_waitcnt lgkmcnt(4)
	v_mfma_f32_16x16x32_bf16 v[26:29], v[224:227], v[228:231], v[26:29]
	v_mfma_f32_16x16x32_bf16 v[30:33], v[224:227], v[236:239], v[30:33]
	v_mfma_f32_16x16x32_bf16 v[10:13], v[224:227], v[240:243], v[10:13]
	v_mfma_f32_16x16x32_bf16 v[14:17], v[224:227], v[252:255], v[14:17]
	s_waitcnt lgkmcnt(0)
	s_barrier
	global_load_dwordx4 v[180:183], v[70:71], off offset:1792
	global_load_dwordx4 v[184:187], v[68:69], off offset:1792
	global_load_dwordx4 v[188:191], v[66:67], off offset:1792
	global_load_dwordx4 v[192:195], v[72:73], off offset:1792
	global_load_dwordx4 v[196:199], v[74:75], off offset:1792
	global_load_dwordx4 v[200:203], v[76:77], off offset:1792
	global_load_dwordx4 v[204:207], v[78:79], off offset:1792
	global_load_dwordx4 v[208:211], v[80:81], off offset:1792
	ds_read_b128 v[228:231], v245 offset:36864
	ds_read_b128 v[212:215], v244
	ds_read_b128 v[236:239], v245 offset:39168
	ds_read_b128 v[240:243], v245 offset:41472
	ds_read_b128 v[252:255], v245 offset:43776
	ds_read_b128 v[216:219], v244 offset:2304
	ds_read_b128 v[220:223], v244 offset:4608
	ds_read_b128 v[224:227], v244 offset:6912
	s_waitcnt lgkmcnt(6)
	v_mfma_f32_16x16x32_bf16 v[50:53], v[212:215], v[228:231], v[50:53]
	s_waitcnt lgkmcnt(5)
	v_mfma_f32_16x16x32_bf16 v[54:57], v[212:215], v[236:239], v[54:57]
	s_waitcnt lgkmcnt(4)
	v_mfma_f32_16x16x32_bf16 v[34:37], v[212:215], v[240:243], v[34:37]
	s_waitcnt lgkmcnt(3)
	v_mfma_f32_16x16x32_bf16 v[38:41], v[212:215], v[252:255], v[38:41]
	ds_read_b128 v[212:215], v244 offset:64
	s_waitcnt lgkmcnt(3)
	v_mfma_f32_16x16x32_bf16 v[58:61], v[216:219], v[228:231], v[58:61]
	v_mfma_f32_16x16x32_bf16 v[62:65], v[216:219], v[236:239], v[62:65]
	v_mfma_f32_16x16x32_bf16 v[42:45], v[216:219], v[240:243], v[42:45]
	v_mfma_f32_16x16x32_bf16 v[46:49], v[216:219], v[252:255], v[46:49]
	ds_read_b128 v[216:219], v244 offset:2368
	s_waitcnt vmcnt(15)
	ds_write_b128 v165, v[122:125] offset:18432
	s_waitcnt vmcnt(14)
	ds_write_b128 v165, v[126:129] offset:23040
	s_waitcnt lgkmcnt(5)
	v_mfma_f32_16x16x32_bf16 v[18:21], v[220:223], v[228:231], v[18:21]
	v_mfma_f32_16x16x32_bf16 v[22:25], v[220:223], v[236:239], v[22:25]
	v_mfma_f32_16x16x32_bf16 v[2:5], v[220:223], v[240:243], v[2:5]
	v_mfma_f32_16x16x32_bf16 v[6:9], v[220:223], v[252:255], v[6:9]
	ds_read_b128 v[220:223], v244 offset:4672
	s_waitcnt vmcnt(13)
	ds_write_b128 v165, v[136:139] offset:27648
	s_waitcnt vmcnt(12)
	ds_write_b128 v165, v[140:143] offset:32256
	s_waitcnt lgkmcnt(7)
	v_mfma_f32_16x16x32_bf16 v[26:29], v[224:227], v[228:231], v[26:29]
	ds_read_b128 v[228:231], v245 offset:36928
	v_mfma_f32_16x16x32_bf16 v[30:33], v[224:227], v[236:239], v[30:33]
	ds_read_b128 v[236:239], v245 offset:39232
	v_mfma_f32_16x16x32_bf16 v[10:13], v[224:227], v[240:243], v[10:13]
	ds_read_b128 v[240:243], v245 offset:41536
	v_mfma_f32_16x16x32_bf16 v[14:17], v[224:227], v[252:255], v[14:17]
	ds_read_b128 v[252:255], v245 offset:43840
	ds_read_b128 v[224:227], v244 offset:6976
	s_waitcnt lgkmcnt(4)
	v_mfma_f32_16x16x32_bf16 v[50:53], v[212:215], v[228:231], v[50:53]
	s_waitcnt lgkmcnt(3)
	v_mfma_f32_16x16x32_bf16 v[54:57], v[212:215], v[236:239], v[54:57]
	s_waitcnt lgkmcnt(2)
	v_mfma_f32_16x16x32_bf16 v[34:37], v[212:215], v[240:243], v[34:37]
	s_waitcnt lgkmcnt(1)
	v_mfma_f32_16x16x32_bf16 v[38:41], v[212:215], v[252:255], v[38:41]
	s_waitcnt vmcnt(11)
	ds_write_b128 v165, v[144:147] offset:55296
	s_waitcnt vmcnt(10)
	ds_write_b128 v165, v[148:151] offset:59904
	v_mfma_f32_16x16x32_bf16 v[58:61], v[216:219], v[228:231], v[58:61]
	v_mfma_f32_16x16x32_bf16 v[62:65], v[216:219], v[236:239], v[62:65]
	v_mfma_f32_16x16x32_bf16 v[42:45], v[216:219], v[240:243], v[42:45]
	v_mfma_f32_16x16x32_bf16 v[46:49], v[216:219], v[252:255], v[46:49]
	s_waitcnt vmcnt(9)
	ds_write_b128 v165, v[172:175] offset:64512
	s_waitcnt vmcnt(8)
	ds_write_b128 v166, v[176:179] offset:32256
	v_mfma_f32_16x16x32_bf16 v[18:21], v[220:223], v[228:231], v[18:21]
	v_mfma_f32_16x16x32_bf16 v[22:25], v[220:223], v[236:239], v[22:25]
	v_mfma_f32_16x16x32_bf16 v[2:5], v[220:223], v[240:243], v[2:5]
	v_mfma_f32_16x16x32_bf16 v[6:9], v[220:223], v[252:255], v[6:9]
	s_waitcnt lgkmcnt(4)
	v_mfma_f32_16x16x32_bf16 v[26:29], v[224:227], v[228:231], v[26:29]
	v_mfma_f32_16x16x32_bf16 v[30:33], v[224:227], v[236:239], v[30:33]
	v_mfma_f32_16x16x32_bf16 v[10:13], v[224:227], v[240:243], v[10:13]
	v_mfma_f32_16x16x32_bf16 v[14:17], v[224:227], v[252:255], v[14:17]
	s_waitcnt lgkmcnt(0)
	s_barrier
	global_load_dwordx4 v[122:125], v[70:71], off offset:1920
	s_nop 0
	global_load_dwordx4 v[68:71], v[68:69], off offset:1920
	s_nop 0
	global_load_dwordx4 v[126:129], v[66:67], off offset:1920
	global_load_dwordx4 v[136:139], v[72:73], off offset:1920
	s_nop 0
	global_load_dwordx4 v[72:75], v[74:75], off offset:1920
	s_nop 0
	global_load_dwordx4 v[140:143], v[76:77], off offset:1920
	s_nop 0
	global_load_dwordx4 v[76:79], v[78:79], off offset:1920
	s_nop 0
	global_load_dwordx4 v[144:147], v[80:81], off offset:1920
	ds_read_b128 v[228:231], v245 offset:55296
	ds_read_b128 v[212:215], v244 offset:18432
	ds_read_b128 v[236:239], v245 offset:57600
	ds_read_b128 v[240:243], v245 offset:59904
	ds_read_b128 v[252:255], v245 offset:62208
	ds_read_b128 v[216:219], v244 offset:20736
	ds_read_b128 v[220:223], v244 offset:23040
	ds_read_b128 v[224:227], v244 offset:25344
	s_waitcnt lgkmcnt(6)
	v_mfma_f32_16x16x32_bf16 v[50:53], v[212:215], v[228:231], v[50:53]
	s_waitcnt lgkmcnt(5)
	v_mfma_f32_16x16x32_bf16 v[54:57], v[212:215], v[236:239], v[54:57]
	s_waitcnt lgkmcnt(4)
	v_mfma_f32_16x16x32_bf16 v[34:37], v[212:215], v[240:243], v[34:37]
	s_waitcnt lgkmcnt(3)
	v_mfma_f32_16x16x32_bf16 v[38:41], v[212:215], v[252:255], v[38:41]
	ds_read_b128 v[212:215], v244 offset:18496
	s_waitcnt lgkmcnt(3)
	v_mfma_f32_16x16x32_bf16 v[58:61], v[216:219], v[228:231], v[58:61]
	v_mfma_f32_16x16x32_bf16 v[62:65], v[216:219], v[236:239], v[62:65]
	v_mfma_f32_16x16x32_bf16 v[42:45], v[216:219], v[240:243], v[42:45]
	v_mfma_f32_16x16x32_bf16 v[46:49], v[216:219], v[252:255], v[46:49]
	ds_read_b128 v[216:219], v244 offset:20800
	s_waitcnt vmcnt(15)
	ds_write_b128 v165, v[180:183]
	s_waitcnt vmcnt(14)
	ds_write_b128 v165, v[184:187] offset:4608
	s_waitcnt lgkmcnt(5)
	v_mfma_f32_16x16x32_bf16 v[18:21], v[220:223], v[228:231], v[18:21]
	v_mfma_f32_16x16x32_bf16 v[22:25], v[220:223], v[236:239], v[22:25]
	v_mfma_f32_16x16x32_bf16 v[2:5], v[220:223], v[240:243], v[2:5]
	v_mfma_f32_16x16x32_bf16 v[6:9], v[220:223], v[252:255], v[6:9]
	ds_read_b128 v[220:223], v244 offset:23104
	s_waitcnt vmcnt(13)
	ds_write_b128 v165, v[188:191] offset:9216
	s_waitcnt vmcnt(12)
	ds_write_b128 v165, v[192:195] offset:13824
	s_waitcnt lgkmcnt(7)
	v_mfma_f32_16x16x32_bf16 v[26:29], v[224:227], v[228:231], v[26:29]
	ds_read_b128 v[228:231], v245 offset:55360
	v_mfma_f32_16x16x32_bf16 v[30:33], v[224:227], v[236:239], v[30:33]
	ds_read_b128 v[236:239], v245 offset:57664
	v_mfma_f32_16x16x32_bf16 v[10:13], v[224:227], v[240:243], v[10:13]
	ds_read_b128 v[240:243], v245 offset:59968
	v_mfma_f32_16x16x32_bf16 v[14:17], v[224:227], v[252:255], v[14:17]
	ds_read_b128 v[252:255], v245 offset:62272
	ds_read_b128 v[224:227], v244 offset:25408
	s_waitcnt lgkmcnt(4)
	v_mfma_f32_16x16x32_bf16 v[50:53], v[212:215], v[228:231], v[50:53]
	s_waitcnt lgkmcnt(3)
	v_mfma_f32_16x16x32_bf16 v[54:57], v[212:215], v[236:239], v[54:57]
	s_waitcnt lgkmcnt(2)
	v_mfma_f32_16x16x32_bf16 v[34:37], v[212:215], v[240:243], v[34:37]
	s_waitcnt lgkmcnt(1)
	v_mfma_f32_16x16x32_bf16 v[38:41], v[212:215], v[252:255], v[38:41]
	s_waitcnt vmcnt(11)
	ds_write_b128 v165, v[196:199] offset:36864
	s_waitcnt vmcnt(10)
	ds_write_b128 v165, v[200:203] offset:41472
	v_mfma_f32_16x16x32_bf16 v[58:61], v[216:219], v[228:231], v[58:61]
	v_mfma_f32_16x16x32_bf16 v[62:65], v[216:219], v[236:239], v[62:65]
	v_mfma_f32_16x16x32_bf16 v[42:45], v[216:219], v[240:243], v[42:45]
	v_mfma_f32_16x16x32_bf16 v[46:49], v[216:219], v[252:255], v[46:49]
	s_waitcnt vmcnt(9)
	ds_write_b128 v165, v[204:207] offset:46080
	s_waitcnt vmcnt(8)
	ds_write_b128 v165, v[208:211] offset:50688
	v_mfma_f32_16x16x32_bf16 v[18:21], v[220:223], v[228:231], v[18:21]
	v_mfma_f32_16x16x32_bf16 v[22:25], v[220:223], v[236:239], v[22:25]
	v_mfma_f32_16x16x32_bf16 v[2:5], v[220:223], v[240:243], v[2:5]
	v_mfma_f32_16x16x32_bf16 v[6:9], v[220:223], v[252:255], v[6:9]
	s_waitcnt lgkmcnt(4)
	v_mfma_f32_16x16x32_bf16 v[26:29], v[224:227], v[228:231], v[26:29]
	v_mfma_f32_16x16x32_bf16 v[30:33], v[224:227], v[236:239], v[30:33]
	v_mfma_f32_16x16x32_bf16 v[10:13], v[224:227], v[240:243], v[10:13]
	v_mfma_f32_16x16x32_bf16 v[14:17], v[224:227], v[252:255], v[14:17]
	s_waitcnt lgkmcnt(0)
	s_barrier
	ds_read_b128 v[228:231], v245 offset:36864
	ds_read_b128 v[212:215], v244
	ds_read_b128 v[236:239], v245 offset:39168
	ds_read_b128 v[240:243], v245 offset:41472
	ds_read_b128 v[252:255], v245 offset:43776
	ds_read_b128 v[216:219], v244 offset:2304
	ds_read_b128 v[220:223], v244 offset:4608
	ds_read_b128 v[224:227], v244 offset:6912
	s_waitcnt lgkmcnt(6)
	v_mfma_f32_16x16x32_bf16 v[50:53], v[212:215], v[228:231], v[50:53]
	s_waitcnt lgkmcnt(5)
	v_mfma_f32_16x16x32_bf16 v[54:57], v[212:215], v[236:239], v[54:57]
	s_waitcnt lgkmcnt(4)
	v_mfma_f32_16x16x32_bf16 v[34:37], v[212:215], v[240:243], v[34:37]
	s_waitcnt lgkmcnt(3)
	v_mfma_f32_16x16x32_bf16 v[38:41], v[212:215], v[252:255], v[38:41]
	ds_read_b128 v[212:215], v244 offset:64
	s_waitcnt lgkmcnt(3)
	v_mfma_f32_16x16x32_bf16 v[58:61], v[216:219], v[228:231], v[58:61]
	v_mfma_f32_16x16x32_bf16 v[62:65], v[216:219], v[236:239], v[62:65]
	v_mfma_f32_16x16x32_bf16 v[42:45], v[216:219], v[240:243], v[42:45]
	v_mfma_f32_16x16x32_bf16 v[46:49], v[216:219], v[252:255], v[46:49]
	ds_read_b128 v[216:219], v244 offset:2368
	s_waitcnt vmcnt(7)
	ds_write_b128 v165, v[122:125] offset:18432
	s_waitcnt vmcnt(6)
	ds_write_b128 v165, v[68:71] offset:23040
	s_waitcnt lgkmcnt(5)
	v_mfma_f32_16x16x32_bf16 v[18:21], v[220:223], v[228:231], v[18:21]
	v_mfma_f32_16x16x32_bf16 v[22:25], v[220:223], v[236:239], v[22:25]
	v_mfma_f32_16x16x32_bf16 v[2:5], v[220:223], v[240:243], v[2:5]
	v_mfma_f32_16x16x32_bf16 v[6:9], v[220:223], v[252:255], v[6:9]
	ds_read_b128 v[220:223], v244 offset:4672
	s_waitcnt vmcnt(5)
	ds_write_b128 v165, v[126:129] offset:27648
	s_waitcnt vmcnt(4)
	ds_write_b128 v165, v[136:139] offset:32256
	s_waitcnt lgkmcnt(7)
	v_mfma_f32_16x16x32_bf16 v[26:29], v[224:227], v[228:231], v[26:29]
	ds_read_b128 v[228:231], v245 offset:36928
	v_mfma_f32_16x16x32_bf16 v[30:33], v[224:227], v[236:239], v[30:33]
	ds_read_b128 v[236:239], v245 offset:39232
	v_mfma_f32_16x16x32_bf16 v[10:13], v[224:227], v[240:243], v[10:13]
	ds_read_b128 v[240:243], v245 offset:41536
	v_mfma_f32_16x16x32_bf16 v[14:17], v[224:227], v[252:255], v[14:17]
	ds_read_b128 v[252:255], v245 offset:43840
	ds_read_b128 v[224:227], v244 offset:6976
	s_waitcnt lgkmcnt(4)
	v_mfma_f32_16x16x32_bf16 v[50:53], v[212:215], v[228:231], v[50:53]
	s_waitcnt lgkmcnt(3)
	v_mfma_f32_16x16x32_bf16 v[54:57], v[212:215], v[236:239], v[54:57]
	s_waitcnt lgkmcnt(2)
	v_mfma_f32_16x16x32_bf16 v[34:37], v[212:215], v[240:243], v[34:37]
	s_waitcnt lgkmcnt(1)
	v_mfma_f32_16x16x32_bf16 v[38:41], v[212:215], v[252:255], v[38:41]
	s_waitcnt vmcnt(3)
	ds_write_b128 v165, v[72:75] offset:55296
	s_waitcnt vmcnt(2)
	ds_write_b128 v165, v[140:143] offset:59904
	v_mfma_f32_16x16x32_bf16 v[58:61], v[216:219], v[228:231], v[58:61]
	v_mfma_f32_16x16x32_bf16 v[62:65], v[216:219], v[236:239], v[62:65]
	v_mfma_f32_16x16x32_bf16 v[42:45], v[216:219], v[240:243], v[42:45]
	v_mfma_f32_16x16x32_bf16 v[46:49], v[216:219], v[252:255], v[46:49]
	s_waitcnt vmcnt(1)
	ds_write_b128 v165, v[76:79] offset:64512
	s_waitcnt vmcnt(0)
	ds_write_b128 v166, v[144:147] offset:32256
	v_mfma_f32_16x16x32_bf16 v[18:21], v[220:223], v[228:231], v[18:21]
	v_mfma_f32_16x16x32_bf16 v[22:25], v[220:223], v[236:239], v[22:25]
	v_mfma_f32_16x16x32_bf16 v[2:5], v[220:223], v[240:243], v[2:5]
	v_mfma_f32_16x16x32_bf16 v[6:9], v[220:223], v[252:255], v[6:9]
	s_waitcnt lgkmcnt(4)
	v_mfma_f32_16x16x32_bf16 v[26:29], v[224:227], v[228:231], v[26:29]
	v_mfma_f32_16x16x32_bf16 v[30:33], v[224:227], v[236:239], v[30:33]
	v_mfma_f32_16x16x32_bf16 v[10:13], v[224:227], v[240:243], v[10:13]
	v_mfma_f32_16x16x32_bf16 v[14:17], v[224:227], v[252:255], v[14:17]
	s_waitcnt lgkmcnt(0)
	s_barrier
	ds_read_b128 v[228:231], v245 offset:55296
	ds_read_b128 v[212:215], v244 offset:18432
	ds_read_b128 v[236:239], v245 offset:57600
	ds_read_b128 v[240:243], v245 offset:59904
	ds_read_b128 v[252:255], v245 offset:62208
	ds_read_b128 v[216:219], v244 offset:20736
	ds_read_b128 v[220:223], v244 offset:23040
	ds_read_b128 v[224:227], v244 offset:25344
	s_waitcnt lgkmcnt(6)
	v_mfma_f32_16x16x32_bf16 v[50:53], v[212:215], v[228:231], v[50:53]
	s_waitcnt lgkmcnt(5)
	v_mfma_f32_16x16x32_bf16 v[54:57], v[212:215], v[236:239], v[54:57]
	s_waitcnt lgkmcnt(4)
	v_mfma_f32_16x16x32_bf16 v[34:37], v[212:215], v[240:243], v[34:37]
	s_waitcnt lgkmcnt(3)
	v_mfma_f32_16x16x32_bf16 v[38:41], v[212:215], v[252:255], v[38:41]
	ds_read_b128 v[212:215], v244 offset:18496
	s_waitcnt lgkmcnt(3)
	v_mfma_f32_16x16x32_bf16 v[58:61], v[216:219], v[228:231], v[58:61]
	v_mfma_f32_16x16x32_bf16 v[62:65], v[216:219], v[236:239], v[62:65]
	v_mfma_f32_16x16x32_bf16 v[42:45], v[216:219], v[240:243], v[42:45]
	v_mfma_f32_16x16x32_bf16 v[46:49], v[216:219], v[252:255], v[46:49]
	ds_read_b128 v[216:219], v244 offset:20800
	s_waitcnt lgkmcnt(3)
	v_mfma_f32_16x16x32_bf16 v[18:21], v[220:223], v[228:231], v[18:21]
	v_mfma_f32_16x16x32_bf16 v[22:25], v[220:223], v[236:239], v[22:25]
	v_mfma_f32_16x16x32_bf16 v[2:5], v[220:223], v[240:243], v[2:5]
	v_mfma_f32_16x16x32_bf16 v[6:9], v[220:223], v[252:255], v[6:9]
	ds_read_b128 v[220:223], v244 offset:23104
	s_waitcnt lgkmcnt(3)
	v_mfma_f32_16x16x32_bf16 v[26:29], v[224:227], v[228:231], v[26:29]
	ds_read_b128 v[228:231], v245 offset:55360
	v_mfma_f32_16x16x32_bf16 v[30:33], v[224:227], v[236:239], v[30:33]
	ds_read_b128 v[236:239], v245 offset:57664
	v_mfma_f32_16x16x32_bf16 v[10:13], v[224:227], v[240:243], v[10:13]
	ds_read_b128 v[240:243], v245 offset:59968
	v_mfma_f32_16x16x32_bf16 v[14:17], v[224:227], v[252:255], v[14:17]
	ds_read_b128 v[252:255], v245 offset:62272
	ds_read_b128 v[224:227], v244 offset:25408
	s_waitcnt lgkmcnt(4)
	v_mfma_f32_16x16x32_bf16 v[50:53], v[212:215], v[228:231], v[50:53]
	s_waitcnt lgkmcnt(3)
	v_mfma_f32_16x16x32_bf16 v[54:57], v[212:215], v[236:239], v[54:57]
	s_waitcnt lgkmcnt(2)
	v_mfma_f32_16x16x32_bf16 v[34:37], v[212:215], v[240:243], v[34:37]
	s_waitcnt lgkmcnt(1)
	v_mfma_f32_16x16x32_bf16 v[38:41], v[212:215], v[252:255], v[38:41]
	v_mfma_f32_16x16x32_bf16 v[58:61], v[216:219], v[228:231], v[58:61]
	v_mfma_f32_16x16x32_bf16 v[62:65], v[216:219], v[236:239], v[62:65]
	v_mfma_f32_16x16x32_bf16 v[42:45], v[216:219], v[240:243], v[42:45]
	v_mfma_f32_16x16x32_bf16 v[46:49], v[216:219], v[252:255], v[46:49]
	v_mfma_f32_16x16x32_bf16 v[18:21], v[220:223], v[228:231], v[18:21]
	v_mfma_f32_16x16x32_bf16 v[22:25], v[220:223], v[236:239], v[22:25]
	v_mfma_f32_16x16x32_bf16 v[2:5], v[220:223], v[240:243], v[2:5]
	v_mfma_f32_16x16x32_bf16 v[6:9], v[220:223], v[252:255], v[6:9]
	s_waitcnt lgkmcnt(0)
	v_mfma_f32_16x16x32_bf16 v[26:29], v[224:227], v[228:231], v[26:29]
	v_mfma_f32_16x16x32_bf16 v[30:33], v[224:227], v[236:239], v[30:33]
	v_mfma_f32_16x16x32_bf16 v[10:13], v[224:227], v[240:243], v[10:13]
	v_mfma_f32_16x16x32_bf16 v[14:17], v[224:227], v[252:255], v[14:17]
	s_waitcnt lgkmcnt(0)
	s_barrier
	s_nop 7
	v_permlane16_swap_b32_e32 v50, v54
	v_permlane16_swap_b32_e32 v51, v55
	v_permlane16_swap_b32_e32 v52, v56
	v_permlane16_swap_b32_e32 v53, v57
	v_permlane16_swap_b32_e32 v58, v62
	v_permlane16_swap_b32_e32 v59, v63
	v_permlane16_swap_b32_e32 v60, v64
	v_permlane16_swap_b32_e32 v61, v65
	v_permlane16_swap_b32_e32 v34, v38
	v_permlane16_swap_b32_e32 v35, v39
	v_permlane16_swap_b32_e32 v36, v40
	v_permlane16_swap_b32_e32 v37, v41
	v_permlane16_swap_b32_e32 v42, v46
	v_permlane16_swap_b32_e32 v43, v47
	v_permlane16_swap_b32_e32 v44, v48
	v_permlane16_swap_b32_e32 v45, v49
	v_permlane16_swap_b32_e32 v18, v22
	v_permlane16_swap_b32_e32 v19, v23
	v_permlane16_swap_b32_e32 v20, v24
	v_permlane16_swap_b32_e32 v21, v25
	v_permlane16_swap_b32_e32 v26, v30
	v_permlane16_swap_b32_e32 v27, v31
	v_permlane16_swap_b32_e32 v28, v32
	v_permlane16_swap_b32_e32 v29, v33
	v_permlane16_swap_b32_e32 v2, v6
	v_permlane16_swap_b32_e32 v3, v7
	v_permlane16_swap_b32_e32 v4, v8
	v_permlane16_swap_b32_e32 v5, v9
	v_permlane16_swap_b32_e32 v10, v14
	v_permlane16_swap_b32_e32 v11, v15
	v_permlane16_swap_b32_e32 v12, v16
	v_permlane16_swap_b32_e32 v13, v17
	v_permlane32_swap_b32_e32 v50, v54
	v_permlane32_swap_b32_e32 v51, v55
	v_permlane32_swap_b32_e32 v52, v56
	v_permlane32_swap_b32_e32 v53, v57
	v_permlane32_swap_b32_e32 v58, v62
	v_permlane32_swap_b32_e32 v59, v63
	v_permlane32_swap_b32_e32 v60, v64
	v_permlane32_swap_b32_e32 v61, v65
	v_permlane32_swap_b32_e32 v34, v38
	v_permlane32_swap_b32_e32 v35, v39
	v_permlane32_swap_b32_e32 v36, v40
	v_permlane32_swap_b32_e32 v37, v41
	v_permlane32_swap_b32_e32 v42, v46
	v_permlane32_swap_b32_e32 v43, v47
	v_permlane32_swap_b32_e32 v44, v48
	v_permlane32_swap_b32_e32 v45, v49
	v_permlane32_swap_b32_e32 v18, v22
	v_permlane32_swap_b32_e32 v19, v23
	v_permlane32_swap_b32_e32 v20, v24
	v_permlane32_swap_b32_e32 v21, v25
	v_permlane32_swap_b32_e32 v26, v30
	v_permlane32_swap_b32_e32 v27, v31
	v_permlane32_swap_b32_e32 v28, v32
	v_permlane32_swap_b32_e32 v29, v33
	v_permlane32_swap_b32_e32 v2, v6
	v_permlane32_swap_b32_e32 v3, v7
	v_permlane32_swap_b32_e32 v4, v8
	v_permlane32_swap_b32_e32 v5, v9
	v_permlane32_swap_b32_e32 v10, v14
	v_permlane32_swap_b32_e32 v11, v15
	v_permlane32_swap_b32_e32 v12, v16
	v_permlane32_swap_b32_e32 v13, v17

.LBB0_1120:
	s_cmp_gt_i32 s52, 9
	s_cselect_b64 s[0:1], -1, 0
	s_cmp_lt_i32 s53, 10
	s_cselect_b64 s[2:3], -1, 0
	s_or_b64 s[0:1], s[0:1], s[2:3]
	s_and_b64 vcc, exec, s[0:1]
	s_cbranch_vccnz .LBB0_1442
	s_add_u32 s0, s82, 0xe954000
	v_readlane_b32 s2, v248, 0
	s_addc_u32 s1, s83, 0
	s_lshr_b32 s23, s2, 3
	s_and_b32 s2, s2, 7
	s_add_i32 s3, s2, 0xfffc
	s_and_b32 s3, s3, 0xffff
	v_lshlrev_b32_e32 v4, 4, v1
	s_lshr_b32 s40, s50, 3
	s_min_u32 s41, s2, s3
	v_and_b32_e32 v82, 0x70, v4
	v_mov_b32_e32 v83, 0
	s_cmp_gt_u32 s2, 3
	v_lshrrev_b32_e32 v154, 3, v1
	v_lshl_add_u64 v[2:3], s[82:83], 0, v[82:83]
	s_mov_b64 s[2:3], 0x9500000
	v_lshl_add_u64 v[84:85], v[2:3], 0, s[2:3]
	v_add_u32_e32 v155, 32, v154
	s_mov_b64 s[2:3], 0xb100000
	v_lshl_add_u64 v[86:87], v[2:3], 0, s[2:3]
	v_lshlrev_b32_e32 v2, 6, v155
	v_add_u32_e32 v156, 64, v154
	s_movk_i32 s4, 0x1000
	v_and_b32_e32 v2, 0xfc0, v2
	v_lshrrev_b32_e32 v3, 6, v155
	v_or3_b32 v158, v3, v2, s4
	v_lshlrev_b32_e32 v2, 6, v156
	v_add_u32_e32 v157, 0x60, v154
	v_and_b32_e32 v2, 0xfc0, v2
	v_lshrrev_b32_e32 v3, 6, v156
	s_cselect_b32 s42, 48, 0
	v_or3_b32 v159, v3, v2, s4
	v_lshlrev_b32_e32 v2, 6, v157
	s_add_u32 s14, s80, 0x6000000
	v_and_b32_e32 v2, 0xfc0, v2
	v_lshrrev_b32_e32 v3, 6, v157
	s_addc_u32 s15, s81, 0
	v_or3_b32 v160, v3, v2, s4
	v_lshrrev_b32_e32 v2, 1, v1
	s_movk_i32 s2, 0x1c0
	s_add_u32 s16, s80, 0x5000000
	v_and_or_b32 v3, v2, s2, v132
	v_and_b32_e32 v2, 16, v2
	s_movk_i32 s2, 0x90
	v_and_b32_e32 v162, 0x5f, v1
	s_addc_u32 s17, s81, 0
	v_mad_u32_u24 v161, v3, s2, v2
	v_mad_u32_u24 v163, v162, s2, v2
	v_mul_u32_u24_e32 v2, 0x48, v154
	v_lshlrev_b32_e32 v88, 2, v131
	s_add_u32 s18, s80, 0x4000000
	s_movk_i32 s2, 0x1f0
	v_lshl_add_u32 v164, v2, 1, v82
	v_lshrrev_b32_e32 v246, 3, v1
	v_and_b32_e32 v246, 15, v246
	v_add_u32_e32 v246, 4, v246
	v_bfe_u32 v246, v246, 3, 1
	v_and_b32_e32 v249, 1, v1
	v_lshlrev_b32_e32 v249, 1, v249
	v_sub_u32_e32 v249, 1, v249
	v_mul_i32_i24_e32 v246, v246, v249
	v_lshlrev_b32_e32 v246, 4, v246
	v_add_u32_e32 v164, v246, v164
	s_addc_u32 s19, s81, 0
	v_and_or_b32 v2, v4, s2, v88
	v_lshlrev_b32_e32 v5, 6, v154
	v_lshlrev_b32_e32 v166, 6, v133
	s_add_u32 s20, s80, 0x3000000
	v_lshlrev_b32_e32 v82, 3, v2
	s_mul_i32 s41, s41, 11
	s_mov_b32 s13, 0
	v_or3_b32 v135, v5, v135, s4
	v_add_u32_e32 v165, 0x9000, v164
	v_or_b32_e32 v167, 0x200000, v166
	v_or_b32_e32 v90, 1, v88
	v_or_b32_e32 v92, 2, v88
	v_or_b32_e32 v94, 3, v88
	v_mov_b32_e32 v89, v83
	v_mov_b32_e32 v91, v83
	v_mov_b32_e32 v93, v83
	v_mov_b32_e32 v95, v83
	v_or_b32_e32 v96, 8, v88
	v_mov_b32_e32 v97, v83
	v_or_b32_e32 v98, 9, v88
	v_mov_b32_e32 v99, v83
	v_or_b32_e32 v100, 10, v88
	v_mov_b32_e32 v101, v83
	v_or_b32_e32 v102, 11, v88
	v_mov_b32_e32 v103, v83
	v_or_b32_e32 v104, 16, v88
	v_mov_b32_e32 v105, v83
	v_or_b32_e32 v106, 17, v88
	v_mov_b32_e32 v107, v83
	v_or_b32_e32 v108, 18, v88
	v_mov_b32_e32 v109, v83
	v_or_b32_e32 v110, 19, v88
	v_mov_b32_e32 v111, v83
	v_or_b32_e32 v112, 24, v88
	v_mov_b32_e32 v113, v83
	v_or_b32_e32 v114, 25, v88
	v_mov_b32_e32 v115, v83
	v_or_b32_e32 v116, 26, v88
	v_mov_b32_e32 v117, v83
	v_or_b32_e32 v118, 27, v88
	v_mov_b32_e32 v119, v83
	s_addc_u32 s21, s81, 0
	v_lshl_add_u64 v[120:121], s[0:1], 0, v[82:83]
	v_or_b32_e32 v168, 32, v88
	s_movk_i32 s43, 0x3f0
	s_mov_b32 s22, 0x3e38aa3b
	s_mov_b64 s[24:25], 0x200000
	v_mov_b32_e32 v169, 0x200000
	v_mov_b32_e32 v170, 0x200020
	s_branch .LBB0_1124

.LBB0_1149:
	v_ashrrev_i32_e32 v3, 31, v2
	v_lshlrev_b64 v[2:3], 11, v[2:3]
	v_lshl_add_u64 v[70:71], v[86:87], 0, v[2:3]
	v_or_b32_e32 v2, s56, v154
	v_ashrrev_i32_e32 v3, 31, v2
	v_lshlrev_b64 v[2:3], 11, v[2:3]
	v_lshl_add_u64 v[72:73], v[84:85], 0, v[2:3]
	v_add_u32_e32 v2, s56, v155
	v_ashrrev_i32_e32 v3, 31, v2
	v_lshlrev_b64 v[2:3], 11, v[2:3]
	v_lshl_add_u64 v[74:75], v[84:85], 0, v[2:3]
	v_add_u32_e32 v2, s56, v156
	v_ashrrev_i32_e32 v3, 31, v2
	v_lshlrev_b64 v[2:3], 11, v[2:3]
	v_lshl_add_u64 v[76:77], v[84:85], 0, v[2:3]
	v_add_u32_e32 v2, s56, v157
	v_ashrrev_i32_e32 v3, 31, v2
	v_ashrrev_i32_e32 v9, 31, v8
	v_ashrrev_i32_e32 v5, 31, v4
	v_lshlrev_b64 v[2:3], 11, v[2:3]
	v_ashrrev_i32_e32 v7, 31, v6
	v_lshlrev_b64 v[8:9], 11, v[8:9]
	v_lshlrev_b64 v[4:5], 11, v[4:5]
	v_lshl_add_u64 v[78:79], v[84:85], 0, v[2:3]
	v_lshlrev_b64 v[2:3], 11, v[6:7]
	v_lshl_add_u64 v[66:67], v[86:87], 0, v[8:9]
	v_lshl_add_u64 v[68:69], v[86:87], 0, v[4:5]
	v_lshl_add_u64 v[80:81], v[86:87], 0, v[2:3]
	global_load_dwordx4 v[2:5], v[70:71], off
	global_load_dwordx4 v[6:9], v[68:69], off
	global_load_dwordx4 v[10:13], v[66:67], off
	global_load_dwordx4 v[14:17], v[80:81], off
	global_load_dwordx4 v[18:21], v[72:73], off
	global_load_dwordx4 v[22:25], v[74:75], off
	global_load_dwordx4 v[26:29], v[76:77], off
	global_load_dwordx4 v[30:33], v[78:79], off
	global_load_dwordx4 v[122:125], v[70:71], off offset:128
	global_load_dwordx4 v[126:129], v[68:69], off offset:128
	global_load_dwordx4 v[136:139], v[66:67], off offset:128
	global_load_dwordx4 v[140:143], v[80:81], off offset:128
	global_load_dwordx4 v[144:147], v[72:73], off offset:128
	global_load_dwordx4 v[148:151], v[74:75], off offset:128
	global_load_dwordx4 v[172:175], v[76:77], off offset:128
	global_load_dwordx4 v[176:179], v[78:79], off offset:128
	s_waitcnt vmcnt(15)
	ds_write_b128 v164, v[2:5] offset:36864
	s_waitcnt vmcnt(14)
	ds_write_b128 v164, v[6:9] offset:41472
	s_waitcnt vmcnt(13)
	ds_write_b128 v164, v[10:13] offset:46080
	s_waitcnt vmcnt(12)
	ds_write_b128 v164, v[14:17] offset:50688
	s_waitcnt vmcnt(11)
	ds_write_b128 v164, v[18:21]
	s_waitcnt vmcnt(10)
	ds_write_b128 v164, v[22:25] offset:4608
	s_waitcnt vmcnt(9)
	ds_write_b128 v164, v[26:29] offset:9216
	s_waitcnt vmcnt(8)
	ds_write_b128 v164, v[30:33] offset:13824
	s_waitcnt lgkmcnt(0)
	s_barrier
	global_load_dwordx4 v[180:183], v[74:75], off offset:256
	global_load_dwordx4 v[188:191], v[76:77], off offset:256
	global_load_dwordx4 v[192:195], v[72:73], off offset:256
	global_load_dwordx4 v[196:199], v[70:71], off offset:256
	global_load_dwordx4 v[200:203], v[68:69], off offset:256
	global_load_dwordx4 v[204:207], v[66:67], off offset:256
	global_load_dwordx4 v[208:211], v[78:79], off offset:256
	global_load_dwordx4 v[212:215], v[80:81], off offset:256
	v_and_b32_e32 v246, 15, v1
	v_add_u32_e32 v246, 4, v246
	v_bfe_u32 v246, v246, 3, 1
	v_bfe_u32 v249, v1, 4, 2
	v_xor_b32_e32 v246, v246, v249
	v_bfe_u32 v249, v1, 5, 1
	v_sub_u32_e32 v246, v246, v249
	v_lshlrev_b32_e32 v246, 4, v246
	v_bfe_u32 v249, v1, 4, 1
	v_mul_u32_u24_e32 v249, 0x900, v249
	v_sub_u32_e32 v246, v246, v249
	v_add_u32_e32 v244, v246, v161
	v_add_u32_e32 v245, v246, v163
	ds_read_b128 v[232:235], v245 offset:36864
	ds_read_b128 v[216:219], v244
	ds_read_b128 v[236:239], v245 offset:39168
	ds_read_b128 v[240:243], v245 offset:41472
	ds_read_b128 v[252:255], v245 offset:43776
	ds_read_b128 v[220:223], v244 offset:2304
	ds_read_b128 v[224:227], v244 offset:4608
	ds_read_b128 v[228:231], v244 offset:6912
	s_waitcnt lgkmcnt(6)
	v_mfma_f32_16x16x32_bf16 v[50:53], v[216:219], v[232:235], 0
	s_waitcnt lgkmcnt(5)
	v_mfma_f32_16x16x32_bf16 v[54:57], v[216:219], v[236:239], 0
	s_waitcnt lgkmcnt(4)
	v_mfma_f32_16x16x32_bf16 v[34:37], v[216:219], v[240:243], 0
	s_waitcnt lgkmcnt(3)
	v_mfma_f32_16x16x32_bf16 v[38:41], v[216:219], v[252:255], 0
	ds_read_b128 v[216:219], v244 offset:64
	s_waitcnt lgkmcnt(3)
	v_mfma_f32_16x16x32_bf16 v[58:61], v[220:223], v[232:235], 0
	v_mfma_f32_16x16x32_bf16 v[62:65], v[220:223], v[236:239], 0
	v_mfma_f32_16x16x32_bf16 v[42:45], v[220:223], v[240:243], 0
	v_mfma_f32_16x16x32_bf16 v[46:49], v[220:223], v[252:255], 0
	ds_read_b128 v[220:223], v244 offset:2368
	s_waitcnt vmcnt(11)
	ds_write_b128 v164, v[144:147] offset:18432
	s_waitcnt vmcnt(10)
	ds_write_b128 v164, v[148:151] offset:23040
	s_waitcnt lgkmcnt(5)
	v_mfma_f32_16x16x32_bf16 v[18:21], v[224:227], v[232:235], 0
	v_mfma_f32_16x16x32_bf16 v[22:25], v[224:227], v[236:239], 0
	v_mfma_f32_16x16x32_bf16 v[2:5], v[224:227], v[240:243], 0
	v_mfma_f32_16x16x32_bf16 v[6:9], v[224:227], v[252:255], 0
	ds_read_b128 v[224:227], v244 offset:4672
	s_waitcnt vmcnt(9)
	ds_write_b128 v164, v[172:175] offset:27648
	s_waitcnt vmcnt(8)
	ds_write_b128 v164, v[176:179] offset:32256
	s_waitcnt lgkmcnt(7)
	v_mfma_f32_16x16x32_bf16 v[26:29], v[228:231], v[232:235], 0
	ds_read_b128 v[232:235], v245 offset:36928
	v_mfma_f32_16x16x32_bf16 v[30:33], v[228:231], v[236:239], 0
	ds_read_b128 v[236:239], v245 offset:39232
	v_mfma_f32_16x16x32_bf16 v[10:13], v[228:231], v[240:243], 0
	ds_read_b128 v[240:243], v245 offset:41536
	v_mfma_f32_16x16x32_bf16 v[14:17], v[228:231], v[252:255], 0
	ds_read_b128 v[252:255], v245 offset:43840
	ds_read_b128 v[228:231], v244 offset:6976
	s_waitcnt lgkmcnt(4)
	v_mfma_f32_16x16x32_bf16 v[50:53], v[216:219], v[232:235], v[50:53]
	s_waitcnt lgkmcnt(3)
	v_mfma_f32_16x16x32_bf16 v[54:57], v[216:219], v[236:239], v[54:57]
	s_waitcnt lgkmcnt(2)
	v_mfma_f32_16x16x32_bf16 v[34:37], v[216:219], v[240:243], v[34:37]
	s_waitcnt lgkmcnt(1)
	v_mfma_f32_16x16x32_bf16 v[38:41], v[216:219], v[252:255], v[38:41]
	ds_write_b128 v164, v[122:125] offset:55296
	ds_write_b128 v164, v[126:129] offset:59904
	v_mfma_f32_16x16x32_bf16 v[58:61], v[220:223], v[232:235], v[58:61]
	v_mfma_f32_16x16x32_bf16 v[62:65], v[220:223], v[236:239], v[62:65]
	v_mfma_f32_16x16x32_bf16 v[42:45], v[220:223], v[240:243], v[42:45]
	v_mfma_f32_16x16x32_bf16 v[46:49], v[220:223], v[252:255], v[46:49]
	ds_write_b128 v164, v[136:139] offset:64512
	ds_write_b128 v165, v[140:143] offset:32256
	v_mfma_f32_16x16x32_bf16 v[18:21], v[224:227], v[232:235], v[18:21]
	v_mfma_f32_16x16x32_bf16 v[22:25], v[224:227], v[236:239], v[22:25]
	v_mfma_f32_16x16x32_bf16 v[2:5], v[224:227], v[240:243], v[2:5]
	v_mfma_f32_16x16x32_bf16 v[6:9], v[224:227], v[252:255], v[6:9]
	s_waitcnt lgkmcnt(4)
	v_mfma_f32_16x16x32_bf16 v[26:29], v[228:231], v[232:235], v[26:29]
	v_mfma_f32_16x16x32_bf16 v[30:33], v[228:231], v[236:239], v[30:33]
	v_mfma_f32_16x16x32_bf16 v[10:13], v[228:231], v[240:243], v[10:13]
	v_mfma_f32_16x16x32_bf16 v[14:17], v[228:231], v[252:255], v[14:17]
	s_waitcnt lgkmcnt(0)
	s_barrier
	global_load_dwordx4 v[122:125], v[72:73], off offset:384
	global_load_dwordx4 v[126:129], v[74:75], off offset:384
	global_load_dwordx4 v[136:139], v[76:77], off offset:384
	global_load_dwordx4 v[140:143], v[78:79], off offset:384
	global_load_dwordx4 v[144:147], v[70:71], off offset:384
	global_load_dwordx4 v[148:151], v[68:69], off offset:384
	global_load_dwordx4 v[172:175], v[66:67], off offset:384
	global_load_dwordx4 v[176:179], v[80:81], off offset:384
	ds_read_b128 v[232:235], v245 offset:55296
	ds_read_b128 v[216:219], v244 offset:18432
	ds_read_b128 v[236:239], v245 offset:57600
	ds_read_b128 v[240:243], v245 offset:59904
	ds_read_b128 v[252:255], v245 offset:62208
	ds_read_b128 v[220:223], v244 offset:20736
	ds_read_b128 v[224:227], v244 offset:23040
	ds_read_b128 v[228:231], v244 offset:25344
	s_waitcnt lgkmcnt(6)
	v_mfma_f32_16x16x32_bf16 v[50:53], v[216:219], v[232:235], v[50:53]
	s_waitcnt lgkmcnt(5)
	v_mfma_f32_16x16x32_bf16 v[54:57], v[216:219], v[236:239], v[54:57]
	s_waitcnt lgkmcnt(4)
	v_mfma_f32_16x16x32_bf16 v[34:37], v[216:219], v[240:243], v[34:37]
	s_waitcnt lgkmcnt(3)
	v_mfma_f32_16x16x32_bf16 v[38:41], v[216:219], v[252:255], v[38:41]
	ds_read_b128 v[216:219], v244 offset:18496
	s_waitcnt lgkmcnt(3)
	v_mfma_f32_16x16x32_bf16 v[58:61], v[220:223], v[232:235], v[58:61]
	v_mfma_f32_16x16x32_bf16 v[62:65], v[220:223], v[236:239], v[62:65]
	v_mfma_f32_16x16x32_bf16 v[42:45], v[220:223], v[240:243], v[42:45]
	v_mfma_f32_16x16x32_bf16 v[46:49], v[220:223], v[252:255], v[46:49]
	ds_read_b128 v[220:223], v244 offset:20800
	s_waitcnt vmcnt(13)
	ds_write_b128 v164, v[192:195]
	ds_write_b128 v164, v[180:183] offset:4608
	s_waitcnt lgkmcnt(5)
	v_mfma_f32_16x16x32_bf16 v[18:21], v[224:227], v[232:235], v[18:21]
	v_mfma_f32_16x16x32_bf16 v[22:25], v[224:227], v[236:239], v[22:25]
	v_mfma_f32_16x16x32_bf16 v[2:5], v[224:227], v[240:243], v[2:5]
	v_mfma_f32_16x16x32_bf16 v[6:9], v[224:227], v[252:255], v[6:9]
	ds_read_b128 v[224:227], v244 offset:23104
	ds_write_b128 v164, v[188:191] offset:9216
	s_waitcnt vmcnt(9)
	ds_write_b128 v164, v[208:211] offset:13824
	s_waitcnt lgkmcnt(7)
	v_mfma_f32_16x16x32_bf16 v[26:29], v[228:231], v[232:235], v[26:29]
	ds_read_b128 v[232:235], v245 offset:55360
	v_mfma_f32_16x16x32_bf16 v[30:33], v[228:231], v[236:239], v[30:33]
	ds_read_b128 v[236:239], v245 offset:57664
	v_mfma_f32_16x16x32_bf16 v[10:13], v[228:231], v[240:243], v[10:13]
	ds_read_b128 v[240:243], v245 offset:59968
	v_mfma_f32_16x16x32_bf16 v[14:17], v[228:231], v[252:255], v[14:17]
	ds_read_b128 v[252:255], v245 offset:62272
	ds_read_b128 v[228:231], v244 offset:25408
	s_waitcnt lgkmcnt(4)
	v_mfma_f32_16x16x32_bf16 v[50:53], v[216:219], v[232:235], v[50:53]
	s_waitcnt lgkmcnt(3)
	v_mfma_f32_16x16x32_bf16 v[54:57], v[216:219], v[236:239], v[54:57]
	s_waitcnt lgkmcnt(2)
	v_mfma_f32_16x16x32_bf16 v[34:37], v[216:219], v[240:243], v[34:37]
	s_waitcnt lgkmcnt(1)
	v_mfma_f32_16x16x32_bf16 v[38:41], v[216:219], v[252:255], v[38:41]
	ds_write_b128 v164, v[196:199] offset:36864
	ds_write_b128 v164, v[200:203] offset:41472
	v_mfma_f32_16x16x32_bf16 v[58:61], v[220:223], v[232:235], v[58:61]
	v_mfma_f32_16x16x32_bf16 v[62:65], v[220:223], v[236:239], v[62:65]
	v_mfma_f32_16x16x32_bf16 v[42:45], v[220:223], v[240:243], v[42:45]
	v_mfma_f32_16x16x32_bf16 v[46:49], v[220:223], v[252:255], v[46:49]
	ds_write_b128 v164, v[204:207] offset:46080
	s_waitcnt vmcnt(8)
	ds_write_b128 v164, v[212:215] offset:50688
	v_mfma_f32_16x16x32_bf16 v[18:21], v[224:227], v[232:235], v[18:21]
	v_mfma_f32_16x16x32_bf16 v[22:25], v[224:227], v[236:239], v[22:25]
	v_mfma_f32_16x16x32_bf16 v[2:5], v[224:227], v[240:243], v[2:5]
	v_mfma_f32_16x16x32_bf16 v[6:9], v[224:227], v[252:255], v[6:9]
	s_waitcnt lgkmcnt(4)
	v_mfma_f32_16x16x32_bf16 v[26:29], v[228:231], v[232:235], v[26:29]
	v_mfma_f32_16x16x32_bf16 v[30:33], v[228:231], v[236:239], v[30:33]
	v_mfma_f32_16x16x32_bf16 v[10:13], v[228:231], v[240:243], v[10:13]
	v_mfma_f32_16x16x32_bf16 v[14:17], v[228:231], v[252:255], v[14:17]
	s_waitcnt lgkmcnt(0)
	s_barrier
	global_load_dwordx4 v[180:183], v[72:73], off offset:512
	global_load_dwordx4 v[188:191], v[74:75], off offset:512
	global_load_dwordx4 v[192:195], v[76:77], off offset:512
	global_load_dwordx4 v[196:199], v[78:79], off offset:512
	global_load_dwordx4 v[200:203], v[70:71], off offset:512
	global_load_dwordx4 v[204:207], v[68:69], off offset:512
	global_load_dwordx4 v[208:211], v[66:67], off offset:512
	global_load_dwordx4 v[212:215], v[80:81], off offset:512
	ds_read_b128 v[232:235], v245 offset:36864
	ds_read_b128 v[216:219], v244
	ds_read_b128 v[236:239], v245 offset:39168
	ds_read_b128 v[240:243], v245 offset:41472
	ds_read_b128 v[252:255], v245 offset:43776
	ds_read_b128 v[220:223], v244 offset:2304
	ds_read_b128 v[224:227], v244 offset:4608
	ds_read_b128 v[228:231], v244 offset:6912
	s_waitcnt lgkmcnt(6)
	v_mfma_f32_16x16x32_bf16 v[50:53], v[216:219], v[232:235], v[50:53]
	s_waitcnt lgkmcnt(5)
	v_mfma_f32_16x16x32_bf16 v[54:57], v[216:219], v[236:239], v[54:57]
	s_waitcnt lgkmcnt(4)
	v_mfma_f32_16x16x32_bf16 v[34:37], v[216:219], v[240:243], v[34:37]
	s_waitcnt lgkmcnt(3)
	v_mfma_f32_16x16x32_bf16 v[38:41], v[216:219], v[252:255], v[38:41]
	ds_read_b128 v[216:219], v244 offset:64
	s_waitcnt lgkmcnt(3)
	v_mfma_f32_16x16x32_bf16 v[58:61], v[220:223], v[232:235], v[58:61]
	v_mfma_f32_16x16x32_bf16 v[62:65], v[220:223], v[236:239], v[62:65]
	v_mfma_f32_16x16x32_bf16 v[42:45], v[220:223], v[240:243], v[42:45]
	v_mfma_f32_16x16x32_bf16 v[46:49], v[220:223], v[252:255], v[46:49]
	ds_read_b128 v[220:223], v244 offset:2368
	s_waitcnt vmcnt(15)
	ds_write_b128 v164, v[122:125] offset:18432
	s_waitcnt vmcnt(14)
	ds_write_b128 v164, v[126:129] offset:23040
	s_waitcnt lgkmcnt(5)
	v_mfma_f32_16x16x32_bf16 v[18:21], v[224:227], v[232:235], v[18:21]
	v_mfma_f32_16x16x32_bf16 v[22:25], v[224:227], v[236:239], v[22:25]
	v_mfma_f32_16x16x32_bf16 v[2:5], v[224:227], v[240:243], v[2:5]
	v_mfma_f32_16x16x32_bf16 v[6:9], v[224:227], v[252:255], v[6:9]
	ds_read_b128 v[224:227], v244 offset:4672
	s_waitcnt vmcnt(13)
	ds_write_b128 v164, v[136:139] offset:27648
	s_waitcnt vmcnt(12)
	ds_write_b128 v164, v[140:143] offset:32256
	s_waitcnt lgkmcnt(7)
	v_mfma_f32_16x16x32_bf16 v[26:29], v[228:231], v[232:235], v[26:29]
	ds_read_b128 v[232:235], v245 offset:36928
	v_mfma_f32_16x16x32_bf16 v[30:33], v[228:231], v[236:239], v[30:33]
	ds_read_b128 v[236:239], v245 offset:39232
	v_mfma_f32_16x16x32_bf16 v[10:13], v[228:231], v[240:243], v[10:13]
	ds_read_b128 v[240:243], v245 offset:41536
	v_mfma_f32_16x16x32_bf16 v[14:17], v[228:231], v[252:255], v[14:17]
	ds_read_b128 v[252:255], v245 offset:43840
	ds_read_b128 v[228:231], v244 offset:6976
	s_waitcnt lgkmcnt(4)
	v_mfma_f32_16x16x32_bf16 v[50:53], v[216:219], v[232:235], v[50:53]
	s_waitcnt lgkmcnt(3)
	v_mfma_f32_16x16x32_bf16 v[54:57], v[216:219], v[236:239], v[54:57]
	s_waitcnt lgkmcnt(2)
	v_mfma_f32_16x16x32_bf16 v[34:37], v[216:219], v[240:243], v[34:37]
	s_waitcnt lgkmcnt(1)
	v_mfma_f32_16x16x32_bf16 v[38:41], v[216:219], v[252:255], v[38:41]
	s_waitcnt vmcnt(11)
	ds_write_b128 v164, v[144:147] offset:55296
	s_waitcnt vmcnt(10)
	ds_write_b128 v164, v[148:151] offset:59904
	v_mfma_f32_16x16x32_bf16 v[58:61], v[220:223], v[232:235], v[58:61]
	v_mfma_f32_16x16x32_bf16 v[62:65], v[220:223], v[236:239], v[62:65]
	v_mfma_f32_16x16x32_bf16 v[42:45], v[220:223], v[240:243], v[42:45]
	v_mfma_f32_16x16x32_bf16 v[46:49], v[220:223], v[252:255], v[46:49]
	s_waitcnt vmcnt(9)
	ds_write_b128 v164, v[172:175] offset:64512
	s_waitcnt vmcnt(8)
	ds_write_b128 v165, v[176:179] offset:32256
	v_mfma_f32_16x16x32_bf16 v[18:21], v[224:227], v[232:235], v[18:21]
	v_mfma_f32_16x16x32_bf16 v[22:25], v[224:227], v[236:239], v[22:25]
	v_mfma_f32_16x16x32_bf16 v[2:5], v[224:227], v[240:243], v[2:5]
	v_mfma_f32_16x16x32_bf16 v[6:9], v[224:227], v[252:255], v[6:9]
	s_waitcnt lgkmcnt(4)
	v_mfma_f32_16x16x32_bf16 v[26:29], v[228:231], v[232:235], v[26:29]
	v_mfma_f32_16x16x32_bf16 v[30:33], v[228:231], v[236:239], v[30:33]
	v_mfma_f32_16x16x32_bf16 v[10:13], v[228:231], v[240:243], v[10:13]
	v_mfma_f32_16x16x32_bf16 v[14:17], v[228:231], v[252:255], v[14:17]
	s_waitcnt lgkmcnt(0)
	s_barrier
	global_load_dwordx4 v[122:125], v[72:73], off offset:640
	global_load_dwordx4 v[126:129], v[74:75], off offset:640
	global_load_dwordx4 v[136:139], v[76:77], off offset:640
	global_load_dwordx4 v[140:143], v[78:79], off offset:640
	global_load_dwordx4 v[144:147], v[70:71], off offset:640
	global_load_dwordx4 v[148:151], v[68:69], off offset:640
	global_load_dwordx4 v[172:175], v[66:67], off offset:640
	global_load_dwordx4 v[176:179], v[80:81], off offset:640
	ds_read_b128 v[232:235], v245 offset:55296
	ds_read_b128 v[216:219], v244 offset:18432
	ds_read_b128 v[236:239], v245 offset:57600
	ds_read_b128 v[240:243], v245 offset:59904
	ds_read_b128 v[252:255], v245 offset:62208
	ds_read_b128 v[220:223], v244 offset:20736
	ds_read_b128 v[224:227], v244 offset:23040
	ds_read_b128 v[228:231], v244 offset:25344
	s_waitcnt lgkmcnt(6)
	v_mfma_f32_16x16x32_bf16 v[50:53], v[216:219], v[232:235], v[50:53]
	s_waitcnt lgkmcnt(5)
	v_mfma_f32_16x16x32_bf16 v[54:57], v[216:219], v[236:239], v[54:57]
	s_waitcnt lgkmcnt(4)
	v_mfma_f32_16x16x32_bf16 v[34:37], v[216:219], v[240:243], v[34:37]
	s_waitcnt lgkmcnt(3)
	v_mfma_f32_16x16x32_bf16 v[38:41], v[216:219], v[252:255], v[38:41]
	ds_read_b128 v[216:219], v244 offset:18496
	s_waitcnt lgkmcnt(3)
	v_mfma_f32_16x16x32_bf16 v[58:61], v[220:223], v[232:235], v[58:61]
	v_mfma_f32_16x16x32_bf16 v[62:65], v[220:223], v[236:239], v[62:65]
	v_mfma_f32_16x16x32_bf16 v[42:45], v[220:223], v[240:243], v[42:45]
	v_mfma_f32_16x16x32_bf16 v[46:49], v[220:223], v[252:255], v[46:49]
	ds_read_b128 v[220:223], v244 offset:20800
	s_waitcnt vmcnt(15)
	ds_write_b128 v164, v[180:183]
	s_waitcnt vmcnt(14)
	ds_write_b128 v164, v[188:191] offset:4608
	s_waitcnt lgkmcnt(5)
	v_mfma_f32_16x16x32_bf16 v[18:21], v[224:227], v[232:235], v[18:21]
	v_mfma_f32_16x16x32_bf16 v[22:25], v[224:227], v[236:239], v[22:25]
	v_mfma_f32_16x16x32_bf16 v[2:5], v[224:227], v[240:243], v[2:5]
	v_mfma_f32_16x16x32_bf16 v[6:9], v[224:227], v[252:255], v[6:9]
	ds_read_b128 v[224:227], v244 offset:23104
	s_waitcnt vmcnt(13)
	ds_write_b128 v164, v[192:195] offset:9216
	s_waitcnt vmcnt(12)
	ds_write_b128 v164, v[196:199] offset:13824
	s_waitcnt lgkmcnt(7)
	v_mfma_f32_16x16x32_bf16 v[26:29], v[228:231], v[232:235], v[26:29]
	ds_read_b128 v[232:235], v245 offset:55360
	v_mfma_f32_16x16x32_bf16 v[30:33], v[228:231], v[236:239], v[30:33]
	ds_read_b128 v[236:239], v245 offset:57664
	v_mfma_f32_16x16x32_bf16 v[10:13], v[228:231], v[240:243], v[10:13]
	ds_read_b128 v[240:243], v245 offset:59968
	v_mfma_f32_16x16x32_bf16 v[14:17], v[228:231], v[252:255], v[14:17]
	ds_read_b128 v[252:255], v245 offset:62272
	ds_read_b128 v[228:231], v244 offset:25408
	s_waitcnt lgkmcnt(4)
	v_mfma_f32_16x16x32_bf16 v[50:53], v[216:219], v[232:235], v[50:53]
	s_waitcnt lgkmcnt(3)
	v_mfma_f32_16x16x32_bf16 v[54:57], v[216:219], v[236:239], v[54:57]
	s_waitcnt lgkmcnt(2)
	v_mfma_f32_16x16x32_bf16 v[34:37], v[216:219], v[240:243], v[34:37]
	s_waitcnt lgkmcnt(1)
	v_mfma_f32_16x16x32_bf16 v[38:41], v[216:219], v[252:255], v[38:41]
	s_waitcnt vmcnt(11)
	ds_write_b128 v164, v[200:203] offset:36864
	s_waitcnt vmcnt(10)
	ds_write_b128 v164, v[204:207] offset:41472
	v_mfma_f32_16x16x32_bf16 v[58:61], v[220:223], v[232:235], v[58:61]
	v_mfma_f32_16x16x32_bf16 v[62:65], v[220:223], v[236:239], v[62:65]
	v_mfma_f32_16x16x32_bf16 v[42:45], v[220:223], v[240:243], v[42:45]
	v_mfma_f32_16x16x32_bf16 v[46:49], v[220:223], v[252:255], v[46:49]
	s_waitcnt vmcnt(9)
	ds_write_b128 v164, v[208:211] offset:46080
	s_waitcnt vmcnt(8)
	ds_write_b128 v164, v[212:215] offset:50688
	v_mfma_f32_16x16x32_bf16 v[18:21], v[224:227], v[232:235], v[18:21]
	v_mfma_f32_16x16x32_bf16 v[22:25], v[224:227], v[236:239], v[22:25]
	v_mfma_f32_16x16x32_bf16 v[2:5], v[224:227], v[240:243], v[2:5]
	v_mfma_f32_16x16x32_bf16 v[6:9], v[224:227], v[252:255], v[6:9]
	s_waitcnt lgkmcnt(4)
	v_mfma_f32_16x16x32_bf16 v[26:29], v[228:231], v[232:235], v[26:29]
	v_mfma_f32_16x16x32_bf16 v[30:33], v[228:231], v[236:239], v[30:33]
	v_mfma_f32_16x16x32_bf16 v[10:13], v[228:231], v[240:243], v[10:13]
	v_mfma_f32_16x16x32_bf16 v[14:17], v[228:231], v[252:255], v[14:17]
	s_waitcnt lgkmcnt(0)
	s_barrier
	global_load_dwordx4 v[180:183], v[72:73], off offset:768
	global_load_dwordx4 v[188:191], v[74:75], off offset:768
	global_load_dwordx4 v[192:195], v[76:77], off offset:768
	global_load_dwordx4 v[196:199], v[78:79], off offset:768
	global_load_dwordx4 v[200:203], v[70:71], off offset:768
	global_load_dwordx4 v[204:207], v[68:69], off offset:768
	global_load_dwordx4 v[208:211], v[66:67], off offset:768
	global_load_dwordx4 v[212:215], v[80:81], off offset:768
	ds_read_b128 v[232:235], v245 offset:36864
	ds_read_b128 v[216:219], v244
	ds_read_b128 v[236:239], v245 offset:39168
	ds_read_b128 v[240:243], v245 offset:41472
	ds_read_b128 v[252:255], v245 offset:43776
	ds_read_b128 v[220:223], v244 offset:2304
	ds_read_b128 v[224:227], v244 offset:4608
	ds_read_b128 v[228:231], v244 offset:6912
	s_waitcnt lgkmcnt(6)
	v_mfma_f32_16x16x32_bf16 v[50:53], v[216:219], v[232:235], v[50:53]
	s_waitcnt lgkmcnt(5)
	v_mfma_f32_16x16x32_bf16 v[54:57], v[216:219], v[236:239], v[54:57]
	s_waitcnt lgkmcnt(4)
	v_mfma_f32_16x16x32_bf16 v[34:37], v[216:219], v[240:243], v[34:37]
	s_waitcnt lgkmcnt(3)
	v_mfma_f32_16x16x32_bf16 v[38:41], v[216:219], v[252:255], v[38:41]
	ds_read_b128 v[216:219], v244 offset:64
	s_waitcnt lgkmcnt(3)
	v_mfma_f32_16x16x32_bf16 v[58:61], v[220:223], v[232:235], v[58:61]
	v_mfma_f32_16x16x32_bf16 v[62:65], v[220:223], v[236:239], v[62:65]
	v_mfma_f32_16x16x32_bf16 v[42:45], v[220:223], v[240:243], v[42:45]
	v_mfma_f32_16x16x32_bf16 v[46:49], v[220:223], v[252:255], v[46:49]
	ds_read_b128 v[220:223], v244 offset:2368
	s_waitcnt vmcnt(15)
	ds_write_b128 v164, v[122:125] offset:18432
	s_waitcnt vmcnt(14)
	ds_write_b128 v164, v[126:129] offset:23040
	s_waitcnt lgkmcnt(5)
	v_mfma_f32_16x16x32_bf16 v[18:21], v[224:227], v[232:235], v[18:21]
	v_mfma_f32_16x16x32_bf16 v[22:25], v[224:227], v[236:239], v[22:25]
	v_mfma_f32_16x16x32_bf16 v[2:5], v[224:227], v[240:243], v[2:5]
	v_mfma_f32_16x16x32_bf16 v[6:9], v[224:227], v[252:255], v[6:9]
	ds_read_b128 v[224:227], v244 offset:4672
	s_waitcnt vmcnt(13)
	ds_write_b128 v164, v[136:139] offset:27648
	s_waitcnt vmcnt(12)
	ds_write_b128 v164, v[140:143] offset:32256
	s_waitcnt lgkmcnt(7)
	v_mfma_f32_16x16x32_bf16 v[26:29], v[228:231], v[232:235], v[26:29]
	ds_read_b128 v[232:235], v245 offset:36928
	v_mfma_f32_16x16x32_bf16 v[30:33], v[228:231], v[236:239], v[30:33]
	ds_read_b128 v[236:239], v245 offset:39232
	v_mfma_f32_16x16x32_bf16 v[10:13], v[228:231], v[240:243], v[10:13]
	ds_read_b128 v[240:243], v245 offset:41536
	v_mfma_f32_16x16x32_bf16 v[14:17], v[228:231], v[252:255], v[14:17]
	ds_read_b128 v[252:255], v245 offset:43840
	ds_read_b128 v[228:231], v244 offset:6976
	s_waitcnt lgkmcnt(4)
	v_mfma_f32_16x16x32_bf16 v[50:53], v[216:219], v[232:235], v[50:53]
	s_waitcnt lgkmcnt(3)
	v_mfma_f32_16x16x32_bf16 v[54:57], v[216:219], v[236:239], v[54:57]
	s_waitcnt lgkmcnt(2)
	v_mfma_f32_16x16x32_bf16 v[34:37], v[216:219], v[240:243], v[34:37]
	s_waitcnt lgkmcnt(1)
	v_mfma_f32_16x16x32_bf16 v[38:41], v[216:219], v[252:255], v[38:41]
	s_waitcnt vmcnt(11)
	ds_write_b128 v164, v[144:147] offset:55296
	s_waitcnt vmcnt(10)
	ds_write_b128 v164, v[148:151] offset:59904
	v_mfma_f32_16x16x32_bf16 v[58:61], v[220:223], v[232:235], v[58:61]
	v_mfma_f32_16x16x32_bf16 v[62:65], v[220:223], v[236:239], v[62:65]
	v_mfma_f32_16x16x32_bf16 v[42:45], v[220:223], v[240:243], v[42:45]
	v_mfma_f32_16x16x32_bf16 v[46:49], v[220:223], v[252:255], v[46:49]
	s_waitcnt vmcnt(9)
	ds_write_b128 v164, v[172:175] offset:64512
	s_waitcnt vmcnt(8)
	ds_write_b128 v165, v[176:179] offset:32256
	v_mfma_f32_16x16x32_bf16 v[18:21], v[224:227], v[232:235], v[18:21]
	v_mfma_f32_16x16x32_bf16 v[22:25], v[224:227], v[236:239], v[22:25]
	v_mfma_f32_16x16x32_bf16 v[2:5], v[224:227], v[240:243], v[2:5]
	v_mfma_f32_16x16x32_bf16 v[6:9], v[224:227], v[252:255], v[6:9]
	s_waitcnt lgkmcnt(4)
	v_mfma_f32_16x16x32_bf16 v[26:29], v[228:231], v[232:235], v[26:29]
	v_mfma_f32_16x16x32_bf16 v[30:33], v[228:231], v[236:239], v[30:33]
	v_mfma_f32_16x16x32_bf16 v[10:13], v[228:231], v[240:243], v[10:13]
	v_mfma_f32_16x16x32_bf16 v[14:17], v[228:231], v[252:255], v[14:17]
	s_waitcnt lgkmcnt(0)
	s_barrier
	global_load_dwordx4 v[122:125], v[72:73], off offset:896
	global_load_dwordx4 v[126:129], v[74:75], off offset:896
	global_load_dwordx4 v[136:139], v[76:77], off offset:896
	global_load_dwordx4 v[140:143], v[78:79], off offset:896
	global_load_dwordx4 v[144:147], v[70:71], off offset:896
	global_load_dwordx4 v[148:151], v[68:69], off offset:896
	global_load_dwordx4 v[172:175], v[66:67], off offset:896
	global_load_dwordx4 v[176:179], v[80:81], off offset:896
	ds_read_b128 v[232:235], v245 offset:55296
	ds_read_b128 v[216:219], v244 offset:18432
	ds_read_b128 v[236:239], v245 offset:57600
	ds_read_b128 v[240:243], v245 offset:59904
	ds_read_b128 v[252:255], v245 offset:62208
	ds_read_b128 v[220:223], v244 offset:20736
	ds_read_b128 v[224:227], v244 offset:23040
	ds_read_b128 v[228:231], v244 offset:25344
	s_waitcnt lgkmcnt(6)
	v_mfma_f32_16x16x32_bf16 v[50:53], v[216:219], v[232:235], v[50:53]
	s_waitcnt lgkmcnt(5)
	v_mfma_f32_16x16x32_bf16 v[54:57], v[216:219], v[236:239], v[54:57]
	s_waitcnt lgkmcnt(4)
	v_mfma_f32_16x16x32_bf16 v[34:37], v[216:219], v[240:243], v[34:37]
	s_waitcnt lgkmcnt(3)
	v_mfma_f32_16x16x32_bf16 v[38:41], v[216:219], v[252:255], v[38:41]
	ds_read_b128 v[216:219], v244 offset:18496
	s_waitcnt lgkmcnt(3)
	v_mfma_f32_16x16x32_bf16 v[58:61], v[220:223], v[232:235], v[58:61]
	v_mfma_f32_16x16x32_bf16 v[62:65], v[220:223], v[236:239], v[62:65]
	v_mfma_f32_16x16x32_bf16 v[42:45], v[220:223], v[240:243], v[42:45]
	v_mfma_f32_16x16x32_bf16 v[46:49], v[220:223], v[252:255], v[46:49]
	ds_read_b128 v[220:223], v244 offset:20800
	s_waitcnt vmcnt(15)
	ds_write_b128 v164, v[180:183]
	s_waitcnt vmcnt(14)
	ds_write_b128 v164, v[188:191] offset:4608
	s_waitcnt lgkmcnt(5)
	v_mfma_f32_16x16x32_bf16 v[18:21], v[224:227], v[232:235], v[18:21]
	v_mfma_f32_16x16x32_bf16 v[22:25], v[224:227], v[236:239], v[22:25]
	v_mfma_f32_16x16x32_bf16 v[2:5], v[224:227], v[240:243], v[2:5]
	v_mfma_f32_16x16x32_bf16 v[6:9], v[224:227], v[252:255], v[6:9]
	ds_read_b128 v[224:227], v244 offset:23104
	s_waitcnt vmcnt(13)
	ds_write_b128 v164, v[192:195] offset:9216
	s_waitcnt vmcnt(12)
	ds_write_b128 v164, v[196:199] offset:13824
	s_waitcnt lgkmcnt(7)
	v_mfma_f32_16x16x32_bf16 v[26:29], v[228:231], v[232:235], v[26:29]
	ds_read_b128 v[232:235], v245 offset:55360
	v_mfma_f32_16x16x32_bf16 v[30:33], v[228:231], v[236:239], v[30:33]
	ds_read_b128 v[236:239], v245 offset:57664
	v_mfma_f32_16x16x32_bf16 v[10:13], v[228:231], v[240:243], v[10:13]
	ds_read_b128 v[240:243], v245 offset:59968
	v_mfma_f32_16x16x32_bf16 v[14:17], v[228:231], v[252:255], v[14:17]
	ds_read_b128 v[252:255], v245 offset:62272
	ds_read_b128 v[228:231], v244 offset:25408
	s_waitcnt lgkmcnt(4)
	v_mfma_f32_16x16x32_bf16 v[50:53], v[216:219], v[232:235], v[50:53]
	s_waitcnt lgkmcnt(3)
	v_mfma_f32_16x16x32_bf16 v[54:57], v[216:219], v[236:239], v[54:57]
	s_waitcnt lgkmcnt(2)
	v_mfma_f32_16x16x32_bf16 v[34:37], v[216:219], v[240:243], v[34:37]
	s_waitcnt lgkmcnt(1)
	v_mfma_f32_16x16x32_bf16 v[38:41], v[216:219], v[252:255], v[38:41]
	s_waitcnt vmcnt(11)
	ds_write_b128 v164, v[200:203] offset:36864
	s_waitcnt vmcnt(10)
	ds_write_b128 v164, v[204:207] offset:41472
	v_mfma_f32_16x16x32_bf16 v[58:61], v[220:223], v[232:235], v[58:61]
	v_mfma_f32_16x16x32_bf16 v[62:65], v[220:223], v[236:239], v[62:65]
	v_mfma_f32_16x16x32_bf16 v[42:45], v[220:223], v[240:243], v[42:45]
	v_mfma_f32_16x16x32_bf16 v[46:49], v[220:223], v[252:255], v[46:49]
	s_waitcnt vmcnt(9)
	ds_write_b128 v164, v[208:211] offset:46080
	s_waitcnt vmcnt(8)
	ds_write_b128 v164, v[212:215] offset:50688
	v_mfma_f32_16x16x32_bf16 v[18:21], v[224:227], v[232:235], v[18:21]
	v_mfma_f32_16x16x32_bf16 v[22:25], v[224:227], v[236:239], v[22:25]
	v_mfma_f32_16x16x32_bf16 v[2:5], v[224:227], v[240:243], v[2:5]
	v_mfma_f32_16x16x32_bf16 v[6:9], v[224:227], v[252:255], v[6:9]
	s_waitcnt lgkmcnt(4)
	v_mfma_f32_16x16x32_bf16 v[26:29], v[228:231], v[232:235], v[26:29]
	v_mfma_f32_16x16x32_bf16 v[30:33], v[228:231], v[236:239], v[30:33]
	v_mfma_f32_16x16x32_bf16 v[10:13], v[228:231], v[240:243], v[10:13]
	v_mfma_f32_16x16x32_bf16 v[14:17], v[228:231], v[252:255], v[14:17]
	s_waitcnt lgkmcnt(0)
	s_barrier
	global_load_dwordx4 v[180:183], v[72:73], off offset:1024
	global_load_dwordx4 v[188:191], v[74:75], off offset:1024
	global_load_dwordx4 v[192:195], v[76:77], off offset:1024
	global_load_dwordx4 v[196:199], v[78:79], off offset:1024
	global_load_dwordx4 v[200:203], v[70:71], off offset:1024
	global_load_dwordx4 v[204:207], v[68:69], off offset:1024
	global_load_dwordx4 v[208:211], v[66:67], off offset:1024
	global_load_dwordx4 v[212:215], v[80:81], off offset:1024
	ds_read_b128 v[232:235], v245 offset:36864
	ds_read_b128 v[216:219], v244
	ds_read_b128 v[236:239], v245 offset:39168
	ds_read_b128 v[240:243], v245 offset:41472
	ds_read_b128 v[252:255], v245 offset:43776
	ds_read_b128 v[220:223], v244 offset:2304
	ds_read_b128 v[224:227], v244 offset:4608
	ds_read_b128 v[228:231], v244 offset:6912
	s_waitcnt lgkmcnt(6)
	v_mfma_f32_16x16x32_bf16 v[50:53], v[216:219], v[232:235], v[50:53]
	s_waitcnt lgkmcnt(5)
	v_mfma_f32_16x16x32_bf16 v[54:57], v[216:219], v[236:239], v[54:57]
	s_waitcnt lgkmcnt(4)
	v_mfma_f32_16x16x32_bf16 v[34:37], v[216:219], v[240:243], v[34:37]
	s_waitcnt lgkmcnt(3)
	v_mfma_f32_16x16x32_bf16 v[38:41], v[216:219], v[252:255], v[38:41]
	ds_read_b128 v[216:219], v244 offset:64
	s_waitcnt lgkmcnt(3)
	v_mfma_f32_16x16x32_bf16 v[58:61], v[220:223], v[232:235], v[58:61]
	v_mfma_f32_16x16x32_bf16 v[62:65], v[220:223], v[236:239], v[62:65]
	v_mfma_f32_16x16x32_bf16 v[42:45], v[220:223], v[240:243], v[42:45]
	v_mfma_f32_16x16x32_bf16 v[46:49], v[220:223], v[252:255], v[46:49]
	ds_read_b128 v[220:223], v244 offset:2368
	s_waitcnt vmcnt(15)
	ds_write_b128 v164, v[122:125] offset:18432
	s_waitcnt vmcnt(14)
	ds_write_b128 v164, v[126:129] offset:23040
	s_waitcnt lgkmcnt(5)
	v_mfma_f32_16x16x32_bf16 v[18:21], v[224:227], v[232:235], v[18:21]
	v_mfma_f32_16x16x32_bf16 v[22:25], v[224:227], v[236:239], v[22:25]
	v_mfma_f32_16x16x32_bf16 v[2:5], v[224:227], v[240:243], v[2:5]
	v_mfma_f32_16x16x32_bf16 v[6:9], v[224:227], v[252:255], v[6:9]
	ds_read_b128 v[224:227], v244 offset:4672
	s_waitcnt vmcnt(13)
	ds_write_b128 v164, v[136:139] offset:27648
	s_waitcnt vmcnt(12)
	ds_write_b128 v164, v[140:143] offset:32256
	s_waitcnt lgkmcnt(7)
	v_mfma_f32_16x16x32_bf16 v[26:29], v[228:231], v[232:235], v[26:29]
	ds_read_b128 v[232:235], v245 offset:36928
	v_mfma_f32_16x16x32_bf16 v[30:33], v[228:231], v[236:239], v[30:33]
	ds_read_b128 v[236:239], v245 offset:39232
	v_mfma_f32_16x16x32_bf16 v[10:13], v[228:231], v[240:243], v[10:13]
	ds_read_b128 v[240:243], v245 offset:41536
	v_mfma_f32_16x16x32_bf16 v[14:17], v[228:231], v[252:255], v[14:17]
	ds_read_b128 v[252:255], v245 offset:43840
	ds_read_b128 v[228:231], v244 offset:6976
	s_waitcnt lgkmcnt(4)
	v_mfma_f32_16x16x32_bf16 v[50:53], v[216:219], v[232:235], v[50:53]
	s_waitcnt lgkmcnt(3)
	v_mfma_f32_16x16x32_bf16 v[54:57], v[216:219], v[236:239], v[54:57]
	s_waitcnt lgkmcnt(2)
	v_mfma_f32_16x16x32_bf16 v[34:37], v[216:219], v[240:243], v[34:37]
	s_waitcnt lgkmcnt(1)
	v_mfma_f32_16x16x32_bf16 v[38:41], v[216:219], v[252:255], v[38:41]
	s_waitcnt vmcnt(11)
	ds_write_b128 v164, v[144:147] offset:55296
	s_waitcnt vmcnt(10)
	ds_write_b128 v164, v[148:151] offset:59904
	v_mfma_f32_16x16x32_bf16 v[58:61], v[220:223], v[232:235], v[58:61]
	v_mfma_f32_16x16x32_bf16 v[62:65], v[220:223], v[236:239], v[62:65]
	v_mfma_f32_16x16x32_bf16 v[42:45], v[220:223], v[240:243], v[42:45]
	v_mfma_f32_16x16x32_bf16 v[46:49], v[220:223], v[252:255], v[46:49]
	s_waitcnt vmcnt(9)
	ds_write_b128 v164, v[172:175] offset:64512
	s_waitcnt vmcnt(8)
	ds_write_b128 v165, v[176:179] offset:32256
	v_mfma_f32_16x16x32_bf16 v[18:21], v[224:227], v[232:235], v[18:21]
	v_mfma_f32_16x16x32_bf16 v[22:25], v[224:227], v[236:239], v[22:25]
	v_mfma_f32_16x16x32_bf16 v[2:5], v[224:227], v[240:243], v[2:5]
	v_mfma_f32_16x16x32_bf16 v[6:9], v[224:227], v[252:255], v[6:9]
	s_waitcnt lgkmcnt(4)
	v_mfma_f32_16x16x32_bf16 v[26:29], v[228:231], v[232:235], v[26:29]
	v_mfma_f32_16x16x32_bf16 v[30:33], v[228:231], v[236:239], v[30:33]
	v_mfma_f32_16x16x32_bf16 v[10:13], v[228:231], v[240:243], v[10:13]
	v_mfma_f32_16x16x32_bf16 v[14:17], v[228:231], v[252:255], v[14:17]
	s_waitcnt lgkmcnt(0)
	s_barrier
	global_load_dwordx4 v[122:125], v[72:73], off offset:1152
	global_load_dwordx4 v[126:129], v[74:75], off offset:1152
	global_load_dwordx4 v[136:139], v[76:77], off offset:1152
	global_load_dwordx4 v[140:143], v[78:79], off offset:1152
	global_load_dwordx4 v[144:147], v[70:71], off offset:1152
	global_load_dwordx4 v[148:151], v[68:69], off offset:1152
	global_load_dwordx4 v[172:175], v[66:67], off offset:1152
	global_load_dwordx4 v[176:179], v[80:81], off offset:1152
	ds_read_b128 v[232:235], v245 offset:55296
	ds_read_b128 v[216:219], v244 offset:18432
	ds_read_b128 v[236:239], v245 offset:57600
	ds_read_b128 v[240:243], v245 offset:59904
	ds_read_b128 v[252:255], v245 offset:62208
	ds_read_b128 v[220:223], v244 offset:20736
	ds_read_b128 v[224:227], v244 offset:23040
	ds_read_b128 v[228:231], v244 offset:25344
	s_waitcnt lgkmcnt(6)
	v_mfma_f32_16x16x32_bf16 v[50:53], v[216:219], v[232:235], v[50:53]
	s_waitcnt lgkmcnt(5)
	v_mfma_f32_16x16x32_bf16 v[54:57], v[216:219], v[236:239], v[54:57]
	s_waitcnt lgkmcnt(4)
	v_mfma_f32_16x16x32_bf16 v[34:37], v[216:219], v[240:243], v[34:37]
	s_waitcnt lgkmcnt(3)
	v_mfma_f32_16x16x32_bf16 v[38:41], v[216:219], v[252:255], v[38:41]
	ds_read_b128 v[216:219], v244 offset:18496
	s_waitcnt lgkmcnt(3)
	v_mfma_f32_16x16x32_bf16 v[58:61], v[220:223], v[232:235], v[58:61]
	v_mfma_f32_16x16x32_bf16 v[62:65], v[220:223], v[236:239], v[62:65]
	v_mfma_f32_16x16x32_bf16 v[42:45], v[220:223], v[240:243], v[42:45]
	v_mfma_f32_16x16x32_bf16 v[46:49], v[220:223], v[252:255], v[46:49]
	ds_read_b128 v[220:223], v244 offset:20800
	s_waitcnt vmcnt(15)
	ds_write_b128 v164, v[180:183]
	s_waitcnt vmcnt(14)
	ds_write_b128 v164, v[188:191] offset:4608
	s_waitcnt lgkmcnt(5)
	v_mfma_f32_16x16x32_bf16 v[18:21], v[224:227], v[232:235], v[18:21]
	v_mfma_f32_16x16x32_bf16 v[22:25], v[224:227], v[236:239], v[22:25]
	v_mfma_f32_16x16x32_bf16 v[2:5], v[224:227], v[240:243], v[2:5]
	v_mfma_f32_16x16x32_bf16 v[6:9], v[224:227], v[252:255], v[6:9]
	ds_read_b128 v[224:227], v244 offset:23104
	s_waitcnt vmcnt(13)
	ds_write_b128 v164, v[192:195] offset:9216
	s_waitcnt vmcnt(12)
	ds_write_b128 v164, v[196:199] offset:13824
	s_waitcnt lgkmcnt(7)
	v_mfma_f32_16x16x32_bf16 v[26:29], v[228:231], v[232:235], v[26:29]
	ds_read_b128 v[232:235], v245 offset:55360
	v_mfma_f32_16x16x32_bf16 v[30:33], v[228:231], v[236:239], v[30:33]
	ds_read_b128 v[236:239], v245 offset:57664
	v_mfma_f32_16x16x32_bf16 v[10:13], v[228:231], v[240:243], v[10:13]
	ds_read_b128 v[240:243], v245 offset:59968
	v_mfma_f32_16x16x32_bf16 v[14:17], v[228:231], v[252:255], v[14:17]
	ds_read_b128 v[252:255], v245 offset:62272
	ds_read_b128 v[228:231], v244 offset:25408
	s_waitcnt lgkmcnt(4)
	v_mfma_f32_16x16x32_bf16 v[50:53], v[216:219], v[232:235], v[50:53]
	s_waitcnt lgkmcnt(3)
	v_mfma_f32_16x16x32_bf16 v[54:57], v[216:219], v[236:239], v[54:57]
	s_waitcnt lgkmcnt(2)
	v_mfma_f32_16x16x32_bf16 v[34:37], v[216:219], v[240:243], v[34:37]
	s_waitcnt lgkmcnt(1)
	v_mfma_f32_16x16x32_bf16 v[38:41], v[216:219], v[252:255], v[38:41]
	s_waitcnt vmcnt(11)
	ds_write_b128 v164, v[200:203] offset:36864
	s_waitcnt vmcnt(10)
	ds_write_b128 v164, v[204:207] offset:41472
	v_mfma_f32_16x16x32_bf16 v[58:61], v[220:223], v[232:235], v[58:61]
	v_mfma_f32_16x16x32_bf16 v[62:65], v[220:223], v[236:239], v[62:65]
	v_mfma_f32_16x16x32_bf16 v[42:45], v[220:223], v[240:243], v[42:45]
	v_mfma_f32_16x16x32_bf16 v[46:49], v[220:223], v[252:255], v[46:49]
	s_waitcnt vmcnt(9)
	ds_write_b128 v164, v[208:211] offset:46080
	s_waitcnt vmcnt(8)
	ds_write_b128 v164, v[212:215] offset:50688
	v_mfma_f32_16x16x32_bf16 v[18:21], v[224:227], v[232:235], v[18:21]
	v_mfma_f32_16x16x32_bf16 v[22:25], v[224:227], v[236:239], v[22:25]
	v_mfma_f32_16x16x32_bf16 v[2:5], v[224:227], v[240:243], v[2:5]
	v_mfma_f32_16x16x32_bf16 v[6:9], v[224:227], v[252:255], v[6:9]
	s_waitcnt lgkmcnt(4)
	v_mfma_f32_16x16x32_bf16 v[26:29], v[228:231], v[232:235], v[26:29]
	v_mfma_f32_16x16x32_bf16 v[30:33], v[228:231], v[236:239], v[30:33]
	v_mfma_f32_16x16x32_bf16 v[10:13], v[228:231], v[240:243], v[10:13]
	v_mfma_f32_16x16x32_bf16 v[14:17], v[228:231], v[252:255], v[14:17]
	s_waitcnt lgkmcnt(0)
	s_barrier
	global_load_dwordx4 v[180:183], v[72:73], off offset:1280
	global_load_dwordx4 v[188:191], v[74:75], off offset:1280
	global_load_dwordx4 v[192:195], v[76:77], off offset:1280
	global_load_dwordx4 v[196:199], v[78:79], off offset:1280
	global_load_dwordx4 v[200:203], v[70:71], off offset:1280
	global_load_dwordx4 v[204:207], v[68:69], off offset:1280
	global_load_dwordx4 v[208:211], v[66:67], off offset:1280
	global_load_dwordx4 v[212:215], v[80:81], off offset:1280
	ds_read_b128 v[232:235], v245 offset:36864
	ds_read_b128 v[216:219], v244
	ds_read_b128 v[236:239], v245 offset:39168
	ds_read_b128 v[240:243], v245 offset:41472
	ds_read_b128 v[252:255], v245 offset:43776
	ds_read_b128 v[220:223], v244 offset:2304
	ds_read_b128 v[224:227], v244 offset:4608
	ds_read_b128 v[228:231], v244 offset:6912
	s_waitcnt lgkmcnt(6)
	v_mfma_f32_16x16x32_bf16 v[50:53], v[216:219], v[232:235], v[50:53]
	s_waitcnt lgkmcnt(5)
	v_mfma_f32_16x16x32_bf16 v[54:57], v[216:219], v[236:239], v[54:57]
	s_waitcnt lgkmcnt(4)
	v_mfma_f32_16x16x32_bf16 v[34:37], v[216:219], v[240:243], v[34:37]
	s_waitcnt lgkmcnt(3)
	v_mfma_f32_16x16x32_bf16 v[38:41], v[216:219], v[252:255], v[38:41]
	ds_read_b128 v[216:219], v244 offset:64
	s_waitcnt lgkmcnt(3)
	v_mfma_f32_16x16x32_bf16 v[58:61], v[220:223], v[232:235], v[58:61]
	v_mfma_f32_16x16x32_bf16 v[62:65], v[220:223], v[236:239], v[62:65]
	v_mfma_f32_16x16x32_bf16 v[42:45], v[220:223], v[240:243], v[42:45]
	v_mfma_f32_16x16x32_bf16 v[46:49], v[220:223], v[252:255], v[46:49]
	ds_read_b128 v[220:223], v244 offset:2368
	s_waitcnt vmcnt(15)
	ds_write_b128 v164, v[122:125] offset:18432
	s_waitcnt vmcnt(14)
	ds_write_b128 v164, v[126:129] offset:23040
	s_waitcnt lgkmcnt(5)
	v_mfma_f32_16x16x32_bf16 v[18:21], v[224:227], v[232:235], v[18:21]
	v_mfma_f32_16x16x32_bf16 v[22:25], v[224:227], v[236:239], v[22:25]
	v_mfma_f32_16x16x32_bf16 v[2:5], v[224:227], v[240:243], v[2:5]
	v_mfma_f32_16x16x32_bf16 v[6:9], v[224:227], v[252:255], v[6:9]
	ds_read_b128 v[224:227], v244 offset:4672
	s_waitcnt vmcnt(13)
	ds_write_b128 v164, v[136:139] offset:27648
	s_waitcnt vmcnt(12)
	ds_write_b128 v164, v[140:143] offset:32256
	s_waitcnt lgkmcnt(7)
	v_mfma_f32_16x16x32_bf16 v[26:29], v[228:231], v[232:235], v[26:29]
	ds_read_b128 v[232:235], v245 offset:36928
	v_mfma_f32_16x16x32_bf16 v[30:33], v[228:231], v[236:239], v[30:33]
	ds_read_b128 v[236:239], v245 offset:39232
	v_mfma_f32_16x16x32_bf16 v[10:13], v[228:231], v[240:243], v[10:13]
	ds_read_b128 v[240:243], v245 offset:41536
	v_mfma_f32_16x16x32_bf16 v[14:17], v[228:231], v[252:255], v[14:17]
	ds_read_b128 v[252:255], v245 offset:43840
	ds_read_b128 v[228:231], v244 offset:6976
	s_waitcnt lgkmcnt(4)
	v_mfma_f32_16x16x32_bf16 v[50:53], v[216:219], v[232:235], v[50:53]
	s_waitcnt lgkmcnt(3)
	v_mfma_f32_16x16x32_bf16 v[54:57], v[216:219], v[236:239], v[54:57]
	s_waitcnt lgkmcnt(2)
	v_mfma_f32_16x16x32_bf16 v[34:37], v[216:219], v[240:243], v[34:37]
	s_waitcnt lgkmcnt(1)
	v_mfma_f32_16x16x32_bf16 v[38:41], v[216:219], v[252:255], v[38:41]
	s_waitcnt vmcnt(11)
	ds_write_b128 v164, v[144:147] offset:55296
	s_waitcnt vmcnt(10)
	ds_write_b128 v164, v[148:151] offset:59904
	v_mfma_f32_16x16x32_bf16 v[58:61], v[220:223], v[232:235], v[58:61]
	v_mfma_f32_16x16x32_bf16 v[62:65], v[220:223], v[236:239], v[62:65]
	v_mfma_f32_16x16x32_bf16 v[42:45], v[220:223], v[240:243], v[42:45]
	v_mfma_f32_16x16x32_bf16 v[46:49], v[220:223], v[252:255], v[46:49]
	s_waitcnt vmcnt(9)
	ds_write_b128 v164, v[172:175] offset:64512
	s_waitcnt vmcnt(8)
	ds_write_b128 v165, v[176:179] offset:32256
	v_mfma_f32_16x16x32_bf16 v[18:21], v[224:227], v[232:235], v[18:21]
	v_mfma_f32_16x16x32_bf16 v[22:25], v[224:227], v[236:239], v[22:25]
	v_mfma_f32_16x16x32_bf16 v[2:5], v[224:227], v[240:243], v[2:5]
	v_mfma_f32_16x16x32_bf16 v[6:9], v[224:227], v[252:255], v[6:9]
	s_waitcnt lgkmcnt(4)
	v_mfma_f32_16x16x32_bf16 v[26:29], v[228:231], v[232:235], v[26:29]
	v_mfma_f32_16x16x32_bf16 v[30:33], v[228:231], v[236:239], v[30:33]
	v_mfma_f32_16x16x32_bf16 v[10:13], v[228:231], v[240:243], v[10:13]
	v_mfma_f32_16x16x32_bf16 v[14:17], v[228:231], v[252:255], v[14:17]
	s_waitcnt lgkmcnt(0)
	s_barrier
	global_load_dwordx4 v[122:125], v[72:73], off offset:1408
	global_load_dwordx4 v[126:129], v[74:75], off offset:1408
	global_load_dwordx4 v[136:139], v[76:77], off offset:1408
	global_load_dwordx4 v[140:143], v[78:79], off offset:1408
	global_load_dwordx4 v[144:147], v[70:71], off offset:1408
	global_load_dwordx4 v[148:151], v[68:69], off offset:1408
	global_load_dwordx4 v[172:175], v[66:67], off offset:1408
	global_load_dwordx4 v[176:179], v[80:81], off offset:1408
	ds_read_b128 v[232:235], v245 offset:55296
	ds_read_b128 v[216:219], v244 offset:18432
	ds_read_b128 v[236:239], v245 offset:57600
	ds_read_b128 v[240:243], v245 offset:59904
	ds_read_b128 v[252:255], v245 offset:62208
	ds_read_b128 v[220:223], v244 offset:20736
	ds_read_b128 v[224:227], v244 offset:23040
	ds_read_b128 v[228:231], v244 offset:25344
	s_waitcnt lgkmcnt(6)
	v_mfma_f32_16x16x32_bf16 v[50:53], v[216:219], v[232:235], v[50:53]
	s_waitcnt lgkmcnt(5)
	v_mfma_f32_16x16x32_bf16 v[54:57], v[216:219], v[236:239], v[54:57]
	s_waitcnt lgkmcnt(4)
	v_mfma_f32_16x16x32_bf16 v[34:37], v[216:219], v[240:243], v[34:37]
	s_waitcnt lgkmcnt(3)
	v_mfma_f32_16x16x32_bf16 v[38:41], v[216:219], v[252:255], v[38:41]
	ds_read_b128 v[216:219], v244 offset:18496
	s_waitcnt lgkmcnt(3)
	v_mfma_f32_16x16x32_bf16 v[58:61], v[220:223], v[232:235], v[58:61]
	v_mfma_f32_16x16x32_bf16 v[62:65], v[220:223], v[236:239], v[62:65]
	v_mfma_f32_16x16x32_bf16 v[42:45], v[220:223], v[240:243], v[42:45]
	v_mfma_f32_16x16x32_bf16 v[46:49], v[220:223], v[252:255], v[46:49]
	ds_read_b128 v[220:223], v244 offset:20800
	s_waitcnt vmcnt(15)
	ds_write_b128 v164, v[180:183]
	s_waitcnt vmcnt(14)
	ds_write_b128 v164, v[188:191] offset:4608
	s_waitcnt lgkmcnt(5)
	v_mfma_f32_16x16x32_bf16 v[18:21], v[224:227], v[232:235], v[18:21]
	v_mfma_f32_16x16x32_bf16 v[22:25], v[224:227], v[236:239], v[22:25]
	v_mfma_f32_16x16x32_bf16 v[2:5], v[224:227], v[240:243], v[2:5]
	v_mfma_f32_16x16x32_bf16 v[6:9], v[224:227], v[252:255], v[6:9]
	ds_read_b128 v[224:227], v244 offset:23104
	s_waitcnt vmcnt(13)
	ds_write_b128 v164, v[192:195] offset:9216
	s_waitcnt vmcnt(12)
	ds_write_b128 v164, v[196:199] offset:13824
	s_waitcnt lgkmcnt(7)
	v_mfma_f32_16x16x32_bf16 v[26:29], v[228:231], v[232:235], v[26:29]
	ds_read_b128 v[232:235], v245 offset:55360
	v_mfma_f32_16x16x32_bf16 v[30:33], v[228:231], v[236:239], v[30:33]
	ds_read_b128 v[236:239], v245 offset:57664
	v_mfma_f32_16x16x32_bf16 v[10:13], v[228:231], v[240:243], v[10:13]
	ds_read_b128 v[240:243], v245 offset:59968
	v_mfma_f32_16x16x32_bf16 v[14:17], v[228:231], v[252:255], v[14:17]
	ds_read_b128 v[252:255], v245 offset:62272
	ds_read_b128 v[228:231], v244 offset:25408
	s_waitcnt lgkmcnt(4)
	v_mfma_f32_16x16x32_bf16 v[50:53], v[216:219], v[232:235], v[50:53]
	s_waitcnt lgkmcnt(3)
	v_mfma_f32_16x16x32_bf16 v[54:57], v[216:219], v[236:239], v[54:57]
	s_waitcnt lgkmcnt(2)
	v_mfma_f32_16x16x32_bf16 v[34:37], v[216:219], v[240:243], v[34:37]
	s_waitcnt lgkmcnt(1)
	v_mfma_f32_16x16x32_bf16 v[38:41], v[216:219], v[252:255], v[38:41]
	s_waitcnt vmcnt(11)
	ds_write_b128 v164, v[200:203] offset:36864
	s_waitcnt vmcnt(10)
	ds_write_b128 v164, v[204:207] offset:41472
	v_mfma_f32_16x16x32_bf16 v[58:61], v[220:223], v[232:235], v[58:61]
	v_mfma_f32_16x16x32_bf16 v[62:65], v[220:223], v[236:239], v[62:65]
	v_mfma_f32_16x16x32_bf16 v[42:45], v[220:223], v[240:243], v[42:45]
	v_mfma_f32_16x16x32_bf16 v[46:49], v[220:223], v[252:255], v[46:49]
	s_waitcnt vmcnt(9)
	ds_write_b128 v164, v[208:211] offset:46080
	s_waitcnt vmcnt(8)
	ds_write_b128 v164, v[212:215] offset:50688
	v_mfma_f32_16x16x32_bf16 v[18:21], v[224:227], v[232:235], v[18:21]
	v_mfma_f32_16x16x32_bf16 v[22:25], v[224:227], v[236:239], v[22:25]
	v_mfma_f32_16x16x32_bf16 v[2:5], v[224:227], v[240:243], v[2:5]
	v_mfma_f32_16x16x32_bf16 v[6:9], v[224:227], v[252:255], v[6:9]
	s_waitcnt lgkmcnt(4)
	v_mfma_f32_16x16x32_bf16 v[26:29], v[228:231], v[232:235], v[26:29]
	v_mfma_f32_16x16x32_bf16 v[30:33], v[228:231], v[236:239], v[30:33]
	v_mfma_f32_16x16x32_bf16 v[10:13], v[228:231], v[240:243], v[10:13]
	v_mfma_f32_16x16x32_bf16 v[14:17], v[228:231], v[252:255], v[14:17]
	s_waitcnt lgkmcnt(0)
	s_barrier
	global_load_dwordx4 v[180:183], v[72:73], off offset:1536
	global_load_dwordx4 v[188:191], v[74:75], off offset:1536
	global_load_dwordx4 v[192:195], v[76:77], off offset:1536
	global_load_dwordx4 v[196:199], v[78:79], off offset:1536
	global_load_dwordx4 v[200:203], v[70:71], off offset:1536
	global_load_dwordx4 v[204:207], v[68:69], off offset:1536
	global_load_dwordx4 v[208:211], v[66:67], off offset:1536
	global_load_dwordx4 v[212:215], v[80:81], off offset:1536
	ds_read_b128 v[232:235], v245 offset:36864
	ds_read_b128 v[216:219], v244
	ds_read_b128 v[236:239], v245 offset:39168
	ds_read_b128 v[240:243], v245 offset:41472
	ds_read_b128 v[252:255], v245 offset:43776
	ds_read_b128 v[220:223], v244 offset:2304
	ds_read_b128 v[224:227], v244 offset:4608
	ds_read_b128 v[228:231], v244 offset:6912
	s_waitcnt lgkmcnt(6)
	v_mfma_f32_16x16x32_bf16 v[50:53], v[216:219], v[232:235], v[50:53]
	s_waitcnt lgkmcnt(5)
	v_mfma_f32_16x16x32_bf16 v[54:57], v[216:219], v[236:239], v[54:57]
	s_waitcnt lgkmcnt(4)
	v_mfma_f32_16x16x32_bf16 v[34:37], v[216:219], v[240:243], v[34:37]
	s_waitcnt lgkmcnt(3)
	v_mfma_f32_16x16x32_bf16 v[38:41], v[216:219], v[252:255], v[38:41]
	ds_read_b128 v[216:219], v244 offset:64
	s_waitcnt lgkmcnt(3)
	v_mfma_f32_16x16x32_bf16 v[58:61], v[220:223], v[232:235], v[58:61]
	v_mfma_f32_16x16x32_bf16 v[62:65], v[220:223], v[236:239], v[62:65]
	v_mfma_f32_16x16x32_bf16 v[42:45], v[220:223], v[240:243], v[42:45]
	v_mfma_f32_16x16x32_bf16 v[46:49], v[220:223], v[252:255], v[46:49]
	ds_read_b128 v[220:223], v244 offset:2368
	s_waitcnt vmcnt(15)
	ds_write_b128 v164, v[122:125] offset:18432
	s_waitcnt vmcnt(14)
	ds_write_b128 v164, v[126:129] offset:23040
	s_waitcnt lgkmcnt(5)
	v_mfma_f32_16x16x32_bf16 v[18:21], v[224:227], v[232:235], v[18:21]
	v_mfma_f32_16x16x32_bf16 v[22:25], v[224:227], v[236:239], v[22:25]
	v_mfma_f32_16x16x32_bf16 v[2:5], v[224:227], v[240:243], v[2:5]
	v_mfma_f32_16x16x32_bf16 v[6:9], v[224:227], v[252:255], v[6:9]
	ds_read_b128 v[224:227], v244 offset:4672
	s_waitcnt vmcnt(13)
	ds_write_b128 v164, v[136:139] offset:27648
	s_waitcnt vmcnt(12)
	ds_write_b128 v164, v[140:143] offset:32256
	s_waitcnt lgkmcnt(7)
	v_mfma_f32_16x16x32_bf16 v[26:29], v[228:231], v[232:235], v[26:29]
	ds_read_b128 v[232:235], v245 offset:36928
	v_mfma_f32_16x16x32_bf16 v[30:33], v[228:231], v[236:239], v[30:33]
	ds_read_b128 v[236:239], v245 offset:39232
	v_mfma_f32_16x16x32_bf16 v[10:13], v[228:231], v[240:243], v[10:13]
	ds_read_b128 v[240:243], v245 offset:41536
	v_mfma_f32_16x16x32_bf16 v[14:17], v[228:231], v[252:255], v[14:17]
	ds_read_b128 v[252:255], v245 offset:43840
	ds_read_b128 v[228:231], v244 offset:6976
	s_waitcnt lgkmcnt(4)
	v_mfma_f32_16x16x32_bf16 v[50:53], v[216:219], v[232:235], v[50:53]
	s_waitcnt lgkmcnt(3)
	v_mfma_f32_16x16x32_bf16 v[54:57], v[216:219], v[236:239], v[54:57]
	s_waitcnt lgkmcnt(2)
	v_mfma_f32_16x16x32_bf16 v[34:37], v[216:219], v[240:243], v[34:37]
	s_waitcnt lgkmcnt(1)
	v_mfma_f32_16x16x32_bf16 v[38:41], v[216:219], v[252:255], v[38:41]
	s_waitcnt vmcnt(11)
	ds_write_b128 v164, v[144:147] offset:55296
	s_waitcnt vmcnt(10)
	ds_write_b128 v164, v[148:151] offset:59904
	v_mfma_f32_16x16x32_bf16 v[58:61], v[220:223], v[232:235], v[58:61]
	v_mfma_f32_16x16x32_bf16 v[62:65], v[220:223], v[236:239], v[62:65]
	v_mfma_f32_16x16x32_bf16 v[42:45], v[220:223], v[240:243], v[42:45]
	v_mfma_f32_16x16x32_bf16 v[46:49], v[220:223], v[252:255], v[46:49]
	s_waitcnt vmcnt(9)
	ds_write_b128 v164, v[172:175] offset:64512
	s_waitcnt vmcnt(8)
	ds_write_b128 v165, v[176:179] offset:32256
	v_mfma_f32_16x16x32_bf16 v[18:21], v[224:227], v[232:235], v[18:21]
	v_mfma_f32_16x16x32_bf16 v[22:25], v[224:227], v[236:239], v[22:25]
	v_mfma_f32_16x16x32_bf16 v[2:5], v[224:227], v[240:243], v[2:5]
	v_mfma_f32_16x16x32_bf16 v[6:9], v[224:227], v[252:255], v[6:9]
	s_waitcnt lgkmcnt(4)
	v_mfma_f32_16x16x32_bf16 v[26:29], v[228:231], v[232:235], v[26:29]
	v_mfma_f32_16x16x32_bf16 v[30:33], v[228:231], v[236:239], v[30:33]
	v_mfma_f32_16x16x32_bf16 v[10:13], v[228:231], v[240:243], v[10:13]
	v_mfma_f32_16x16x32_bf16 v[14:17], v[228:231], v[252:255], v[14:17]
	s_waitcnt lgkmcnt(0)
	s_barrier
	global_load_dwordx4 v[122:125], v[72:73], off offset:1664
	global_load_dwordx4 v[126:129], v[74:75], off offset:1664
	global_load_dwordx4 v[136:139], v[76:77], off offset:1664
	global_load_dwordx4 v[140:143], v[78:79], off offset:1664
	global_load_dwordx4 v[144:147], v[70:71], off offset:1664
	global_load_dwordx4 v[148:151], v[68:69], off offset:1664
	global_load_dwordx4 v[172:175], v[66:67], off offset:1664
	global_load_dwordx4 v[176:179], v[80:81], off offset:1664
	ds_read_b128 v[232:235], v245 offset:55296
	ds_read_b128 v[216:219], v244 offset:18432
	ds_read_b128 v[236:239], v245 offset:57600
	ds_read_b128 v[240:243], v245 offset:59904
	ds_read_b128 v[252:255], v245 offset:62208
	ds_read_b128 v[220:223], v244 offset:20736
	ds_read_b128 v[224:227], v244 offset:23040
	ds_read_b128 v[228:231], v244 offset:25344
	s_waitcnt lgkmcnt(6)
	v_mfma_f32_16x16x32_bf16 v[50:53], v[216:219], v[232:235], v[50:53]
	s_waitcnt lgkmcnt(5)
	v_mfma_f32_16x16x32_bf16 v[54:57], v[216:219], v[236:239], v[54:57]
	s_waitcnt lgkmcnt(4)
	v_mfma_f32_16x16x32_bf16 v[34:37], v[216:219], v[240:243], v[34:37]
	s_waitcnt lgkmcnt(3)
	v_mfma_f32_16x16x32_bf16 v[38:41], v[216:219], v[252:255], v[38:41]
	ds_read_b128 v[216:219], v244 offset:18496
	s_waitcnt lgkmcnt(3)
	v_mfma_f32_16x16x32_bf16 v[58:61], v[220:223], v[232:235], v[58:61]
	v_mfma_f32_16x16x32_bf16 v[62:65], v[220:223], v[236:239], v[62:65]
	v_mfma_f32_16x16x32_bf16 v[42:45], v[220:223], v[240:243], v[42:45]
	v_mfma_f32_16x16x32_bf16 v[46:49], v[220:223], v[252:255], v[46:49]
	ds_read_b128 v[220:223], v244 offset:20800
	s_waitcnt vmcnt(15)
	ds_write_b128 v164, v[180:183]
	s_waitcnt vmcnt(14)
	ds_write_b128 v164, v[188:191] offset:4608
	s_waitcnt lgkmcnt(5)
	v_mfma_f32_16x16x32_bf16 v[18:21], v[224:227], v[232:235], v[18:21]
	v_mfma_f32_16x16x32_bf16 v[22:25], v[224:227], v[236:239], v[22:25]
	v_mfma_f32_16x16x32_bf16 v[2:5], v[224:227], v[240:243], v[2:5]
	v_mfma_f32_16x16x32_bf16 v[6:9], v[224:227], v[252:255], v[6:9]
	ds_read_b128 v[224:227], v244 offset:23104
	s_waitcnt vmcnt(13)
	ds_write_b128 v164, v[192:195] offset:9216
	s_waitcnt vmcnt(12)
	ds_write_b128 v164, v[196:199] offset:13824
	s_waitcnt lgkmcnt(7)
	v_mfma_f32_16x16x32_bf16 v[26:29], v[228:231], v[232:235], v[26:29]
	ds_read_b128 v[232:235], v245 offset:55360
	v_mfma_f32_16x16x32_bf16 v[30:33], v[228:231], v[236:239], v[30:33]
	ds_read_b128 v[236:239], v245 offset:57664
	v_mfma_f32_16x16x32_bf16 v[10:13], v[228:231], v[240:243], v[10:13]
	ds_read_b128 v[240:243], v245 offset:59968
	v_mfma_f32_16x16x32_bf16 v[14:17], v[228:231], v[252:255], v[14:17]
	ds_read_b128 v[252:255], v245 offset:62272
	ds_read_b128 v[228:231], v244 offset:25408
	s_waitcnt lgkmcnt(4)
	v_mfma_f32_16x16x32_bf16 v[50:53], v[216:219], v[232:235], v[50:53]
	s_waitcnt lgkmcnt(3)
	v_mfma_f32_16x16x32_bf16 v[54:57], v[216:219], v[236:239], v[54:57]
	s_waitcnt lgkmcnt(2)
	v_mfma_f32_16x16x32_bf16 v[34:37], v[216:219], v[240:243], v[34:37]
	s_waitcnt lgkmcnt(1)
	v_mfma_f32_16x16x32_bf16 v[38:41], v[216:219], v[252:255], v[38:41]
	s_waitcnt vmcnt(11)
	ds_write_b128 v164, v[200:203] offset:36864
	s_waitcnt vmcnt(10)
	ds_write_b128 v164, v[204:207] offset:41472
	v_mfma_f32_16x16x32_bf16 v[58:61], v[220:223], v[232:235], v[58:61]
	v_mfma_f32_16x16x32_bf16 v[62:65], v[220:223], v[236:239], v[62:65]
	v_mfma_f32_16x16x32_bf16 v[42:45], v[220:223], v[240:243], v[42:45]
	v_mfma_f32_16x16x32_bf16 v[46:49], v[220:223], v[252:255], v[46:49]
	s_waitcnt vmcnt(9)
	ds_write_b128 v164, v[208:211] offset:46080
	s_waitcnt vmcnt(8)
	ds_write_b128 v164, v[212:215] offset:50688
	v_mfma_f32_16x16x32_bf16 v[18:21], v[224:227], v[232:235], v[18:21]
	v_mfma_f32_16x16x32_bf16 v[22:25], v[224:227], v[236:239], v[22:25]
	v_mfma_f32_16x16x32_bf16 v[2:5], v[224:227], v[240:243], v[2:5]
	v_mfma_f32_16x16x32_bf16 v[6:9], v[224:227], v[252:255], v[6:9]
	s_waitcnt lgkmcnt(4)
	v_mfma_f32_16x16x32_bf16 v[26:29], v[228:231], v[232:235], v[26:29]
	v_mfma_f32_16x16x32_bf16 v[30:33], v[228:231], v[236:239], v[30:33]
	v_mfma_f32_16x16x32_bf16 v[10:13], v[228:231], v[240:243], v[10:13]
	v_mfma_f32_16x16x32_bf16 v[14:17], v[228:231], v[252:255], v[14:17]
	s_waitcnt lgkmcnt(0)
	s_barrier
	global_load_dwordx4 v[180:183], v[72:73], off offset:1792
	global_load_dwordx4 v[188:191], v[74:75], off offset:1792
	global_load_dwordx4 v[192:195], v[76:77], off offset:1792
	global_load_dwordx4 v[196:199], v[78:79], off offset:1792
	global_load_dwordx4 v[200:203], v[70:71], off offset:1792
	global_load_dwordx4 v[204:207], v[68:69], off offset:1792
	global_load_dwordx4 v[208:211], v[66:67], off offset:1792
	global_load_dwordx4 v[212:215], v[80:81], off offset:1792
	ds_read_b128 v[232:235], v245 offset:36864
	ds_read_b128 v[216:219], v244
	ds_read_b128 v[236:239], v245 offset:39168
	ds_read_b128 v[240:243], v245 offset:41472
	ds_read_b128 v[252:255], v245 offset:43776
	ds_read_b128 v[220:223], v244 offset:2304
	ds_read_b128 v[224:227], v244 offset:4608
	ds_read_b128 v[228:231], v244 offset:6912
	s_waitcnt lgkmcnt(6)
	v_mfma_f32_16x16x32_bf16 v[50:53], v[216:219], v[232:235], v[50:53]
	s_waitcnt lgkmcnt(5)
	v_mfma_f32_16x16x32_bf16 v[54:57], v[216:219], v[236:239], v[54:57]
	s_waitcnt lgkmcnt(4)
	v_mfma_f32_16x16x32_bf16 v[34:37], v[216:219], v[240:243], v[34:37]
	s_waitcnt lgkmcnt(3)
	v_mfma_f32_16x16x32_bf16 v[38:41], v[216:219], v[252:255], v[38:41]
	ds_read_b128 v[216:219], v244 offset:64
	s_waitcnt lgkmcnt(3)
	v_mfma_f32_16x16x32_bf16 v[58:61], v[220:223], v[232:235], v[58:61]
	v_mfma_f32_16x16x32_bf16 v[62:65], v[220:223], v[236:239], v[62:65]
	v_mfma_f32_16x16x32_bf16 v[42:45], v[220:223], v[240:243], v[42:45]
	v_mfma_f32_16x16x32_bf16 v[46:49], v[220:223], v[252:255], v[46:49]
	ds_read_b128 v[220:223], v244 offset:2368
	s_waitcnt vmcnt(15)
	ds_write_b128 v164, v[122:125] offset:18432
	s_waitcnt vmcnt(14)
	ds_write_b128 v164, v[126:129] offset:23040
	s_waitcnt lgkmcnt(5)
	v_mfma_f32_16x16x32_bf16 v[18:21], v[224:227], v[232:235], v[18:21]
	v_mfma_f32_16x16x32_bf16 v[22:25], v[224:227], v[236:239], v[22:25]
	v_mfma_f32_16x16x32_bf16 v[2:5], v[224:227], v[240:243], v[2:5]
	v_mfma_f32_16x16x32_bf16 v[6:9], v[224:227], v[252:255], v[6:9]
	ds_read_b128 v[224:227], v244 offset:4672
	s_waitcnt vmcnt(13)
	ds_write_b128 v164, v[136:139] offset:27648
	s_waitcnt vmcnt(12)
	ds_write_b128 v164, v[140:143] offset:32256
	s_waitcnt lgkmcnt(7)
	v_mfma_f32_16x16x32_bf16 v[26:29], v[228:231], v[232:235], v[26:29]
	ds_read_b128 v[232:235], v245 offset:36928
	v_mfma_f32_16x16x32_bf16 v[30:33], v[228:231], v[236:239], v[30:33]
	ds_read_b128 v[236:239], v245 offset:39232
	v_mfma_f32_16x16x32_bf16 v[10:13], v[228:231], v[240:243], v[10:13]
	ds_read_b128 v[240:243], v245 offset:41536
	v_mfma_f32_16x16x32_bf16 v[14:17], v[228:231], v[252:255], v[14:17]
	ds_read_b128 v[252:255], v245 offset:43840
	ds_read_b128 v[228:231], v244 offset:6976
	s_waitcnt lgkmcnt(4)
	v_mfma_f32_16x16x32_bf16 v[50:53], v[216:219], v[232:235], v[50:53]
	s_waitcnt lgkmcnt(3)
	v_mfma_f32_16x16x32_bf16 v[54:57], v[216:219], v[236:239], v[54:57]
	s_waitcnt lgkmcnt(2)
	v_mfma_f32_16x16x32_bf16 v[34:37], v[216:219], v[240:243], v[34:37]
	s_waitcnt lgkmcnt(1)
	v_mfma_f32_16x16x32_bf16 v[38:41], v[216:219], v[252:255], v[38:41]
	s_waitcnt vmcnt(11)
	ds_write_b128 v164, v[144:147] offset:55296
	s_waitcnt vmcnt(10)
	ds_write_b128 v164, v[148:151] offset:59904
	v_mfma_f32_16x16x32_bf16 v[58:61], v[220:223], v[232:235], v[58:61]
	v_mfma_f32_16x16x32_bf16 v[62:65], v[220:223], v[236:239], v[62:65]
	v_mfma_f32_16x16x32_bf16 v[42:45], v[220:223], v[240:243], v[42:45]
	v_mfma_f32_16x16x32_bf16 v[46:49], v[220:223], v[252:255], v[46:49]
	s_waitcnt vmcnt(9)
	ds_write_b128 v164, v[172:175] offset:64512
	s_waitcnt vmcnt(8)
	ds_write_b128 v165, v[176:179] offset:32256
	v_mfma_f32_16x16x32_bf16 v[18:21], v[224:227], v[232:235], v[18:21]
	v_mfma_f32_16x16x32_bf16 v[22:25], v[224:227], v[236:239], v[22:25]
	v_mfma_f32_16x16x32_bf16 v[2:5], v[224:227], v[240:243], v[2:5]
	v_mfma_f32_16x16x32_bf16 v[6:9], v[224:227], v[252:255], v[6:9]
	s_waitcnt lgkmcnt(4)
	v_mfma_f32_16x16x32_bf16 v[26:29], v[228:231], v[232:235], v[26:29]
	v_mfma_f32_16x16x32_bf16 v[30:33], v[228:231], v[236:239], v[30:33]
	v_mfma_f32_16x16x32_bf16 v[10:13], v[228:231], v[240:243], v[10:13]
	v_mfma_f32_16x16x32_bf16 v[14:17], v[228:231], v[252:255], v[14:17]
	s_waitcnt lgkmcnt(0)
	s_barrier
	global_load_dwordx4 v[122:125], v[72:73], off offset:1920
	s_nop 0
	global_load_dwordx4 v[72:75], v[74:75], off offset:1920
	s_nop 0
	global_load_dwordx4 v[126:129], v[76:77], off offset:1920
	s_nop 0
	global_load_dwordx4 v[76:79], v[78:79], off offset:1920
	s_nop 0
	global_load_dwordx4 v[136:139], v[70:71], off offset:1920
	s_nop 0
	global_load_dwordx4 v[68:71], v[68:69], off offset:1920
	s_nop 0
	global_load_dwordx4 v[140:143], v[66:67], off offset:1920
	global_load_dwordx4 v[144:147], v[80:81], off offset:1920
	ds_read_b128 v[232:235], v245 offset:55296
	ds_read_b128 v[216:219], v244 offset:18432
	ds_read_b128 v[236:239], v245 offset:57600
	ds_read_b128 v[240:243], v245 offset:59904
	ds_read_b128 v[252:255], v245 offset:62208
	ds_read_b128 v[220:223], v244 offset:20736
	ds_read_b128 v[224:227], v244 offset:23040
	ds_read_b128 v[228:231], v244 offset:25344
	s_waitcnt lgkmcnt(6)
	v_mfma_f32_16x16x32_bf16 v[50:53], v[216:219], v[232:235], v[50:53]
	s_waitcnt lgkmcnt(5)
	v_mfma_f32_16x16x32_bf16 v[54:57], v[216:219], v[236:239], v[54:57]
	s_waitcnt lgkmcnt(4)
	v_mfma_f32_16x16x32_bf16 v[34:37], v[216:219], v[240:243], v[34:37]
	s_waitcnt lgkmcnt(3)
	v_mfma_f32_16x16x32_bf16 v[38:41], v[216:219], v[252:255], v[38:41]
	ds_read_b128 v[216:219], v244 offset:18496
	s_waitcnt lgkmcnt(3)
	v_mfma_f32_16x16x32_bf16 v[58:61], v[220:223], v[232:235], v[58:61]
	v_mfma_f32_16x16x32_bf16 v[62:65], v[220:223], v[236:239], v[62:65]
	v_mfma_f32_16x16x32_bf16 v[42:45], v[220:223], v[240:243], v[42:45]
	v_mfma_f32_16x16x32_bf16 v[46:49], v[220:223], v[252:255], v[46:49]
	ds_read_b128 v[220:223], v244 offset:20800
	s_waitcnt vmcnt(15)
	ds_write_b128 v164, v[180:183]
	s_waitcnt vmcnt(14)
	ds_write_b128 v164, v[188:191] offset:4608
	s_waitcnt lgkmcnt(5)
	v_mfma_f32_16x16x32_bf16 v[18:21], v[224:227], v[232:235], v[18:21]
	v_mfma_f32_16x16x32_bf16 v[22:25], v[224:227], v[236:239], v[22:25]
	v_mfma_f32_16x16x32_bf16 v[2:5], v[224:227], v[240:243], v[2:5]
	v_mfma_f32_16x16x32_bf16 v[6:9], v[224:227], v[252:255], v[6:9]
	ds_read_b128 v[224:227], v244 offset:23104
	s_waitcnt vmcnt(13)
	ds_write_b128 v164, v[192:195] offset:9216
	s_waitcnt vmcnt(12)
	ds_write_b128 v164, v[196:199] offset:13824
	s_waitcnt lgkmcnt(7)
	v_mfma_f32_16x16x32_bf16 v[26:29], v[228:231], v[232:235], v[26:29]
	ds_read_b128 v[232:235], v245 offset:55360
	v_mfma_f32_16x16x32_bf16 v[30:33], v[228:231], v[236:239], v[30:33]
	ds_read_b128 v[236:239], v245 offset:57664
	v_mfma_f32_16x16x32_bf16 v[10:13], v[228:231], v[240:243], v[10:13]
	ds_read_b128 v[240:243], v245 offset:59968
	v_mfma_f32_16x16x32_bf16 v[14:17], v[228:231], v[252:255], v[14:17]
	ds_read_b128 v[252:255], v245 offset:62272
	ds_read_b128 v[228:231], v244 offset:25408
	s_waitcnt lgkmcnt(4)
	v_mfma_f32_16x16x32_bf16 v[50:53], v[216:219], v[232:235], v[50:53]
	s_waitcnt lgkmcnt(3)
	v_mfma_f32_16x16x32_bf16 v[54:57], v[216:219], v[236:239], v[54:57]
	s_waitcnt lgkmcnt(2)
	v_mfma_f32_16x16x32_bf16 v[34:37], v[216:219], v[240:243], v[34:37]
	s_waitcnt lgkmcnt(1)
	v_mfma_f32_16x16x32_bf16 v[38:41], v[216:219], v[252:255], v[38:41]
	s_waitcnt vmcnt(11)
	ds_write_b128 v164, v[200:203] offset:36864
	s_waitcnt vmcnt(10)
	ds_write_b128 v164, v[204:207] offset:41472
	v_mfma_f32_16x16x32_bf16 v[58:61], v[220:223], v[232:235], v[58:61]
	v_mfma_f32_16x16x32_bf16 v[62:65], v[220:223], v[236:239], v[62:65]
	v_mfma_f32_16x16x32_bf16 v[42:45], v[220:223], v[240:243], v[42:45]
	v_mfma_f32_16x16x32_bf16 v[46:49], v[220:223], v[252:255], v[46:49]
	s_waitcnt vmcnt(9)
	ds_write_b128 v164, v[208:211] offset:46080
	s_waitcnt vmcnt(8)
	ds_write_b128 v164, v[212:215] offset:50688
	v_mfma_f32_16x16x32_bf16 v[18:21], v[224:227], v[232:235], v[18:21]
	v_mfma_f32_16x16x32_bf16 v[22:25], v[224:227], v[236:239], v[22:25]
	v_mfma_f32_16x16x32_bf16 v[2:5], v[224:227], v[240:243], v[2:5]
	v_mfma_f32_16x16x32_bf16 v[6:9], v[224:227], v[252:255], v[6:9]
	s_waitcnt lgkmcnt(4)
	v_mfma_f32_16x16x32_bf16 v[26:29], v[228:231], v[232:235], v[26:29]
	v_mfma_f32_16x16x32_bf16 v[30:33], v[228:231], v[236:239], v[30:33]
	v_mfma_f32_16x16x32_bf16 v[10:13], v[228:231], v[240:243], v[10:13]
	v_mfma_f32_16x16x32_bf16 v[14:17], v[228:231], v[252:255], v[14:17]
	s_waitcnt lgkmcnt(0)
	s_barrier
	ds_read_b128 v[232:235], v245 offset:36864
	ds_read_b128 v[216:219], v244
	ds_read_b128 v[236:239], v245 offset:39168
	ds_read_b128 v[240:243], v245 offset:41472
	ds_read_b128 v[252:255], v245 offset:43776
	ds_read_b128 v[220:223], v244 offset:2304
	ds_read_b128 v[224:227], v244 offset:4608
	ds_read_b128 v[228:231], v244 offset:6912
	s_waitcnt lgkmcnt(6)
	v_mfma_f32_16x16x32_bf16 v[50:53], v[216:219], v[232:235], v[50:53]
	s_waitcnt lgkmcnt(5)
	v_mfma_f32_16x16x32_bf16 v[54:57], v[216:219], v[236:239], v[54:57]
	s_waitcnt lgkmcnt(4)
	v_mfma_f32_16x16x32_bf16 v[34:37], v[216:219], v[240:243], v[34:37]
	s_waitcnt lgkmcnt(3)
	v_mfma_f32_16x16x32_bf16 v[38:41], v[216:219], v[252:255], v[38:41]
	ds_read_b128 v[216:219], v244 offset:64
	s_waitcnt lgkmcnt(3)
	v_mfma_f32_16x16x32_bf16 v[58:61], v[220:223], v[232:235], v[58:61]
	v_mfma_f32_16x16x32_bf16 v[62:65], v[220:223], v[236:239], v[62:65]
	v_mfma_f32_16x16x32_bf16 v[42:45], v[220:223], v[240:243], v[42:45]
	v_mfma_f32_16x16x32_bf16 v[46:49], v[220:223], v[252:255], v[46:49]
	ds_read_b128 v[220:223], v244 offset:2368
	s_waitcnt vmcnt(7)
	ds_write_b128 v164, v[122:125] offset:18432
	s_waitcnt vmcnt(6)
	ds_write_b128 v164, v[72:75] offset:23040
	s_waitcnt lgkmcnt(5)
	v_mfma_f32_16x16x32_bf16 v[18:21], v[224:227], v[232:235], v[18:21]
	v_mfma_f32_16x16x32_bf16 v[22:25], v[224:227], v[236:239], v[22:25]
	v_mfma_f32_16x16x32_bf16 v[2:5], v[224:227], v[240:243], v[2:5]
	v_mfma_f32_16x16x32_bf16 v[6:9], v[224:227], v[252:255], v[6:9]
	ds_read_b128 v[224:227], v244 offset:4672
	s_waitcnt vmcnt(5)
	ds_write_b128 v164, v[126:129] offset:27648
	s_waitcnt vmcnt(4)
	ds_write_b128 v164, v[76:79] offset:32256
	s_waitcnt lgkmcnt(7)
	v_mfma_f32_16x16x32_bf16 v[26:29], v[228:231], v[232:235], v[26:29]
	ds_read_b128 v[232:235], v245 offset:36928
	v_mfma_f32_16x16x32_bf16 v[30:33], v[228:231], v[236:239], v[30:33]
	ds_read_b128 v[236:239], v245 offset:39232
	v_mfma_f32_16x16x32_bf16 v[10:13], v[228:231], v[240:243], v[10:13]
	ds_read_b128 v[240:243], v245 offset:41536
	v_mfma_f32_16x16x32_bf16 v[14:17], v[228:231], v[252:255], v[14:17]
	ds_read_b128 v[252:255], v245 offset:43840
	ds_read_b128 v[228:231], v244 offset:6976
	s_waitcnt lgkmcnt(4)
	v_mfma_f32_16x16x32_bf16 v[50:53], v[216:219], v[232:235], v[50:53]
	s_waitcnt lgkmcnt(3)
	v_mfma_f32_16x16x32_bf16 v[54:57], v[216:219], v[236:239], v[54:57]
	s_waitcnt lgkmcnt(2)
	v_mfma_f32_16x16x32_bf16 v[34:37], v[216:219], v[240:243], v[34:37]
	s_waitcnt lgkmcnt(1)
	v_mfma_f32_16x16x32_bf16 v[38:41], v[216:219], v[252:255], v[38:41]
	s_waitcnt vmcnt(3)
	ds_write_b128 v164, v[136:139] offset:55296
	s_waitcnt vmcnt(2)
	ds_write_b128 v164, v[68:71] offset:59904
	v_mfma_f32_16x16x32_bf16 v[58:61], v[220:223], v[232:235], v[58:61]
	v_mfma_f32_16x16x32_bf16 v[62:65], v[220:223], v[236:239], v[62:65]
	v_mfma_f32_16x16x32_bf16 v[42:45], v[220:223], v[240:243], v[42:45]
	v_mfma_f32_16x16x32_bf16 v[46:49], v[220:223], v[252:255], v[46:49]
	s_waitcnt vmcnt(1)
	ds_write_b128 v164, v[140:143] offset:64512
	s_waitcnt vmcnt(0)
	ds_write_b128 v165, v[144:147] offset:32256
	v_mfma_f32_16x16x32_bf16 v[18:21], v[224:227], v[232:235], v[18:21]
	v_mfma_f32_16x16x32_bf16 v[22:25], v[224:227], v[236:239], v[22:25]
	v_mfma_f32_16x16x32_bf16 v[2:5], v[224:227], v[240:243], v[2:5]
	v_mfma_f32_16x16x32_bf16 v[6:9], v[224:227], v[252:255], v[6:9]
	s_waitcnt lgkmcnt(4)
	v_mfma_f32_16x16x32_bf16 v[26:29], v[228:231], v[232:235], v[26:29]
	v_mfma_f32_16x16x32_bf16 v[30:33], v[228:231], v[236:239], v[30:33]
	v_mfma_f32_16x16x32_bf16 v[10:13], v[228:231], v[240:243], v[10:13]
	v_mfma_f32_16x16x32_bf16 v[14:17], v[228:231], v[252:255], v[14:17]
	s_waitcnt lgkmcnt(0)
	s_barrier
	ds_read_b128 v[232:235], v245 offset:55296
	ds_read_b128 v[216:219], v244 offset:18432
	ds_read_b128 v[236:239], v245 offset:57600
	ds_read_b128 v[240:243], v245 offset:59904
	ds_read_b128 v[252:255], v245 offset:62208
	ds_read_b128 v[220:223], v244 offset:20736
	ds_read_b128 v[224:227], v244 offset:23040
	ds_read_b128 v[228:231], v244 offset:25344
	s_waitcnt lgkmcnt(6)
	v_mfma_f32_16x16x32_bf16 v[50:53], v[216:219], v[232:235], v[50:53]
	s_waitcnt lgkmcnt(5)
	v_mfma_f32_16x16x32_bf16 v[54:57], v[216:219], v[236:239], v[54:57]
	s_waitcnt lgkmcnt(4)
	v_mfma_f32_16x16x32_bf16 v[34:37], v[216:219], v[240:243], v[34:37]
	s_waitcnt lgkmcnt(3)
	v_mfma_f32_16x16x32_bf16 v[38:41], v[216:219], v[252:255], v[38:41]
	ds_read_b128 v[216:219], v244 offset:18496
	s_waitcnt lgkmcnt(3)
	v_mfma_f32_16x16x32_bf16 v[58:61], v[220:223], v[232:235], v[58:61]
	v_mfma_f32_16x16x32_bf16 v[62:65], v[220:223], v[236:239], v[62:65]
	v_mfma_f32_16x16x32_bf16 v[42:45], v[220:223], v[240:243], v[42:45]
	v_mfma_f32_16x16x32_bf16 v[46:49], v[220:223], v[252:255], v[46:49]
	ds_read_b128 v[220:223], v244 offset:20800
	s_waitcnt lgkmcnt(3)
	v_mfma_f32_16x16x32_bf16 v[18:21], v[224:227], v[232:235], v[18:21]
	v_mfma_f32_16x16x32_bf16 v[22:25], v[224:227], v[236:239], v[22:25]
	v_mfma_f32_16x16x32_bf16 v[2:5], v[224:227], v[240:243], v[2:5]
	v_mfma_f32_16x16x32_bf16 v[6:9], v[224:227], v[252:255], v[6:9]
	ds_read_b128 v[224:227], v244 offset:23104
	s_waitcnt lgkmcnt(3)
	v_mfma_f32_16x16x32_bf16 v[26:29], v[228:231], v[232:235], v[26:29]
	ds_read_b128 v[232:235], v245 offset:55360
	v_mfma_f32_16x16x32_bf16 v[30:33], v[228:231], v[236:239], v[30:33]
	ds_read_b128 v[236:239], v245 offset:57664
	v_mfma_f32_16x16x32_bf16 v[10:13], v[228:231], v[240:243], v[10:13]
	ds_read_b128 v[240:243], v245 offset:59968
	v_mfma_f32_16x16x32_bf16 v[14:17], v[228:231], v[252:255], v[14:17]
	ds_read_b128 v[252:255], v245 offset:62272
	ds_read_b128 v[228:231], v244 offset:25408
	s_waitcnt lgkmcnt(4)
	v_mfma_f32_16x16x32_bf16 v[50:53], v[216:219], v[232:235], v[50:53]
	s_waitcnt lgkmcnt(3)
	v_mfma_f32_16x16x32_bf16 v[54:57], v[216:219], v[236:239], v[54:57]
	s_waitcnt lgkmcnt(2)
	v_mfma_f32_16x16x32_bf16 v[34:37], v[216:219], v[240:243], v[34:37]
	s_waitcnt lgkmcnt(1)
	v_mfma_f32_16x16x32_bf16 v[38:41], v[216:219], v[252:255], v[38:41]
	v_mfma_f32_16x16x32_bf16 v[58:61], v[220:223], v[232:235], v[58:61]
	v_mfma_f32_16x16x32_bf16 v[62:65], v[220:223], v[236:239], v[62:65]
	v_mfma_f32_16x16x32_bf16 v[42:45], v[220:223], v[240:243], v[42:45]
	v_mfma_f32_16x16x32_bf16 v[46:49], v[220:223], v[252:255], v[46:49]
	v_mfma_f32_16x16x32_bf16 v[18:21], v[224:227], v[232:235], v[18:21]
	v_mfma_f32_16x16x32_bf16 v[22:25], v[224:227], v[236:239], v[22:25]
	v_mfma_f32_16x16x32_bf16 v[2:5], v[224:227], v[240:243], v[2:5]
	v_mfma_f32_16x16x32_bf16 v[6:9], v[224:227], v[252:255], v[6:9]
	s_waitcnt lgkmcnt(0)
	v_mfma_f32_16x16x32_bf16 v[26:29], v[228:231], v[232:235], v[26:29]
	v_mfma_f32_16x16x32_bf16 v[30:33], v[228:231], v[236:239], v[30:33]
	v_mfma_f32_16x16x32_bf16 v[10:13], v[228:231], v[240:243], v[10:13]
	v_mfma_f32_16x16x32_bf16 v[14:17], v[228:231], v[252:255], v[14:17]
	s_mov_b64 s[2:3], 0
	s_waitcnt lgkmcnt(0)
	s_barrier
	s_nop 7
	v_permlane16_swap_b32_e32 v50, v54
	v_permlane16_swap_b32_e32 v51, v55
	v_permlane16_swap_b32_e32 v52, v56
	v_permlane16_swap_b32_e32 v53, v57
	v_permlane16_swap_b32_e32 v58, v62
	v_permlane16_swap_b32_e32 v59, v63
	v_permlane16_swap_b32_e32 v60, v64
	v_permlane16_swap_b32_e32 v61, v65
	v_permlane16_swap_b32_e32 v34, v38
	v_permlane16_swap_b32_e32 v35, v39
	v_permlane16_swap_b32_e32 v36, v40
	v_permlane16_swap_b32_e32 v37, v41
	v_permlane16_swap_b32_e32 v42, v46
	v_permlane16_swap_b32_e32 v43, v47
	v_permlane16_swap_b32_e32 v44, v48
	v_permlane16_swap_b32_e32 v45, v49
	v_permlane16_swap_b32_e32 v18, v22
	v_permlane16_swap_b32_e32 v19, v23
	v_permlane16_swap_b32_e32 v20, v24
	v_permlane16_swap_b32_e32 v21, v25
	v_permlane16_swap_b32_e32 v26, v30
	v_permlane16_swap_b32_e32 v27, v31
	v_permlane16_swap_b32_e32 v28, v32
	v_permlane16_swap_b32_e32 v29, v33
	v_permlane16_swap_b32_e32 v2, v6
	v_permlane16_swap_b32_e32 v3, v7
	v_permlane16_swap_b32_e32 v4, v8
	v_permlane16_swap_b32_e32 v5, v9
	v_permlane16_swap_b32_e32 v10, v14
	v_permlane16_swap_b32_e32 v11, v15
	v_permlane16_swap_b32_e32 v12, v16
	v_permlane16_swap_b32_e32 v13, v17
	v_permlane32_swap_b32_e32 v50, v54
	v_permlane32_swap_b32_e32 v51, v55
	v_permlane32_swap_b32_e32 v52, v56
	v_permlane32_swap_b32_e32 v53, v57
	v_permlane32_swap_b32_e32 v58, v62
	v_permlane32_swap_b32_e32 v59, v63
	v_permlane32_swap_b32_e32 v60, v64
	v_permlane32_swap_b32_e32 v61, v65
	v_permlane32_swap_b32_e32 v34, v38
	v_permlane32_swap_b32_e32 v35, v39
	v_permlane32_swap_b32_e32 v36, v40
	v_permlane32_swap_b32_e32 v37, v41
	v_permlane32_swap_b32_e32 v42, v46
	v_permlane32_swap_b32_e32 v43, v47
	v_permlane32_swap_b32_e32 v44, v48
	v_permlane32_swap_b32_e32 v45, v49
	v_permlane32_swap_b32_e32 v18, v22
	v_permlane32_swap_b32_e32 v19, v23
	v_permlane32_swap_b32_e32 v20, v24
	v_permlane32_swap_b32_e32 v21, v25
	v_permlane32_swap_b32_e32 v26, v30
	v_permlane32_swap_b32_e32 v27, v31
	v_permlane32_swap_b32_e32 v28, v32
	v_permlane32_swap_b32_e32 v29, v33
	v_permlane32_swap_b32_e32 v2, v6
	v_permlane32_swap_b32_e32 v3, v7
	v_permlane32_swap_b32_e32 v4, v8
	v_permlane32_swap_b32_e32 v5, v9
	v_permlane32_swap_b32_e32 v10, v14
	v_permlane32_swap_b32_e32 v11, v15
	v_permlane32_swap_b32_e32 v12, v16
	v_permlane32_swap_b32_e32 v13, v17

.LBB0_1167:
	v_ashrrev_i32_e32 v3, 31, v2
	v_lshlrev_b64 v[2:3], 11, v[2:3]
	v_ashrrev_i32_e32 v9, 31, v8
	v_lshl_add_u64 v[70:71], v[86:87], 0, v[2:3]
	v_lshlrev_b64 v[2:3], 11, v[8:9]
	v_lshl_add_u64 v[72:73], v[86:87], 0, v[2:3]
	v_or_b32_e32 v2, s56, v154
	v_ashrrev_i32_e32 v3, 31, v2
	v_lshlrev_b64 v[2:3], 11, v[2:3]
	v_lshl_add_u64 v[74:75], v[84:85], 0, v[2:3]
	v_add_u32_e32 v2, s56, v155
	v_ashrrev_i32_e32 v3, 31, v2
	v_lshlrev_b64 v[2:3], 11, v[2:3]
	v_lshl_add_u64 v[76:77], v[84:85], 0, v[2:3]
	v_add_u32_e32 v2, s56, v156
	v_ashrrev_i32_e32 v3, 31, v2
	v_lshlrev_b64 v[2:3], 11, v[2:3]
	v_lshl_add_u64 v[78:79], v[84:85], 0, v[2:3]
	v_add_u32_e32 v2, s56, v157
	v_ashrrev_i32_e32 v7, 31, v6
	v_ashrrev_i32_e32 v5, 31, v4
	v_ashrrev_i32_e32 v3, 31, v2
	v_lshlrev_b64 v[6:7], 11, v[6:7]
	v_lshlrev_b64 v[4:5], 11, v[4:5]
	v_lshlrev_b64 v[2:3], 11, v[2:3]
	v_lshl_add_u64 v[66:67], v[86:87], 0, v[6:7]
	v_lshl_add_u64 v[68:69], v[86:87], 0, v[4:5]
	v_lshl_add_u64 v[80:81], v[84:85], 0, v[2:3]
	global_load_dwordx4 v[2:5], v[70:71], off
	global_load_dwordx4 v[6:9], v[68:69], off
	global_load_dwordx4 v[10:13], v[66:67], off
	global_load_dwordx4 v[14:17], v[72:73], off
	global_load_dwordx4 v[18:21], v[74:75], off
	global_load_dwordx4 v[22:25], v[76:77], off
	global_load_dwordx4 v[26:29], v[78:79], off
	global_load_dwordx4 v[30:33], v[80:81], off
	global_load_dwordx4 v[122:125], v[70:71], off offset:128
	global_load_dwordx4 v[126:129], v[68:69], off offset:128
	global_load_dwordx4 v[136:139], v[66:67], off offset:128
	global_load_dwordx4 v[140:143], v[72:73], off offset:128
	global_load_dwordx4 v[144:147], v[74:75], off offset:128
	global_load_dwordx4 v[148:151], v[76:77], off offset:128
	global_load_dwordx4 v[172:175], v[78:79], off offset:128
	global_load_dwordx4 v[176:179], v[80:81], off offset:128
	s_waitcnt vmcnt(15)
	ds_write_b128 v164, v[2:5]
	s_waitcnt vmcnt(14)
	ds_write_b128 v164, v[6:9] offset:4608
	s_waitcnt vmcnt(13)
	ds_write_b128 v164, v[10:13] offset:9216
	s_waitcnt vmcnt(12)
	ds_write_b128 v164, v[14:17] offset:13824
	s_waitcnt vmcnt(11)
	ds_write_b128 v164, v[18:21] offset:36864
	s_waitcnt vmcnt(10)
	ds_write_b128 v164, v[22:25] offset:41472
	s_waitcnt vmcnt(9)
	ds_write_b128 v164, v[26:29] offset:46080
	s_waitcnt vmcnt(8)
	ds_write_b128 v164, v[30:33] offset:50688
	s_waitcnt lgkmcnt(0)
	s_barrier
	global_load_dwordx4 v[180:183], v[68:69], off offset:256
	global_load_dwordx4 v[188:191], v[66:67], off offset:256
	global_load_dwordx4 v[192:195], v[70:71], off offset:256
	global_load_dwordx4 v[196:199], v[72:73], off offset:256
	global_load_dwordx4 v[200:203], v[74:75], off offset:256
	global_load_dwordx4 v[204:207], v[76:77], off offset:256
	global_load_dwordx4 v[208:211], v[78:79], off offset:256
	global_load_dwordx4 v[212:215], v[80:81], off offset:256
	v_and_b32_e32 v246, 15, v1
	v_add_u32_e32 v246, 4, v246
	v_bfe_u32 v246, v246, 3, 1
	v_bfe_u32 v249, v1, 4, 2
	v_xor_b32_e32 v246, v246, v249
	v_bfe_u32 v249, v1, 5, 1
	v_sub_u32_e32 v246, v246, v249
	v_lshlrev_b32_e32 v246, 4, v246
	v_bfe_u32 v249, v1, 4, 1
	v_mul_u32_u24_e32 v249, 0x900, v249
	v_sub_u32_e32 v246, v246, v249
	v_add_u32_e32 v244, v246, v161
	v_add_u32_e32 v245, v246, v163
	ds_read_b128 v[232:235], v245 offset:36864
	ds_read_b128 v[216:219], v244
	ds_read_b128 v[236:239], v245 offset:39168
	ds_read_b128 v[240:243], v245 offset:41472
	ds_read_b128 v[252:255], v245 offset:43776
	ds_read_b128 v[220:223], v244 offset:2304
	ds_read_b128 v[224:227], v244 offset:4608
	ds_read_b128 v[228:231], v244 offset:6912
	s_waitcnt lgkmcnt(6)
	v_mfma_f32_16x16x32_bf16 v[50:53], v[216:219], v[232:235], 0
	s_waitcnt lgkmcnt(5)
	v_mfma_f32_16x16x32_bf16 v[54:57], v[216:219], v[236:239], 0
	s_waitcnt lgkmcnt(4)
	v_mfma_f32_16x16x32_bf16 v[34:37], v[216:219], v[240:243], 0
	s_waitcnt lgkmcnt(3)
	v_mfma_f32_16x16x32_bf16 v[38:41], v[216:219], v[252:255], 0
	ds_read_b128 v[216:219], v244 offset:64
	s_waitcnt lgkmcnt(3)
	v_mfma_f32_16x16x32_bf16 v[58:61], v[220:223], v[232:235], 0
	v_mfma_f32_16x16x32_bf16 v[62:65], v[220:223], v[236:239], 0
	v_mfma_f32_16x16x32_bf16 v[42:45], v[220:223], v[240:243], 0
	v_mfma_f32_16x16x32_bf16 v[46:49], v[220:223], v[252:255], 0
	ds_read_b128 v[220:223], v244 offset:2368
	s_waitcnt vmcnt(15)
	ds_write_b128 v164, v[122:125] offset:18432
	s_waitcnt vmcnt(14)
	ds_write_b128 v164, v[126:129] offset:23040
	s_waitcnt lgkmcnt(5)
	v_mfma_f32_16x16x32_bf16 v[18:21], v[224:227], v[232:235], 0
	v_mfma_f32_16x16x32_bf16 v[22:25], v[224:227], v[236:239], 0
	v_mfma_f32_16x16x32_bf16 v[2:5], v[224:227], v[240:243], 0
	v_mfma_f32_16x16x32_bf16 v[6:9], v[224:227], v[252:255], 0
	ds_read_b128 v[224:227], v244 offset:4672
	s_waitcnt vmcnt(13)
	ds_write_b128 v164, v[136:139] offset:27648
	s_waitcnt vmcnt(12)
	ds_write_b128 v164, v[140:143] offset:32256
	s_waitcnt lgkmcnt(7)
	v_mfma_f32_16x16x32_bf16 v[26:29], v[228:231], v[232:235], 0
	ds_read_b128 v[232:235], v245 offset:36928
	v_mfma_f32_16x16x32_bf16 v[30:33], v[228:231], v[236:239], 0
	ds_read_b128 v[236:239], v245 offset:39232
	v_mfma_f32_16x16x32_bf16 v[10:13], v[228:231], v[240:243], 0
	ds_read_b128 v[240:243], v245 offset:41536
	v_mfma_f32_16x16x32_bf16 v[14:17], v[228:231], v[252:255], 0
	ds_read_b128 v[252:255], v245 offset:43840
	ds_read_b128 v[228:231], v244 offset:6976
	s_waitcnt lgkmcnt(4)
	v_mfma_f32_16x16x32_bf16 v[50:53], v[216:219], v[232:235], v[50:53]
	s_waitcnt lgkmcnt(3)
	v_mfma_f32_16x16x32_bf16 v[54:57], v[216:219], v[236:239], v[54:57]
	s_waitcnt lgkmcnt(2)
	v_mfma_f32_16x16x32_bf16 v[34:37], v[216:219], v[240:243], v[34:37]
	s_waitcnt lgkmcnt(1)
	v_mfma_f32_16x16x32_bf16 v[38:41], v[216:219], v[252:255], v[38:41]
	s_waitcnt vmcnt(11)
	ds_write_b128 v164, v[144:147] offset:55296
	s_waitcnt vmcnt(10)
	ds_write_b128 v164, v[148:151] offset:59904
	v_mfma_f32_16x16x32_bf16 v[58:61], v[220:223], v[232:235], v[58:61]
	v_mfma_f32_16x16x32_bf16 v[62:65], v[220:223], v[236:239], v[62:65]
	v_mfma_f32_16x16x32_bf16 v[42:45], v[220:223], v[240:243], v[42:45]
	v_mfma_f32_16x16x32_bf16 v[46:49], v[220:223], v[252:255], v[46:49]
	s_waitcnt vmcnt(9)
	ds_write_b128 v164, v[172:175] offset:64512
	s_waitcnt vmcnt(8)
	ds_write_b128 v165, v[176:179] offset:32256
	v_mfma_f32_16x16x32_bf16 v[18:21], v[224:227], v[232:235], v[18:21]
	v_mfma_f32_16x16x32_bf16 v[22:25], v[224:227], v[236:239], v[22:25]
	v_mfma_f32_16x16x32_bf16 v[2:5], v[224:227], v[240:243], v[2:5]
	v_mfma_f32_16x16x32_bf16 v[6:9], v[224:227], v[252:255], v[6:9]
	s_waitcnt lgkmcnt(4)
	v_mfma_f32_16x16x32_bf16 v[26:29], v[228:231], v[232:235], v[26:29]
	v_mfma_f32_16x16x32_bf16 v[30:33], v[228:231], v[236:239], v[30:33]
	v_mfma_f32_16x16x32_bf16 v[10:13], v[228:231], v[240:243], v[10:13]
	v_mfma_f32_16x16x32_bf16 v[14:17], v[228:231], v[252:255], v[14:17]
	s_waitcnt lgkmcnt(0)
	s_barrier
	global_load_dwordx4 v[122:125], v[70:71], off offset:384
	global_load_dwordx4 v[126:129], v[68:69], off offset:384
	global_load_dwordx4 v[136:139], v[66:67], off offset:384
	global_load_dwordx4 v[140:143], v[72:73], off offset:384
	global_load_dwordx4 v[144:147], v[74:75], off offset:384
	global_load_dwordx4 v[148:151], v[76:77], off offset:384
	global_load_dwordx4 v[172:175], v[78:79], off offset:384
	global_load_dwordx4 v[176:179], v[80:81], off offset:384
	ds_read_b128 v[232:235], v245 offset:55296
	ds_read_b128 v[216:219], v244 offset:18432
	ds_read_b128 v[236:239], v245 offset:57600
	ds_read_b128 v[240:243], v245 offset:59904
	ds_read_b128 v[252:255], v245 offset:62208
	ds_read_b128 v[220:223], v244 offset:20736
	ds_read_b128 v[224:227], v244 offset:23040
	ds_read_b128 v[228:231], v244 offset:25344
	s_waitcnt lgkmcnt(6)
	v_mfma_f32_16x16x32_bf16 v[50:53], v[216:219], v[232:235], v[50:53]
	s_waitcnt lgkmcnt(5)
	v_mfma_f32_16x16x32_bf16 v[54:57], v[216:219], v[236:239], v[54:57]
	s_waitcnt lgkmcnt(4)
	v_mfma_f32_16x16x32_bf16 v[34:37], v[216:219], v[240:243], v[34:37]
	s_waitcnt lgkmcnt(3)
	v_mfma_f32_16x16x32_bf16 v[38:41], v[216:219], v[252:255], v[38:41]
	ds_read_b128 v[216:219], v244 offset:18496
	s_waitcnt lgkmcnt(3)
	v_mfma_f32_16x16x32_bf16 v[58:61], v[220:223], v[232:235], v[58:61]
	v_mfma_f32_16x16x32_bf16 v[62:65], v[220:223], v[236:239], v[62:65]
	v_mfma_f32_16x16x32_bf16 v[42:45], v[220:223], v[240:243], v[42:45]
	v_mfma_f32_16x16x32_bf16 v[46:49], v[220:223], v[252:255], v[46:49]
	ds_read_b128 v[220:223], v244 offset:20800
	s_waitcnt vmcnt(13)
	ds_write_b128 v164, v[192:195]
	ds_write_b128 v164, v[180:183] offset:4608
	s_waitcnt lgkmcnt(5)
	v_mfma_f32_16x16x32_bf16 v[18:21], v[224:227], v[232:235], v[18:21]
	v_mfma_f32_16x16x32_bf16 v[22:25], v[224:227], v[236:239], v[22:25]
	v_mfma_f32_16x16x32_bf16 v[2:5], v[224:227], v[240:243], v[2:5]
	v_mfma_f32_16x16x32_bf16 v[6:9], v[224:227], v[252:255], v[6:9]
	ds_read_b128 v[224:227], v244 offset:23104
	ds_write_b128 v164, v[188:191] offset:9216
	s_waitcnt vmcnt(12)
	ds_write_b128 v164, v[196:199] offset:13824
	s_waitcnt lgkmcnt(7)
	v_mfma_f32_16x16x32_bf16 v[26:29], v[228:231], v[232:235], v[26:29]
	ds_read_b128 v[232:235], v245 offset:55360
	v_mfma_f32_16x16x32_bf16 v[30:33], v[228:231], v[236:239], v[30:33]
	ds_read_b128 v[236:239], v245 offset:57664
	v_mfma_f32_16x16x32_bf16 v[10:13], v[228:231], v[240:243], v[10:13]
	ds_read_b128 v[240:243], v245 offset:59968
	v_mfma_f32_16x16x32_bf16 v[14:17], v[228:231], v[252:255], v[14:17]
	ds_read_b128 v[252:255], v245 offset:62272
	ds_read_b128 v[228:231], v244 offset:25408
	s_waitcnt lgkmcnt(4)
	v_mfma_f32_16x16x32_bf16 v[50:53], v[216:219], v[232:235], v[50:53]
	s_waitcnt lgkmcnt(3)
	v_mfma_f32_16x16x32_bf16 v[54:57], v[216:219], v[236:239], v[54:57]
	s_waitcnt lgkmcnt(2)
	v_mfma_f32_16x16x32_bf16 v[34:37], v[216:219], v[240:243], v[34:37]
	s_waitcnt lgkmcnt(1)
	v_mfma_f32_16x16x32_bf16 v[38:41], v[216:219], v[252:255], v[38:41]
	s_waitcnt vmcnt(11)
	ds_write_b128 v164, v[200:203] offset:36864
	s_waitcnt vmcnt(10)
	ds_write_b128 v164, v[204:207] offset:41472
	v_mfma_f32_16x16x32_bf16 v[58:61], v[220:223], v[232:235], v[58:61]
	v_mfma_f32_16x16x32_bf16 v[62:65], v[220:223], v[236:239], v[62:65]
	v_mfma_f32_16x16x32_bf16 v[42:45], v[220:223], v[240:243], v[42:45]
	v_mfma_f32_16x16x32_bf16 v[46:49], v[220:223], v[252:255], v[46:49]
	s_waitcnt vmcnt(9)
	ds_write_b128 v164, v[208:211] offset:46080
	s_waitcnt vmcnt(8)
	ds_write_b128 v164, v[212:215] offset:50688
	v_mfma_f32_16x16x32_bf16 v[18:21], v[224:227], v[232:235], v[18:21]
	v_mfma_f32_16x16x32_bf16 v[22:25], v[224:227], v[236:239], v[22:25]
	v_mfma_f32_16x16x32_bf16 v[2:5], v[224:227], v[240:243], v[2:5]
	v_mfma_f32_16x16x32_bf16 v[6:9], v[224:227], v[252:255], v[6:9]
	s_waitcnt lgkmcnt(4)
	v_mfma_f32_16x16x32_bf16 v[26:29], v[228:231], v[232:235], v[26:29]
	v_mfma_f32_16x16x32_bf16 v[30:33], v[228:231], v[236:239], v[30:33]
	v_mfma_f32_16x16x32_bf16 v[10:13], v[228:231], v[240:243], v[10:13]
	v_mfma_f32_16x16x32_bf16 v[14:17], v[228:231], v[252:255], v[14:17]
	s_waitcnt lgkmcnt(0)
	s_barrier
	global_load_dwordx4 v[180:183], v[70:71], off offset:512
	global_load_dwordx4 v[188:191], v[68:69], off offset:512
	global_load_dwordx4 v[192:195], v[66:67], off offset:512
	global_load_dwordx4 v[196:199], v[72:73], off offset:512
	global_load_dwordx4 v[200:203], v[74:75], off offset:512
	global_load_dwordx4 v[204:207], v[76:77], off offset:512
	global_load_dwordx4 v[208:211], v[78:79], off offset:512
	global_load_dwordx4 v[212:215], v[80:81], off offset:512
	ds_read_b128 v[232:235], v245 offset:36864
	ds_read_b128 v[216:219], v244
	ds_read_b128 v[236:239], v245 offset:39168
	ds_read_b128 v[240:243], v245 offset:41472
	ds_read_b128 v[252:255], v245 offset:43776
	ds_read_b128 v[220:223], v244 offset:2304
	ds_read_b128 v[224:227], v244 offset:4608
	ds_read_b128 v[228:231], v244 offset:6912
	s_waitcnt lgkmcnt(6)
	v_mfma_f32_16x16x32_bf16 v[50:53], v[216:219], v[232:235], v[50:53]
	s_waitcnt lgkmcnt(5)
	v_mfma_f32_16x16x32_bf16 v[54:57], v[216:219], v[236:239], v[54:57]
	s_waitcnt lgkmcnt(4)
	v_mfma_f32_16x16x32_bf16 v[34:37], v[216:219], v[240:243], v[34:37]
	s_waitcnt lgkmcnt(3)
	v_mfma_f32_16x16x32_bf16 v[38:41], v[216:219], v[252:255], v[38:41]
	ds_read_b128 v[216:219], v244 offset:64
	s_waitcnt lgkmcnt(3)
	v_mfma_f32_16x16x32_bf16 v[58:61], v[220:223], v[232:235], v[58:61]
	v_mfma_f32_16x16x32_bf16 v[62:65], v[220:223], v[236:239], v[62:65]
	v_mfma_f32_16x16x32_bf16 v[42:45], v[220:223], v[240:243], v[42:45]
	v_mfma_f32_16x16x32_bf16 v[46:49], v[220:223], v[252:255], v[46:49]
	ds_read_b128 v[220:223], v244 offset:2368
	s_waitcnt vmcnt(15)
	ds_write_b128 v164, v[122:125] offset:18432
	s_waitcnt vmcnt(14)
	ds_write_b128 v164, v[126:129] offset:23040
	s_waitcnt lgkmcnt(5)
	v_mfma_f32_16x16x32_bf16 v[18:21], v[224:227], v[232:235], v[18:21]
	v_mfma_f32_16x16x32_bf16 v[22:25], v[224:227], v[236:239], v[22:25]
	v_mfma_f32_16x16x32_bf16 v[2:5], v[224:227], v[240:243], v[2:5]
	v_mfma_f32_16x16x32_bf16 v[6:9], v[224:227], v[252:255], v[6:9]
	ds_read_b128 v[224:227], v244 offset:4672
	s_waitcnt vmcnt(13)
	ds_write_b128 v164, v[136:139] offset:27648
	s_waitcnt vmcnt(12)
	ds_write_b128 v164, v[140:143] offset:32256
	s_waitcnt lgkmcnt(7)
	v_mfma_f32_16x16x32_bf16 v[26:29], v[228:231], v[232:235], v[26:29]
	ds_read_b128 v[232:235], v245 offset:36928
	v_mfma_f32_16x16x32_bf16 v[30:33], v[228:231], v[236:239], v[30:33]
	ds_read_b128 v[236:239], v245 offset:39232
	v_mfma_f32_16x16x32_bf16 v[10:13], v[228:231], v[240:243], v[10:13]
	ds_read_b128 v[240:243], v245 offset:41536
	v_mfma_f32_16x16x32_bf16 v[14:17], v[228:231], v[252:255], v[14:17]
	ds_read_b128 v[252:255], v245 offset:43840
	ds_read_b128 v[228:231], v244 offset:6976
	s_waitcnt lgkmcnt(4)
	v_mfma_f32_16x16x32_bf16 v[50:53], v[216:219], v[232:235], v[50:53]
	s_waitcnt lgkmcnt(3)
	v_mfma_f32_16x16x32_bf16 v[54:57], v[216:219], v[236:239], v[54:57]
	s_waitcnt lgkmcnt(2)
	v_mfma_f32_16x16x32_bf16 v[34:37], v[216:219], v[240:243], v[34:37]
	s_waitcnt lgkmcnt(1)
	v_mfma_f32_16x16x32_bf16 v[38:41], v[216:219], v[252:255], v[38:41]
	s_waitcnt vmcnt(11)
	ds_write_b128 v164, v[144:147] offset:55296
	s_waitcnt vmcnt(10)
	ds_write_b128 v164, v[148:151] offset:59904
	v_mfma_f32_16x16x32_bf16 v[58:61], v[220:223], v[232:235], v[58:61]
	v_mfma_f32_16x16x32_bf16 v[62:65], v[220:223], v[236:239], v[62:65]
	v_mfma_f32_16x16x32_bf16 v[42:45], v[220:223], v[240:243], v[42:45]
	v_mfma_f32_16x16x32_bf16 v[46:49], v[220:223], v[252:255], v[46:49]
	s_waitcnt vmcnt(9)
	ds_write_b128 v164, v[172:175] offset:64512
	s_waitcnt vmcnt(8)
	ds_write_b128 v165, v[176:179] offset:32256
	v_mfma_f32_16x16x32_bf16 v[18:21], v[224:227], v[232:235], v[18:21]
	v_mfma_f32_16x16x32_bf16 v[22:25], v[224:227], v[236:239], v[22:25]
	v_mfma_f32_16x16x32_bf16 v[2:5], v[224:227], v[240:243], v[2:5]
	v_mfma_f32_16x16x32_bf16 v[6:9], v[224:227], v[252:255], v[6:9]
	s_waitcnt lgkmcnt(4)
	v_mfma_f32_16x16x32_bf16 v[26:29], v[228:231], v[232:235], v[26:29]
	v_mfma_f32_16x16x32_bf16 v[30:33], v[228:231], v[236:239], v[30:33]
	v_mfma_f32_16x16x32_bf16 v[10:13], v[228:231], v[240:243], v[10:13]
	v_mfma_f32_16x16x32_bf16 v[14:17], v[228:231], v[252:255], v[14:17]
	s_waitcnt lgkmcnt(0)
	s_barrier
	global_load_dwordx4 v[122:125], v[70:71], off offset:640
	global_load_dwordx4 v[126:129], v[68:69], off offset:640
	global_load_dwordx4 v[136:139], v[66:67], off offset:640
	global_load_dwordx4 v[140:143], v[72:73], off offset:640
	global_load_dwordx4 v[144:147], v[74:75], off offset:640
	global_load_dwordx4 v[148:151], v[76:77], off offset:640
	global_load_dwordx4 v[172:175], v[78:79], off offset:640
	global_load_dwordx4 v[176:179], v[80:81], off offset:640
	ds_read_b128 v[232:235], v245 offset:55296
	ds_read_b128 v[216:219], v244 offset:18432
	ds_read_b128 v[236:239], v245 offset:57600
	ds_read_b128 v[240:243], v245 offset:59904
	ds_read_b128 v[252:255], v245 offset:62208
	ds_read_b128 v[220:223], v244 offset:20736
	ds_read_b128 v[224:227], v244 offset:23040
	ds_read_b128 v[228:231], v244 offset:25344
	s_waitcnt lgkmcnt(6)
	v_mfma_f32_16x16x32_bf16 v[50:53], v[216:219], v[232:235], v[50:53]
	s_waitcnt lgkmcnt(5)
	v_mfma_f32_16x16x32_bf16 v[54:57], v[216:219], v[236:239], v[54:57]
	s_waitcnt lgkmcnt(4)
	v_mfma_f32_16x16x32_bf16 v[34:37], v[216:219], v[240:243], v[34:37]
	s_waitcnt lgkmcnt(3)
	v_mfma_f32_16x16x32_bf16 v[38:41], v[216:219], v[252:255], v[38:41]
	ds_read_b128 v[216:219], v244 offset:18496
	s_waitcnt lgkmcnt(3)
	v_mfma_f32_16x16x32_bf16 v[58:61], v[220:223], v[232:235], v[58:61]
	v_mfma_f32_16x16x32_bf16 v[62:65], v[220:223], v[236:239], v[62:65]
	v_mfma_f32_16x16x32_bf16 v[42:45], v[220:223], v[240:243], v[42:45]
	v_mfma_f32_16x16x32_bf16 v[46:49], v[220:223], v[252:255], v[46:49]
	ds_read_b128 v[220:223], v244 offset:20800
	s_waitcnt vmcnt(15)
	ds_write_b128 v164, v[180:183]
	s_waitcnt vmcnt(14)
	ds_write_b128 v164, v[188:191] offset:4608
	s_waitcnt lgkmcnt(5)
	v_mfma_f32_16x16x32_bf16 v[18:21], v[224:227], v[232:235], v[18:21]
	v_mfma_f32_16x16x32_bf16 v[22:25], v[224:227], v[236:239], v[22:25]
	v_mfma_f32_16x16x32_bf16 v[2:5], v[224:227], v[240:243], v[2:5]
	v_mfma_f32_16x16x32_bf16 v[6:9], v[224:227], v[252:255], v[6:9]
	ds_read_b128 v[224:227], v244 offset:23104
	s_waitcnt vmcnt(13)
	ds_write_b128 v164, v[192:195] offset:9216
	s_waitcnt vmcnt(12)
	ds_write_b128 v164, v[196:199] offset:13824
	s_waitcnt lgkmcnt(7)
	v_mfma_f32_16x16x32_bf16 v[26:29], v[228:231], v[232:235], v[26:29]
	ds_read_b128 v[232:235], v245 offset:55360
	v_mfma_f32_16x16x32_bf16 v[30:33], v[228:231], v[236:239], v[30:33]
	ds_read_b128 v[236:239], v245 offset:57664
	v_mfma_f32_16x16x32_bf16 v[10:13], v[228:231], v[240:243], v[10:13]
	ds_read_b128 v[240:243], v245 offset:59968
	v_mfma_f32_16x16x32_bf16 v[14:17], v[228:231], v[252:255], v[14:17]
	ds_read_b128 v[252:255], v245 offset:62272
	ds_read_b128 v[228:231], v244 offset:25408
	s_waitcnt lgkmcnt(4)
	v_mfma_f32_16x16x32_bf16 v[50:53], v[216:219], v[232:235], v[50:53]
	s_waitcnt lgkmcnt(3)
	v_mfma_f32_16x16x32_bf16 v[54:57], v[216:219], v[236:239], v[54:57]
	s_waitcnt lgkmcnt(2)
	v_mfma_f32_16x16x32_bf16 v[34:37], v[216:219], v[240:243], v[34:37]
	s_waitcnt lgkmcnt(1)
	v_mfma_f32_16x16x32_bf16 v[38:41], v[216:219], v[252:255], v[38:41]
	s_waitcnt vmcnt(11)
	ds_write_b128 v164, v[200:203] offset:36864
	s_waitcnt vmcnt(10)
	ds_write_b128 v164, v[204:207] offset:41472
	v_mfma_f32_16x16x32_bf16 v[58:61], v[220:223], v[232:235], v[58:61]
	v_mfma_f32_16x16x32_bf16 v[62:65], v[220:223], v[236:239], v[62:65]
	v_mfma_f32_16x16x32_bf16 v[42:45], v[220:223], v[240:243], v[42:45]
	v_mfma_f32_16x16x32_bf16 v[46:49], v[220:223], v[252:255], v[46:49]
	s_waitcnt vmcnt(9)
	ds_write_b128 v164, v[208:211] offset:46080
	s_waitcnt vmcnt(8)
	ds_write_b128 v164, v[212:215] offset:50688
	v_mfma_f32_16x16x32_bf16 v[18:21], v[224:227], v[232:235], v[18:21]
	v_mfma_f32_16x16x32_bf16 v[22:25], v[224:227], v[236:239], v[22:25]
	v_mfma_f32_16x16x32_bf16 v[2:5], v[224:227], v[240:243], v[2:5]
	v_mfma_f32_16x16x32_bf16 v[6:9], v[224:227], v[252:255], v[6:9]
	s_waitcnt lgkmcnt(4)
	v_mfma_f32_16x16x32_bf16 v[26:29], v[228:231], v[232:235], v[26:29]
	v_mfma_f32_16x16x32_bf16 v[30:33], v[228:231], v[236:239], v[30:33]
	v_mfma_f32_16x16x32_bf16 v[10:13], v[228:231], v[240:243], v[10:13]
	v_mfma_f32_16x16x32_bf16 v[14:17], v[228:231], v[252:255], v[14:17]
	s_waitcnt lgkmcnt(0)
	s_barrier
	global_load_dwordx4 v[180:183], v[70:71], off offset:768
	global_load_dwordx4 v[188:191], v[68:69], off offset:768
	global_load_dwordx4 v[192:195], v[66:67], off offset:768
	global_load_dwordx4 v[196:199], v[72:73], off offset:768
	global_load_dwordx4 v[200:203], v[74:75], off offset:768
	global_load_dwordx4 v[204:207], v[76:77], off offset:768
	global_load_dwordx4 v[208:211], v[78:79], off offset:768
	global_load_dwordx4 v[212:215], v[80:81], off offset:768
	ds_read_b128 v[232:235], v245 offset:36864
	ds_read_b128 v[216:219], v244
	ds_read_b128 v[236:239], v245 offset:39168
	ds_read_b128 v[240:243], v245 offset:41472
	ds_read_b128 v[252:255], v245 offset:43776
	ds_read_b128 v[220:223], v244 offset:2304
	ds_read_b128 v[224:227], v244 offset:4608
	ds_read_b128 v[228:231], v244 offset:6912
	s_waitcnt lgkmcnt(6)
	v_mfma_f32_16x16x32_bf16 v[50:53], v[216:219], v[232:235], v[50:53]
	s_waitcnt lgkmcnt(5)
	v_mfma_f32_16x16x32_bf16 v[54:57], v[216:219], v[236:239], v[54:57]
	s_waitcnt lgkmcnt(4)
	v_mfma_f32_16x16x32_bf16 v[34:37], v[216:219], v[240:243], v[34:37]
	s_waitcnt lgkmcnt(3)
	v_mfma_f32_16x16x32_bf16 v[38:41], v[216:219], v[252:255], v[38:41]
	ds_read_b128 v[216:219], v244 offset:64
	s_waitcnt lgkmcnt(3)
	v_mfma_f32_16x16x32_bf16 v[58:61], v[220:223], v[232:235], v[58:61]
	v_mfma_f32_16x16x32_bf16 v[62:65], v[220:223], v[236:239], v[62:65]
	v_mfma_f32_16x16x32_bf16 v[42:45], v[220:223], v[240:243], v[42:45]
	v_mfma_f32_16x16x32_bf16 v[46:49], v[220:223], v[252:255], v[46:49]
	ds_read_b128 v[220:223], v244 offset:2368
	s_waitcnt vmcnt(15)
	ds_write_b128 v164, v[122:125] offset:18432
	s_waitcnt vmcnt(14)
	ds_write_b128 v164, v[126:129] offset:23040
	s_waitcnt lgkmcnt(5)
	v_mfma_f32_16x16x32_bf16 v[18:21], v[224:227], v[232:235], v[18:21]
	v_mfma_f32_16x16x32_bf16 v[22:25], v[224:227], v[236:239], v[22:25]
	v_mfma_f32_16x16x32_bf16 v[2:5], v[224:227], v[240:243], v[2:5]
	v_mfma_f32_16x16x32_bf16 v[6:9], v[224:227], v[252:255], v[6:9]
	ds_read_b128 v[224:227], v244 offset:4672
	s_waitcnt vmcnt(13)
	ds_write_b128 v164, v[136:139] offset:27648
	s_waitcnt vmcnt(12)
	ds_write_b128 v164, v[140:143] offset:32256
	s_waitcnt lgkmcnt(7)
	v_mfma_f32_16x16x32_bf16 v[26:29], v[228:231], v[232:235], v[26:29]
	ds_read_b128 v[232:235], v245 offset:36928
	v_mfma_f32_16x16x32_bf16 v[30:33], v[228:231], v[236:239], v[30:33]
	ds_read_b128 v[236:239], v245 offset:39232
	v_mfma_f32_16x16x32_bf16 v[10:13], v[228:231], v[240:243], v[10:13]
	ds_read_b128 v[240:243], v245 offset:41536
	v_mfma_f32_16x16x32_bf16 v[14:17], v[228:231], v[252:255], v[14:17]
	ds_read_b128 v[252:255], v245 offset:43840
	ds_read_b128 v[228:231], v244 offset:6976
	s_waitcnt lgkmcnt(4)
	v_mfma_f32_16x16x32_bf16 v[50:53], v[216:219], v[232:235], v[50:53]
	s_waitcnt lgkmcnt(3)
	v_mfma_f32_16x16x32_bf16 v[54:57], v[216:219], v[236:239], v[54:57]
	s_waitcnt lgkmcnt(2)
	v_mfma_f32_16x16x32_bf16 v[34:37], v[216:219], v[240:243], v[34:37]
	s_waitcnt lgkmcnt(1)
	v_mfma_f32_16x16x32_bf16 v[38:41], v[216:219], v[252:255], v[38:41]
	s_waitcnt vmcnt(11)
	ds_write_b128 v164, v[144:147] offset:55296
	s_waitcnt vmcnt(10)
	ds_write_b128 v164, v[148:151] offset:59904
	v_mfma_f32_16x16x32_bf16 v[58:61], v[220:223], v[232:235], v[58:61]
	v_mfma_f32_16x16x32_bf16 v[62:65], v[220:223], v[236:239], v[62:65]
	v_mfma_f32_16x16x32_bf16 v[42:45], v[220:223], v[240:243], v[42:45]
	v_mfma_f32_16x16x32_bf16 v[46:49], v[220:223], v[252:255], v[46:49]
	s_waitcnt vmcnt(9)
	ds_write_b128 v164, v[172:175] offset:64512
	s_waitcnt vmcnt(8)
	ds_write_b128 v165, v[176:179] offset:32256
	v_mfma_f32_16x16x32_bf16 v[18:21], v[224:227], v[232:235], v[18:21]
	v_mfma_f32_16x16x32_bf16 v[22:25], v[224:227], v[236:239], v[22:25]
	v_mfma_f32_16x16x32_bf16 v[2:5], v[224:227], v[240:243], v[2:5]
	v_mfma_f32_16x16x32_bf16 v[6:9], v[224:227], v[252:255], v[6:9]
	s_waitcnt lgkmcnt(4)
	v_mfma_f32_16x16x32_bf16 v[26:29], v[228:231], v[232:235], v[26:29]
	v_mfma_f32_16x16x32_bf16 v[30:33], v[228:231], v[236:239], v[30:33]
	v_mfma_f32_16x16x32_bf16 v[10:13], v[228:231], v[240:243], v[10:13]
	v_mfma_f32_16x16x32_bf16 v[14:17], v[228:231], v[252:255], v[14:17]
	s_waitcnt lgkmcnt(0)
	s_barrier
	global_load_dwordx4 v[122:125], v[70:71], off offset:896
	global_load_dwordx4 v[126:129], v[68:69], off offset:896
	global_load_dwordx4 v[136:139], v[66:67], off offset:896
	global_load_dwordx4 v[140:143], v[72:73], off offset:896
	global_load_dwordx4 v[144:147], v[74:75], off offset:896
	global_load_dwordx4 v[148:151], v[76:77], off offset:896
	global_load_dwordx4 v[172:175], v[78:79], off offset:896
	global_load_dwordx4 v[176:179], v[80:81], off offset:896
	ds_read_b128 v[232:235], v245 offset:55296
	ds_read_b128 v[216:219], v244 offset:18432
	ds_read_b128 v[236:239], v245 offset:57600
	ds_read_b128 v[240:243], v245 offset:59904
	ds_read_b128 v[252:255], v245 offset:62208
	ds_read_b128 v[220:223], v244 offset:20736
	ds_read_b128 v[224:227], v244 offset:23040
	ds_read_b128 v[228:231], v244 offset:25344
	s_waitcnt lgkmcnt(6)
	v_mfma_f32_16x16x32_bf16 v[50:53], v[216:219], v[232:235], v[50:53]
	s_waitcnt lgkmcnt(5)
	v_mfma_f32_16x16x32_bf16 v[54:57], v[216:219], v[236:239], v[54:57]
	s_waitcnt lgkmcnt(4)
	v_mfma_f32_16x16x32_bf16 v[34:37], v[216:219], v[240:243], v[34:37]
	s_waitcnt lgkmcnt(3)
	v_mfma_f32_16x16x32_bf16 v[38:41], v[216:219], v[252:255], v[38:41]
	ds_read_b128 v[216:219], v244 offset:18496
	s_waitcnt lgkmcnt(3)
	v_mfma_f32_16x16x32_bf16 v[58:61], v[220:223], v[232:235], v[58:61]
	v_mfma_f32_16x16x32_bf16 v[62:65], v[220:223], v[236:239], v[62:65]
	v_mfma_f32_16x16x32_bf16 v[42:45], v[220:223], v[240:243], v[42:45]
	v_mfma_f32_16x16x32_bf16 v[46:49], v[220:223], v[252:255], v[46:49]
	ds_read_b128 v[220:223], v244 offset:20800
	s_waitcnt vmcnt(15)
	ds_write_b128 v164, v[180:183]
	s_waitcnt vmcnt(14)
	ds_write_b128 v164, v[188:191] offset:4608
	s_waitcnt lgkmcnt(5)
	v_mfma_f32_16x16x32_bf16 v[18:21], v[224:227], v[232:235], v[18:21]
	v_mfma_f32_16x16x32_bf16 v[22:25], v[224:227], v[236:239], v[22:25]
	v_mfma_f32_16x16x32_bf16 v[2:5], v[224:227], v[240:243], v[2:5]
	v_mfma_f32_16x16x32_bf16 v[6:9], v[224:227], v[252:255], v[6:9]
	ds_read_b128 v[224:227], v244 offset:23104
	s_waitcnt vmcnt(13)
	ds_write_b128 v164, v[192:195] offset:9216
	s_waitcnt vmcnt(12)
	ds_write_b128 v164, v[196:199] offset:13824
	s_waitcnt lgkmcnt(7)
	v_mfma_f32_16x16x32_bf16 v[26:29], v[228:231], v[232:235], v[26:29]
	ds_read_b128 v[232:235], v245 offset:55360
	v_mfma_f32_16x16x32_bf16 v[30:33], v[228:231], v[236:239], v[30:33]
	ds_read_b128 v[236:239], v245 offset:57664
	v_mfma_f32_16x16x32_bf16 v[10:13], v[228:231], v[240:243], v[10:13]
	ds_read_b128 v[240:243], v245 offset:59968
	v_mfma_f32_16x16x32_bf16 v[14:17], v[228:231], v[252:255], v[14:17]
	ds_read_b128 v[252:255], v245 offset:62272
	ds_read_b128 v[228:231], v244 offset:25408
	s_waitcnt lgkmcnt(4)
	v_mfma_f32_16x16x32_bf16 v[50:53], v[216:219], v[232:235], v[50:53]
	s_waitcnt lgkmcnt(3)
	v_mfma_f32_16x16x32_bf16 v[54:57], v[216:219], v[236:239], v[54:57]
	s_waitcnt lgkmcnt(2)
	v_mfma_f32_16x16x32_bf16 v[34:37], v[216:219], v[240:243], v[34:37]
	s_waitcnt lgkmcnt(1)
	v_mfma_f32_16x16x32_bf16 v[38:41], v[216:219], v[252:255], v[38:41]
	s_waitcnt vmcnt(11)
	ds_write_b128 v164, v[200:203] offset:36864
	s_waitcnt vmcnt(10)
	ds_write_b128 v164, v[204:207] offset:41472
	v_mfma_f32_16x16x32_bf16 v[58:61], v[220:223], v[232:235], v[58:61]
	v_mfma_f32_16x16x32_bf16 v[62:65], v[220:223], v[236:239], v[62:65]
	v_mfma_f32_16x16x32_bf16 v[42:45], v[220:223], v[240:243], v[42:45]
	v_mfma_f32_16x16x32_bf16 v[46:49], v[220:223], v[252:255], v[46:49]
	s_waitcnt vmcnt(9)
	ds_write_b128 v164, v[208:211] offset:46080
	s_waitcnt vmcnt(8)
	ds_write_b128 v164, v[212:215] offset:50688
	v_mfma_f32_16x16x32_bf16 v[18:21], v[224:227], v[232:235], v[18:21]
	v_mfma_f32_16x16x32_bf16 v[22:25], v[224:227], v[236:239], v[22:25]
	v_mfma_f32_16x16x32_bf16 v[2:5], v[224:227], v[240:243], v[2:5]
	v_mfma_f32_16x16x32_bf16 v[6:9], v[224:227], v[252:255], v[6:9]
	s_waitcnt lgkmcnt(4)
	v_mfma_f32_16x16x32_bf16 v[26:29], v[228:231], v[232:235], v[26:29]
	v_mfma_f32_16x16x32_bf16 v[30:33], v[228:231], v[236:239], v[30:33]
	v_mfma_f32_16x16x32_bf16 v[10:13], v[228:231], v[240:243], v[10:13]
	v_mfma_f32_16x16x32_bf16 v[14:17], v[228:231], v[252:255], v[14:17]
	s_waitcnt lgkmcnt(0)
	s_barrier
	global_load_dwordx4 v[180:183], v[70:71], off offset:1024
	global_load_dwordx4 v[188:191], v[68:69], off offset:1024
	global_load_dwordx4 v[192:195], v[66:67], off offset:1024
	global_load_dwordx4 v[196:199], v[72:73], off offset:1024
	global_load_dwordx4 v[200:203], v[74:75], off offset:1024
	global_load_dwordx4 v[204:207], v[76:77], off offset:1024
	global_load_dwordx4 v[208:211], v[78:79], off offset:1024
	global_load_dwordx4 v[212:215], v[80:81], off offset:1024
	ds_read_b128 v[232:235], v245 offset:36864
	ds_read_b128 v[216:219], v244
	ds_read_b128 v[236:239], v245 offset:39168
	ds_read_b128 v[240:243], v245 offset:41472
	ds_read_b128 v[252:255], v245 offset:43776
	ds_read_b128 v[220:223], v244 offset:2304
	ds_read_b128 v[224:227], v244 offset:4608
	ds_read_b128 v[228:231], v244 offset:6912
	s_waitcnt lgkmcnt(6)
	v_mfma_f32_16x16x32_bf16 v[50:53], v[216:219], v[232:235], v[50:53]
	s_waitcnt lgkmcnt(5)
	v_mfma_f32_16x16x32_bf16 v[54:57], v[216:219], v[236:239], v[54:57]
	s_waitcnt lgkmcnt(4)
	v_mfma_f32_16x16x32_bf16 v[34:37], v[216:219], v[240:243], v[34:37]
	s_waitcnt lgkmcnt(3)
	v_mfma_f32_16x16x32_bf16 v[38:41], v[216:219], v[252:255], v[38:41]
	ds_read_b128 v[216:219], v244 offset:64
	s_waitcnt lgkmcnt(3)
	v_mfma_f32_16x16x32_bf16 v[58:61], v[220:223], v[232:235], v[58:61]
	v_mfma_f32_16x16x32_bf16 v[62:65], v[220:223], v[236:239], v[62:65]
	v_mfma_f32_16x16x32_bf16 v[42:45], v[220:223], v[240:243], v[42:45]
	v_mfma_f32_16x16x32_bf16 v[46:49], v[220:223], v[252:255], v[46:49]
	ds_read_b128 v[220:223], v244 offset:2368
	s_waitcnt vmcnt(15)
	ds_write_b128 v164, v[122:125] offset:18432
	s_waitcnt vmcnt(14)
	ds_write_b128 v164, v[126:129] offset:23040
	s_waitcnt lgkmcnt(5)
	v_mfma_f32_16x16x32_bf16 v[18:21], v[224:227], v[232:235], v[18:21]
	v_mfma_f32_16x16x32_bf16 v[22:25], v[224:227], v[236:239], v[22:25]
	v_mfma_f32_16x16x32_bf16 v[2:5], v[224:227], v[240:243], v[2:5]
	v_mfma_f32_16x16x32_bf16 v[6:9], v[224:227], v[252:255], v[6:9]
	ds_read_b128 v[224:227], v244 offset:4672
	s_waitcnt vmcnt(13)
	ds_write_b128 v164, v[136:139] offset:27648
	s_waitcnt vmcnt(12)
	ds_write_b128 v164, v[140:143] offset:32256
	s_waitcnt lgkmcnt(7)
	v_mfma_f32_16x16x32_bf16 v[26:29], v[228:231], v[232:235], v[26:29]
	ds_read_b128 v[232:235], v245 offset:36928
	v_mfma_f32_16x16x32_bf16 v[30:33], v[228:231], v[236:239], v[30:33]
	ds_read_b128 v[236:239], v245 offset:39232
	v_mfma_f32_16x16x32_bf16 v[10:13], v[228:231], v[240:243], v[10:13]
	ds_read_b128 v[240:243], v245 offset:41536
	v_mfma_f32_16x16x32_bf16 v[14:17], v[228:231], v[252:255], v[14:17]
	ds_read_b128 v[252:255], v245 offset:43840
	ds_read_b128 v[228:231], v244 offset:6976
	s_waitcnt lgkmcnt(4)
	v_mfma_f32_16x16x32_bf16 v[50:53], v[216:219], v[232:235], v[50:53]
	s_waitcnt lgkmcnt(3)
	v_mfma_f32_16x16x32_bf16 v[54:57], v[216:219], v[236:239], v[54:57]
	s_waitcnt lgkmcnt(2)
	v_mfma_f32_16x16x32_bf16 v[34:37], v[216:219], v[240:243], v[34:37]
	s_waitcnt lgkmcnt(1)
	v_mfma_f32_16x16x32_bf16 v[38:41], v[216:219], v[252:255], v[38:41]
	s_waitcnt vmcnt(11)
	ds_write_b128 v164, v[144:147] offset:55296
	s_waitcnt vmcnt(10)
	ds_write_b128 v164, v[148:151] offset:59904
	v_mfma_f32_16x16x32_bf16 v[58:61], v[220:223], v[232:235], v[58:61]
	v_mfma_f32_16x16x32_bf16 v[62:65], v[220:223], v[236:239], v[62:65]
	v_mfma_f32_16x16x32_bf16 v[42:45], v[220:223], v[240:243], v[42:45]
	v_mfma_f32_16x16x32_bf16 v[46:49], v[220:223], v[252:255], v[46:49]
	s_waitcnt vmcnt(9)
	ds_write_b128 v164, v[172:175] offset:64512
	s_waitcnt vmcnt(8)
	ds_write_b128 v165, v[176:179] offset:32256
	v_mfma_f32_16x16x32_bf16 v[18:21], v[224:227], v[232:235], v[18:21]
	v_mfma_f32_16x16x32_bf16 v[22:25], v[224:227], v[236:239], v[22:25]
	v_mfma_f32_16x16x32_bf16 v[2:5], v[224:227], v[240:243], v[2:5]
	v_mfma_f32_16x16x32_bf16 v[6:9], v[224:227], v[252:255], v[6:9]
	s_waitcnt lgkmcnt(4)
	v_mfma_f32_16x16x32_bf16 v[26:29], v[228:231], v[232:235], v[26:29]
	v_mfma_f32_16x16x32_bf16 v[30:33], v[228:231], v[236:239], v[30:33]
	v_mfma_f32_16x16x32_bf16 v[10:13], v[228:231], v[240:243], v[10:13]
	v_mfma_f32_16x16x32_bf16 v[14:17], v[228:231], v[252:255], v[14:17]
	s_waitcnt lgkmcnt(0)
	s_barrier
	global_load_dwordx4 v[122:125], v[70:71], off offset:1152
	global_load_dwordx4 v[126:129], v[68:69], off offset:1152
	global_load_dwordx4 v[136:139], v[66:67], off offset:1152
	global_load_dwordx4 v[140:143], v[72:73], off offset:1152
	global_load_dwordx4 v[144:147], v[74:75], off offset:1152
	global_load_dwordx4 v[148:151], v[76:77], off offset:1152
	global_load_dwordx4 v[172:175], v[78:79], off offset:1152
	global_load_dwordx4 v[176:179], v[80:81], off offset:1152
	ds_read_b128 v[232:235], v245 offset:55296
	ds_read_b128 v[216:219], v244 offset:18432
	ds_read_b128 v[236:239], v245 offset:57600
	ds_read_b128 v[240:243], v245 offset:59904
	ds_read_b128 v[252:255], v245 offset:62208
	ds_read_b128 v[220:223], v244 offset:20736
	ds_read_b128 v[224:227], v244 offset:23040
	ds_read_b128 v[228:231], v244 offset:25344
	s_waitcnt lgkmcnt(6)
	v_mfma_f32_16x16x32_bf16 v[50:53], v[216:219], v[232:235], v[50:53]
	s_waitcnt lgkmcnt(5)
	v_mfma_f32_16x16x32_bf16 v[54:57], v[216:219], v[236:239], v[54:57]
	s_waitcnt lgkmcnt(4)
	v_mfma_f32_16x16x32_bf16 v[34:37], v[216:219], v[240:243], v[34:37]
	s_waitcnt lgkmcnt(3)
	v_mfma_f32_16x16x32_bf16 v[38:41], v[216:219], v[252:255], v[38:41]
	ds_read_b128 v[216:219], v244 offset:18496
	s_waitcnt lgkmcnt(3)
	v_mfma_f32_16x16x32_bf16 v[58:61], v[220:223], v[232:235], v[58:61]
	v_mfma_f32_16x16x32_bf16 v[62:65], v[220:223], v[236:239], v[62:65]
	v_mfma_f32_16x16x32_bf16 v[42:45], v[220:223], v[240:243], v[42:45]
	v_mfma_f32_16x16x32_bf16 v[46:49], v[220:223], v[252:255], v[46:49]
	ds_read_b128 v[220:223], v244 offset:20800
	s_waitcnt vmcnt(15)
	ds_write_b128 v164, v[180:183]
	s_waitcnt vmcnt(14)
	ds_write_b128 v164, v[188:191] offset:4608
	s_waitcnt lgkmcnt(5)
	v_mfma_f32_16x16x32_bf16 v[18:21], v[224:227], v[232:235], v[18:21]
	v_mfma_f32_16x16x32_bf16 v[22:25], v[224:227], v[236:239], v[22:25]
	v_mfma_f32_16x16x32_bf16 v[2:5], v[224:227], v[240:243], v[2:5]
	v_mfma_f32_16x16x32_bf16 v[6:9], v[224:227], v[252:255], v[6:9]
	ds_read_b128 v[224:227], v244 offset:23104
	s_waitcnt vmcnt(13)
	ds_write_b128 v164, v[192:195] offset:9216
	s_waitcnt vmcnt(12)
	ds_write_b128 v164, v[196:199] offset:13824
	s_waitcnt lgkmcnt(7)
	v_mfma_f32_16x16x32_bf16 v[26:29], v[228:231], v[232:235], v[26:29]
	ds_read_b128 v[232:235], v245 offset:55360
	v_mfma_f32_16x16x32_bf16 v[30:33], v[228:231], v[236:239], v[30:33]
	ds_read_b128 v[236:239], v245 offset:57664
	v_mfma_f32_16x16x32_bf16 v[10:13], v[228:231], v[240:243], v[10:13]
	ds_read_b128 v[240:243], v245 offset:59968
	v_mfma_f32_16x16x32_bf16 v[14:17], v[228:231], v[252:255], v[14:17]
	ds_read_b128 v[252:255], v245 offset:62272
	ds_read_b128 v[228:231], v244 offset:25408
	s_waitcnt lgkmcnt(4)
	v_mfma_f32_16x16x32_bf16 v[50:53], v[216:219], v[232:235], v[50:53]
	s_waitcnt lgkmcnt(3)
	v_mfma_f32_16x16x32_bf16 v[54:57], v[216:219], v[236:239], v[54:57]
	s_waitcnt lgkmcnt(2)
	v_mfma_f32_16x16x32_bf16 v[34:37], v[216:219], v[240:243], v[34:37]
	s_waitcnt lgkmcnt(1)
	v_mfma_f32_16x16x32_bf16 v[38:41], v[216:219], v[252:255], v[38:41]
	s_waitcnt vmcnt(11)
	ds_write_b128 v164, v[200:203] offset:36864
	s_waitcnt vmcnt(10)
	ds_write_b128 v164, v[204:207] offset:41472
	v_mfma_f32_16x16x32_bf16 v[58:61], v[220:223], v[232:235], v[58:61]
	v_mfma_f32_16x16x32_bf16 v[62:65], v[220:223], v[236:239], v[62:65]
	v_mfma_f32_16x16x32_bf16 v[42:45], v[220:223], v[240:243], v[42:45]
	v_mfma_f32_16x16x32_bf16 v[46:49], v[220:223], v[252:255], v[46:49]
	s_waitcnt vmcnt(9)
	ds_write_b128 v164, v[208:211] offset:46080
	s_waitcnt vmcnt(8)
	ds_write_b128 v164, v[212:215] offset:50688
	v_mfma_f32_16x16x32_bf16 v[18:21], v[224:227], v[232:235], v[18:21]
	v_mfma_f32_16x16x32_bf16 v[22:25], v[224:227], v[236:239], v[22:25]
	v_mfma_f32_16x16x32_bf16 v[2:5], v[224:227], v[240:243], v[2:5]
	v_mfma_f32_16x16x32_bf16 v[6:9], v[224:227], v[252:255], v[6:9]
	s_waitcnt lgkmcnt(4)
	v_mfma_f32_16x16x32_bf16 v[26:29], v[228:231], v[232:235], v[26:29]
	v_mfma_f32_16x16x32_bf16 v[30:33], v[228:231], v[236:239], v[30:33]
	v_mfma_f32_16x16x32_bf16 v[10:13], v[228:231], v[240:243], v[10:13]
	v_mfma_f32_16x16x32_bf16 v[14:17], v[228:231], v[252:255], v[14:17]
	s_waitcnt lgkmcnt(0)
	s_barrier
	global_load_dwordx4 v[180:183], v[70:71], off offset:1280
	global_load_dwordx4 v[188:191], v[68:69], off offset:1280
	global_load_dwordx4 v[192:195], v[66:67], off offset:1280
	global_load_dwordx4 v[196:199], v[72:73], off offset:1280
	global_load_dwordx4 v[200:203], v[74:75], off offset:1280
	global_load_dwordx4 v[204:207], v[76:77], off offset:1280
	global_load_dwordx4 v[208:211], v[78:79], off offset:1280
	global_load_dwordx4 v[212:215], v[80:81], off offset:1280
	ds_read_b128 v[232:235], v245 offset:36864
	ds_read_b128 v[216:219], v244
	ds_read_b128 v[236:239], v245 offset:39168
	ds_read_b128 v[240:243], v245 offset:41472
	ds_read_b128 v[252:255], v245 offset:43776
	ds_read_b128 v[220:223], v244 offset:2304
	ds_read_b128 v[224:227], v244 offset:4608
	ds_read_b128 v[228:231], v244 offset:6912
	s_waitcnt lgkmcnt(6)
	v_mfma_f32_16x16x32_bf16 v[50:53], v[216:219], v[232:235], v[50:53]
	s_waitcnt lgkmcnt(5)
	v_mfma_f32_16x16x32_bf16 v[54:57], v[216:219], v[236:239], v[54:57]
	s_waitcnt lgkmcnt(4)
	v_mfma_f32_16x16x32_bf16 v[34:37], v[216:219], v[240:243], v[34:37]
	s_waitcnt lgkmcnt(3)
	v_mfma_f32_16x16x32_bf16 v[38:41], v[216:219], v[252:255], v[38:41]
	ds_read_b128 v[216:219], v244 offset:64
	s_waitcnt lgkmcnt(3)
	v_mfma_f32_16x16x32_bf16 v[58:61], v[220:223], v[232:235], v[58:61]
	v_mfma_f32_16x16x32_bf16 v[62:65], v[220:223], v[236:239], v[62:65]
	v_mfma_f32_16x16x32_bf16 v[42:45], v[220:223], v[240:243], v[42:45]
	v_mfma_f32_16x16x32_bf16 v[46:49], v[220:223], v[252:255], v[46:49]
	ds_read_b128 v[220:223], v244 offset:2368
	s_waitcnt vmcnt(15)
	ds_write_b128 v164, v[122:125] offset:18432
	s_waitcnt vmcnt(14)
	ds_write_b128 v164, v[126:129] offset:23040
	s_waitcnt lgkmcnt(5)
	v_mfma_f32_16x16x32_bf16 v[18:21], v[224:227], v[232:235], v[18:21]
	v_mfma_f32_16x16x32_bf16 v[22:25], v[224:227], v[236:239], v[22:25]
	v_mfma_f32_16x16x32_bf16 v[2:5], v[224:227], v[240:243], v[2:5]
	v_mfma_f32_16x16x32_bf16 v[6:9], v[224:227], v[252:255], v[6:9]
	ds_read_b128 v[224:227], v244 offset:4672
	s_waitcnt vmcnt(13)
	ds_write_b128 v164, v[136:139] offset:27648
	s_waitcnt vmcnt(12)
	ds_write_b128 v164, v[140:143] offset:32256
	s_waitcnt lgkmcnt(7)
	v_mfma_f32_16x16x32_bf16 v[26:29], v[228:231], v[232:235], v[26:29]
	ds_read_b128 v[232:235], v245 offset:36928
	v_mfma_f32_16x16x32_bf16 v[30:33], v[228:231], v[236:239], v[30:33]
	ds_read_b128 v[236:239], v245 offset:39232
	v_mfma_f32_16x16x32_bf16 v[10:13], v[228:231], v[240:243], v[10:13]
	ds_read_b128 v[240:243], v245 offset:41536
	v_mfma_f32_16x16x32_bf16 v[14:17], v[228:231], v[252:255], v[14:17]
	ds_read_b128 v[252:255], v245 offset:43840
	ds_read_b128 v[228:231], v244 offset:6976
	s_waitcnt lgkmcnt(4)
	v_mfma_f32_16x16x32_bf16 v[50:53], v[216:219], v[232:235], v[50:53]
	s_waitcnt lgkmcnt(3)
	v_mfma_f32_16x16x32_bf16 v[54:57], v[216:219], v[236:239], v[54:57]
	s_waitcnt lgkmcnt(2)
	v_mfma_f32_16x16x32_bf16 v[34:37], v[216:219], v[240:243], v[34:37]
	s_waitcnt lgkmcnt(1)
	v_mfma_f32_16x16x32_bf16 v[38:41], v[216:219], v[252:255], v[38:41]
	s_waitcnt vmcnt(11)
	ds_write_b128 v164, v[144:147] offset:55296
	s_waitcnt vmcnt(10)
	ds_write_b128 v164, v[148:151] offset:59904
	v_mfma_f32_16x16x32_bf16 v[58:61], v[220:223], v[232:235], v[58:61]
	v_mfma_f32_16x16x32_bf16 v[62:65], v[220:223], v[236:239], v[62:65]
	v_mfma_f32_16x16x32_bf16 v[42:45], v[220:223], v[240:243], v[42:45]
	v_mfma_f32_16x16x32_bf16 v[46:49], v[220:223], v[252:255], v[46:49]
	s_waitcnt vmcnt(9)
	ds_write_b128 v164, v[172:175] offset:64512
	s_waitcnt vmcnt(8)
	ds_write_b128 v165, v[176:179] offset:32256
	v_mfma_f32_16x16x32_bf16 v[18:21], v[224:227], v[232:235], v[18:21]
	v_mfma_f32_16x16x32_bf16 v[22:25], v[224:227], v[236:239], v[22:25]
	v_mfma_f32_16x16x32_bf16 v[2:5], v[224:227], v[240:243], v[2:5]
	v_mfma_f32_16x16x32_bf16 v[6:9], v[224:227], v[252:255], v[6:9]
	s_waitcnt lgkmcnt(4)
	v_mfma_f32_16x16x32_bf16 v[26:29], v[228:231], v[232:235], v[26:29]
	v_mfma_f32_16x16x32_bf16 v[30:33], v[228:231], v[236:239], v[30:33]
	v_mfma_f32_16x16x32_bf16 v[10:13], v[228:231], v[240:243], v[10:13]
	v_mfma_f32_16x16x32_bf16 v[14:17], v[228:231], v[252:255], v[14:17]
	s_waitcnt lgkmcnt(0)
	s_barrier
	global_load_dwordx4 v[122:125], v[70:71], off offset:1408
	global_load_dwordx4 v[126:129], v[68:69], off offset:1408
	global_load_dwordx4 v[136:139], v[66:67], off offset:1408
	global_load_dwordx4 v[140:143], v[72:73], off offset:1408
	global_load_dwordx4 v[144:147], v[74:75], off offset:1408
	global_load_dwordx4 v[148:151], v[76:77], off offset:1408
	global_load_dwordx4 v[172:175], v[78:79], off offset:1408
	global_load_dwordx4 v[176:179], v[80:81], off offset:1408
	ds_read_b128 v[232:235], v245 offset:55296
	ds_read_b128 v[216:219], v244 offset:18432
	ds_read_b128 v[236:239], v245 offset:57600
	ds_read_b128 v[240:243], v245 offset:59904
	ds_read_b128 v[252:255], v245 offset:62208
	ds_read_b128 v[220:223], v244 offset:20736
	ds_read_b128 v[224:227], v244 offset:23040
	ds_read_b128 v[228:231], v244 offset:25344
	s_waitcnt lgkmcnt(6)
	v_mfma_f32_16x16x32_bf16 v[50:53], v[216:219], v[232:235], v[50:53]
	s_waitcnt lgkmcnt(5)
	v_mfma_f32_16x16x32_bf16 v[54:57], v[216:219], v[236:239], v[54:57]
	s_waitcnt lgkmcnt(4)
	v_mfma_f32_16x16x32_bf16 v[34:37], v[216:219], v[240:243], v[34:37]
	s_waitcnt lgkmcnt(3)
	v_mfma_f32_16x16x32_bf16 v[38:41], v[216:219], v[252:255], v[38:41]
	ds_read_b128 v[216:219], v244 offset:18496
	s_waitcnt lgkmcnt(3)
	v_mfma_f32_16x16x32_bf16 v[58:61], v[220:223], v[232:235], v[58:61]
	v_mfma_f32_16x16x32_bf16 v[62:65], v[220:223], v[236:239], v[62:65]
	v_mfma_f32_16x16x32_bf16 v[42:45], v[220:223], v[240:243], v[42:45]
	v_mfma_f32_16x16x32_bf16 v[46:49], v[220:223], v[252:255], v[46:49]
	ds_read_b128 v[220:223], v244 offset:20800
	s_waitcnt vmcnt(15)
	ds_write_b128 v164, v[180:183]
	s_waitcnt vmcnt(14)
	ds_write_b128 v164, v[188:191] offset:4608
	s_waitcnt lgkmcnt(5)
	v_mfma_f32_16x16x32_bf16 v[18:21], v[224:227], v[232:235], v[18:21]
	v_mfma_f32_16x16x32_bf16 v[22:25], v[224:227], v[236:239], v[22:25]
	v_mfma_f32_16x16x32_bf16 v[2:5], v[224:227], v[240:243], v[2:5]
	v_mfma_f32_16x16x32_bf16 v[6:9], v[224:227], v[252:255], v[6:9]
	ds_read_b128 v[224:227], v244 offset:23104
	s_waitcnt vmcnt(13)
	ds_write_b128 v164, v[192:195] offset:9216
	s_waitcnt vmcnt(12)
	ds_write_b128 v164, v[196:199] offset:13824
	s_waitcnt lgkmcnt(7)
	v_mfma_f32_16x16x32_bf16 v[26:29], v[228:231], v[232:235], v[26:29]
	ds_read_b128 v[232:235], v245 offset:55360
	v_mfma_f32_16x16x32_bf16 v[30:33], v[228:231], v[236:239], v[30:33]
	ds_read_b128 v[236:239], v245 offset:57664
	v_mfma_f32_16x16x32_bf16 v[10:13], v[228:231], v[240:243], v[10:13]
	ds_read_b128 v[240:243], v245 offset:59968
	v_mfma_f32_16x16x32_bf16 v[14:17], v[228:231], v[252:255], v[14:17]
	ds_read_b128 v[252:255], v245 offset:62272
	ds_read_b128 v[228:231], v244 offset:25408
	s_waitcnt lgkmcnt(4)
	v_mfma_f32_16x16x32_bf16 v[50:53], v[216:219], v[232:235], v[50:53]
	s_waitcnt lgkmcnt(3)
	v_mfma_f32_16x16x32_bf16 v[54:57], v[216:219], v[236:239], v[54:57]
	s_waitcnt lgkmcnt(2)
	v_mfma_f32_16x16x32_bf16 v[34:37], v[216:219], v[240:243], v[34:37]
	s_waitcnt lgkmcnt(1)
	v_mfma_f32_16x16x32_bf16 v[38:41], v[216:219], v[252:255], v[38:41]
	s_waitcnt vmcnt(11)
	ds_write_b128 v164, v[200:203] offset:36864
	s_waitcnt vmcnt(10)
	ds_write_b128 v164, v[204:207] offset:41472
	v_mfma_f32_16x16x32_bf16 v[58:61], v[220:223], v[232:235], v[58:61]
	v_mfma_f32_16x16x32_bf16 v[62:65], v[220:223], v[236:239], v[62:65]
	v_mfma_f32_16x16x32_bf16 v[42:45], v[220:223], v[240:243], v[42:45]
	v_mfma_f32_16x16x32_bf16 v[46:49], v[220:223], v[252:255], v[46:49]
	s_waitcnt vmcnt(9)
	ds_write_b128 v164, v[208:211] offset:46080
	s_waitcnt vmcnt(8)
	ds_write_b128 v164, v[212:215] offset:50688
	v_mfma_f32_16x16x32_bf16 v[18:21], v[224:227], v[232:235], v[18:21]
	v_mfma_f32_16x16x32_bf16 v[22:25], v[224:227], v[236:239], v[22:25]
	v_mfma_f32_16x16x32_bf16 v[2:5], v[224:227], v[240:243], v[2:5]
	v_mfma_f32_16x16x32_bf16 v[6:9], v[224:227], v[252:255], v[6:9]
	s_waitcnt lgkmcnt(4)
	v_mfma_f32_16x16x32_bf16 v[26:29], v[228:231], v[232:235], v[26:29]
	v_mfma_f32_16x16x32_bf16 v[30:33], v[228:231], v[236:239], v[30:33]
	v_mfma_f32_16x16x32_bf16 v[10:13], v[228:231], v[240:243], v[10:13]
	v_mfma_f32_16x16x32_bf16 v[14:17], v[228:231], v[252:255], v[14:17]
	s_waitcnt lgkmcnt(0)
	s_barrier
	global_load_dwordx4 v[180:183], v[70:71], off offset:1536
	global_load_dwordx4 v[188:191], v[68:69], off offset:1536
	global_load_dwordx4 v[192:195], v[66:67], off offset:1536
	global_load_dwordx4 v[196:199], v[72:73], off offset:1536
	global_load_dwordx4 v[200:203], v[74:75], off offset:1536
	global_load_dwordx4 v[204:207], v[76:77], off offset:1536
	global_load_dwordx4 v[208:211], v[78:79], off offset:1536
	global_load_dwordx4 v[212:215], v[80:81], off offset:1536
	ds_read_b128 v[232:235], v245 offset:36864
	ds_read_b128 v[216:219], v244
	ds_read_b128 v[236:239], v245 offset:39168
	ds_read_b128 v[240:243], v245 offset:41472
	ds_read_b128 v[252:255], v245 offset:43776
	ds_read_b128 v[220:223], v244 offset:2304
	ds_read_b128 v[224:227], v244 offset:4608
	ds_read_b128 v[228:231], v244 offset:6912
	s_waitcnt lgkmcnt(6)
	v_mfma_f32_16x16x32_bf16 v[50:53], v[216:219], v[232:235], v[50:53]
	s_waitcnt lgkmcnt(5)
	v_mfma_f32_16x16x32_bf16 v[54:57], v[216:219], v[236:239], v[54:57]
	s_waitcnt lgkmcnt(4)
	v_mfma_f32_16x16x32_bf16 v[34:37], v[216:219], v[240:243], v[34:37]
	s_waitcnt lgkmcnt(3)
	v_mfma_f32_16x16x32_bf16 v[38:41], v[216:219], v[252:255], v[38:41]
	ds_read_b128 v[216:219], v244 offset:64
	s_waitcnt lgkmcnt(3)
	v_mfma_f32_16x16x32_bf16 v[58:61], v[220:223], v[232:235], v[58:61]
	v_mfma_f32_16x16x32_bf16 v[62:65], v[220:223], v[236:239], v[62:65]
	v_mfma_f32_16x16x32_bf16 v[42:45], v[220:223], v[240:243], v[42:45]
	v_mfma_f32_16x16x32_bf16 v[46:49], v[220:223], v[252:255], v[46:49]
	ds_read_b128 v[220:223], v244 offset:2368
	s_waitcnt vmcnt(15)
	ds_write_b128 v164, v[122:125] offset:18432
	s_waitcnt vmcnt(14)
	ds_write_b128 v164, v[126:129] offset:23040
	s_waitcnt lgkmcnt(5)
	v_mfma_f32_16x16x32_bf16 v[18:21], v[224:227], v[232:235], v[18:21]
	v_mfma_f32_16x16x32_bf16 v[22:25], v[224:227], v[236:239], v[22:25]
	v_mfma_f32_16x16x32_bf16 v[2:5], v[224:227], v[240:243], v[2:5]
	v_mfma_f32_16x16x32_bf16 v[6:9], v[224:227], v[252:255], v[6:9]
	ds_read_b128 v[224:227], v244 offset:4672
	s_waitcnt vmcnt(13)
	ds_write_b128 v164, v[136:139] offset:27648
	s_waitcnt vmcnt(12)
	ds_write_b128 v164, v[140:143] offset:32256
	s_waitcnt lgkmcnt(7)
	v_mfma_f32_16x16x32_bf16 v[26:29], v[228:231], v[232:235], v[26:29]
	ds_read_b128 v[232:235], v245 offset:36928
	v_mfma_f32_16x16x32_bf16 v[30:33], v[228:231], v[236:239], v[30:33]
	ds_read_b128 v[236:239], v245 offset:39232
	v_mfma_f32_16x16x32_bf16 v[10:13], v[228:231], v[240:243], v[10:13]
	ds_read_b128 v[240:243], v245 offset:41536
	v_mfma_f32_16x16x32_bf16 v[14:17], v[228:231], v[252:255], v[14:17]
	ds_read_b128 v[252:255], v245 offset:43840
	ds_read_b128 v[228:231], v244 offset:6976
	s_waitcnt lgkmcnt(4)
	v_mfma_f32_16x16x32_bf16 v[50:53], v[216:219], v[232:235], v[50:53]
	s_waitcnt lgkmcnt(3)
	v_mfma_f32_16x16x32_bf16 v[54:57], v[216:219], v[236:239], v[54:57]
	s_waitcnt lgkmcnt(2)
	v_mfma_f32_16x16x32_bf16 v[34:37], v[216:219], v[240:243], v[34:37]
	s_waitcnt lgkmcnt(1)
	v_mfma_f32_16x16x32_bf16 v[38:41], v[216:219], v[252:255], v[38:41]
	s_waitcnt vmcnt(11)
	ds_write_b128 v164, v[144:147] offset:55296
	s_waitcnt vmcnt(10)
	ds_write_b128 v164, v[148:151] offset:59904
	v_mfma_f32_16x16x32_bf16 v[58:61], v[220:223], v[232:235], v[58:61]
	v_mfma_f32_16x16x32_bf16 v[62:65], v[220:223], v[236:239], v[62:65]
	v_mfma_f32_16x16x32_bf16 v[42:45], v[220:223], v[240:243], v[42:45]
	v_mfma_f32_16x16x32_bf16 v[46:49], v[220:223], v[252:255], v[46:49]
	s_waitcnt vmcnt(9)
	ds_write_b128 v164, v[172:175] offset:64512
	s_waitcnt vmcnt(8)
	ds_write_b128 v165, v[176:179] offset:32256
	v_mfma_f32_16x16x32_bf16 v[18:21], v[224:227], v[232:235], v[18:21]
	v_mfma_f32_16x16x32_bf16 v[22:25], v[224:227], v[236:239], v[22:25]
	v_mfma_f32_16x16x32_bf16 v[2:5], v[224:227], v[240:243], v[2:5]
	v_mfma_f32_16x16x32_bf16 v[6:9], v[224:227], v[252:255], v[6:9]
	s_waitcnt lgkmcnt(4)
	v_mfma_f32_16x16x32_bf16 v[26:29], v[228:231], v[232:235], v[26:29]
	v_mfma_f32_16x16x32_bf16 v[30:33], v[228:231], v[236:239], v[30:33]
	v_mfma_f32_16x16x32_bf16 v[10:13], v[228:231], v[240:243], v[10:13]
	v_mfma_f32_16x16x32_bf16 v[14:17], v[228:231], v[252:255], v[14:17]
	s_waitcnt lgkmcnt(0)
	s_barrier
	global_load_dwordx4 v[122:125], v[70:71], off offset:1664
	global_load_dwordx4 v[126:129], v[68:69], off offset:1664
	global_load_dwordx4 v[136:139], v[66:67], off offset:1664
	global_load_dwordx4 v[140:143], v[72:73], off offset:1664
	global_load_dwordx4 v[144:147], v[74:75], off offset:1664
	global_load_dwordx4 v[148:151], v[76:77], off offset:1664
	global_load_dwordx4 v[172:175], v[78:79], off offset:1664
	global_load_dwordx4 v[176:179], v[80:81], off offset:1664
	ds_read_b128 v[232:235], v245 offset:55296
	ds_read_b128 v[216:219], v244 offset:18432
	ds_read_b128 v[236:239], v245 offset:57600
	ds_read_b128 v[240:243], v245 offset:59904
	ds_read_b128 v[252:255], v245 offset:62208
	ds_read_b128 v[220:223], v244 offset:20736
	ds_read_b128 v[224:227], v244 offset:23040
	ds_read_b128 v[228:231], v244 offset:25344
	s_waitcnt lgkmcnt(6)
	v_mfma_f32_16x16x32_bf16 v[50:53], v[216:219], v[232:235], v[50:53]
	s_waitcnt lgkmcnt(5)
	v_mfma_f32_16x16x32_bf16 v[54:57], v[216:219], v[236:239], v[54:57]
	s_waitcnt lgkmcnt(4)
	v_mfma_f32_16x16x32_bf16 v[34:37], v[216:219], v[240:243], v[34:37]
	s_waitcnt lgkmcnt(3)
	v_mfma_f32_16x16x32_bf16 v[38:41], v[216:219], v[252:255], v[38:41]
	ds_read_b128 v[216:219], v244 offset:18496
	s_waitcnt lgkmcnt(3)
	v_mfma_f32_16x16x32_bf16 v[58:61], v[220:223], v[232:235], v[58:61]
	v_mfma_f32_16x16x32_bf16 v[62:65], v[220:223], v[236:239], v[62:65]
	v_mfma_f32_16x16x32_bf16 v[42:45], v[220:223], v[240:243], v[42:45]
	v_mfma_f32_16x16x32_bf16 v[46:49], v[220:223], v[252:255], v[46:49]
	ds_read_b128 v[220:223], v244 offset:20800
	s_waitcnt vmcnt(15)
	ds_write_b128 v164, v[180:183]
	s_waitcnt vmcnt(14)
	ds_write_b128 v164, v[188:191] offset:4608
	s_waitcnt lgkmcnt(5)
	v_mfma_f32_16x16x32_bf16 v[18:21], v[224:227], v[232:235], v[18:21]
	v_mfma_f32_16x16x32_bf16 v[22:25], v[224:227], v[236:239], v[22:25]
	v_mfma_f32_16x16x32_bf16 v[2:5], v[224:227], v[240:243], v[2:5]
	v_mfma_f32_16x16x32_bf16 v[6:9], v[224:227], v[252:255], v[6:9]
	ds_read_b128 v[224:227], v244 offset:23104
	s_waitcnt vmcnt(13)
	ds_write_b128 v164, v[192:195] offset:9216
	s_waitcnt vmcnt(12)
	ds_write_b128 v164, v[196:199] offset:13824
	s_waitcnt lgkmcnt(7)
	v_mfma_f32_16x16x32_bf16 v[26:29], v[228:231], v[232:235], v[26:29]
	ds_read_b128 v[232:235], v245 offset:55360
	v_mfma_f32_16x16x32_bf16 v[30:33], v[228:231], v[236:239], v[30:33]
	ds_read_b128 v[236:239], v245 offset:57664
	v_mfma_f32_16x16x32_bf16 v[10:13], v[228:231], v[240:243], v[10:13]
	ds_read_b128 v[240:243], v245 offset:59968
	v_mfma_f32_16x16x32_bf16 v[14:17], v[228:231], v[252:255], v[14:17]
	ds_read_b128 v[252:255], v245 offset:62272
	ds_read_b128 v[228:231], v244 offset:25408
	s_waitcnt lgkmcnt(4)
	v_mfma_f32_16x16x32_bf16 v[50:53], v[216:219], v[232:235], v[50:53]
	s_waitcnt lgkmcnt(3)
	v_mfma_f32_16x16x32_bf16 v[54:57], v[216:219], v[236:239], v[54:57]
	s_waitcnt lgkmcnt(2)
	v_mfma_f32_16x16x32_bf16 v[34:37], v[216:219], v[240:243], v[34:37]
	s_waitcnt lgkmcnt(1)
	v_mfma_f32_16x16x32_bf16 v[38:41], v[216:219], v[252:255], v[38:41]
	s_waitcnt vmcnt(11)
	ds_write_b128 v164, v[200:203] offset:36864
	s_waitcnt vmcnt(10)
	ds_write_b128 v164, v[204:207] offset:41472
	v_mfma_f32_16x16x32_bf16 v[58:61], v[220:223], v[232:235], v[58:61]
	v_mfma_f32_16x16x32_bf16 v[62:65], v[220:223], v[236:239], v[62:65]
	v_mfma_f32_16x16x32_bf16 v[42:45], v[220:223], v[240:243], v[42:45]
	v_mfma_f32_16x16x32_bf16 v[46:49], v[220:223], v[252:255], v[46:49]
	s_waitcnt vmcnt(9)
	ds_write_b128 v164, v[208:211] offset:46080
	s_waitcnt vmcnt(8)
	ds_write_b128 v164, v[212:215] offset:50688
	v_mfma_f32_16x16x32_bf16 v[18:21], v[224:227], v[232:235], v[18:21]
	v_mfma_f32_16x16x32_bf16 v[22:25], v[224:227], v[236:239], v[22:25]
	v_mfma_f32_16x16x32_bf16 v[2:5], v[224:227], v[240:243], v[2:5]
	v_mfma_f32_16x16x32_bf16 v[6:9], v[224:227], v[252:255], v[6:9]
	s_waitcnt lgkmcnt(4)
	v_mfma_f32_16x16x32_bf16 v[26:29], v[228:231], v[232:235], v[26:29]
	v_mfma_f32_16x16x32_bf16 v[30:33], v[228:231], v[236:239], v[30:33]
	v_mfma_f32_16x16x32_bf16 v[10:13], v[228:231], v[240:243], v[10:13]
	v_mfma_f32_16x16x32_bf16 v[14:17], v[228:231], v[252:255], v[14:17]
	s_waitcnt lgkmcnt(0)
	s_barrier
	global_load_dwordx4 v[180:183], v[70:71], off offset:1792
	global_load_dwordx4 v[188:191], v[68:69], off offset:1792
	global_load_dwordx4 v[192:195], v[66:67], off offset:1792
	global_load_dwordx4 v[196:199], v[72:73], off offset:1792
	global_load_dwordx4 v[200:203], v[74:75], off offset:1792
	global_load_dwordx4 v[204:207], v[76:77], off offset:1792
	global_load_dwordx4 v[208:211], v[78:79], off offset:1792
	global_load_dwordx4 v[212:215], v[80:81], off offset:1792
	ds_read_b128 v[232:235], v245 offset:36864
	ds_read_b128 v[216:219], v244
	ds_read_b128 v[236:239], v245 offset:39168
	ds_read_b128 v[240:243], v245 offset:41472
	ds_read_b128 v[252:255], v245 offset:43776
	ds_read_b128 v[220:223], v244 offset:2304
	ds_read_b128 v[224:227], v244 offset:4608
	ds_read_b128 v[228:231], v244 offset:6912
	s_waitcnt lgkmcnt(6)
	v_mfma_f32_16x16x32_bf16 v[50:53], v[216:219], v[232:235], v[50:53]
	s_waitcnt lgkmcnt(5)
	v_mfma_f32_16x16x32_bf16 v[54:57], v[216:219], v[236:239], v[54:57]
	s_waitcnt lgkmcnt(4)
	v_mfma_f32_16x16x32_bf16 v[34:37], v[216:219], v[240:243], v[34:37]
	s_waitcnt lgkmcnt(3)
	v_mfma_f32_16x16x32_bf16 v[38:41], v[216:219], v[252:255], v[38:41]
	ds_read_b128 v[216:219], v244 offset:64
	s_waitcnt lgkmcnt(3)
	v_mfma_f32_16x16x32_bf16 v[58:61], v[220:223], v[232:235], v[58:61]
	v_mfma_f32_16x16x32_bf16 v[62:65], v[220:223], v[236:239], v[62:65]
	v_mfma_f32_16x16x32_bf16 v[42:45], v[220:223], v[240:243], v[42:45]
	v_mfma_f32_16x16x32_bf16 v[46:49], v[220:223], v[252:255], v[46:49]
	ds_read_b128 v[220:223], v244 offset:2368
	s_waitcnt vmcnt(15)
	ds_write_b128 v164, v[122:125] offset:18432
	s_waitcnt vmcnt(14)
	ds_write_b128 v164, v[126:129] offset:23040
	s_waitcnt lgkmcnt(5)
	v_mfma_f32_16x16x32_bf16 v[18:21], v[224:227], v[232:235], v[18:21]
	v_mfma_f32_16x16x32_bf16 v[22:25], v[224:227], v[236:239], v[22:25]
	v_mfma_f32_16x16x32_bf16 v[2:5], v[224:227], v[240:243], v[2:5]
	v_mfma_f32_16x16x32_bf16 v[6:9], v[224:227], v[252:255], v[6:9]
	ds_read_b128 v[224:227], v244 offset:4672
	s_waitcnt vmcnt(13)
	ds_write_b128 v164, v[136:139] offset:27648
	s_waitcnt vmcnt(12)
	ds_write_b128 v164, v[140:143] offset:32256
	s_waitcnt lgkmcnt(7)
	v_mfma_f32_16x16x32_bf16 v[26:29], v[228:231], v[232:235], v[26:29]
	ds_read_b128 v[232:235], v245 offset:36928
	v_mfma_f32_16x16x32_bf16 v[30:33], v[228:231], v[236:239], v[30:33]
	ds_read_b128 v[236:239], v245 offset:39232
	v_mfma_f32_16x16x32_bf16 v[10:13], v[228:231], v[240:243], v[10:13]
	ds_read_b128 v[240:243], v245 offset:41536
	v_mfma_f32_16x16x32_bf16 v[14:17], v[228:231], v[252:255], v[14:17]
	ds_read_b128 v[252:255], v245 offset:43840
	ds_read_b128 v[228:231], v244 offset:6976
	s_waitcnt lgkmcnt(4)
	v_mfma_f32_16x16x32_bf16 v[50:53], v[216:219], v[232:235], v[50:53]
	s_waitcnt lgkmcnt(3)
	v_mfma_f32_16x16x32_bf16 v[54:57], v[216:219], v[236:239], v[54:57]
	s_waitcnt lgkmcnt(2)
	v_mfma_f32_16x16x32_bf16 v[34:37], v[216:219], v[240:243], v[34:37]
	s_waitcnt lgkmcnt(1)
	v_mfma_f32_16x16x32_bf16 v[38:41], v[216:219], v[252:255], v[38:41]
	s_waitcnt vmcnt(11)
	ds_write_b128 v164, v[144:147] offset:55296
	s_waitcnt vmcnt(10)
	ds_write_b128 v164, v[148:151] offset:59904
	v_mfma_f32_16x16x32_bf16 v[58:61], v[220:223], v[232:235], v[58:61]
	v_mfma_f32_16x16x32_bf16 v[62:65], v[220:223], v[236:239], v[62:65]
	v_mfma_f32_16x16x32_bf16 v[42:45], v[220:223], v[240:243], v[42:45]
	v_mfma_f32_16x16x32_bf16 v[46:49], v[220:223], v[252:255], v[46:49]
	s_waitcnt vmcnt(9)
	ds_write_b128 v164, v[172:175] offset:64512
	s_waitcnt vmcnt(8)
	ds_write_b128 v165, v[176:179] offset:32256
	v_mfma_f32_16x16x32_bf16 v[18:21], v[224:227], v[232:235], v[18:21]
	v_mfma_f32_16x16x32_bf16 v[22:25], v[224:227], v[236:239], v[22:25]
	v_mfma_f32_16x16x32_bf16 v[2:5], v[224:227], v[240:243], v[2:5]
	v_mfma_f32_16x16x32_bf16 v[6:9], v[224:227], v[252:255], v[6:9]
	s_waitcnt lgkmcnt(4)
	v_mfma_f32_16x16x32_bf16 v[26:29], v[228:231], v[232:235], v[26:29]
	v_mfma_f32_16x16x32_bf16 v[30:33], v[228:231], v[236:239], v[30:33]
	v_mfma_f32_16x16x32_bf16 v[10:13], v[228:231], v[240:243], v[10:13]
	v_mfma_f32_16x16x32_bf16 v[14:17], v[228:231], v[252:255], v[14:17]
	s_waitcnt lgkmcnt(0)
	s_barrier
	global_load_dwordx4 v[122:125], v[70:71], off offset:1920
	s_nop 0
	global_load_dwordx4 v[68:71], v[68:69], off offset:1920
	s_nop 0
	global_load_dwordx4 v[126:129], v[66:67], off offset:1920
	global_load_dwordx4 v[136:139], v[72:73], off offset:1920
	s_nop 0
	global_load_dwordx4 v[72:75], v[74:75], off offset:1920
	s_nop 0
	global_load_dwordx4 v[140:143], v[76:77], off offset:1920
	s_nop 0
	global_load_dwordx4 v[76:79], v[78:79], off offset:1920
	s_nop 0
	global_load_dwordx4 v[144:147], v[80:81], off offset:1920
	ds_read_b128 v[232:235], v245 offset:55296
	ds_read_b128 v[216:219], v244 offset:18432
	ds_read_b128 v[236:239], v245 offset:57600
	ds_read_b128 v[240:243], v245 offset:59904
	ds_read_b128 v[252:255], v245 offset:62208
	ds_read_b128 v[220:223], v244 offset:20736
	ds_read_b128 v[224:227], v244 offset:23040
	ds_read_b128 v[228:231], v244 offset:25344
	s_waitcnt lgkmcnt(6)
	v_mfma_f32_16x16x32_bf16 v[50:53], v[216:219], v[232:235], v[50:53]
	s_waitcnt lgkmcnt(5)
	v_mfma_f32_16x16x32_bf16 v[54:57], v[216:219], v[236:239], v[54:57]
	s_waitcnt lgkmcnt(4)
	v_mfma_f32_16x16x32_bf16 v[34:37], v[216:219], v[240:243], v[34:37]
	s_waitcnt lgkmcnt(3)
	v_mfma_f32_16x16x32_bf16 v[38:41], v[216:219], v[252:255], v[38:41]
	ds_read_b128 v[216:219], v244 offset:18496
	s_waitcnt lgkmcnt(3)
	v_mfma_f32_16x16x32_bf16 v[58:61], v[220:223], v[232:235], v[58:61]
	v_mfma_f32_16x16x32_bf16 v[62:65], v[220:223], v[236:239], v[62:65]
	v_mfma_f32_16x16x32_bf16 v[42:45], v[220:223], v[240:243], v[42:45]
	v_mfma_f32_16x16x32_bf16 v[46:49], v[220:223], v[252:255], v[46:49]
	ds_read_b128 v[220:223], v244 offset:20800
	s_waitcnt vmcnt(15)
	ds_write_b128 v164, v[180:183]
	s_waitcnt vmcnt(14)
	ds_write_b128 v164, v[188:191] offset:4608
	s_waitcnt lgkmcnt(5)
	v_mfma_f32_16x16x32_bf16 v[18:21], v[224:227], v[232:235], v[18:21]
	v_mfma_f32_16x16x32_bf16 v[22:25], v[224:227], v[236:239], v[22:25]
	v_mfma_f32_16x16x32_bf16 v[2:5], v[224:227], v[240:243], v[2:5]
	v_mfma_f32_16x16x32_bf16 v[6:9], v[224:227], v[252:255], v[6:9]
	ds_read_b128 v[224:227], v244 offset:23104
	s_waitcnt vmcnt(13)
	ds_write_b128 v164, v[192:195] offset:9216
	s_waitcnt vmcnt(12)
	ds_write_b128 v164, v[196:199] offset:13824
	s_waitcnt lgkmcnt(7)
	v_mfma_f32_16x16x32_bf16 v[26:29], v[228:231], v[232:235], v[26:29]
	ds_read_b128 v[232:235], v245 offset:55360
	v_mfma_f32_16x16x32_bf16 v[30:33], v[228:231], v[236:239], v[30:33]
	ds_read_b128 v[236:239], v245 offset:57664
	v_mfma_f32_16x16x32_bf16 v[10:13], v[228:231], v[240:243], v[10:13]
	ds_read_b128 v[240:243], v245 offset:59968
	v_mfma_f32_16x16x32_bf16 v[14:17], v[228:231], v[252:255], v[14:17]
	ds_read_b128 v[252:255], v245 offset:62272
	ds_read_b128 v[228:231], v244 offset:25408
	s_waitcnt lgkmcnt(4)
	v_mfma_f32_16x16x32_bf16 v[50:53], v[216:219], v[232:235], v[50:53]
	s_waitcnt lgkmcnt(3)
	v_mfma_f32_16x16x32_bf16 v[54:57], v[216:219], v[236:239], v[54:57]
	s_waitcnt lgkmcnt(2)
	v_mfma_f32_16x16x32_bf16 v[34:37], v[216:219], v[240:243], v[34:37]
	s_waitcnt lgkmcnt(1)
	v_mfma_f32_16x16x32_bf16 v[38:41], v[216:219], v[252:255], v[38:41]
	s_waitcnt vmcnt(11)
	ds_write_b128 v164, v[200:203] offset:36864
	s_waitcnt vmcnt(10)
	ds_write_b128 v164, v[204:207] offset:41472
	v_mfma_f32_16x16x32_bf16 v[58:61], v[220:223], v[232:235], v[58:61]
	v_mfma_f32_16x16x32_bf16 v[62:65], v[220:223], v[236:239], v[62:65]
	v_mfma_f32_16x16x32_bf16 v[42:45], v[220:223], v[240:243], v[42:45]
	v_mfma_f32_16x16x32_bf16 v[46:49], v[220:223], v[252:255], v[46:49]
	s_waitcnt vmcnt(9)
	ds_write_b128 v164, v[208:211] offset:46080
	s_waitcnt vmcnt(8)
	ds_write_b128 v164, v[212:215] offset:50688
	v_mfma_f32_16x16x32_bf16 v[18:21], v[224:227], v[232:235], v[18:21]
	v_mfma_f32_16x16x32_bf16 v[22:25], v[224:227], v[236:239], v[22:25]
	v_mfma_f32_16x16x32_bf16 v[2:5], v[224:227], v[240:243], v[2:5]
	v_mfma_f32_16x16x32_bf16 v[6:9], v[224:227], v[252:255], v[6:9]
	s_waitcnt lgkmcnt(4)
	v_mfma_f32_16x16x32_bf16 v[26:29], v[228:231], v[232:235], v[26:29]
	v_mfma_f32_16x16x32_bf16 v[30:33], v[228:231], v[236:239], v[30:33]
	v_mfma_f32_16x16x32_bf16 v[10:13], v[228:231], v[240:243], v[10:13]
	v_mfma_f32_16x16x32_bf16 v[14:17], v[228:231], v[252:255], v[14:17]
	s_waitcnt lgkmcnt(0)
	s_barrier
	ds_read_b128 v[232:235], v245 offset:36864
	ds_read_b128 v[216:219], v244
	ds_read_b128 v[236:239], v245 offset:39168
	ds_read_b128 v[240:243], v245 offset:41472
	ds_read_b128 v[252:255], v245 offset:43776
	ds_read_b128 v[220:223], v244 offset:2304
	ds_read_b128 v[224:227], v244 offset:4608
	ds_read_b128 v[228:231], v244 offset:6912
	s_waitcnt lgkmcnt(6)
	v_mfma_f32_16x16x32_bf16 v[50:53], v[216:219], v[232:235], v[50:53]
	s_waitcnt lgkmcnt(5)
	v_mfma_f32_16x16x32_bf16 v[54:57], v[216:219], v[236:239], v[54:57]
	s_waitcnt lgkmcnt(4)
	v_mfma_f32_16x16x32_bf16 v[34:37], v[216:219], v[240:243], v[34:37]
	s_waitcnt lgkmcnt(3)
	v_mfma_f32_16x16x32_bf16 v[38:41], v[216:219], v[252:255], v[38:41]
	ds_read_b128 v[216:219], v244 offset:64
	s_waitcnt lgkmcnt(3)
	v_mfma_f32_16x16x32_bf16 v[58:61], v[220:223], v[232:235], v[58:61]
	v_mfma_f32_16x16x32_bf16 v[62:65], v[220:223], v[236:239], v[62:65]
	v_mfma_f32_16x16x32_bf16 v[42:45], v[220:223], v[240:243], v[42:45]
	v_mfma_f32_16x16x32_bf16 v[46:49], v[220:223], v[252:255], v[46:49]
	ds_read_b128 v[220:223], v244 offset:2368
	s_waitcnt vmcnt(7)
	ds_write_b128 v164, v[122:125] offset:18432
	s_waitcnt vmcnt(6)
	ds_write_b128 v164, v[68:71] offset:23040
	s_waitcnt lgkmcnt(5)
	v_mfma_f32_16x16x32_bf16 v[18:21], v[224:227], v[232:235], v[18:21]
	v_mfma_f32_16x16x32_bf16 v[22:25], v[224:227], v[236:239], v[22:25]
	v_mfma_f32_16x16x32_bf16 v[2:5], v[224:227], v[240:243], v[2:5]
	v_mfma_f32_16x16x32_bf16 v[6:9], v[224:227], v[252:255], v[6:9]
	ds_read_b128 v[224:227], v244 offset:4672
	s_waitcnt vmcnt(5)
	ds_write_b128 v164, v[126:129] offset:27648
	s_waitcnt vmcnt(4)
	ds_write_b128 v164, v[136:139] offset:32256
	s_waitcnt lgkmcnt(7)
	v_mfma_f32_16x16x32_bf16 v[26:29], v[228:231], v[232:235], v[26:29]
	ds_read_b128 v[232:235], v245 offset:36928
	v_mfma_f32_16x16x32_bf16 v[30:33], v[228:231], v[236:239], v[30:33]
	ds_read_b128 v[236:239], v245 offset:39232
	v_mfma_f32_16x16x32_bf16 v[10:13], v[228:231], v[240:243], v[10:13]
	ds_read_b128 v[240:243], v245 offset:41536
	v_mfma_f32_16x16x32_bf16 v[14:17], v[228:231], v[252:255], v[14:17]
	ds_read_b128 v[252:255], v245 offset:43840
	ds_read_b128 v[228:231], v244 offset:6976
	s_waitcnt lgkmcnt(4)
	v_mfma_f32_16x16x32_bf16 v[50:53], v[216:219], v[232:235], v[50:53]
	s_waitcnt lgkmcnt(3)
	v_mfma_f32_16x16x32_bf16 v[54:57], v[216:219], v[236:239], v[54:57]
	s_waitcnt lgkmcnt(2)
	v_mfma_f32_16x16x32_bf16 v[34:37], v[216:219], v[240:243], v[34:37]
	s_waitcnt lgkmcnt(1)
	v_mfma_f32_16x16x32_bf16 v[38:41], v[216:219], v[252:255], v[38:41]
	s_waitcnt vmcnt(3)
	ds_write_b128 v164, v[72:75] offset:55296
	s_waitcnt vmcnt(2)
	ds_write_b128 v164, v[140:143] offset:59904
	v_mfma_f32_16x16x32_bf16 v[58:61], v[220:223], v[232:235], v[58:61]
	v_mfma_f32_16x16x32_bf16 v[62:65], v[220:223], v[236:239], v[62:65]
	v_mfma_f32_16x16x32_bf16 v[42:45], v[220:223], v[240:243], v[42:45]
	v_mfma_f32_16x16x32_bf16 v[46:49], v[220:223], v[252:255], v[46:49]
	s_waitcnt vmcnt(1)
	ds_write_b128 v164, v[76:79] offset:64512
	s_waitcnt vmcnt(0)
	ds_write_b128 v165, v[144:147] offset:32256
	v_mfma_f32_16x16x32_bf16 v[18:21], v[224:227], v[232:235], v[18:21]
	v_mfma_f32_16x16x32_bf16 v[22:25], v[224:227], v[236:239], v[22:25]
	v_mfma_f32_16x16x32_bf16 v[2:5], v[224:227], v[240:243], v[2:5]
	v_mfma_f32_16x16x32_bf16 v[6:9], v[224:227], v[252:255], v[6:9]
	s_waitcnt lgkmcnt(4)
	v_mfma_f32_16x16x32_bf16 v[26:29], v[228:231], v[232:235], v[26:29]
	v_mfma_f32_16x16x32_bf16 v[30:33], v[228:231], v[236:239], v[30:33]
	v_mfma_f32_16x16x32_bf16 v[10:13], v[228:231], v[240:243], v[10:13]
	v_mfma_f32_16x16x32_bf16 v[14:17], v[228:231], v[252:255], v[14:17]
	s_waitcnt lgkmcnt(0)
	s_barrier
	ds_read_b128 v[232:235], v245 offset:55296
	ds_read_b128 v[216:219], v244 offset:18432
	ds_read_b128 v[236:239], v245 offset:57600
	ds_read_b128 v[240:243], v245 offset:59904
	ds_read_b128 v[252:255], v245 offset:62208
	ds_read_b128 v[220:223], v244 offset:20736
	ds_read_b128 v[224:227], v244 offset:23040
	ds_read_b128 v[228:231], v244 offset:25344
	s_waitcnt lgkmcnt(6)
	v_mfma_f32_16x16x32_bf16 v[50:53], v[216:219], v[232:235], v[50:53]
	s_waitcnt lgkmcnt(5)
	v_mfma_f32_16x16x32_bf16 v[54:57], v[216:219], v[236:239], v[54:57]
	s_waitcnt lgkmcnt(4)
	v_mfma_f32_16x16x32_bf16 v[34:37], v[216:219], v[240:243], v[34:37]
	s_waitcnt lgkmcnt(3)
	v_mfma_f32_16x16x32_bf16 v[38:41], v[216:219], v[252:255], v[38:41]
	ds_read_b128 v[216:219], v244 offset:18496
	s_waitcnt lgkmcnt(3)
	v_mfma_f32_16x16x32_bf16 v[58:61], v[220:223], v[232:235], v[58:61]
	v_mfma_f32_16x16x32_bf16 v[62:65], v[220:223], v[236:239], v[62:65]
	v_mfma_f32_16x16x32_bf16 v[42:45], v[220:223], v[240:243], v[42:45]
	v_mfma_f32_16x16x32_bf16 v[46:49], v[220:223], v[252:255], v[46:49]
	ds_read_b128 v[220:223], v244 offset:20800
	s_waitcnt lgkmcnt(3)
	v_mfma_f32_16x16x32_bf16 v[18:21], v[224:227], v[232:235], v[18:21]
	v_mfma_f32_16x16x32_bf16 v[22:25], v[224:227], v[236:239], v[22:25]
	v_mfma_f32_16x16x32_bf16 v[2:5], v[224:227], v[240:243], v[2:5]
	v_mfma_f32_16x16x32_bf16 v[6:9], v[224:227], v[252:255], v[6:9]
	ds_read_b128 v[224:227], v244 offset:23104
	s_waitcnt lgkmcnt(3)
	v_mfma_f32_16x16x32_bf16 v[26:29], v[228:231], v[232:235], v[26:29]
	ds_read_b128 v[232:235], v245 offset:55360
	v_mfma_f32_16x16x32_bf16 v[30:33], v[228:231], v[236:239], v[30:33]
	ds_read_b128 v[236:239], v245 offset:57664
	v_mfma_f32_16x16x32_bf16 v[10:13], v[228:231], v[240:243], v[10:13]
	ds_read_b128 v[240:243], v245 offset:59968
	v_mfma_f32_16x16x32_bf16 v[14:17], v[228:231], v[252:255], v[14:17]
	ds_read_b128 v[252:255], v245 offset:62272
	ds_read_b128 v[228:231], v244 offset:25408
	s_waitcnt lgkmcnt(4)
	v_mfma_f32_16x16x32_bf16 v[50:53], v[216:219], v[232:235], v[50:53]
	s_waitcnt lgkmcnt(3)
	v_mfma_f32_16x16x32_bf16 v[54:57], v[216:219], v[236:239], v[54:57]
	s_waitcnt lgkmcnt(2)
	v_mfma_f32_16x16x32_bf16 v[34:37], v[216:219], v[240:243], v[34:37]
	s_waitcnt lgkmcnt(1)
	v_mfma_f32_16x16x32_bf16 v[38:41], v[216:219], v[252:255], v[38:41]
	v_mfma_f32_16x16x32_bf16 v[58:61], v[220:223], v[232:235], v[58:61]
	v_mfma_f32_16x16x32_bf16 v[62:65], v[220:223], v[236:239], v[62:65]
	v_mfma_f32_16x16x32_bf16 v[42:45], v[220:223], v[240:243], v[42:45]
	v_mfma_f32_16x16x32_bf16 v[46:49], v[220:223], v[252:255], v[46:49]
	v_mfma_f32_16x16x32_bf16 v[18:21], v[224:227], v[232:235], v[18:21]
	v_mfma_f32_16x16x32_bf16 v[22:25], v[224:227], v[236:239], v[22:25]
	v_mfma_f32_16x16x32_bf16 v[2:5], v[224:227], v[240:243], v[2:5]
	v_mfma_f32_16x16x32_bf16 v[6:9], v[224:227], v[252:255], v[6:9]
	s_waitcnt lgkmcnt(0)
	v_mfma_f32_16x16x32_bf16 v[26:29], v[228:231], v[232:235], v[26:29]
	v_mfma_f32_16x16x32_bf16 v[30:33], v[228:231], v[236:239], v[30:33]
	v_mfma_f32_16x16x32_bf16 v[10:13], v[228:231], v[240:243], v[10:13]
	v_mfma_f32_16x16x32_bf16 v[14:17], v[228:231], v[252:255], v[14:17]
	s_waitcnt lgkmcnt(0)
	s_barrier
	s_nop 7
	v_permlane16_swap_b32_e32 v50, v54
	v_permlane16_swap_b32_e32 v51, v55
	v_permlane16_swap_b32_e32 v52, v56
	v_permlane16_swap_b32_e32 v53, v57
	v_permlane16_swap_b32_e32 v58, v62
	v_permlane16_swap_b32_e32 v59, v63
	v_permlane16_swap_b32_e32 v60, v64
	v_permlane16_swap_b32_e32 v61, v65
	v_permlane16_swap_b32_e32 v34, v38
	v_permlane16_swap_b32_e32 v35, v39
	v_permlane16_swap_b32_e32 v36, v40
	v_permlane16_swap_b32_e32 v37, v41
	v_permlane16_swap_b32_e32 v42, v46
	v_permlane16_swap_b32_e32 v43, v47
	v_permlane16_swap_b32_e32 v44, v48
	v_permlane16_swap_b32_e32 v45, v49
	v_permlane16_swap_b32_e32 v18, v22
	v_permlane16_swap_b32_e32 v19, v23
	v_permlane16_swap_b32_e32 v20, v24
	v_permlane16_swap_b32_e32 v21, v25
	v_permlane16_swap_b32_e32 v26, v30
	v_permlane16_swap_b32_e32 v27, v31
	v_permlane16_swap_b32_e32 v28, v32
	v_permlane16_swap_b32_e32 v29, v33
	v_permlane16_swap_b32_e32 v2, v6
	v_permlane16_swap_b32_e32 v3, v7
	v_permlane16_swap_b32_e32 v4, v8
	v_permlane16_swap_b32_e32 v5, v9
	v_permlane16_swap_b32_e32 v10, v14
	v_permlane16_swap_b32_e32 v11, v15
	v_permlane16_swap_b32_e32 v12, v16
	v_permlane16_swap_b32_e32 v13, v17
	v_permlane32_swap_b32_e32 v50, v54
	v_permlane32_swap_b32_e32 v51, v55
	v_permlane32_swap_b32_e32 v52, v56
	v_permlane32_swap_b32_e32 v53, v57
	v_permlane32_swap_b32_e32 v58, v62
	v_permlane32_swap_b32_e32 v59, v63
	v_permlane32_swap_b32_e32 v60, v64
	v_permlane32_swap_b32_e32 v61, v65
	v_permlane32_swap_b32_e32 v34, v38
	v_permlane32_swap_b32_e32 v35, v39
	v_permlane32_swap_b32_e32 v36, v40
	v_permlane32_swap_b32_e32 v37, v41
	v_permlane32_swap_b32_e32 v42, v46
	v_permlane32_swap_b32_e32 v43, v47
	v_permlane32_swap_b32_e32 v44, v48
	v_permlane32_swap_b32_e32 v45, v49
	v_permlane32_swap_b32_e32 v18, v22
	v_permlane32_swap_b32_e32 v19, v23
	v_permlane32_swap_b32_e32 v20, v24
	v_permlane32_swap_b32_e32 v21, v25
	v_permlane32_swap_b32_e32 v26, v30
	v_permlane32_swap_b32_e32 v27, v31
	v_permlane32_swap_b32_e32 v28, v32
	v_permlane32_swap_b32_e32 v29, v33
	v_permlane32_swap_b32_e32 v2, v6
	v_permlane32_swap_b32_e32 v3, v7
	v_permlane32_swap_b32_e32 v4, v8
	v_permlane32_swap_b32_e32 v5, v9
	v_permlane32_swap_b32_e32 v10, v14
	v_permlane32_swap_b32_e32 v11, v15
	v_permlane32_swap_b32_e32 v12, v16
	v_permlane32_swap_b32_e32 v13, v17
